# GEMM MMA blocks: double-snake MFMA order (each MFMA shares its accumulator or one source with the previous one; K-halves of alternate accumulators issued in reverse order)
# speedup vs baseline: 1.0110x; 1.0014x over previous
; #define PG8_STAGE(bufoff, gbase, voff) do { _Pragma("unroll") for (int _i = 0; _i < 2; ++_i) \
;         __builtin_amdgcn_global_load_lds((const unsigned*)((const char*)(gbase) + (voff)[_i]), (LAS unsigned*)(lds + (bufoff) + ldsw + _i * 8192), 16, 0, 0); } while (0)
; #define PG8_LDA(dst, b, h) do { _Pragma("unroll") for (int m = 0; m < 4; ++m) _Pragma("unroll") for (int k = 0; k < 2; ++k) dst[m][k] = *(const LAS bf16x8*)(lds + PG8_SA(b, h) + aoff + m * 2048 + k * 1024); } while (0)
; #define PG8_LDB(dst, b, h) do { _Pragma("unroll") for (int n = 0; n < 2; ++n) _Pragma("unroll") for (int k = 0; k < 2; ++k) dst[n][k] = *(const LAS bf16x8*)(lds + PG8_SB(b, h) + boff + n * 2048 + k * 1024); } while (0)
; #define PG8_MMA(ai, bj, At, Bt) do { __builtin_amdgcn_s_setprio(1); _Pragma("unroll") for (int m = 0; m < 4; ++m) _Pragma("unroll") for (int n = 0; n < 2; ++n) _Pragma("unroll") for (int k = 0; k < 2; ++k) \
;         acc[ai][bj][m][n] = __builtin_amdgcn_mfma_f32_16x16x32_bf16(Bt[n][k], At[m][k], acc[ai][bj][m][n], 0, 0, 0); __builtin_amdgcn_s_setprio(0); } while (0)
; #define PG8_WAIT_L(n) asm volatile("s_waitcnt lgkmcnt(" #n ")" ::: "memory")
; #define PG8_BAR __builtin_amdgcn_s_barrier()
; #define PG8_SCHED __builtin_amdgcn_sched_barrier(0)
; template <class Epi>
; DEVINL void gemm_phase(LAS unsigned char* lds, const Gemm g, const Order& S, const Epi& E) {
;     ...
;             PG8_LDB(B0, 0, 0); PG8_SCHED; PG8_LDA(At, 0, 0); PG8_STAGE(PG8_SA(1, 1), a1 + hstepA, voffA);
;             PG8_WAIT_L(8); PG8_BAR; PG8_WAIT_L(0); PG8_MMA(0, 0, At, B0); PG8_BAR; PG8_SCHED;
;             PG8_LDB(B1, 0, 1); PG8_STAGE(PG8_SB(0, 0), b2, voffB);
;             PG8_BAR; PG8_WAIT_L(0); PG8_MMA(0, 1, At, B1); PG8_BAR;
;             PG8_LDA(At, 0, 1); PG8_STAGE(PG8_SA(0, 0), a2, voffA);
;             PG8_BAR; PG8_WAIT_L(0); PG8_MMA(1, 0, At, B0); PG8_BAR; PG8_SCHED;
.LBB0_340:
	ds_read_b128 v[152:155], v149
	ds_read_b128 v[156:159], v149 offset:1024
	ds_read_b128 v[160:163], v149 offset:2048
	ds_read_b128 v[164:167], v149 offset:3072
	s_add_i32 s93, s10, 2
	s_add_u32 s2, s12, 0xfff80080
	s_addc_u32 s3, s13, -1
	s_cmp_eq_u32 s76, s10
	s_cselect_b32 s10, s85, s86
	s_cselect_b32 s15, s17, s3
	s_cselect_b32 s14, s61, s2
	s_cselect_b32 s11, s84, s87
	v_lshl_add_u64 v[144:145], s[12:13], 0, v[136:137]
	s_add_i32 m0, s67, 0xc000
	ds_read_b128 v[168:171], v150
	ds_read_b128 v[172:175], v150 offset:1024
	ds_read_b128 v[176:179], v150 offset:2048
	ds_read_b128 v[180:183], v150 offset:3072
	ds_read_b128 v[184:187], v150 offset:4096
	ds_read_b128 v[188:191], v150 offset:5120
	ds_read_b128 v[192:195], v150 offset:6144
	ds_read_b128 v[196:199], v150 offset:7168
	global_load_lds_dwordx4 v[144:145], off
	v_lshl_add_u64 v[144:145], s[12:13], 0, v[138:139]
	s_add_i32 m0, s67, 0xe000
	s_nop 0
	global_load_lds_dwordx4 v[144:145], off
	s_waitcnt lgkmcnt(8)
	s_barrier
	s_waitcnt lgkmcnt(0)
	s_setprio 1
	s_waitcnt lgkmcnt(0)
	v_mfma_f32_16x16x32_bf16 v[124:127], v[152:155], v[168:171], v[124:127]
	v_mfma_f32_16x16x32_bf16 v[124:127], v[156:159], v[172:175], v[124:127]
	v_mfma_f32_16x16x32_bf16 v[116:119], v[164:167], v[172:175], v[116:119]
	v_mfma_f32_16x16x32_bf16 v[116:119], v[160:163], v[168:171], v[116:119]
	v_mfma_f32_16x16x32_bf16 v[100:103], v[160:163], v[176:179], v[100:103]
	v_mfma_f32_16x16x32_bf16 v[100:103], v[164:167], v[180:183], v[100:103]
	v_mfma_f32_16x16x32_bf16 v[108:111], v[156:159], v[180:183], v[108:111]
	v_mfma_f32_16x16x32_bf16 v[108:111], v[152:155], v[176:179], v[108:111]
	v_mfma_f32_16x16x32_bf16 v[92:95], v[152:155], v[184:187], v[92:95]
	v_mfma_f32_16x16x32_bf16 v[92:95], v[156:159], v[188:191], v[92:95]
	v_mfma_f32_16x16x32_bf16 v[84:87], v[164:167], v[188:191], v[84:87]
	v_mfma_f32_16x16x32_bf16 v[84:87], v[160:163], v[184:187], v[84:87]
	v_mfma_f32_16x16x32_bf16 v[68:71], v[160:163], v[192:195], v[68:71]
	v_mfma_f32_16x16x32_bf16 v[68:71], v[164:167], v[196:199], v[68:71]
	v_mfma_f32_16x16x32_bf16 v[76:79], v[156:159], v[196:199], v[76:79]
	v_mfma_f32_16x16x32_bf16 v[76:79], v[152:155], v[192:195], v[76:79]
	s_setprio 0
	s_barrier
	s_add_i32 s2, s80, s38
	v_lshl_add_u64 v[144:145], s[10:11], 0, v[132:133]
	s_mov_b32 m0, s2
	ds_read_b128 v[200:203], v151
	ds_read_b128 v[204:207], v151 offset:1024
	ds_read_b128 v[208:211], v151 offset:2048
	ds_read_b128 v[218:221], v151 offset:3072
	global_load_lds_dwordx4 v[144:145], off
	v_lshl_add_u64 v[212:213], s[10:11], 0, v[128:129]
	s_add_i32 m0, s2, 0x2000
	s_nop 0
	global_load_lds_dwordx4 v[212:213], off
	s_barrier
	s_waitcnt lgkmcnt(0)
	s_setprio 1
	s_waitcnt lgkmcnt(0)
	v_mfma_f32_16x16x32_bf16 v[120:123], v[200:203], v[168:171], v[120:123]
	v_mfma_f32_16x16x32_bf16 v[120:123], v[204:207], v[172:175], v[120:123]
	v_mfma_f32_16x16x32_bf16 v[112:115], v[218:221], v[172:175], v[112:115]
	v_mfma_f32_16x16x32_bf16 v[112:115], v[208:211], v[168:171], v[112:115]
	v_mfma_f32_16x16x32_bf16 v[96:99], v[208:211], v[176:179], v[96:99]
	v_mfma_f32_16x16x32_bf16 v[96:99], v[218:221], v[180:183], v[96:99]
	v_mfma_f32_16x16x32_bf16 v[104:107], v[204:207], v[180:183], v[104:107]
	v_mfma_f32_16x16x32_bf16 v[104:107], v[200:203], v[176:179], v[104:107]
	v_mfma_f32_16x16x32_bf16 v[88:91], v[200:203], v[184:187], v[88:91]
	v_mfma_f32_16x16x32_bf16 v[88:91], v[204:207], v[188:191], v[88:91]
	v_mfma_f32_16x16x32_bf16 v[80:83], v[218:221], v[188:191], v[80:83]
	v_mfma_f32_16x16x32_bf16 v[80:83], v[208:211], v[184:187], v[80:83]
	v_mfma_f32_16x16x32_bf16 v[64:67], v[208:211], v[192:195], v[64:67]
	v_mfma_f32_16x16x32_bf16 v[64:67], v[218:221], v[196:199], v[64:67]
	v_mfma_f32_16x16x32_bf16 v[72:75], v[204:207], v[196:199], v[72:75]
	v_mfma_f32_16x16x32_bf16 v[72:75], v[200:203], v[192:195], v[72:75]
	s_setprio 0
	s_mov_b32 m0, s67
	v_lshl_add_u64 v[222:223], s[14:15], 0, v[134:135]
	s_barrier
	ds_read_b128 v[168:171], v150 offset:16384
	ds_read_b128 v[172:175], v150 offset:17408
	ds_read_b128 v[176:179], v150 offset:18432
	ds_read_b128 v[180:183], v150 offset:19456
	ds_read_b128 v[184:187], v150 offset:20480
	ds_read_b128 v[188:191], v150 offset:21504
	ds_read_b128 v[192:195], v150 offset:22528
	ds_read_b128 v[196:199], v150 offset:23552
	global_load_lds_dwordx4 v[222:223], off
	v_lshl_add_u64 v[224:225], s[14:15], 0, v[130:131]
	s_mov_b32 m0, s68
	s_nop 0
	global_load_lds_dwordx4 v[224:225], off
	s_barrier
	s_waitcnt lgkmcnt(0)
	s_setprio 1
	s_waitcnt lgkmcnt(0)
	v_mfma_f32_16x16x32_bf16 v[60:63], v[152:155], v[168:171], v[60:63]
	v_mfma_f32_16x16x32_bf16 v[60:63], v[156:159], v[172:175], v[60:63]
	v_mfma_f32_16x16x32_bf16 v[52:55], v[164:167], v[172:175], v[52:55]
	v_mfma_f32_16x16x32_bf16 v[52:55], v[160:163], v[168:171], v[52:55]
	v_mfma_f32_16x16x32_bf16 v[36:39], v[160:163], v[176:179], v[36:39]
	v_mfma_f32_16x16x32_bf16 v[36:39], v[164:167], v[180:183], v[36:39]
	v_mfma_f32_16x16x32_bf16 v[44:47], v[156:159], v[180:183], v[44:47]
	v_mfma_f32_16x16x32_bf16 v[44:47], v[152:155], v[176:179], v[44:47]
	v_mfma_f32_16x16x32_bf16 v[28:31], v[152:155], v[184:187], v[28:31]
	v_mfma_f32_16x16x32_bf16 v[28:31], v[156:159], v[188:191], v[28:31]
	v_mfma_f32_16x16x32_bf16 v[20:23], v[164:167], v[188:191], v[20:23]
	v_mfma_f32_16x16x32_bf16 v[20:23], v[160:163], v[184:187], v[20:23]
	v_mfma_f32_16x16x32_bf16 v[4:7], v[160:163], v[192:195], v[4:7]
	v_mfma_f32_16x16x32_bf16 v[4:7], v[164:167], v[196:199], v[4:7]
	v_mfma_f32_16x16x32_bf16 v[12:15], v[156:159], v[196:199], v[12:15]
	v_mfma_f32_16x16x32_bf16 v[12:15], v[152:155], v[192:195], v[12:15]
	s_setprio 0
	s_barrier
; #define PG8_STAGE(bufoff, gbase, voff) do { _Pragma("unroll") for (int _i = 0; _i < 2; ++_i) \
;         __builtin_amdgcn_global_load_lds((const unsigned*)((const char*)(gbase) + (voff)[_i]), (LAS unsigned*)(lds + (bufoff) + ldsw + _i * 8192), 16, 0, 0); } while (0)
; #define PG8_LDA(dst, b, h) do { _Pragma("unroll") for (int m = 0; m < 4; ++m) _Pragma("unroll") for (int k = 0; k < 2; ++k) dst[m][k] = *(const LAS bf16x8*)(lds + PG8_SA(b, h) + aoff + m * 2048 + k * 1024); } while (0)
; #define PG8_LDB(dst, b, h) do { _Pragma("unroll") for (int n = 0; n < 2; ++n) _Pragma("unroll") for (int k = 0; k < 2; ++k) dst[n][k] = *(const LAS bf16x8*)(lds + PG8_SB(b, h) + boff + n * 2048 + k * 1024); } while (0)
; #define PG8_MMA(ai, bj, At, Bt) do { __builtin_amdgcn_s_setprio(1); _Pragma("unroll") for (int m = 0; m < 4; ++m) _Pragma("unroll") for (int n = 0; n < 2; ++n) _Pragma("unroll") for (int k = 0; k < 2; ++k) \
;         acc[ai][bj][m][n] = __builtin_amdgcn_mfma_f32_16x16x32_bf16(Bt[n][k], At[m][k], acc[ai][bj][m][n], 0, 0, 0); __builtin_amdgcn_s_setprio(0); } while (0)
; #define PG8_WAIT_V(n) asm volatile("s_waitcnt vmcnt(" #n ")" ::: "memory")
; #define PG8_WAIT_L(n) asm volatile("s_waitcnt lgkmcnt(" #n ")" ::: "memory")
; #define PG8_BAR __builtin_amdgcn_s_barrier()
; #define PG8_SCHED __builtin_amdgcn_sched_barrier(0)
; template <class Epi>
; DEVINL void gemm_phase(LAS unsigned char* lds, const Gemm g, const Order& S, const Epi& E) {
;     ...
;             PG8_STAGE(PG8_SB(0, 1), b2 + hstepB, voffB);
;             PG8_WAIT_V(6); PG8_BAR; PG8_MMA(1, 1, At, B1); PG8_BAR;
;             PG8_LDB(B0, 1, 0); PG8_SCHED; PG8_LDA(At, 1, 0); PG8_STAGE(PG8_SA(0, 1), a2 + hstepA, voffA);
;             PG8_WAIT_L(8); PG8_BAR; PG8_WAIT_L(0); PG8_MMA(0, 0, At, B0); PG8_BAR; PG8_SCHED;
;             PG8_LDB(B1, 1, 1); PG8_STAGE(PG8_SB(1, 0), b3, voffB);
	s_add_u32 s96, s10, 0x80000
	s_addc_u32 s97, s11, 0
	s_add_i32 s2, s81, s38
	v_lshl_add_u64 v[152:153], s[96:97], 0, v[132:133]
	s_mov_b32 m0, s2
	s_nop 0
	global_load_lds_dwordx4 v[152:153], off
	v_lshl_add_u64 v[152:153], s[96:97], 0, v[128:129]
	s_add_i32 m0, s2, 0x2000
	s_nop 0
	global_load_lds_dwordx4 v[152:153], off
	s_waitcnt vmcnt(6)
	s_barrier
	s_setprio 1
	v_mfma_f32_16x16x32_bf16 v[56:59], v[200:203], v[168:171], v[56:59]
	v_mfma_f32_16x16x32_bf16 v[56:59], v[204:207], v[172:175], v[56:59]
	v_mfma_f32_16x16x32_bf16 v[48:51], v[218:221], v[172:175], v[48:51]
	v_mfma_f32_16x16x32_bf16 v[48:51], v[208:211], v[168:171], v[48:51]
	v_mfma_f32_16x16x32_bf16 v[32:35], v[208:211], v[176:179], v[32:35]
	v_mfma_f32_16x16x32_bf16 v[32:35], v[218:221], v[180:183], v[32:35]
	v_mfma_f32_16x16x32_bf16 v[40:43], v[204:207], v[180:183], v[40:43]
	v_mfma_f32_16x16x32_bf16 v[40:43], v[200:203], v[176:179], v[40:43]
	v_mfma_f32_16x16x32_bf16 v[24:27], v[200:203], v[184:187], v[24:27]
	v_mfma_f32_16x16x32_bf16 v[24:27], v[204:207], v[188:191], v[24:27]
	v_mfma_f32_16x16x32_bf16 v[16:19], v[218:221], v[188:191], v[16:19]
	v_mfma_f32_16x16x32_bf16 v[16:19], v[208:211], v[184:187], v[16:19]
	v_mfma_f32_16x16x32_bf16 v[0:3], v[208:211], v[192:195], v[0:3]
	v_mfma_f32_16x16x32_bf16 v[0:3], v[218:221], v[196:199], v[0:3]
	v_mfma_f32_16x16x32_bf16 v[8:11], v[204:207], v[196:199], v[8:11]
	v_mfma_f32_16x16x32_bf16 v[8:11], v[200:203], v[192:195], v[8:11]
	s_setprio 0
	s_add_i32 s2, 16, 0x18000
	v_add_u32_e32 v164, s2, v147
	s_barrier
	ds_read_b128 v[152:155], v164
	ds_read_b128 v[156:159], v164 offset:1024
	ds_read_b128 v[160:163], v164 offset:2048
	ds_read_b128 v[164:167], v164 offset:3072
	s_add_u32 s14, s14, 0x80000
	s_addc_u32 s15, s15, 0
	s_mov_b32 m0, s69
	v_lshl_add_u64 v[200:201], s[14:15], 0, v[134:135]
	ds_read_b128 v[168:171], v150 offset:32768
	ds_read_b128 v[172:175], v150 offset:33792
	ds_read_b128 v[176:179], v150 offset:34816
	ds_read_b128 v[180:183], v150 offset:35840
	ds_read_b128 v[184:187], v150 offset:36864
	ds_read_b128 v[188:191], v150 offset:37888
	ds_read_b128 v[192:195], v150 offset:38912
	ds_read_b128 v[196:199], v150 offset:39936
	global_load_lds_dwordx4 v[200:201], off
	v_lshl_add_u64 v[200:201], s[14:15], 0, v[130:131]
	s_mov_b32 m0, s72
	s_nop 0
	global_load_lds_dwordx4 v[200:201], off
	s_waitcnt lgkmcnt(8)
	s_barrier
	s_waitcnt lgkmcnt(0)
	s_setprio 1
	s_waitcnt lgkmcnt(0)
	v_mfma_f32_16x16x32_bf16 v[124:127], v[152:155], v[168:171], v[124:127]
	v_mfma_f32_16x16x32_bf16 v[124:127], v[156:159], v[172:175], v[124:127]
	v_mfma_f32_16x16x32_bf16 v[116:119], v[164:167], v[172:175], v[116:119]
	v_mfma_f32_16x16x32_bf16 v[116:119], v[160:163], v[168:171], v[116:119]
	v_mfma_f32_16x16x32_bf16 v[100:103], v[160:163], v[176:179], v[100:103]
	v_mfma_f32_16x16x32_bf16 v[100:103], v[164:167], v[180:183], v[100:103]
	v_mfma_f32_16x16x32_bf16 v[108:111], v[156:159], v[180:183], v[108:111]
	v_mfma_f32_16x16x32_bf16 v[108:111], v[152:155], v[176:179], v[108:111]
	v_mfma_f32_16x16x32_bf16 v[92:95], v[152:155], v[184:187], v[92:95]
	v_mfma_f32_16x16x32_bf16 v[92:95], v[156:159], v[188:191], v[92:95]
	v_mfma_f32_16x16x32_bf16 v[84:87], v[164:167], v[188:191], v[84:87]
	v_mfma_f32_16x16x32_bf16 v[84:87], v[160:163], v[184:187], v[84:87]
	v_mfma_f32_16x16x32_bf16 v[68:71], v[160:163], v[192:195], v[68:71]
	v_mfma_f32_16x16x32_bf16 v[68:71], v[164:167], v[196:199], v[68:71]
	v_mfma_f32_16x16x32_bf16 v[76:79], v[156:159], v[196:199], v[76:79]
	v_mfma_f32_16x16x32_bf16 v[76:79], v[152:155], v[192:195], v[76:79]
	s_setprio 0
	s_barrier
	s_add_i32 s3, 16, 0x1c000
	s_add_i32 s2, s2, s38
	v_add_u32_e32 v214, s3, v147
	v_lshl_add_u64 v[144:145], v[144:145], 0, s[6:7]
	s_mov_b32 m0, s2
	ds_read_b128 v[200:203], v214
	ds_read_b128 v[204:207], v214 offset:1024
	ds_read_b128 v[208:211], v214 offset:2048
	ds_read_b128 v[218:221], v214 offset:3072
	global_load_lds_dwordx4 v[144:145], off
	v_lshl_add_u64 v[144:145], v[212:213], 0, s[6:7]
	s_add_i32 m0, s2, 0x2000
	s_nop 0
	global_load_lds_dwordx4 v[144:145], off
	s_barrier
; #define PG8_STAGE(bufoff, gbase, voff) do { _Pragma("unroll") for (int _i = 0; _i < 2; ++_i) \
;         __builtin_amdgcn_global_load_lds((const unsigned*)((const char*)(gbase) + (voff)[_i]), (LAS unsigned*)(lds + (bufoff) + ldsw + _i * 8192), 16, 0, 0); } while (0)
; #define PG8_LDA(dst, b, h) do { _Pragma("unroll") for (int m = 0; m < 4; ++m) _Pragma("unroll") for (int k = 0; k < 2; ++k) dst[m][k] = *(const LAS bf16x8*)(lds + PG8_SA(b, h) + aoff + m * 2048 + k * 1024); } while (0)
; #define PG8_MMA(ai, bj, At, Bt) do { __builtin_amdgcn_s_setprio(1); _Pragma("unroll") for (int m = 0; m < 4; ++m) _Pragma("unroll") for (int n = 0; n < 2; ++n) _Pragma("unroll") for (int k = 0; k < 2; ++k) \
;         acc[ai][bj][m][n] = __builtin_amdgcn_mfma_f32_16x16x32_bf16(Bt[n][k], At[m][k], acc[ai][bj][m][n], 0, 0, 0); __builtin_amdgcn_s_setprio(0); } while (0)
; #define PG8_WAIT_V(n) asm volatile("s_waitcnt vmcnt(" #n ")" ::: "memory")
; #define PG8_WAIT_L(n) asm volatile("s_waitcnt lgkmcnt(" #n ")" ::: "memory")
; #define PG8_BAR __builtin_amdgcn_s_barrier()
; #define PG8_SCHED __builtin_amdgcn_sched_barrier(0)
; template <class Epi>
; DEVINL void gemm_phase(LAS unsigned char* lds, const Gemm g, const Order& S, const Epi& E) {
;     ...
;             PG8_BAR; PG8_WAIT_L(0); PG8_MMA(0, 1, At, B1); PG8_BAR;
;             PG8_LDA(At, 1, 1); PG8_STAGE(PG8_SA(1, 0), a3, voffA);
;             PG8_BAR; PG8_WAIT_L(0); PG8_MMA(1, 0, At, B0); PG8_BAR; PG8_SCHED;
;             PG8_STAGE(PG8_SB(1, 1), b3 + hstepB, voffB);
;             PG8_WAIT_V(6); PG8_BAR; PG8_MMA(1, 1, At, B1); PG8_BAR;
;         }
	s_waitcnt lgkmcnt(0)
	s_setprio 1
	s_waitcnt lgkmcnt(0)
	v_mfma_f32_16x16x32_bf16 v[120:123], v[200:203], v[168:171], v[120:123]
	v_mfma_f32_16x16x32_bf16 v[120:123], v[204:207], v[172:175], v[120:123]
	v_mfma_f32_16x16x32_bf16 v[112:115], v[218:221], v[172:175], v[112:115]
	v_mfma_f32_16x16x32_bf16 v[112:115], v[208:211], v[168:171], v[112:115]
	v_mfma_f32_16x16x32_bf16 v[96:99], v[208:211], v[176:179], v[96:99]
	v_mfma_f32_16x16x32_bf16 v[96:99], v[218:221], v[180:183], v[96:99]
	v_mfma_f32_16x16x32_bf16 v[104:107], v[204:207], v[180:183], v[104:107]
	v_mfma_f32_16x16x32_bf16 v[104:107], v[200:203], v[176:179], v[104:107]
	v_mfma_f32_16x16x32_bf16 v[88:91], v[200:203], v[184:187], v[88:91]
	v_mfma_f32_16x16x32_bf16 v[88:91], v[204:207], v[188:191], v[88:91]
	v_mfma_f32_16x16x32_bf16 v[80:83], v[218:221], v[188:191], v[80:83]
	v_mfma_f32_16x16x32_bf16 v[80:83], v[208:211], v[184:187], v[80:83]
	v_mfma_f32_16x16x32_bf16 v[64:67], v[208:211], v[192:195], v[64:67]
	v_mfma_f32_16x16x32_bf16 v[64:67], v[218:221], v[196:199], v[64:67]
	v_mfma_f32_16x16x32_bf16 v[72:75], v[204:207], v[196:199], v[72:75]
	v_mfma_f32_16x16x32_bf16 v[72:75], v[200:203], v[192:195], v[72:75]
	s_setprio 0
	s_mov_b32 m0, s74
	v_lshl_add_u64 v[144:145], v[222:223], 0, s[6:7]
	s_barrier
	ds_read_b128 v[168:171], v150 offset:49152
	ds_read_b128 v[172:175], v150 offset:50176
	ds_read_b128 v[176:179], v150 offset:51200
	ds_read_b128 v[180:183], v150 offset:52224
	ds_read_b128 v[184:187], v150 offset:53248
	ds_read_b128 v[188:191], v150 offset:54272
	ds_read_b128 v[192:195], v150 offset:55296
	ds_read_b128 v[196:199], v150 offset:56320
	global_load_lds_dwordx4 v[144:145], off
	v_lshl_add_u64 v[144:145], v[224:225], 0, s[6:7]
	s_mov_b32 m0, s75
	s_nop 0
	global_load_lds_dwordx4 v[144:145], off
	s_barrier
	s_waitcnt lgkmcnt(0)
	s_setprio 1
	s_waitcnt lgkmcnt(0)
	v_mfma_f32_16x16x32_bf16 v[60:63], v[152:155], v[168:171], v[60:63]
	v_mfma_f32_16x16x32_bf16 v[60:63], v[156:159], v[172:175], v[60:63]
	v_mfma_f32_16x16x32_bf16 v[52:55], v[164:167], v[172:175], v[52:55]
	v_mfma_f32_16x16x32_bf16 v[52:55], v[160:163], v[168:171], v[52:55]
	v_mfma_f32_16x16x32_bf16 v[36:39], v[160:163], v[176:179], v[36:39]
	v_mfma_f32_16x16x32_bf16 v[36:39], v[164:167], v[180:183], v[36:39]
	v_mfma_f32_16x16x32_bf16 v[44:47], v[156:159], v[180:183], v[44:47]
	v_mfma_f32_16x16x32_bf16 v[44:47], v[152:155], v[176:179], v[44:47]
	v_mfma_f32_16x16x32_bf16 v[28:31], v[152:155], v[184:187], v[28:31]
	v_mfma_f32_16x16x32_bf16 v[28:31], v[156:159], v[188:191], v[28:31]
	v_mfma_f32_16x16x32_bf16 v[20:23], v[164:167], v[188:191], v[20:23]
	v_mfma_f32_16x16x32_bf16 v[20:23], v[160:163], v[184:187], v[20:23]
	v_mfma_f32_16x16x32_bf16 v[4:7], v[160:163], v[192:195], v[4:7]
	v_mfma_f32_16x16x32_bf16 v[4:7], v[164:167], v[196:199], v[4:7]
	v_mfma_f32_16x16x32_bf16 v[12:15], v[156:159], v[196:199], v[12:15]
	v_mfma_f32_16x16x32_bf16 v[12:15], v[152:155], v[192:195], v[12:15]
	s_setprio 0
	s_barrier
	s_add_u32 s10, s10, 0x80080
	s_addc_u32 s11, s11, 0
	s_add_i32 s2, s3, s38
	v_lshl_add_u64 v[144:145], s[10:11], 0, v[132:133]
	s_mov_b32 m0, s2
	s_nop 0
	global_load_lds_dwordx4 v[144:145], off
	v_lshl_add_u64 v[144:145], s[10:11], 0, v[128:129]
	s_add_i32 m0, s2, 0x2000
	s_nop 0
	global_load_lds_dwordx4 v[144:145], off
	s_waitcnt vmcnt(6)
	s_barrier
	s_setprio 1
	v_mfma_f32_16x16x32_bf16 v[56:59], v[200:203], v[168:171], v[56:59]
	v_mfma_f32_16x16x32_bf16 v[56:59], v[204:207], v[172:175], v[56:59]
	v_mfma_f32_16x16x32_bf16 v[48:51], v[218:221], v[172:175], v[48:51]
	v_mfma_f32_16x16x32_bf16 v[48:51], v[208:211], v[168:171], v[48:51]
	v_mfma_f32_16x16x32_bf16 v[32:35], v[208:211], v[176:179], v[32:35]
	v_mfma_f32_16x16x32_bf16 v[32:35], v[218:221], v[180:183], v[32:35]
	v_mfma_f32_16x16x32_bf16 v[40:43], v[204:207], v[180:183], v[40:43]
	v_mfma_f32_16x16x32_bf16 v[40:43], v[200:203], v[176:179], v[40:43]
	v_mfma_f32_16x16x32_bf16 v[24:27], v[200:203], v[184:187], v[24:27]
	v_mfma_f32_16x16x32_bf16 v[24:27], v[204:207], v[188:191], v[24:27]
	v_mfma_f32_16x16x32_bf16 v[16:19], v[218:221], v[188:191], v[16:19]
	v_mfma_f32_16x16x32_bf16 v[16:19], v[208:211], v[184:187], v[16:19]
	v_mfma_f32_16x16x32_bf16 v[0:3], v[208:211], v[192:195], v[0:3]
	v_mfma_f32_16x16x32_bf16 v[0:3], v[218:221], v[196:199], v[0:3]
	v_mfma_f32_16x16x32_bf16 v[8:11], v[204:207], v[196:199], v[8:11]
	v_mfma_f32_16x16x32_bf16 v[8:11], v[200:203], v[192:195], v[8:11]
	s_setprio 0
	s_add_u32 s12, s12, 0x100
	s_addc_u32 s13, s13, 0
	s_add_u32 s86, s86, 0x100
	s_addc_u32 s87, s87, 0
	s_cmp_ge_i32 s93, s73
	s_mov_b32 s10, s93
	s_barrier
	s_cbranch_scc0 .LBB0_340
	s_branch .LBB0_335

; #define PG8_STAGE(bufoff, gbase, voff) do { _Pragma("unroll") for (int _i = 0; _i < 2; ++_i) \
;         __builtin_amdgcn_global_load_lds((const unsigned*)((const char*)(gbase) + (voff)[_i]), (LAS unsigned*)(lds + (bufoff) + ldsw + _i * 8192), 16, 0, 0); } while (0)
; #define PG8_LDA(dst, b, h) do { _Pragma("unroll") for (int m = 0; m < 4; ++m) _Pragma("unroll") for (int k = 0; k < 2; ++k) dst[m][k] = *(const LAS bf16x8*)(lds + PG8_SA(b, h) + aoff + m * 2048 + k * 1024); } while (0)
; #define PG8_LDB(dst, b, h) do { _Pragma("unroll") for (int n = 0; n < 2; ++n) _Pragma("unroll") for (int k = 0; k < 2; ++k) dst[n][k] = *(const LAS bf16x8*)(lds + PG8_SB(b, h) + boff + n * 2048 + k * 1024); } while (0)
; #define PG8_MMA(ai, bj, At, Bt) do { __builtin_amdgcn_s_setprio(1); _Pragma("unroll") for (int m = 0; m < 4; ++m) _Pragma("unroll") for (int n = 0; n < 2; ++n) _Pragma("unroll") for (int k = 0; k < 2; ++k) \
;         acc[ai][bj][m][n] = __builtin_amdgcn_mfma_f32_16x16x32_bf16(Bt[n][k], At[m][k], acc[ai][bj][m][n], 0, 0, 0); __builtin_amdgcn_s_setprio(0); } while (0)
; #define PG8_WAIT_L(n) asm volatile("s_waitcnt lgkmcnt(" #n ")" ::: "memory")
; #define PG8_BAR __builtin_amdgcn_s_barrier()
; #define PG8_SCHED __builtin_amdgcn_sched_barrier(0)
; template <class Epi>
; DEVINL void gemm_phase(LAS unsigned char* lds, const Gemm g, const Order& S, const Epi& E) {
;     ...
;             const char* a1 = cA + (size_t)(t + 1) * kstep;
;             const char* a2 = last ? nA : cA + (size_t)(t + 2) * kstep; const char* b2 = last ? nB : cB + (size_t)(t + 2) * kstep;
;             const char* a3 = a2 + kstep; const char* b3 = b2 + kstep;
;             PG8_LDB(B0, 0, 0); PG8_SCHED; PG8_LDA(At, 0, 0); PG8_STAGE(PG8_SA(1, 1), a1 + hstepA, voffA);
;             PG8_WAIT_L(8); PG8_BAR; PG8_WAIT_L(0); PG8_MMA(0, 0, At, B0); PG8_BAR; PG8_SCHED;
;             PG8_LDB(B1, 0, 1); PG8_STAGE(PG8_SB(0, 0), b2, voffB);
;             PG8_BAR; PG8_WAIT_L(0); PG8_MMA(0, 1, At, B1); PG8_BAR;
;             PG8_LDA(At, 0, 1); PG8_STAGE(PG8_SA(0, 0), a2, voffA);
;             PG8_BAR; PG8_WAIT_L(0); PG8_MMA(1, 0, At, B0); PG8_BAR; PG8_SCHED;
.LBB0_361:
	ds_read_b128 v[146:149], v143
	ds_read_b128 v[150:153], v143 offset:1024
	ds_read_b128 v[154:157], v143 offset:2048
	ds_read_b128 v[158:161], v143 offset:3072
	s_add_i32 s87, s10, 2
	s_add_u32 s2, s12, 0xfff80080
	s_addc_u32 s3, s13, -1
	s_cmp_eq_u32 s36, s10
	s_cselect_b32 s10, s84, s85
	s_cselect_b32 s15, s63, s3
	s_cselect_b32 s14, s65, s2
	s_cselect_b32 s11, s83, s86
	v_lshl_add_u64 v[194:195], s[12:13], 0, v[136:137]
	s_add_i32 m0, s5, 0xc000
	ds_read_b128 v[162:165], v144
	ds_read_b128 v[166:169], v144 offset:1024
	ds_read_b128 v[170:173], v144 offset:2048
	ds_read_b128 v[174:177], v144 offset:3072
	ds_read_b128 v[178:181], v144 offset:4096
	ds_read_b128 v[182:185], v144 offset:5120
	ds_read_b128 v[186:189], v144 offset:6144
	ds_read_b128 v[190:193], v144 offset:7168
	global_load_lds_dwordx4 v[194:195], off
	v_lshl_add_u64 v[194:195], s[12:13], 0, v[138:139]
	s_add_i32 m0, s5, 0xe000
	s_nop 0
	global_load_lds_dwordx4 v[194:195], off
	s_waitcnt lgkmcnt(8)
	s_barrier
	s_waitcnt lgkmcnt(0)
	s_setprio 1
	s_waitcnt lgkmcnt(0)
	v_mfma_f32_16x16x32_bf16 v[120:123], v[146:149], v[162:165], v[120:123]
	v_mfma_f32_16x16x32_bf16 v[120:123], v[150:153], v[166:169], v[120:123]
	v_mfma_f32_16x16x32_bf16 v[124:127], v[158:161], v[166:169], v[124:127]
	v_mfma_f32_16x16x32_bf16 v[124:127], v[154:157], v[162:165], v[124:127]
	v_mfma_f32_16x16x32_bf16 v[104:107], v[154:157], v[170:173], v[104:107]
	v_mfma_f32_16x16x32_bf16 v[104:107], v[158:161], v[174:177], v[104:107]
	v_mfma_f32_16x16x32_bf16 v[108:111], v[150:153], v[174:177], v[108:111]
	v_mfma_f32_16x16x32_bf16 v[108:111], v[146:149], v[170:173], v[108:111]
	v_mfma_f32_16x16x32_bf16 v[92:95], v[146:149], v[178:181], v[92:95]
	v_mfma_f32_16x16x32_bf16 v[92:95], v[150:153], v[182:185], v[92:95]
	v_mfma_f32_16x16x32_bf16 v[88:91], v[158:161], v[182:185], v[88:91]
	v_mfma_f32_16x16x32_bf16 v[88:91], v[154:157], v[178:181], v[88:91]
	v_mfma_f32_16x16x32_bf16 v[72:75], v[154:157], v[186:189], v[72:75]
	v_mfma_f32_16x16x32_bf16 v[72:75], v[158:161], v[190:193], v[72:75]
	v_mfma_f32_16x16x32_bf16 v[76:79], v[150:153], v[190:193], v[76:79]
	v_mfma_f32_16x16x32_bf16 v[76:79], v[146:149], v[186:189], v[76:79]
	s_setprio 0
	s_barrier
	s_add_i32 s2, s80, s68
	v_lshl_add_u64 v[210:211], s[10:11], 0, v[130:131]
	s_mov_b32 m0, s2
	ds_read_b128 v[194:197], v145
	ds_read_b128 v[198:201], v145 offset:1024
	ds_read_b128 v[202:205], v145 offset:2048
	ds_read_b128 v[206:209], v145 offset:3072
	global_load_lds_dwordx4 v[210:211], off
	v_lshl_add_u64 v[212:213], s[10:11], 0, v[134:135]
	s_add_i32 m0, s2, 0x2000
	s_nop 0
	global_load_lds_dwordx4 v[212:213], off
	s_barrier
	s_waitcnt lgkmcnt(0)
	s_setprio 1
	s_waitcnt lgkmcnt(0)
	v_mfma_f32_16x16x32_bf16 v[116:119], v[194:197], v[162:165], v[116:119]
	v_mfma_f32_16x16x32_bf16 v[116:119], v[198:201], v[166:169], v[116:119]
	v_mfma_f32_16x16x32_bf16 v[112:115], v[206:209], v[166:169], v[112:115]
	v_mfma_f32_16x16x32_bf16 v[112:115], v[202:205], v[162:165], v[112:115]
	v_mfma_f32_16x16x32_bf16 v[96:99], v[202:205], v[170:173], v[96:99]
	v_mfma_f32_16x16x32_bf16 v[96:99], v[206:209], v[174:177], v[96:99]
	v_mfma_f32_16x16x32_bf16 v[100:103], v[198:201], v[174:177], v[100:103]
	v_mfma_f32_16x16x32_bf16 v[100:103], v[194:197], v[170:173], v[100:103]
	v_mfma_f32_16x16x32_bf16 v[84:87], v[194:197], v[178:181], v[84:87]
	v_mfma_f32_16x16x32_bf16 v[84:87], v[198:201], v[182:185], v[84:87]
	v_mfma_f32_16x16x32_bf16 v[80:83], v[206:209], v[182:185], v[80:83]
	v_mfma_f32_16x16x32_bf16 v[80:83], v[202:205], v[178:181], v[80:83]
	v_mfma_f32_16x16x32_bf16 v[64:67], v[202:205], v[186:189], v[64:67]
	v_mfma_f32_16x16x32_bf16 v[64:67], v[206:209], v[190:193], v[64:67]
	v_mfma_f32_16x16x32_bf16 v[68:71], v[198:201], v[190:193], v[68:71]
	v_mfma_f32_16x16x32_bf16 v[68:71], v[194:197], v[186:189], v[68:71]
	s_setprio 0
	s_mov_b32 m0, s5
	v_lshl_add_u64 v[218:219], s[14:15], 0, v[128:129]
	s_barrier
	ds_read_b128 v[162:165], v144 offset:16384
	ds_read_b128 v[166:169], v144 offset:17408
	ds_read_b128 v[170:173], v144 offset:18432
	ds_read_b128 v[174:177], v144 offset:19456
	ds_read_b128 v[178:181], v144 offset:20480
	ds_read_b128 v[182:185], v144 offset:21504
	ds_read_b128 v[186:189], v144 offset:22528
	ds_read_b128 v[190:193], v144 offset:23552
	global_load_lds_dwordx4 v[218:219], off
	v_lshl_add_u64 v[220:221], s[14:15], 0, v[132:133]
	s_mov_b32 m0, s69
	s_nop 0
	global_load_lds_dwordx4 v[220:221], off
	s_barrier
	s_waitcnt lgkmcnt(0)
	s_setprio 1
	s_waitcnt lgkmcnt(0)
	v_mfma_f32_16x16x32_bf16 v[60:63], v[146:149], v[162:165], v[60:63]
	v_mfma_f32_16x16x32_bf16 v[60:63], v[150:153], v[166:169], v[60:63]
	v_mfma_f32_16x16x32_bf16 v[56:59], v[158:161], v[166:169], v[56:59]
	v_mfma_f32_16x16x32_bf16 v[56:59], v[154:157], v[162:165], v[56:59]
	v_mfma_f32_16x16x32_bf16 v[40:43], v[154:157], v[170:173], v[40:43]
	v_mfma_f32_16x16x32_bf16 v[40:43], v[158:161], v[174:177], v[40:43]
	v_mfma_f32_16x16x32_bf16 v[44:47], v[150:153], v[174:177], v[44:47]
	v_mfma_f32_16x16x32_bf16 v[44:47], v[146:149], v[170:173], v[44:47]
	v_mfma_f32_16x16x32_bf16 v[28:31], v[146:149], v[178:181], v[28:31]
	v_mfma_f32_16x16x32_bf16 v[28:31], v[150:153], v[182:185], v[28:31]
	v_mfma_f32_16x16x32_bf16 v[24:27], v[158:161], v[182:185], v[24:27]
	v_mfma_f32_16x16x32_bf16 v[24:27], v[154:157], v[178:181], v[24:27]
	v_mfma_f32_16x16x32_bf16 v[8:11], v[154:157], v[186:189], v[8:11]
	v_mfma_f32_16x16x32_bf16 v[8:11], v[158:161], v[190:193], v[8:11]
	v_mfma_f32_16x16x32_bf16 v[12:15], v[150:153], v[190:193], v[12:15]
	v_mfma_f32_16x16x32_bf16 v[12:15], v[146:149], v[186:189], v[12:15]
	s_setprio 0
	s_barrier
; #define PG8_STAGE(bufoff, gbase, voff) do { _Pragma("unroll") for (int _i = 0; _i < 2; ++_i) \
;         __builtin_amdgcn_global_load_lds((const unsigned*)((const char*)(gbase) + (voff)[_i]), (LAS unsigned*)(lds + (bufoff) + ldsw + _i * 8192), 16, 0, 0); } while (0)
; #define PG8_LDA(dst, b, h) do { _Pragma("unroll") for (int m = 0; m < 4; ++m) _Pragma("unroll") for (int k = 0; k < 2; ++k) dst[m][k] = *(const LAS bf16x8*)(lds + PG8_SA(b, h) + aoff + m * 2048 + k * 1024); } while (0)
; #define PG8_LDB(dst, b, h) do { _Pragma("unroll") for (int n = 0; n < 2; ++n) _Pragma("unroll") for (int k = 0; k < 2; ++k) dst[n][k] = *(const LAS bf16x8*)(lds + PG8_SB(b, h) + boff + n * 2048 + k * 1024); } while (0)
; #define PG8_MMA(ai, bj, At, Bt) do { __builtin_amdgcn_s_setprio(1); _Pragma("unroll") for (int m = 0; m < 4; ++m) _Pragma("unroll") for (int n = 0; n < 2; ++n) _Pragma("unroll") for (int k = 0; k < 2; ++k) \
;         acc[ai][bj][m][n] = __builtin_amdgcn_mfma_f32_16x16x32_bf16(Bt[n][k], At[m][k], acc[ai][bj][m][n], 0, 0, 0); __builtin_amdgcn_s_setprio(0); } while (0)
; #define PG8_WAIT_V(n) asm volatile("s_waitcnt vmcnt(" #n ")" ::: "memory")
; #define PG8_WAIT_L(n) asm volatile("s_waitcnt lgkmcnt(" #n ")" ::: "memory")
; #define PG8_BAR __builtin_amdgcn_s_barrier()
; #define PG8_SCHED __builtin_amdgcn_sched_barrier(0)
; template <class Epi>
; DEVINL void gemm_phase(LAS unsigned char* lds, const Gemm g, const Order& S, const Epi& E) {
;     ...
;             PG8_STAGE(PG8_SB(0, 1), b2 + hstepB, voffB);
;             PG8_WAIT_V(6); PG8_BAR; PG8_MMA(1, 1, At, B1); PG8_BAR;
;             PG8_LDB(B0, 1, 0); PG8_SCHED; PG8_LDA(At, 1, 0); PG8_STAGE(PG8_SA(0, 1), a2 + hstepA, voffA);
;             PG8_WAIT_L(8); PG8_BAR; PG8_WAIT_L(0); PG8_MMA(0, 0, At, B0); PG8_BAR; PG8_SCHED;
;             PG8_LDB(B1, 1, 1); PG8_STAGE(PG8_SB(1, 0), b3, voffB);
	s_add_u32 vcc_lo, s10, 0x80000
	s_addc_u32 vcc_hi, s11, 0
	s_add_i32 s2, s81, s68
	v_lshl_add_u64 v[146:147], vcc, 0, v[130:131]
	s_mov_b32 m0, s2
	s_nop 0
	global_load_lds_dwordx4 v[146:147], off
	v_lshl_add_u64 v[146:147], vcc, 0, v[134:135]
	s_add_i32 m0, s2, 0x2000
	s_nop 0
	global_load_lds_dwordx4 v[146:147], off
	s_waitcnt vmcnt(6)
	s_barrier
	s_setprio 1
	v_mfma_f32_16x16x32_bf16 v[52:55], v[194:197], v[162:165], v[52:55]
	v_mfma_f32_16x16x32_bf16 v[52:55], v[198:201], v[166:169], v[52:55]
	v_mfma_f32_16x16x32_bf16 v[48:51], v[206:209], v[166:169], v[48:51]
	v_mfma_f32_16x16x32_bf16 v[48:51], v[202:205], v[162:165], v[48:51]
	v_mfma_f32_16x16x32_bf16 v[32:35], v[202:205], v[170:173], v[32:35]
	v_mfma_f32_16x16x32_bf16 v[32:35], v[206:209], v[174:177], v[32:35]
	v_mfma_f32_16x16x32_bf16 v[36:39], v[198:201], v[174:177], v[36:39]
	v_mfma_f32_16x16x32_bf16 v[36:39], v[194:197], v[170:173], v[36:39]
	v_mfma_f32_16x16x32_bf16 v[20:23], v[194:197], v[178:181], v[20:23]
	v_mfma_f32_16x16x32_bf16 v[20:23], v[198:201], v[182:185], v[20:23]
	v_mfma_f32_16x16x32_bf16 v[16:19], v[206:209], v[182:185], v[16:19]
	v_mfma_f32_16x16x32_bf16 v[16:19], v[202:205], v[178:181], v[16:19]
	v_mfma_f32_16x16x32_bf16 v[0:3], v[202:205], v[186:189], v[0:3]
	v_mfma_f32_16x16x32_bf16 v[0:3], v[206:209], v[190:193], v[0:3]
	v_mfma_f32_16x16x32_bf16 v[4:7], v[198:201], v[190:193], v[4:7]
	v_mfma_f32_16x16x32_bf16 v[4:7], v[194:197], v[186:189], v[4:7]
	s_setprio 0
	s_add_i32 s2, 16, 0x18000
	v_add_u32_e32 v158, s2, v141
	s_barrier
	ds_read_b128 v[146:149], v158
	ds_read_b128 v[150:153], v158 offset:1024
	ds_read_b128 v[154:157], v158 offset:2048
	ds_read_b128 v[158:161], v158 offset:3072
	s_add_u32 s14, s14, 0x80000
	s_addc_u32 s15, s15, 0
	s_mov_b32 m0, s72
	v_lshl_add_u64 v[194:195], s[14:15], 0, v[128:129]
	ds_read_b128 v[162:165], v144 offset:32768
	ds_read_b128 v[166:169], v144 offset:33792
	ds_read_b128 v[170:173], v144 offset:34816
	ds_read_b128 v[174:177], v144 offset:35840
	ds_read_b128 v[178:181], v144 offset:36864
	ds_read_b128 v[182:185], v144 offset:37888
	ds_read_b128 v[186:189], v144 offset:38912
	ds_read_b128 v[190:193], v144 offset:39936
	global_load_lds_dwordx4 v[194:195], off
	v_lshl_add_u64 v[194:195], s[14:15], 0, v[132:133]
	s_mov_b32 m0, s73
	s_nop 0
	global_load_lds_dwordx4 v[194:195], off
	s_waitcnt lgkmcnt(8)
	s_barrier
	s_waitcnt lgkmcnt(0)
	s_setprio 1
	s_waitcnt lgkmcnt(0)
	v_mfma_f32_16x16x32_bf16 v[120:123], v[146:149], v[162:165], v[120:123]
	v_mfma_f32_16x16x32_bf16 v[120:123], v[150:153], v[166:169], v[120:123]
	v_mfma_f32_16x16x32_bf16 v[124:127], v[158:161], v[166:169], v[124:127]
	v_mfma_f32_16x16x32_bf16 v[124:127], v[154:157], v[162:165], v[124:127]
	v_mfma_f32_16x16x32_bf16 v[104:107], v[154:157], v[170:173], v[104:107]
	v_mfma_f32_16x16x32_bf16 v[104:107], v[158:161], v[174:177], v[104:107]
	v_mfma_f32_16x16x32_bf16 v[108:111], v[150:153], v[174:177], v[108:111]
	v_mfma_f32_16x16x32_bf16 v[108:111], v[146:149], v[170:173], v[108:111]
	v_mfma_f32_16x16x32_bf16 v[92:95], v[146:149], v[178:181], v[92:95]
	v_mfma_f32_16x16x32_bf16 v[92:95], v[150:153], v[182:185], v[92:95]
	v_mfma_f32_16x16x32_bf16 v[88:91], v[158:161], v[182:185], v[88:91]
	v_mfma_f32_16x16x32_bf16 v[88:91], v[154:157], v[178:181], v[88:91]
	v_mfma_f32_16x16x32_bf16 v[72:75], v[154:157], v[186:189], v[72:75]
	v_mfma_f32_16x16x32_bf16 v[72:75], v[158:161], v[190:193], v[72:75]
	v_mfma_f32_16x16x32_bf16 v[76:79], v[150:153], v[190:193], v[76:79]
	v_mfma_f32_16x16x32_bf16 v[76:79], v[146:149], v[186:189], v[76:79]
	s_setprio 0
	s_barrier
	s_add_i32 s3, 16, 0x1c000
	s_add_i32 s2, s2, s68
	v_add_u32_e32 v206, s3, v141
	v_lshl_add_u64 v[210:211], v[210:211], 0, s[0:1]
	s_mov_b32 m0, s2
	ds_read_b128 v[194:197], v206
	ds_read_b128 v[198:201], v206 offset:1024
	ds_read_b128 v[202:205], v206 offset:2048
	ds_read_b128 v[206:209], v206 offset:3072
	global_load_lds_dwordx4 v[210:211], off
	v_lshl_add_u64 v[210:211], v[212:213], 0, s[0:1]
	s_add_i32 m0, s2, 0x2000
	s_nop 0
	global_load_lds_dwordx4 v[210:211], off
	s_barrier
; #define PG8_STAGE(bufoff, gbase, voff) do { _Pragma("unroll") for (int _i = 0; _i < 2; ++_i) \
;         __builtin_amdgcn_global_load_lds((const unsigned*)((const char*)(gbase) + (voff)[_i]), (LAS unsigned*)(lds + (bufoff) + ldsw + _i * 8192), 16, 0, 0); } while (0)
; #define PG8_LDA(dst, b, h) do { _Pragma("unroll") for (int m = 0; m < 4; ++m) _Pragma("unroll") for (int k = 0; k < 2; ++k) dst[m][k] = *(const LAS bf16x8*)(lds + PG8_SA(b, h) + aoff + m * 2048 + k * 1024); } while (0)
; #define PG8_MMA(ai, bj, At, Bt) do { __builtin_amdgcn_s_setprio(1); _Pragma("unroll") for (int m = 0; m < 4; ++m) _Pragma("unroll") for (int n = 0; n < 2; ++n) _Pragma("unroll") for (int k = 0; k < 2; ++k) \
;         acc[ai][bj][m][n] = __builtin_amdgcn_mfma_f32_16x16x32_bf16(Bt[n][k], At[m][k], acc[ai][bj][m][n], 0, 0, 0); __builtin_amdgcn_s_setprio(0); } while (0)
; #define PG8_WAIT_V(n) asm volatile("s_waitcnt vmcnt(" #n ")" ::: "memory")
; #define PG8_WAIT_L(n) asm volatile("s_waitcnt lgkmcnt(" #n ")" ::: "memory")
; #define PG8_BAR __builtin_amdgcn_s_barrier()
; #define PG8_SCHED __builtin_amdgcn_sched_barrier(0)
; template <class Epi>
; DEVINL void gemm_phase(LAS unsigned char* lds, const Gemm g, const Order& S, const Epi& E) {
;     ...
;             PG8_BAR; PG8_WAIT_L(0); PG8_MMA(0, 1, At, B1); PG8_BAR;
;             PG8_LDA(At, 1, 1); PG8_STAGE(PG8_SA(1, 0), a3, voffA);
;             PG8_BAR; PG8_WAIT_L(0); PG8_MMA(1, 0, At, B0); PG8_BAR; PG8_SCHED;
;             PG8_STAGE(PG8_SB(1, 1), b3 + hstepB, voffB);
;             PG8_WAIT_V(6); PG8_BAR; PG8_MMA(1, 1, At, B1); PG8_BAR;
;         }
	s_waitcnt lgkmcnt(0)
	s_setprio 1
	s_waitcnt lgkmcnt(0)
	v_mfma_f32_16x16x32_bf16 v[116:119], v[194:197], v[162:165], v[116:119]
	v_mfma_f32_16x16x32_bf16 v[116:119], v[198:201], v[166:169], v[116:119]
	v_mfma_f32_16x16x32_bf16 v[112:115], v[206:209], v[166:169], v[112:115]
	v_mfma_f32_16x16x32_bf16 v[112:115], v[202:205], v[162:165], v[112:115]
	v_mfma_f32_16x16x32_bf16 v[96:99], v[202:205], v[170:173], v[96:99]
	v_mfma_f32_16x16x32_bf16 v[96:99], v[206:209], v[174:177], v[96:99]
	v_mfma_f32_16x16x32_bf16 v[100:103], v[198:201], v[174:177], v[100:103]
	v_mfma_f32_16x16x32_bf16 v[100:103], v[194:197], v[170:173], v[100:103]
	v_mfma_f32_16x16x32_bf16 v[84:87], v[194:197], v[178:181], v[84:87]
	v_mfma_f32_16x16x32_bf16 v[84:87], v[198:201], v[182:185], v[84:87]
	v_mfma_f32_16x16x32_bf16 v[80:83], v[206:209], v[182:185], v[80:83]
	v_mfma_f32_16x16x32_bf16 v[80:83], v[202:205], v[178:181], v[80:83]
	v_mfma_f32_16x16x32_bf16 v[64:67], v[202:205], v[186:189], v[64:67]
	v_mfma_f32_16x16x32_bf16 v[64:67], v[206:209], v[190:193], v[64:67]
	v_mfma_f32_16x16x32_bf16 v[68:71], v[198:201], v[190:193], v[68:71]
	v_mfma_f32_16x16x32_bf16 v[68:71], v[194:197], v[186:189], v[68:71]
	s_setprio 0
	s_mov_b32 m0, s75
	v_lshl_add_u64 v[210:211], v[218:219], 0, s[0:1]
	s_barrier
	ds_read_b128 v[162:165], v144 offset:49152
	ds_read_b128 v[166:169], v144 offset:50176
	ds_read_b128 v[170:173], v144 offset:51200
	ds_read_b128 v[174:177], v144 offset:52224
	ds_read_b128 v[178:181], v144 offset:53248
	ds_read_b128 v[182:185], v144 offset:54272
	ds_read_b128 v[186:189], v144 offset:55296
	ds_read_b128 v[190:193], v144 offset:56320
	global_load_lds_dwordx4 v[210:211], off
	v_lshl_add_u64 v[210:211], v[220:221], 0, s[0:1]
	s_mov_b32 m0, s76
	s_nop 0
	global_load_lds_dwordx4 v[210:211], off
	s_barrier
	s_waitcnt lgkmcnt(0)
	s_setprio 1
	s_waitcnt lgkmcnt(0)
	v_mfma_f32_16x16x32_bf16 v[60:63], v[146:149], v[162:165], v[60:63]
	v_mfma_f32_16x16x32_bf16 v[60:63], v[150:153], v[166:169], v[60:63]
	v_mfma_f32_16x16x32_bf16 v[56:59], v[158:161], v[166:169], v[56:59]
	v_mfma_f32_16x16x32_bf16 v[56:59], v[154:157], v[162:165], v[56:59]
	v_mfma_f32_16x16x32_bf16 v[40:43], v[154:157], v[170:173], v[40:43]
	v_mfma_f32_16x16x32_bf16 v[40:43], v[158:161], v[174:177], v[40:43]
	v_mfma_f32_16x16x32_bf16 v[44:47], v[150:153], v[174:177], v[44:47]
	v_mfma_f32_16x16x32_bf16 v[44:47], v[146:149], v[170:173], v[44:47]
	v_mfma_f32_16x16x32_bf16 v[28:31], v[146:149], v[178:181], v[28:31]
	v_mfma_f32_16x16x32_bf16 v[28:31], v[150:153], v[182:185], v[28:31]
	v_mfma_f32_16x16x32_bf16 v[24:27], v[158:161], v[182:185], v[24:27]
	v_mfma_f32_16x16x32_bf16 v[24:27], v[154:157], v[178:181], v[24:27]
	v_mfma_f32_16x16x32_bf16 v[8:11], v[154:157], v[186:189], v[8:11]
	v_mfma_f32_16x16x32_bf16 v[8:11], v[158:161], v[190:193], v[8:11]
	v_mfma_f32_16x16x32_bf16 v[12:15], v[150:153], v[190:193], v[12:15]
	v_mfma_f32_16x16x32_bf16 v[12:15], v[146:149], v[186:189], v[12:15]
	s_setprio 0
	s_barrier
	s_add_u32 s10, s10, 0x80080
	s_addc_u32 s11, s11, 0
	s_add_i32 s2, s3, s68
	v_lshl_add_u64 v[146:147], s[10:11], 0, v[130:131]
	s_mov_b32 m0, s2
	s_nop 0
	global_load_lds_dwordx4 v[146:147], off
	v_lshl_add_u64 v[146:147], s[10:11], 0, v[134:135]
	s_add_i32 m0, s2, 0x2000
	s_nop 0
	global_load_lds_dwordx4 v[146:147], off
	s_waitcnt vmcnt(6)
	s_barrier
	s_setprio 1
	v_mfma_f32_16x16x32_bf16 v[52:55], v[194:197], v[162:165], v[52:55]
	v_mfma_f32_16x16x32_bf16 v[52:55], v[198:201], v[166:169], v[52:55]
	v_mfma_f32_16x16x32_bf16 v[48:51], v[206:209], v[166:169], v[48:51]
	v_mfma_f32_16x16x32_bf16 v[48:51], v[202:205], v[162:165], v[48:51]
	v_mfma_f32_16x16x32_bf16 v[32:35], v[202:205], v[170:173], v[32:35]
	v_mfma_f32_16x16x32_bf16 v[32:35], v[206:209], v[174:177], v[32:35]
	v_mfma_f32_16x16x32_bf16 v[36:39], v[198:201], v[174:177], v[36:39]
	v_mfma_f32_16x16x32_bf16 v[36:39], v[194:197], v[170:173], v[36:39]
	v_mfma_f32_16x16x32_bf16 v[20:23], v[194:197], v[178:181], v[20:23]
	v_mfma_f32_16x16x32_bf16 v[20:23], v[198:201], v[182:185], v[20:23]
	v_mfma_f32_16x16x32_bf16 v[16:19], v[206:209], v[182:185], v[16:19]
	v_mfma_f32_16x16x32_bf16 v[16:19], v[202:205], v[178:181], v[16:19]
	v_mfma_f32_16x16x32_bf16 v[0:3], v[202:205], v[186:189], v[0:3]
	v_mfma_f32_16x16x32_bf16 v[0:3], v[206:209], v[190:193], v[0:3]
	v_mfma_f32_16x16x32_bf16 v[4:7], v[198:201], v[190:193], v[4:7]
	v_mfma_f32_16x16x32_bf16 v[4:7], v[194:197], v[186:189], v[4:7]
	s_setprio 0
	s_add_u32 s12, s12, 0x100
	s_addc_u32 s13, s13, 0
	s_add_u32 s85, s85, 0x100
	s_addc_u32 s86, s86, 0
	s_cmp_ge_i32 s87, s74
	s_mov_b32 s10, s87
	s_barrier
	s_cbranch_scc0 .LBB0_361
	s_branch .LBB0_352

; #define PG8_STAGE(bufoff, gbase, voff) do { _Pragma("unroll") for (int _i = 0; _i < 2; ++_i) \
;         __builtin_amdgcn_global_load_lds((const unsigned*)((const char*)(gbase) + (voff)[_i]), (LAS unsigned*)(lds + (bufoff) + ldsw + _i * 8192), 16, 0, 0); } while (0)
; #define PG8_LDA(dst, b, h) do { _Pragma("unroll") for (int m = 0; m < 4; ++m) _Pragma("unroll") for (int k = 0; k < 2; ++k) dst[m][k] = *(const LAS bf16x8*)(lds + PG8_SA(b, h) + aoff + m * 2048 + k * 1024); } while (0)
; #define PG8_LDB(dst, b, h) do { _Pragma("unroll") for (int n = 0; n < 2; ++n) _Pragma("unroll") for (int k = 0; k < 2; ++k) dst[n][k] = *(const LAS bf16x8*)(lds + PG8_SB(b, h) + boff + n * 2048 + k * 1024); } while (0)
; #define PG8_MMA(ai, bj, At, Bt) do { __builtin_amdgcn_s_setprio(1); _Pragma("unroll") for (int m = 0; m < 4; ++m) _Pragma("unroll") for (int n = 0; n < 2; ++n) _Pragma("unroll") for (int k = 0; k < 2; ++k) \
;         acc[ai][bj][m][n] = __builtin_amdgcn_mfma_f32_16x16x32_bf16(Bt[n][k], At[m][k], acc[ai][bj][m][n], 0, 0, 0); __builtin_amdgcn_s_setprio(0); } while (0)
; #define PG8_WAIT_L(n) asm volatile("s_waitcnt lgkmcnt(" #n ")" ::: "memory")
; #define PG8_BAR __builtin_amdgcn_s_barrier()
; #define PG8_SCHED __builtin_amdgcn_sched_barrier(0)
; template <class Epi>
; DEVINL void gemm_phase(LAS unsigned char* lds, const Gemm g, const Order& S, const Epi& E) {
;     ...
;             const char* a1 = cA + (size_t)(t + 1) * kstep;
;             const char* a2 = last ? nA : cA + (size_t)(t + 2) * kstep; const char* b2 = last ? nB : cB + (size_t)(t + 2) * kstep;
;             const char* a3 = a2 + kstep; const char* b3 = b2 + kstep;
;             PG8_LDB(B0, 0, 0); PG8_SCHED; PG8_LDA(At, 0, 0); PG8_STAGE(PG8_SA(1, 1), a1 + hstepA, voffA);
;             PG8_WAIT_L(8); PG8_BAR; PG8_WAIT_L(0); PG8_MMA(0, 0, At, B0); PG8_BAR; PG8_SCHED;
;             PG8_LDB(B1, 0, 1); PG8_STAGE(PG8_SB(0, 0), b2, voffB);
;             PG8_BAR; PG8_WAIT_L(0); PG8_MMA(0, 1, At, B1); PG8_BAR;
;             PG8_LDA(At, 0, 1); PG8_STAGE(PG8_SA(0, 0), a2, voffA);
;             PG8_BAR; PG8_WAIT_L(0); PG8_MMA(1, 0, At, B0); PG8_BAR; PG8_SCHED;
.LBB0_382:
	ds_read_b128 v[146:149], v143
	ds_read_b128 v[150:153], v143 offset:1024
	ds_read_b128 v[154:157], v143 offset:2048
	ds_read_b128 v[158:161], v143 offset:3072
	s_add_i32 s87, s12, 2
	s_add_u32 s2, s14, 0xfff80080
	s_addc_u32 s3, s15, -1
	s_cmp_eq_u32 s78, s12
	s_cselect_b32 s12, s84, s85
	s_cselect_b32 vcc_hi, s65, s3
	s_cselect_b32 vcc_lo, s66, s2
	s_cselect_b32 s13, s67, s86
	v_lshl_add_u64 v[194:195], s[14:15], 0, v[136:137]
	s_add_i32 m0, s5, 0xc000
	ds_read_b128 v[162:165], v144
	ds_read_b128 v[166:169], v144 offset:1024
	ds_read_b128 v[170:173], v144 offset:2048
	ds_read_b128 v[174:177], v144 offset:3072
	ds_read_b128 v[178:181], v144 offset:4096
	ds_read_b128 v[182:185], v144 offset:5120
	ds_read_b128 v[186:189], v144 offset:6144
	ds_read_b128 v[190:193], v144 offset:7168
	global_load_lds_dwordx4 v[194:195], off
	v_lshl_add_u64 v[194:195], s[14:15], 0, v[138:139]
	s_add_i32 m0, s5, 0xe000
	s_nop 0
	global_load_lds_dwordx4 v[194:195], off
	s_waitcnt lgkmcnt(8)
	s_barrier
	s_waitcnt lgkmcnt(0)
	s_setprio 1
	s_waitcnt lgkmcnt(0)
	v_mfma_f32_16x16x32_bf16 v[120:123], v[146:149], v[162:165], v[120:123]
	v_mfma_f32_16x16x32_bf16 v[120:123], v[150:153], v[166:169], v[120:123]
	v_mfma_f32_16x16x32_bf16 v[124:127], v[158:161], v[166:169], v[124:127]
	v_mfma_f32_16x16x32_bf16 v[124:127], v[154:157], v[162:165], v[124:127]
	v_mfma_f32_16x16x32_bf16 v[104:107], v[154:157], v[170:173], v[104:107]
	v_mfma_f32_16x16x32_bf16 v[104:107], v[158:161], v[174:177], v[104:107]
	v_mfma_f32_16x16x32_bf16 v[108:111], v[150:153], v[174:177], v[108:111]
	v_mfma_f32_16x16x32_bf16 v[108:111], v[146:149], v[170:173], v[108:111]
	v_mfma_f32_16x16x32_bf16 v[92:95], v[146:149], v[178:181], v[92:95]
	v_mfma_f32_16x16x32_bf16 v[92:95], v[150:153], v[182:185], v[92:95]
	v_mfma_f32_16x16x32_bf16 v[88:91], v[158:161], v[182:185], v[88:91]
	v_mfma_f32_16x16x32_bf16 v[88:91], v[154:157], v[178:181], v[88:91]
	v_mfma_f32_16x16x32_bf16 v[72:75], v[154:157], v[186:189], v[72:75]
	v_mfma_f32_16x16x32_bf16 v[72:75], v[158:161], v[190:193], v[72:75]
	v_mfma_f32_16x16x32_bf16 v[76:79], v[150:153], v[190:193], v[76:79]
	v_mfma_f32_16x16x32_bf16 v[76:79], v[146:149], v[186:189], v[76:79]
	s_setprio 0
	s_barrier
	s_add_i32 s2, s81, s68
	v_lshl_add_u64 v[210:211], s[12:13], 0, v[130:131]
	s_mov_b32 m0, s2
	ds_read_b128 v[194:197], v145
	ds_read_b128 v[198:201], v145 offset:1024
	ds_read_b128 v[202:205], v145 offset:2048
	ds_read_b128 v[206:209], v145 offset:3072
	global_load_lds_dwordx4 v[210:211], off
	v_lshl_add_u64 v[212:213], s[12:13], 0, v[134:135]
	s_add_i32 m0, s2, 0x2000
	s_nop 0
	global_load_lds_dwordx4 v[212:213], off
	s_barrier
	s_waitcnt lgkmcnt(0)
	s_setprio 1
	s_waitcnt lgkmcnt(0)
	v_mfma_f32_16x16x32_bf16 v[116:119], v[194:197], v[162:165], v[116:119]
	v_mfma_f32_16x16x32_bf16 v[116:119], v[198:201], v[166:169], v[116:119]
	v_mfma_f32_16x16x32_bf16 v[112:115], v[206:209], v[166:169], v[112:115]
	v_mfma_f32_16x16x32_bf16 v[112:115], v[202:205], v[162:165], v[112:115]
	v_mfma_f32_16x16x32_bf16 v[96:99], v[202:205], v[170:173], v[96:99]
	v_mfma_f32_16x16x32_bf16 v[96:99], v[206:209], v[174:177], v[96:99]
	v_mfma_f32_16x16x32_bf16 v[100:103], v[198:201], v[174:177], v[100:103]
	v_mfma_f32_16x16x32_bf16 v[100:103], v[194:197], v[170:173], v[100:103]
	v_mfma_f32_16x16x32_bf16 v[84:87], v[194:197], v[178:181], v[84:87]
	v_mfma_f32_16x16x32_bf16 v[84:87], v[198:201], v[182:185], v[84:87]
	v_mfma_f32_16x16x32_bf16 v[80:83], v[206:209], v[182:185], v[80:83]
	v_mfma_f32_16x16x32_bf16 v[80:83], v[202:205], v[178:181], v[80:83]
	v_mfma_f32_16x16x32_bf16 v[64:67], v[202:205], v[186:189], v[64:67]
	v_mfma_f32_16x16x32_bf16 v[64:67], v[206:209], v[190:193], v[64:67]
	v_mfma_f32_16x16x32_bf16 v[68:71], v[198:201], v[190:193], v[68:71]
	v_mfma_f32_16x16x32_bf16 v[68:71], v[194:197], v[186:189], v[68:71]
	s_setprio 0
	s_mov_b32 m0, s5
	v_lshl_add_u64 v[218:219], vcc, 0, v[128:129]
	s_barrier
	ds_read_b128 v[162:165], v144 offset:16384
	ds_read_b128 v[166:169], v144 offset:17408
	ds_read_b128 v[170:173], v144 offset:18432
	ds_read_b128 v[174:177], v144 offset:19456
	ds_read_b128 v[178:181], v144 offset:20480
	ds_read_b128 v[182:185], v144 offset:21504
	ds_read_b128 v[186:189], v144 offset:22528
	ds_read_b128 v[190:193], v144 offset:23552
	global_load_lds_dwordx4 v[218:219], off
	v_lshl_add_u64 v[220:221], vcc, 0, v[132:133]
	s_mov_b32 m0, s69
	s_nop 0
	global_load_lds_dwordx4 v[220:221], off
	s_barrier
	s_waitcnt lgkmcnt(0)
	s_setprio 1
	s_waitcnt lgkmcnt(0)
	v_mfma_f32_16x16x32_bf16 v[60:63], v[146:149], v[162:165], v[60:63]
	v_mfma_f32_16x16x32_bf16 v[60:63], v[150:153], v[166:169], v[60:63]
	v_mfma_f32_16x16x32_bf16 v[56:59], v[158:161], v[166:169], v[56:59]
	v_mfma_f32_16x16x32_bf16 v[56:59], v[154:157], v[162:165], v[56:59]
	v_mfma_f32_16x16x32_bf16 v[40:43], v[154:157], v[170:173], v[40:43]
	v_mfma_f32_16x16x32_bf16 v[40:43], v[158:161], v[174:177], v[40:43]
	v_mfma_f32_16x16x32_bf16 v[44:47], v[150:153], v[174:177], v[44:47]
	v_mfma_f32_16x16x32_bf16 v[44:47], v[146:149], v[170:173], v[44:47]
	v_mfma_f32_16x16x32_bf16 v[28:31], v[146:149], v[178:181], v[28:31]
	v_mfma_f32_16x16x32_bf16 v[28:31], v[150:153], v[182:185], v[28:31]
	v_mfma_f32_16x16x32_bf16 v[24:27], v[158:161], v[182:185], v[24:27]
	v_mfma_f32_16x16x32_bf16 v[24:27], v[154:157], v[178:181], v[24:27]
	v_mfma_f32_16x16x32_bf16 v[8:11], v[154:157], v[186:189], v[8:11]
	v_mfma_f32_16x16x32_bf16 v[8:11], v[158:161], v[190:193], v[8:11]
	v_mfma_f32_16x16x32_bf16 v[12:15], v[150:153], v[190:193], v[12:15]
	v_mfma_f32_16x16x32_bf16 v[12:15], v[146:149], v[186:189], v[12:15]
	s_setprio 0
	s_barrier
; #define PG8_STAGE(bufoff, gbase, voff) do { _Pragma("unroll") for (int _i = 0; _i < 2; ++_i) \
;         __builtin_amdgcn_global_load_lds((const unsigned*)((const char*)(gbase) + (voff)[_i]), (LAS unsigned*)(lds + (bufoff) + ldsw + _i * 8192), 16, 0, 0); } while (0)
; #define PG8_LDA(dst, b, h) do { _Pragma("unroll") for (int m = 0; m < 4; ++m) _Pragma("unroll") for (int k = 0; k < 2; ++k) dst[m][k] = *(const LAS bf16x8*)(lds + PG8_SA(b, h) + aoff + m * 2048 + k * 1024); } while (0)
; #define PG8_LDB(dst, b, h) do { _Pragma("unroll") for (int n = 0; n < 2; ++n) _Pragma("unroll") for (int k = 0; k < 2; ++k) dst[n][k] = *(const LAS bf16x8*)(lds + PG8_SB(b, h) + boff + n * 2048 + k * 1024); } while (0)
; #define PG8_MMA(ai, bj, At, Bt) do { __builtin_amdgcn_s_setprio(1); _Pragma("unroll") for (int m = 0; m < 4; ++m) _Pragma("unroll") for (int n = 0; n < 2; ++n) _Pragma("unroll") for (int k = 0; k < 2; ++k) \
;         acc[ai][bj][m][n] = __builtin_amdgcn_mfma_f32_16x16x32_bf16(Bt[n][k], At[m][k], acc[ai][bj][m][n], 0, 0, 0); __builtin_amdgcn_s_setprio(0); } while (0)
; #define PG8_WAIT_V(n) asm volatile("s_waitcnt vmcnt(" #n ")" ::: "memory")
; #define PG8_WAIT_L(n) asm volatile("s_waitcnt lgkmcnt(" #n ")" ::: "memory")
; #define PG8_BAR __builtin_amdgcn_s_barrier()
; #define PG8_SCHED __builtin_amdgcn_sched_barrier(0)
; template <class Epi>
; DEVINL void gemm_phase(LAS unsigned char* lds, const Gemm g, const Order& S, const Epi& E) {
;     ...
;             PG8_STAGE(PG8_SB(0, 1), b2 + hstepB, voffB);
;             PG8_WAIT_V(6); PG8_BAR; PG8_MMA(1, 1, At, B1); PG8_BAR;
;             PG8_LDB(B0, 1, 0); PG8_SCHED; PG8_LDA(At, 1, 0); PG8_STAGE(PG8_SA(0, 1), a2 + hstepA, voffA);
;             PG8_WAIT_L(8); PG8_BAR; PG8_WAIT_L(0); PG8_MMA(0, 0, At, B0); PG8_BAR; PG8_SCHED;
;             PG8_LDB(B1, 1, 1); PG8_STAGE(PG8_SB(1, 0), b3, voffB);
	s_add_u32 s2, s12, 0x80000
	s_addc_u32 s3, s13, 0
	s_add_i32 s93, s82, s68
	v_lshl_add_u64 v[146:147], s[2:3], 0, v[130:131]
	s_mov_b32 m0, s93
	s_nop 0
	global_load_lds_dwordx4 v[146:147], off
	v_lshl_add_u64 v[146:147], s[2:3], 0, v[134:135]
	s_add_i32 m0, s93, 0x2000
	s_nop 0
	global_load_lds_dwordx4 v[146:147], off
	s_waitcnt vmcnt(6)
	s_barrier
	s_setprio 1
	v_mfma_f32_16x16x32_bf16 v[52:55], v[194:197], v[162:165], v[52:55]
	v_mfma_f32_16x16x32_bf16 v[52:55], v[198:201], v[166:169], v[52:55]
	v_mfma_f32_16x16x32_bf16 v[48:51], v[206:209], v[166:169], v[48:51]
	v_mfma_f32_16x16x32_bf16 v[48:51], v[202:205], v[162:165], v[48:51]
	v_mfma_f32_16x16x32_bf16 v[32:35], v[202:205], v[170:173], v[32:35]
	v_mfma_f32_16x16x32_bf16 v[32:35], v[206:209], v[174:177], v[32:35]
	v_mfma_f32_16x16x32_bf16 v[36:39], v[198:201], v[174:177], v[36:39]
	v_mfma_f32_16x16x32_bf16 v[36:39], v[194:197], v[170:173], v[36:39]
	v_mfma_f32_16x16x32_bf16 v[20:23], v[194:197], v[178:181], v[20:23]
	v_mfma_f32_16x16x32_bf16 v[20:23], v[198:201], v[182:185], v[20:23]
	v_mfma_f32_16x16x32_bf16 v[16:19], v[206:209], v[182:185], v[16:19]
	v_mfma_f32_16x16x32_bf16 v[16:19], v[202:205], v[178:181], v[16:19]
	v_mfma_f32_16x16x32_bf16 v[0:3], v[202:205], v[186:189], v[0:3]
	v_mfma_f32_16x16x32_bf16 v[0:3], v[206:209], v[190:193], v[0:3]
	v_mfma_f32_16x16x32_bf16 v[4:7], v[198:201], v[190:193], v[4:7]
	v_mfma_f32_16x16x32_bf16 v[4:7], v[194:197], v[186:189], v[4:7]
	s_setprio 0
	s_add_i32 s93, 16, 0x18000
	v_add_u32_e32 v158, s93, v141
	s_barrier
	ds_read_b128 v[146:149], v158
	ds_read_b128 v[150:153], v158 offset:1024
	ds_read_b128 v[154:157], v158 offset:2048
	ds_read_b128 v[158:161], v158 offset:3072
	s_add_u32 s2, vcc_lo, 0x80000
	s_addc_u32 s3, vcc_hi, 0
	s_mov_b32 m0, s72
	v_lshl_add_u64 v[194:195], s[2:3], 0, v[128:129]
	ds_read_b128 v[162:165], v144 offset:32768
	ds_read_b128 v[166:169], v144 offset:33792
	ds_read_b128 v[170:173], v144 offset:34816
	ds_read_b128 v[174:177], v144 offset:35840
	ds_read_b128 v[178:181], v144 offset:36864
	ds_read_b128 v[182:185], v144 offset:37888
	ds_read_b128 v[186:189], v144 offset:38912
	ds_read_b128 v[190:193], v144 offset:39936
	global_load_lds_dwordx4 v[194:195], off
	v_lshl_add_u64 v[194:195], s[2:3], 0, v[132:133]
	s_mov_b32 m0, s73
	s_nop 0
	global_load_lds_dwordx4 v[194:195], off
	s_waitcnt lgkmcnt(8)
	s_barrier
	s_waitcnt lgkmcnt(0)
	s_setprio 1
	s_waitcnt lgkmcnt(0)
	v_mfma_f32_16x16x32_bf16 v[120:123], v[146:149], v[162:165], v[120:123]
	v_mfma_f32_16x16x32_bf16 v[120:123], v[150:153], v[166:169], v[120:123]
	v_mfma_f32_16x16x32_bf16 v[124:127], v[158:161], v[166:169], v[124:127]
	v_mfma_f32_16x16x32_bf16 v[124:127], v[154:157], v[162:165], v[124:127]
	v_mfma_f32_16x16x32_bf16 v[104:107], v[154:157], v[170:173], v[104:107]
	v_mfma_f32_16x16x32_bf16 v[104:107], v[158:161], v[174:177], v[104:107]
	v_mfma_f32_16x16x32_bf16 v[108:111], v[150:153], v[174:177], v[108:111]
	v_mfma_f32_16x16x32_bf16 v[108:111], v[146:149], v[170:173], v[108:111]
	v_mfma_f32_16x16x32_bf16 v[92:95], v[146:149], v[178:181], v[92:95]
	v_mfma_f32_16x16x32_bf16 v[92:95], v[150:153], v[182:185], v[92:95]
	v_mfma_f32_16x16x32_bf16 v[88:91], v[158:161], v[182:185], v[88:91]
	v_mfma_f32_16x16x32_bf16 v[88:91], v[154:157], v[178:181], v[88:91]
	v_mfma_f32_16x16x32_bf16 v[72:75], v[154:157], v[186:189], v[72:75]
	v_mfma_f32_16x16x32_bf16 v[72:75], v[158:161], v[190:193], v[72:75]
	v_mfma_f32_16x16x32_bf16 v[76:79], v[150:153], v[190:193], v[76:79]
	v_mfma_f32_16x16x32_bf16 v[76:79], v[146:149], v[186:189], v[76:79]
	s_setprio 0
	s_barrier
	s_add_i32 vcc_lo, 16, 0x1c000
	s_add_i32 s2, s93, s68
	v_add_u32_e32 v206, vcc_lo, v141
	v_lshl_add_u64 v[210:211], v[210:211], 0, s[0:1]
	s_mov_b32 m0, s2
	ds_read_b128 v[194:197], v206
	ds_read_b128 v[198:201], v206 offset:1024
	ds_read_b128 v[202:205], v206 offset:2048
	ds_read_b128 v[206:209], v206 offset:3072
	global_load_lds_dwordx4 v[210:211], off
	v_lshl_add_u64 v[210:211], v[212:213], 0, s[0:1]
	s_add_i32 m0, s2, 0x2000
	s_nop 0
	global_load_lds_dwordx4 v[210:211], off
	s_barrier
; #define PG8_STAGE(bufoff, gbase, voff) do { _Pragma("unroll") for (int _i = 0; _i < 2; ++_i) \
;         __builtin_amdgcn_global_load_lds((const unsigned*)((const char*)(gbase) + (voff)[_i]), (LAS unsigned*)(lds + (bufoff) + ldsw + _i * 8192), 16, 0, 0); } while (0)
; #define PG8_LDA(dst, b, h) do { _Pragma("unroll") for (int m = 0; m < 4; ++m) _Pragma("unroll") for (int k = 0; k < 2; ++k) dst[m][k] = *(const LAS bf16x8*)(lds + PG8_SA(b, h) + aoff + m * 2048 + k * 1024); } while (0)
; #define PG8_MMA(ai, bj, At, Bt) do { __builtin_amdgcn_s_setprio(1); _Pragma("unroll") for (int m = 0; m < 4; ++m) _Pragma("unroll") for (int n = 0; n < 2; ++n) _Pragma("unroll") for (int k = 0; k < 2; ++k) \
;         acc[ai][bj][m][n] = __builtin_amdgcn_mfma_f32_16x16x32_bf16(Bt[n][k], At[m][k], acc[ai][bj][m][n], 0, 0, 0); __builtin_amdgcn_s_setprio(0); } while (0)
; #define PG8_WAIT_V(n) asm volatile("s_waitcnt vmcnt(" #n ")" ::: "memory")
; #define PG8_WAIT_L(n) asm volatile("s_waitcnt lgkmcnt(" #n ")" ::: "memory")
; #define PG8_BAR __builtin_amdgcn_s_barrier()
; #define PG8_SCHED __builtin_amdgcn_sched_barrier(0)
; template <class Epi>
; DEVINL void gemm_phase(LAS unsigned char* lds, const Gemm g, const Order& S, const Epi& E) {
;     ...
;             PG8_BAR; PG8_WAIT_L(0); PG8_MMA(0, 1, At, B1); PG8_BAR;
;             PG8_LDA(At, 1, 1); PG8_STAGE(PG8_SA(1, 0), a3, voffA);
;             PG8_BAR; PG8_WAIT_L(0); PG8_MMA(1, 0, At, B0); PG8_BAR; PG8_SCHED;
;             PG8_STAGE(PG8_SB(1, 1), b3 + hstepB, voffB);
;             PG8_WAIT_V(6); PG8_BAR; PG8_MMA(1, 1, At, B1); PG8_BAR;
;         }
	s_waitcnt lgkmcnt(0)
	s_setprio 1
	s_waitcnt lgkmcnt(0)
	v_mfma_f32_16x16x32_bf16 v[116:119], v[194:197], v[162:165], v[116:119]
	v_mfma_f32_16x16x32_bf16 v[116:119], v[198:201], v[166:169], v[116:119]
	v_mfma_f32_16x16x32_bf16 v[112:115], v[206:209], v[166:169], v[112:115]
	v_mfma_f32_16x16x32_bf16 v[112:115], v[202:205], v[162:165], v[112:115]
	v_mfma_f32_16x16x32_bf16 v[96:99], v[202:205], v[170:173], v[96:99]
	v_mfma_f32_16x16x32_bf16 v[96:99], v[206:209], v[174:177], v[96:99]
	v_mfma_f32_16x16x32_bf16 v[100:103], v[198:201], v[174:177], v[100:103]
	v_mfma_f32_16x16x32_bf16 v[100:103], v[194:197], v[170:173], v[100:103]
	v_mfma_f32_16x16x32_bf16 v[84:87], v[194:197], v[178:181], v[84:87]
	v_mfma_f32_16x16x32_bf16 v[84:87], v[198:201], v[182:185], v[84:87]
	v_mfma_f32_16x16x32_bf16 v[80:83], v[206:209], v[182:185], v[80:83]
	v_mfma_f32_16x16x32_bf16 v[80:83], v[202:205], v[178:181], v[80:83]
	v_mfma_f32_16x16x32_bf16 v[64:67], v[202:205], v[186:189], v[64:67]
	v_mfma_f32_16x16x32_bf16 v[64:67], v[206:209], v[190:193], v[64:67]
	v_mfma_f32_16x16x32_bf16 v[68:71], v[198:201], v[190:193], v[68:71]
	v_mfma_f32_16x16x32_bf16 v[68:71], v[194:197], v[186:189], v[68:71]
	s_setprio 0
	s_mov_b32 m0, s76
	v_lshl_add_u64 v[210:211], v[218:219], 0, s[0:1]
	s_barrier
	ds_read_b128 v[162:165], v144 offset:49152
	ds_read_b128 v[166:169], v144 offset:50176
	ds_read_b128 v[170:173], v144 offset:51200
	ds_read_b128 v[174:177], v144 offset:52224
	ds_read_b128 v[178:181], v144 offset:53248
	ds_read_b128 v[182:185], v144 offset:54272
	ds_read_b128 v[186:189], v144 offset:55296
	ds_read_b128 v[190:193], v144 offset:56320
	global_load_lds_dwordx4 v[210:211], off
	v_lshl_add_u64 v[210:211], v[220:221], 0, s[0:1]
	s_mov_b32 m0, s77
	s_nop 0
	global_load_lds_dwordx4 v[210:211], off
	s_barrier
	s_waitcnt lgkmcnt(0)
	s_setprio 1
	s_waitcnt lgkmcnt(0)
	v_mfma_f32_16x16x32_bf16 v[60:63], v[146:149], v[162:165], v[60:63]
	v_mfma_f32_16x16x32_bf16 v[60:63], v[150:153], v[166:169], v[60:63]
	v_mfma_f32_16x16x32_bf16 v[56:59], v[158:161], v[166:169], v[56:59]
	v_mfma_f32_16x16x32_bf16 v[56:59], v[154:157], v[162:165], v[56:59]
	v_mfma_f32_16x16x32_bf16 v[40:43], v[154:157], v[170:173], v[40:43]
	v_mfma_f32_16x16x32_bf16 v[40:43], v[158:161], v[174:177], v[40:43]
	v_mfma_f32_16x16x32_bf16 v[44:47], v[150:153], v[174:177], v[44:47]
	v_mfma_f32_16x16x32_bf16 v[44:47], v[146:149], v[170:173], v[44:47]
	v_mfma_f32_16x16x32_bf16 v[28:31], v[146:149], v[178:181], v[28:31]
	v_mfma_f32_16x16x32_bf16 v[28:31], v[150:153], v[182:185], v[28:31]
	v_mfma_f32_16x16x32_bf16 v[24:27], v[158:161], v[182:185], v[24:27]
	v_mfma_f32_16x16x32_bf16 v[24:27], v[154:157], v[178:181], v[24:27]
	v_mfma_f32_16x16x32_bf16 v[8:11], v[154:157], v[186:189], v[8:11]
	v_mfma_f32_16x16x32_bf16 v[8:11], v[158:161], v[190:193], v[8:11]
	v_mfma_f32_16x16x32_bf16 v[12:15], v[150:153], v[190:193], v[12:15]
	v_mfma_f32_16x16x32_bf16 v[12:15], v[146:149], v[186:189], v[12:15]
	s_setprio 0
	s_barrier
	s_add_u32 s2, s12, 0x80080
	s_addc_u32 s3, s13, 0
	s_add_i32 s12, vcc_lo, s68
	v_lshl_add_u64 v[146:147], s[2:3], 0, v[130:131]
	s_mov_b32 m0, s12
	s_nop 0
	global_load_lds_dwordx4 v[146:147], off
	v_lshl_add_u64 v[146:147], s[2:3], 0, v[134:135]
	s_add_i32 m0, s12, 0x2000
	s_nop 0
	global_load_lds_dwordx4 v[146:147], off
	s_waitcnt vmcnt(6)
	s_barrier
	s_setprio 1
	v_mfma_f32_16x16x32_bf16 v[52:55], v[194:197], v[162:165], v[52:55]
	v_mfma_f32_16x16x32_bf16 v[52:55], v[198:201], v[166:169], v[52:55]
	v_mfma_f32_16x16x32_bf16 v[48:51], v[206:209], v[166:169], v[48:51]
	v_mfma_f32_16x16x32_bf16 v[48:51], v[202:205], v[162:165], v[48:51]
	v_mfma_f32_16x16x32_bf16 v[32:35], v[202:205], v[170:173], v[32:35]
	v_mfma_f32_16x16x32_bf16 v[32:35], v[206:209], v[174:177], v[32:35]
	v_mfma_f32_16x16x32_bf16 v[36:39], v[198:201], v[174:177], v[36:39]
	v_mfma_f32_16x16x32_bf16 v[36:39], v[194:197], v[170:173], v[36:39]
	v_mfma_f32_16x16x32_bf16 v[20:23], v[194:197], v[178:181], v[20:23]
	v_mfma_f32_16x16x32_bf16 v[20:23], v[198:201], v[182:185], v[20:23]
	v_mfma_f32_16x16x32_bf16 v[16:19], v[206:209], v[182:185], v[16:19]
	v_mfma_f32_16x16x32_bf16 v[16:19], v[202:205], v[178:181], v[16:19]
	v_mfma_f32_16x16x32_bf16 v[0:3], v[202:205], v[186:189], v[0:3]
	v_mfma_f32_16x16x32_bf16 v[0:3], v[206:209], v[190:193], v[0:3]
	v_mfma_f32_16x16x32_bf16 v[4:7], v[198:201], v[190:193], v[4:7]
	v_mfma_f32_16x16x32_bf16 v[4:7], v[194:197], v[186:189], v[4:7]
	s_setprio 0
	s_add_u32 s14, s14, 0x100
	s_addc_u32 s15, s15, 0
	s_add_u32 s85, s85, 0x100
	s_addc_u32 s86, s86, 0
	s_cmp_ge_i32 s87, s75
	s_mov_b32 s12, s87
	s_barrier
	s_cbranch_scc0 .LBB0_382
	s_branch .LBB0_373

; #define PG8_STAGE(bufoff, gbase, voff) do { _Pragma("unroll") for (int _i = 0; _i < 2; ++_i) \
;         __builtin_amdgcn_global_load_lds((const unsigned*)((const char*)(gbase) + (voff)[_i]), (LAS unsigned*)(lds + (bufoff) + ldsw + _i * 8192), 16, 0, 0); } while (0)
; #define PG8_LDA(dst, b, h) do { _Pragma("unroll") for (int m = 0; m < 4; ++m) _Pragma("unroll") for (int k = 0; k < 2; ++k) dst[m][k] = *(const LAS bf16x8*)(lds + PG8_SA(b, h) + aoff + m * 2048 + k * 1024); } while (0)
; #define PG8_LDB(dst, b, h) do { _Pragma("unroll") for (int n = 0; n < 2; ++n) _Pragma("unroll") for (int k = 0; k < 2; ++k) dst[n][k] = *(const LAS bf16x8*)(lds + PG8_SB(b, h) + boff + n * 2048 + k * 1024); } while (0)
; #define PG8_MMA(ai, bj, At, Bt) do { __builtin_amdgcn_s_setprio(1); _Pragma("unroll") for (int m = 0; m < 4; ++m) _Pragma("unroll") for (int n = 0; n < 2; ++n) _Pragma("unroll") for (int k = 0; k < 2; ++k) \
;         acc[ai][bj][m][n] = __builtin_amdgcn_mfma_f32_16x16x32_bf16(Bt[n][k], At[m][k], acc[ai][bj][m][n], 0, 0, 0); __builtin_amdgcn_s_setprio(0); } while (0)
; #define PG8_WAIT_L(n) asm volatile("s_waitcnt lgkmcnt(" #n ")" ::: "memory")
; #define PG8_BAR __builtin_amdgcn_s_barrier()
; #define PG8_SCHED __builtin_amdgcn_sched_barrier(0)
; template <class Epi>
; DEVINL void gemm_phase(LAS unsigned char* lds, const Gemm g, const Order& S, const Epi& E) {
;     ...
;             const char* a1 = cA + (size_t)(t + 1) * kstep;
;             const char* a2 = last ? nA : cA + (size_t)(t + 2) * kstep; const char* b2 = last ? nB : cB + (size_t)(t + 2) * kstep;
;             const char* a3 = a2 + kstep; const char* b3 = b2 + kstep;
;             PG8_LDB(B0, 0, 0); PG8_SCHED; PG8_LDA(At, 0, 0); PG8_STAGE(PG8_SA(1, 1), a1 + hstepA, voffA);
;             PG8_WAIT_L(8); PG8_BAR; PG8_WAIT_L(0); PG8_MMA(0, 0, At, B0); PG8_BAR; PG8_SCHED;
;             PG8_LDB(B1, 0, 1); PG8_STAGE(PG8_SB(0, 0), b2, voffB);
;             PG8_BAR; PG8_WAIT_L(0); PG8_MMA(0, 1, At, B1); PG8_BAR;
;             PG8_LDA(At, 0, 1); PG8_STAGE(PG8_SA(0, 0), a2, voffA);
;             PG8_BAR; PG8_WAIT_L(0); PG8_MMA(1, 0, At, B0); PG8_BAR; PG8_SCHED;
.LBB0_459:
	ds_read_b128 v[150:153], v147
	ds_read_b128 v[154:157], v147 offset:1024
	ds_read_b128 v[158:161], v147 offset:2048
	ds_read_b128 v[162:165], v147 offset:3072
	s_add_i32 s85, s14, 2
	s_add_u32 s10, s12, 0x100
	s_addc_u32 s11, s13, 0
	s_cmp_eq_u32 s74, s14
	s_cselect_b32 s14, s4, s83
	s_cselect_b32 s65, s9, s11
	s_cselect_b32 s64, s8, s10
	s_cselect_b32 s15, s5, s84
	v_lshl_add_u64 v[198:199], s[12:13], 0, v[136:137]
	s_add_i32 m0, s38, 0xc000
	ds_read_b128 v[166:169], v148
	ds_read_b128 v[170:173], v148 offset:1024
	ds_read_b128 v[174:177], v148 offset:2048
	ds_read_b128 v[178:181], v148 offset:3072
	ds_read_b128 v[182:185], v148 offset:4096
	ds_read_b128 v[186:189], v148 offset:5120
	ds_read_b128 v[190:193], v148 offset:6144
	ds_read_b128 v[194:197], v148 offset:7168
	global_load_lds_dwordx4 v[198:199], off
	v_lshl_add_u64 v[198:199], s[12:13], 0, v[138:139]
	s_add_i32 m0, s38, 0xe000
	s_nop 0
	global_load_lds_dwordx4 v[198:199], off
	s_waitcnt lgkmcnt(8)
	s_barrier
	s_waitcnt lgkmcnt(0)
	s_setprio 1
	s_waitcnt lgkmcnt(0)
	v_mfma_f32_16x16x32_bf16 v[120:123], v[150:153], v[166:169], v[120:123]
	v_mfma_f32_16x16x32_bf16 v[120:123], v[154:157], v[170:173], v[120:123]
	v_mfma_f32_16x16x32_bf16 v[124:127], v[162:165], v[170:173], v[124:127]
	v_mfma_f32_16x16x32_bf16 v[124:127], v[158:161], v[166:169], v[124:127]
	v_mfma_f32_16x16x32_bf16 v[104:107], v[158:161], v[174:177], v[104:107]
	v_mfma_f32_16x16x32_bf16 v[104:107], v[162:165], v[178:181], v[104:107]
	v_mfma_f32_16x16x32_bf16 v[108:111], v[154:157], v[178:181], v[108:111]
	v_mfma_f32_16x16x32_bf16 v[108:111], v[150:153], v[174:177], v[108:111]
	v_mfma_f32_16x16x32_bf16 v[92:95], v[150:153], v[182:185], v[92:95]
	v_mfma_f32_16x16x32_bf16 v[92:95], v[154:157], v[186:189], v[92:95]
	v_mfma_f32_16x16x32_bf16 v[88:91], v[162:165], v[186:189], v[88:91]
	v_mfma_f32_16x16x32_bf16 v[88:91], v[158:161], v[182:185], v[88:91]
	v_mfma_f32_16x16x32_bf16 v[72:75], v[158:161], v[190:193], v[72:75]
	v_mfma_f32_16x16x32_bf16 v[72:75], v[162:165], v[194:197], v[72:75]
	v_mfma_f32_16x16x32_bf16 v[76:79], v[154:157], v[194:197], v[76:79]
	v_mfma_f32_16x16x32_bf16 v[76:79], v[150:153], v[190:193], v[76:79]
	s_setprio 0
	s_barrier
	s_add_i32 s2, s78, s37
	v_lshl_add_u64 v[218:219], s[14:15], 0, v[130:131]
	s_mov_b32 m0, s2
	ds_read_b128 v[198:201], v149
	ds_read_b128 v[202:205], v149 offset:1024
	ds_read_b128 v[206:209], v149 offset:2048
	ds_read_b128 v[210:213], v149 offset:3072
	global_load_lds_dwordx4 v[218:219], off
	v_lshl_add_u64 v[220:221], s[14:15], 0, v[134:135]
	s_add_i32 m0, s2, 0x2000
	s_nop 0
	global_load_lds_dwordx4 v[220:221], off
	s_barrier
	s_waitcnt lgkmcnt(0)
	s_setprio 1
	s_waitcnt lgkmcnt(0)
	v_mfma_f32_16x16x32_bf16 v[116:119], v[198:201], v[166:169], v[116:119]
	v_mfma_f32_16x16x32_bf16 v[116:119], v[202:205], v[170:173], v[116:119]
	v_mfma_f32_16x16x32_bf16 v[112:115], v[210:213], v[170:173], v[112:115]
	v_mfma_f32_16x16x32_bf16 v[112:115], v[206:209], v[166:169], v[112:115]
	v_mfma_f32_16x16x32_bf16 v[96:99], v[206:209], v[174:177], v[96:99]
	v_mfma_f32_16x16x32_bf16 v[96:99], v[210:213], v[178:181], v[96:99]
	v_mfma_f32_16x16x32_bf16 v[100:103], v[202:205], v[178:181], v[100:103]
	v_mfma_f32_16x16x32_bf16 v[100:103], v[198:201], v[174:177], v[100:103]
	v_mfma_f32_16x16x32_bf16 v[84:87], v[198:201], v[182:185], v[84:87]
	v_mfma_f32_16x16x32_bf16 v[84:87], v[202:205], v[186:189], v[84:87]
	v_mfma_f32_16x16x32_bf16 v[80:83], v[210:213], v[186:189], v[80:83]
	v_mfma_f32_16x16x32_bf16 v[80:83], v[206:209], v[182:185], v[80:83]
	v_mfma_f32_16x16x32_bf16 v[64:67], v[206:209], v[190:193], v[64:67]
	v_mfma_f32_16x16x32_bf16 v[64:67], v[210:213], v[194:197], v[64:67]
	v_mfma_f32_16x16x32_bf16 v[68:71], v[202:205], v[194:197], v[68:71]
	v_mfma_f32_16x16x32_bf16 v[68:71], v[198:201], v[190:193], v[68:71]
	s_setprio 0
	s_mov_b32 m0, s38
	v_lshl_add_u64 v[222:223], s[64:65], 0, v[128:129]
	s_barrier
	ds_read_b128 v[166:169], v148 offset:16384
	ds_read_b128 v[170:173], v148 offset:17408
	ds_read_b128 v[174:177], v148 offset:18432
	ds_read_b128 v[178:181], v148 offset:19456
	ds_read_b128 v[182:185], v148 offset:20480
	ds_read_b128 v[186:189], v148 offset:21504
	ds_read_b128 v[190:193], v148 offset:22528
	ds_read_b128 v[194:197], v148 offset:23552
	global_load_lds_dwordx4 v[222:223], off
	v_lshl_add_u64 v[224:225], s[64:65], 0, v[132:133]
	s_mov_b32 m0, s39
	s_nop 0
	global_load_lds_dwordx4 v[224:225], off
	s_barrier
	s_waitcnt lgkmcnt(0)
	s_setprio 1
	s_waitcnt lgkmcnt(0)
	v_mfma_f32_16x16x32_bf16 v[60:63], v[150:153], v[166:169], v[60:63]
	v_mfma_f32_16x16x32_bf16 v[60:63], v[154:157], v[170:173], v[60:63]
	v_mfma_f32_16x16x32_bf16 v[56:59], v[162:165], v[170:173], v[56:59]
	v_mfma_f32_16x16x32_bf16 v[56:59], v[158:161], v[166:169], v[56:59]
	v_mfma_f32_16x16x32_bf16 v[40:43], v[158:161], v[174:177], v[40:43]
	v_mfma_f32_16x16x32_bf16 v[40:43], v[162:165], v[178:181], v[40:43]
	v_mfma_f32_16x16x32_bf16 v[44:47], v[154:157], v[178:181], v[44:47]
	v_mfma_f32_16x16x32_bf16 v[44:47], v[150:153], v[174:177], v[44:47]
	v_mfma_f32_16x16x32_bf16 v[28:31], v[150:153], v[182:185], v[28:31]
	v_mfma_f32_16x16x32_bf16 v[28:31], v[154:157], v[186:189], v[28:31]
	v_mfma_f32_16x16x32_bf16 v[24:27], v[162:165], v[186:189], v[24:27]
	v_mfma_f32_16x16x32_bf16 v[24:27], v[158:161], v[182:185], v[24:27]
	v_mfma_f32_16x16x32_bf16 v[8:11], v[158:161], v[190:193], v[8:11]
	v_mfma_f32_16x16x32_bf16 v[8:11], v[162:165], v[194:197], v[8:11]
	v_mfma_f32_16x16x32_bf16 v[12:15], v[154:157], v[194:197], v[12:15]
	v_mfma_f32_16x16x32_bf16 v[12:15], v[150:153], v[190:193], v[12:15]
	s_setprio 0
	s_barrier
; #define PG8_STAGE(bufoff, gbase, voff) do { _Pragma("unroll") for (int _i = 0; _i < 2; ++_i) \
;         __builtin_amdgcn_global_load_lds((const unsigned*)((const char*)(gbase) + (voff)[_i]), (LAS unsigned*)(lds + (bufoff) + ldsw + _i * 8192), 16, 0, 0); } while (0)
; #define PG8_LDA(dst, b, h) do { _Pragma("unroll") for (int m = 0; m < 4; ++m) _Pragma("unroll") for (int k = 0; k < 2; ++k) dst[m][k] = *(const LAS bf16x8*)(lds + PG8_SA(b, h) + aoff + m * 2048 + k * 1024); } while (0)
; #define PG8_LDB(dst, b, h) do { _Pragma("unroll") for (int n = 0; n < 2; ++n) _Pragma("unroll") for (int k = 0; k < 2; ++k) dst[n][k] = *(const LAS bf16x8*)(lds + PG8_SB(b, h) + boff + n * 2048 + k * 1024); } while (0)
; #define PG8_MMA(ai, bj, At, Bt) do { __builtin_amdgcn_s_setprio(1); _Pragma("unroll") for (int m = 0; m < 4; ++m) _Pragma("unroll") for (int n = 0; n < 2; ++n) _Pragma("unroll") for (int k = 0; k < 2; ++k) \
;         acc[ai][bj][m][n] = __builtin_amdgcn_mfma_f32_16x16x32_bf16(Bt[n][k], At[m][k], acc[ai][bj][m][n], 0, 0, 0); __builtin_amdgcn_s_setprio(0); } while (0)
; #define PG8_WAIT_V(n) asm volatile("s_waitcnt vmcnt(" #n ")" ::: "memory")
; #define PG8_WAIT_L(n) asm volatile("s_waitcnt lgkmcnt(" #n ")" ::: "memory")
; #define PG8_BAR __builtin_amdgcn_s_barrier()
; #define PG8_SCHED __builtin_amdgcn_sched_barrier(0)
; template <class Epi>
; DEVINL void gemm_phase(LAS unsigned char* lds, const Gemm g, const Order& S, const Epi& E) {
;     ...
;             PG8_STAGE(PG8_SB(0, 1), b2 + hstepB, voffB);
;             PG8_WAIT_V(6); PG8_BAR; PG8_MMA(1, 1, At, B1); PG8_BAR;
;             PG8_LDB(B0, 1, 0); PG8_SCHED; PG8_LDA(At, 1, 0); PG8_STAGE(PG8_SA(0, 1), a2 + hstepA, voffA);
;             PG8_WAIT_L(8); PG8_BAR; PG8_WAIT_L(0); PG8_MMA(0, 0, At, B0); PG8_BAR; PG8_SCHED;
;             PG8_LDB(B1, 1, 1); PG8_STAGE(PG8_SB(1, 0), b3, voffB);
	s_add_u32 s2, s14, 0x158000
	s_addc_u32 s3, s15, 0
	s_add_i32 s12, s79, s37
	v_lshl_add_u64 v[150:151], s[2:3], 0, v[130:131]
	s_mov_b32 m0, s12
	s_nop 0
	global_load_lds_dwordx4 v[150:151], off
	v_lshl_add_u64 v[150:151], s[2:3], 0, v[134:135]
	s_add_i32 m0, s12, 0x2000
	s_nop 0
	global_load_lds_dwordx4 v[150:151], off
	s_waitcnt vmcnt(6)
	s_barrier
	s_setprio 1
	v_mfma_f32_16x16x32_bf16 v[52:55], v[198:201], v[166:169], v[52:55]
	v_mfma_f32_16x16x32_bf16 v[52:55], v[202:205], v[170:173], v[52:55]
	v_mfma_f32_16x16x32_bf16 v[48:51], v[210:213], v[170:173], v[48:51]
	v_mfma_f32_16x16x32_bf16 v[48:51], v[206:209], v[166:169], v[48:51]
	v_mfma_f32_16x16x32_bf16 v[32:35], v[206:209], v[174:177], v[32:35]
	v_mfma_f32_16x16x32_bf16 v[32:35], v[210:213], v[178:181], v[32:35]
	v_mfma_f32_16x16x32_bf16 v[36:39], v[202:205], v[178:181], v[36:39]
	v_mfma_f32_16x16x32_bf16 v[36:39], v[198:201], v[174:177], v[36:39]
	v_mfma_f32_16x16x32_bf16 v[20:23], v[198:201], v[182:185], v[20:23]
	v_mfma_f32_16x16x32_bf16 v[20:23], v[202:205], v[186:189], v[20:23]
	v_mfma_f32_16x16x32_bf16 v[16:19], v[210:213], v[186:189], v[16:19]
	v_mfma_f32_16x16x32_bf16 v[16:19], v[206:209], v[182:185], v[16:19]
	v_mfma_f32_16x16x32_bf16 v[0:3], v[206:209], v[190:193], v[0:3]
	v_mfma_f32_16x16x32_bf16 v[0:3], v[210:213], v[194:197], v[0:3]
	v_mfma_f32_16x16x32_bf16 v[4:7], v[202:205], v[194:197], v[4:7]
	v_mfma_f32_16x16x32_bf16 v[4:7], v[198:201], v[190:193], v[4:7]
	s_setprio 0
	s_add_i32 s12, 16, 0x18000
	v_add_u32_e32 v162, s12, v145
	s_barrier
	ds_read_b128 v[150:153], v162
	ds_read_b128 v[154:157], v162 offset:1024
	ds_read_b128 v[158:161], v162 offset:2048
	ds_read_b128 v[162:165], v162 offset:3072
	s_add_u32 s2, s64, 0x158000
	s_addc_u32 s3, s65, 0
	s_mov_b32 m0, s66
	v_lshl_add_u64 v[198:199], s[2:3], 0, v[128:129]
	ds_read_b128 v[166:169], v148 offset:32768
	ds_read_b128 v[170:173], v148 offset:33792
	ds_read_b128 v[174:177], v148 offset:34816
	ds_read_b128 v[178:181], v148 offset:35840
	ds_read_b128 v[182:185], v148 offset:36864
	ds_read_b128 v[186:189], v148 offset:37888
	ds_read_b128 v[190:193], v148 offset:38912
	ds_read_b128 v[194:197], v148 offset:39936
	global_load_lds_dwordx4 v[198:199], off
	v_lshl_add_u64 v[198:199], s[2:3], 0, v[132:133]
	s_mov_b32 m0, s67
	s_nop 0
	global_load_lds_dwordx4 v[198:199], off
	s_waitcnt lgkmcnt(8)
	s_barrier
	s_waitcnt lgkmcnt(0)
	s_setprio 1
	s_waitcnt lgkmcnt(0)
	v_mfma_f32_16x16x32_bf16 v[120:123], v[150:153], v[166:169], v[120:123]
	v_mfma_f32_16x16x32_bf16 v[120:123], v[154:157], v[170:173], v[120:123]
	v_mfma_f32_16x16x32_bf16 v[124:127], v[162:165], v[170:173], v[124:127]
	v_mfma_f32_16x16x32_bf16 v[124:127], v[158:161], v[166:169], v[124:127]
	v_mfma_f32_16x16x32_bf16 v[104:107], v[158:161], v[174:177], v[104:107]
	v_mfma_f32_16x16x32_bf16 v[104:107], v[162:165], v[178:181], v[104:107]
	v_mfma_f32_16x16x32_bf16 v[108:111], v[154:157], v[178:181], v[108:111]
	v_mfma_f32_16x16x32_bf16 v[108:111], v[150:153], v[174:177], v[108:111]
	v_mfma_f32_16x16x32_bf16 v[92:95], v[150:153], v[182:185], v[92:95]
	v_mfma_f32_16x16x32_bf16 v[92:95], v[154:157], v[186:189], v[92:95]
	v_mfma_f32_16x16x32_bf16 v[88:91], v[162:165], v[186:189], v[88:91]
	v_mfma_f32_16x16x32_bf16 v[88:91], v[158:161], v[182:185], v[88:91]
	v_mfma_f32_16x16x32_bf16 v[72:75], v[158:161], v[190:193], v[72:75]
	v_mfma_f32_16x16x32_bf16 v[72:75], v[162:165], v[194:197], v[72:75]
	v_mfma_f32_16x16x32_bf16 v[76:79], v[154:157], v[194:197], v[76:79]
	v_mfma_f32_16x16x32_bf16 v[76:79], v[150:153], v[190:193], v[76:79]
	s_setprio 0
	s_barrier
	s_add_i32 s13, 16, 0x1c000
	s_add_i32 s2, s12, s37
	v_add_u32_e32 v210, s13, v145
	v_lshl_add_u64 v[218:219], v[218:219], 0, s[6:7]
	s_mov_b32 m0, s2
	ds_read_b128 v[198:201], v210
	ds_read_b128 v[202:205], v210 offset:1024
	ds_read_b128 v[206:209], v210 offset:2048
	ds_read_b128 v[210:213], v210 offset:3072
	global_load_lds_dwordx4 v[218:219], off
	v_lshl_add_u64 v[218:219], v[220:221], 0, s[6:7]
	s_add_i32 m0, s2, 0x2000
	s_nop 0
	global_load_lds_dwordx4 v[218:219], off
	s_barrier
; #define PG8_STAGE(bufoff, gbase, voff) do { _Pragma("unroll") for (int _i = 0; _i < 2; ++_i) \
;         __builtin_amdgcn_global_load_lds((const unsigned*)((const char*)(gbase) + (voff)[_i]), (LAS unsigned*)(lds + (bufoff) + ldsw + _i * 8192), 16, 0, 0); } while (0)
; #define PG8_LDA(dst, b, h) do { _Pragma("unroll") for (int m = 0; m < 4; ++m) _Pragma("unroll") for (int k = 0; k < 2; ++k) dst[m][k] = *(const LAS bf16x8*)(lds + PG8_SA(b, h) + aoff + m * 2048 + k * 1024); } while (0)
; #define PG8_MMA(ai, bj, At, Bt) do { __builtin_amdgcn_s_setprio(1); _Pragma("unroll") for (int m = 0; m < 4; ++m) _Pragma("unroll") for (int n = 0; n < 2; ++n) _Pragma("unroll") for (int k = 0; k < 2; ++k) \
;         acc[ai][bj][m][n] = __builtin_amdgcn_mfma_f32_16x16x32_bf16(Bt[n][k], At[m][k], acc[ai][bj][m][n], 0, 0, 0); __builtin_amdgcn_s_setprio(0); } while (0)
; #define PG8_WAIT_V(n) asm volatile("s_waitcnt vmcnt(" #n ")" ::: "memory")
; #define PG8_WAIT_L(n) asm volatile("s_waitcnt lgkmcnt(" #n ")" ::: "memory")
; #define PG8_BAR __builtin_amdgcn_s_barrier()
; #define PG8_SCHED __builtin_amdgcn_sched_barrier(0)
; template <class Epi>
; DEVINL void gemm_phase(LAS unsigned char* lds, const Gemm g, const Order& S, const Epi& E) {
;     ...
;             PG8_BAR; PG8_WAIT_L(0); PG8_MMA(0, 1, At, B1); PG8_BAR;
;             PG8_LDA(At, 1, 1); PG8_STAGE(PG8_SA(1, 0), a3, voffA);
;             PG8_BAR; PG8_WAIT_L(0); PG8_MMA(1, 0, At, B0); PG8_BAR; PG8_SCHED;
;             PG8_STAGE(PG8_SB(1, 1), b3 + hstepB, voffB);
;             PG8_WAIT_V(6); PG8_BAR; PG8_MMA(1, 1, At, B1); PG8_BAR;
;         }
	s_waitcnt lgkmcnt(0)
	s_setprio 1
	s_waitcnt lgkmcnt(0)
	v_mfma_f32_16x16x32_bf16 v[116:119], v[198:201], v[166:169], v[116:119]
	v_mfma_f32_16x16x32_bf16 v[116:119], v[202:205], v[170:173], v[116:119]
	v_mfma_f32_16x16x32_bf16 v[112:115], v[210:213], v[170:173], v[112:115]
	v_mfma_f32_16x16x32_bf16 v[112:115], v[206:209], v[166:169], v[112:115]
	v_mfma_f32_16x16x32_bf16 v[96:99], v[206:209], v[174:177], v[96:99]
	v_mfma_f32_16x16x32_bf16 v[96:99], v[210:213], v[178:181], v[96:99]
	v_mfma_f32_16x16x32_bf16 v[100:103], v[202:205], v[178:181], v[100:103]
	v_mfma_f32_16x16x32_bf16 v[100:103], v[198:201], v[174:177], v[100:103]
	v_mfma_f32_16x16x32_bf16 v[84:87], v[198:201], v[182:185], v[84:87]
	v_mfma_f32_16x16x32_bf16 v[84:87], v[202:205], v[186:189], v[84:87]
	v_mfma_f32_16x16x32_bf16 v[80:83], v[210:213], v[186:189], v[80:83]
	v_mfma_f32_16x16x32_bf16 v[80:83], v[206:209], v[182:185], v[80:83]
	v_mfma_f32_16x16x32_bf16 v[64:67], v[206:209], v[190:193], v[64:67]
	v_mfma_f32_16x16x32_bf16 v[64:67], v[210:213], v[194:197], v[64:67]
	v_mfma_f32_16x16x32_bf16 v[68:71], v[202:205], v[194:197], v[68:71]
	v_mfma_f32_16x16x32_bf16 v[68:71], v[198:201], v[190:193], v[68:71]
	s_setprio 0
	s_mov_b32 m0, s69
	v_lshl_add_u64 v[218:219], v[222:223], 0, s[6:7]
	s_barrier
	ds_read_b128 v[166:169], v148 offset:49152
	ds_read_b128 v[170:173], v148 offset:50176
	ds_read_b128 v[174:177], v148 offset:51200
	ds_read_b128 v[178:181], v148 offset:52224
	ds_read_b128 v[182:185], v148 offset:53248
	ds_read_b128 v[186:189], v148 offset:54272
	ds_read_b128 v[190:193], v148 offset:55296
	ds_read_b128 v[194:197], v148 offset:56320
	global_load_lds_dwordx4 v[218:219], off
	v_lshl_add_u64 v[218:219], v[224:225], 0, s[6:7]
	s_mov_b32 m0, s72
	s_nop 0
	global_load_lds_dwordx4 v[218:219], off
	s_barrier
	s_waitcnt lgkmcnt(0)
	s_setprio 1
	s_waitcnt lgkmcnt(0)
	v_mfma_f32_16x16x32_bf16 v[60:63], v[150:153], v[166:169], v[60:63]
	v_mfma_f32_16x16x32_bf16 v[60:63], v[154:157], v[170:173], v[60:63]
	v_mfma_f32_16x16x32_bf16 v[56:59], v[162:165], v[170:173], v[56:59]
	v_mfma_f32_16x16x32_bf16 v[56:59], v[158:161], v[166:169], v[56:59]
	v_mfma_f32_16x16x32_bf16 v[40:43], v[158:161], v[174:177], v[40:43]
	v_mfma_f32_16x16x32_bf16 v[40:43], v[162:165], v[178:181], v[40:43]
	v_mfma_f32_16x16x32_bf16 v[44:47], v[154:157], v[178:181], v[44:47]
	v_mfma_f32_16x16x32_bf16 v[44:47], v[150:153], v[174:177], v[44:47]
	v_mfma_f32_16x16x32_bf16 v[28:31], v[150:153], v[182:185], v[28:31]
	v_mfma_f32_16x16x32_bf16 v[28:31], v[154:157], v[186:189], v[28:31]
	v_mfma_f32_16x16x32_bf16 v[24:27], v[162:165], v[186:189], v[24:27]
	v_mfma_f32_16x16x32_bf16 v[24:27], v[158:161], v[182:185], v[24:27]
	v_mfma_f32_16x16x32_bf16 v[8:11], v[158:161], v[190:193], v[8:11]
	v_mfma_f32_16x16x32_bf16 v[8:11], v[162:165], v[194:197], v[8:11]
	v_mfma_f32_16x16x32_bf16 v[12:15], v[154:157], v[194:197], v[12:15]
	v_mfma_f32_16x16x32_bf16 v[12:15], v[150:153], v[190:193], v[12:15]
	s_setprio 0
	s_barrier
	s_add_u32 s2, s14, 0x158080
	s_addc_u32 s3, s15, 0
	s_add_i32 s12, s13, s37
	v_lshl_add_u64 v[150:151], s[2:3], 0, v[130:131]
	s_mov_b32 m0, s12
	s_nop 0
	global_load_lds_dwordx4 v[150:151], off
	v_lshl_add_u64 v[150:151], s[2:3], 0, v[134:135]
	s_add_i32 m0, s12, 0x2000
	s_nop 0
	global_load_lds_dwordx4 v[150:151], off
	s_waitcnt vmcnt(6)
	s_barrier
	s_setprio 1
	v_mfma_f32_16x16x32_bf16 v[52:55], v[198:201], v[166:169], v[52:55]
	v_mfma_f32_16x16x32_bf16 v[52:55], v[202:205], v[170:173], v[52:55]
	v_mfma_f32_16x16x32_bf16 v[48:51], v[210:213], v[170:173], v[48:51]
	v_mfma_f32_16x16x32_bf16 v[48:51], v[206:209], v[166:169], v[48:51]
	v_mfma_f32_16x16x32_bf16 v[32:35], v[206:209], v[174:177], v[32:35]
	v_mfma_f32_16x16x32_bf16 v[32:35], v[210:213], v[178:181], v[32:35]
	v_mfma_f32_16x16x32_bf16 v[36:39], v[202:205], v[178:181], v[36:39]
	v_mfma_f32_16x16x32_bf16 v[36:39], v[198:201], v[174:177], v[36:39]
	v_mfma_f32_16x16x32_bf16 v[20:23], v[198:201], v[182:185], v[20:23]
	v_mfma_f32_16x16x32_bf16 v[20:23], v[202:205], v[186:189], v[20:23]
	v_mfma_f32_16x16x32_bf16 v[16:19], v[210:213], v[186:189], v[16:19]
	v_mfma_f32_16x16x32_bf16 v[16:19], v[206:209], v[182:185], v[16:19]
	v_mfma_f32_16x16x32_bf16 v[0:3], v[206:209], v[190:193], v[0:3]
	v_mfma_f32_16x16x32_bf16 v[0:3], v[210:213], v[194:197], v[0:3]
	v_mfma_f32_16x16x32_bf16 v[4:7], v[202:205], v[194:197], v[4:7]
	v_mfma_f32_16x16x32_bf16 v[4:7], v[198:201], v[190:193], v[4:7]
	s_setprio 0
	s_add_u32 s83, s83, 0x100
	s_addc_u32 s84, s84, 0
	s_cmp_ge_i32 s85, s68
	s_mov_b64 s[12:13], s[10:11]
	s_mov_b32 s14, s85
	s_barrier
	s_cbranch_scc0 .LBB0_459
	s_branch .LBB0_446

; #define PG8_STAGE(bufoff, gbase, voff) do { _Pragma("unroll") for (int _i = 0; _i < 2; ++_i) \
;         __builtin_amdgcn_global_load_lds((const unsigned*)((const char*)(gbase) + (voff)[_i]), (LAS unsigned*)(lds + (bufoff) + ldsw + _i * 8192), 16, 0, 0); } while (0)
; #define PG8_LDA(dst, b, h) do { _Pragma("unroll") for (int m = 0; m < 4; ++m) _Pragma("unroll") for (int k = 0; k < 2; ++k) dst[m][k] = *(const LAS bf16x8*)(lds + PG8_SA(b, h) + aoff + m * 2048 + k * 1024); } while (0)
; #define PG8_LDB(dst, b, h) do { _Pragma("unroll") for (int n = 0; n < 2; ++n) _Pragma("unroll") for (int k = 0; k < 2; ++k) dst[n][k] = *(const LAS bf16x8*)(lds + PG8_SB(b, h) + boff + n * 2048 + k * 1024); } while (0)
; #define PG8_MMA(ai, bj, At, Bt) do { __builtin_amdgcn_s_setprio(1); _Pragma("unroll") for (int m = 0; m < 4; ++m) _Pragma("unroll") for (int n = 0; n < 2; ++n) _Pragma("unroll") for (int k = 0; k < 2; ++k) \
;         acc[ai][bj][m][n] = __builtin_amdgcn_mfma_f32_16x16x32_bf16(Bt[n][k], At[m][k], acc[ai][bj][m][n], 0, 0, 0); __builtin_amdgcn_s_setprio(0); } while (0)
; #define PG8_WAIT_L(n) asm volatile("s_waitcnt lgkmcnt(" #n ")" ::: "memory")
; #define PG8_BAR __builtin_amdgcn_s_barrier()
; #define PG8_SCHED __builtin_amdgcn_sched_barrier(0)
; template <class Epi>
; DEVINL void gemm_phase(LAS unsigned char* lds, const Gemm g, const Order& S, const Epi& E) {
;     ...
;             const char* a1 = cA + (size_t)(t + 1) * kstep;
;             const char* a2 = last ? nA : cA + (size_t)(t + 2) * kstep; const char* b2 = last ? nB : cB + (size_t)(t + 2) * kstep;
;             const char* a3 = a2 + kstep; const char* b3 = b2 + kstep;
;             PG8_LDB(B0, 0, 0); PG8_SCHED; PG8_LDA(At, 0, 0); PG8_STAGE(PG8_SA(1, 1), a1 + hstepA, voffA);
;             PG8_WAIT_L(8); PG8_BAR; PG8_WAIT_L(0); PG8_MMA(0, 0, At, B0); PG8_BAR; PG8_SCHED;
;             PG8_LDB(B1, 0, 1); PG8_STAGE(PG8_SB(0, 0), b2, voffB);
;             PG8_BAR; PG8_WAIT_L(0); PG8_MMA(0, 1, At, B1); PG8_BAR;
;             PG8_LDA(At, 0, 1); PG8_STAGE(PG8_SA(0, 0), a2, voffA);
;             PG8_BAR; PG8_WAIT_L(0); PG8_MMA(1, 0, At, B0); PG8_BAR; PG8_SCHED;
.LBB0_650:
	ds_read_b128 v[128:131], v175
	ds_read_b128 v[132:135], v175 offset:1024
	ds_read_b128 v[136:139], v175 offset:2048
	ds_read_b128 v[140:143], v175 offset:3072
	s_add_i32 s64, s14, 2
	s_add_u32 s2, s12, 0xfff80080
	s_addc_u32 s3, s13, -1
	s_cmp_eq_u32 s49, s14
	s_cselect_b32 s14, s57, s58
	s_cselect_b32 s45, s11, s3
	s_cselect_b32 s44, s17, s2
	s_cselect_b32 s15, s56, s59
	v_lshl_add_u64 v[170:171], s[12:13], 0, v[156:157]
	s_add_i32 m0, s29, 0xc000
	ds_read_b128 v[166:169], v176
	ds_read_b128 v[178:181], v176 offset:1024
	ds_read_b128 v[182:185], v176 offset:2048
	ds_read_b128 v[186:189], v176 offset:3072
	ds_read_b128 v[190:193], v176 offset:4096
	ds_read_b128 v[194:197], v176 offset:5120
	ds_read_b128 v[198:201], v176 offset:6144
	ds_read_b128 v[202:205], v176 offset:7168
	global_load_lds_dwordx4 v[170:171], off
	v_lshl_add_u64 v[170:171], s[12:13], 0, v[158:159]
	s_add_i32 m0, s29, 0xe000
	s_nop 0
	global_load_lds_dwordx4 v[170:171], off
	s_waitcnt lgkmcnt(8)
	s_barrier
	s_waitcnt lgkmcnt(0)
	s_setprio 1
	s_waitcnt lgkmcnt(0)
	v_mfma_f32_16x16x32_bf16 v[124:127], v[128:131], v[166:169], v[124:127]
	v_mfma_f32_16x16x32_bf16 v[124:127], v[132:135], v[178:181], v[124:127]
	v_mfma_f32_16x16x32_bf16 v[120:123], v[140:143], v[178:181], v[120:123]
	v_mfma_f32_16x16x32_bf16 v[120:123], v[136:139], v[166:169], v[120:123]
	v_mfma_f32_16x16x32_bf16 v[104:107], v[136:139], v[182:185], v[104:107]
	v_mfma_f32_16x16x32_bf16 v[104:107], v[140:143], v[186:189], v[104:107]
	v_mfma_f32_16x16x32_bf16 v[108:111], v[132:135], v[186:189], v[108:111]
	v_mfma_f32_16x16x32_bf16 v[108:111], v[128:131], v[182:185], v[108:111]
	v_mfma_f32_16x16x32_bf16 v[92:95], v[128:131], v[190:193], v[92:95]
	v_mfma_f32_16x16x32_bf16 v[92:95], v[132:135], v[194:197], v[92:95]
	v_mfma_f32_16x16x32_bf16 v[88:91], v[140:143], v[194:197], v[88:91]
	v_mfma_f32_16x16x32_bf16 v[88:91], v[136:139], v[190:193], v[88:91]
	v_mfma_f32_16x16x32_bf16 v[72:75], v[136:139], v[198:201], v[72:75]
	v_mfma_f32_16x16x32_bf16 v[72:75], v[140:143], v[202:205], v[72:75]
	v_mfma_f32_16x16x32_bf16 v[76:79], v[132:135], v[202:205], v[76:79]
	v_mfma_f32_16x16x32_bf16 v[76:79], v[128:131], v[198:201], v[76:79]
	s_setprio 0
	s_barrier
	s_add_i32 s2, s52, s26
	v_lshl_add_u64 v[170:171], s[14:15], 0, v[148:149]
	s_mov_b32 m0, s2
	ds_read_b128 v[206:209], v177
	ds_read_b128 v[210:213], v177 offset:1024
	ds_read_b128 v[218:221], v177 offset:2048
	ds_read_b128 v[222:225], v177 offset:3072
	global_load_lds_dwordx4 v[170:171], off
	v_lshl_add_u64 v[226:227], s[14:15], 0, v[144:145]
	s_add_i32 m0, s2, 0x2000
	s_nop 0
	global_load_lds_dwordx4 v[226:227], off
	s_barrier
	s_waitcnt lgkmcnt(0)
	s_setprio 1
	s_waitcnt lgkmcnt(0)
	v_mfma_f32_16x16x32_bf16 v[116:119], v[206:209], v[166:169], v[116:119]
	v_mfma_f32_16x16x32_bf16 v[116:119], v[210:213], v[178:181], v[116:119]
	v_mfma_f32_16x16x32_bf16 v[112:115], v[222:225], v[178:181], v[112:115]
	v_mfma_f32_16x16x32_bf16 v[112:115], v[218:221], v[166:169], v[112:115]
	v_mfma_f32_16x16x32_bf16 v[96:99], v[218:221], v[182:185], v[96:99]
	v_mfma_f32_16x16x32_bf16 v[96:99], v[222:225], v[186:189], v[96:99]
	v_mfma_f32_16x16x32_bf16 v[100:103], v[210:213], v[186:189], v[100:103]
	v_mfma_f32_16x16x32_bf16 v[100:103], v[206:209], v[182:185], v[100:103]
	v_mfma_f32_16x16x32_bf16 v[84:87], v[206:209], v[190:193], v[84:87]
	v_mfma_f32_16x16x32_bf16 v[84:87], v[210:213], v[194:197], v[84:87]
	v_mfma_f32_16x16x32_bf16 v[80:83], v[222:225], v[194:197], v[80:83]
	v_mfma_f32_16x16x32_bf16 v[80:83], v[218:221], v[190:193], v[80:83]
	v_mfma_f32_16x16x32_bf16 v[64:67], v[218:221], v[198:201], v[64:67]
	v_mfma_f32_16x16x32_bf16 v[64:67], v[222:225], v[202:205], v[64:67]
	v_mfma_f32_16x16x32_bf16 v[68:71], v[210:213], v[202:205], v[68:71]
	v_mfma_f32_16x16x32_bf16 v[68:71], v[206:209], v[198:201], v[68:71]
	s_setprio 0
	s_mov_b32 m0, s29
	v_lshl_add_u64 v[228:229], s[44:45], 0, v[150:151]
	s_barrier
	ds_read_b128 v[166:169], v176 offset:16384
	ds_read_b128 v[178:181], v176 offset:17408
	ds_read_b128 v[182:185], v176 offset:18432
	ds_read_b128 v[186:189], v176 offset:19456
	ds_read_b128 v[190:193], v176 offset:20480
	ds_read_b128 v[194:197], v176 offset:21504
	ds_read_b128 v[198:201], v176 offset:22528
	ds_read_b128 v[202:205], v176 offset:23552
	global_load_lds_dwordx4 v[228:229], off
	v_lshl_add_u64 v[230:231], s[44:45], 0, v[146:147]
	s_mov_b32 m0, s30
	s_nop 0
	global_load_lds_dwordx4 v[230:231], off
	s_barrier
	s_waitcnt lgkmcnt(0)
	s_setprio 1
	s_waitcnt lgkmcnt(0)
	v_mfma_f32_16x16x32_bf16 v[60:63], v[128:131], v[166:169], v[60:63]
	v_mfma_f32_16x16x32_bf16 v[60:63], v[132:135], v[178:181], v[60:63]
	v_mfma_f32_16x16x32_bf16 v[56:59], v[140:143], v[178:181], v[56:59]
	v_mfma_f32_16x16x32_bf16 v[56:59], v[136:139], v[166:169], v[56:59]
	v_mfma_f32_16x16x32_bf16 v[40:43], v[136:139], v[182:185], v[40:43]
	v_mfma_f32_16x16x32_bf16 v[40:43], v[140:143], v[186:189], v[40:43]
	v_mfma_f32_16x16x32_bf16 v[44:47], v[132:135], v[186:189], v[44:47]
	v_mfma_f32_16x16x32_bf16 v[44:47], v[128:131], v[182:185], v[44:47]
	v_mfma_f32_16x16x32_bf16 v[28:31], v[128:131], v[190:193], v[28:31]
	v_mfma_f32_16x16x32_bf16 v[28:31], v[132:135], v[194:197], v[28:31]
	v_mfma_f32_16x16x32_bf16 v[24:27], v[140:143], v[194:197], v[24:27]
	v_mfma_f32_16x16x32_bf16 v[24:27], v[136:139], v[190:193], v[24:27]
	v_mfma_f32_16x16x32_bf16 v[8:11], v[136:139], v[198:201], v[8:11]
	v_mfma_f32_16x16x32_bf16 v[8:11], v[140:143], v[202:205], v[8:11]
	v_mfma_f32_16x16x32_bf16 v[12:15], v[132:135], v[202:205], v[12:15]
	v_mfma_f32_16x16x32_bf16 v[12:15], v[128:131], v[198:201], v[12:15]
	s_setprio 0
	s_barrier
; #define PG8_STAGE(bufoff, gbase, voff) do { _Pragma("unroll") for (int _i = 0; _i < 2; ++_i) \
;         __builtin_amdgcn_global_load_lds((const unsigned*)((const char*)(gbase) + (voff)[_i]), (LAS unsigned*)(lds + (bufoff) + ldsw + _i * 8192), 16, 0, 0); } while (0)
; #define PG8_LDA(dst, b, h) do { _Pragma("unroll") for (int m = 0; m < 4; ++m) _Pragma("unroll") for (int k = 0; k < 2; ++k) dst[m][k] = *(const LAS bf16x8*)(lds + PG8_SA(b, h) + aoff + m * 2048 + k * 1024); } while (0)
; #define PG8_LDB(dst, b, h) do { _Pragma("unroll") for (int n = 0; n < 2; ++n) _Pragma("unroll") for (int k = 0; k < 2; ++k) dst[n][k] = *(const LAS bf16x8*)(lds + PG8_SB(b, h) + boff + n * 2048 + k * 1024); } while (0)
; #define PG8_MMA(ai, bj, At, Bt) do { __builtin_amdgcn_s_setprio(1); _Pragma("unroll") for (int m = 0; m < 4; ++m) _Pragma("unroll") for (int n = 0; n < 2; ++n) _Pragma("unroll") for (int k = 0; k < 2; ++k) \
;         acc[ai][bj][m][n] = __builtin_amdgcn_mfma_f32_16x16x32_bf16(Bt[n][k], At[m][k], acc[ai][bj][m][n], 0, 0, 0); __builtin_amdgcn_s_setprio(0); } while (0)
; #define PG8_WAIT_V(n) asm volatile("s_waitcnt vmcnt(" #n ")" ::: "memory")
; #define PG8_WAIT_L(n) asm volatile("s_waitcnt lgkmcnt(" #n ")" ::: "memory")
; #define PG8_BAR __builtin_amdgcn_s_barrier()
; #define PG8_SCHED __builtin_amdgcn_sched_barrier(0)
; template <class Epi>
; DEVINL void gemm_phase(LAS unsigned char* lds, const Gemm g, const Order& S, const Epi& E) {
;     ...
;             PG8_STAGE(PG8_SB(0, 1), b2 + hstepB, voffB);
;             PG8_WAIT_V(6); PG8_BAR; PG8_MMA(1, 1, At, B1); PG8_BAR;
;             PG8_LDB(B0, 1, 0); PG8_SCHED; PG8_LDA(At, 1, 0); PG8_STAGE(PG8_SA(0, 1), a2 + hstepA, voffA);
;             PG8_WAIT_L(8); PG8_BAR; PG8_WAIT_L(0); PG8_MMA(0, 0, At, B0); PG8_BAR; PG8_SCHED;
;             PG8_LDB(B1, 1, 1); PG8_STAGE(PG8_SB(1, 0), b3, voffB);
	s_add_u32 s2, s14, 0x80000
	s_addc_u32 s3, s15, 0
	s_add_i32 s65, s53, s26
	v_lshl_add_u64 v[128:129], s[2:3], 0, v[148:149]
	s_mov_b32 m0, s65
	s_nop 0
	global_load_lds_dwordx4 v[128:129], off
	v_lshl_add_u64 v[128:129], s[2:3], 0, v[144:145]
	s_add_i32 m0, s65, 0x2000
	s_nop 0
	global_load_lds_dwordx4 v[128:129], off
	s_waitcnt vmcnt(6)
	s_barrier
	s_setprio 1
	v_mfma_f32_16x16x32_bf16 v[52:55], v[206:209], v[166:169], v[52:55]
	v_mfma_f32_16x16x32_bf16 v[52:55], v[210:213], v[178:181], v[52:55]
	v_mfma_f32_16x16x32_bf16 v[48:51], v[222:225], v[178:181], v[48:51]
	v_mfma_f32_16x16x32_bf16 v[48:51], v[218:221], v[166:169], v[48:51]
	v_mfma_f32_16x16x32_bf16 v[32:35], v[218:221], v[182:185], v[32:35]
	v_mfma_f32_16x16x32_bf16 v[32:35], v[222:225], v[186:189], v[32:35]
	v_mfma_f32_16x16x32_bf16 v[36:39], v[210:213], v[186:189], v[36:39]
	v_mfma_f32_16x16x32_bf16 v[36:39], v[206:209], v[182:185], v[36:39]
	v_mfma_f32_16x16x32_bf16 v[20:23], v[206:209], v[190:193], v[20:23]
	v_mfma_f32_16x16x32_bf16 v[20:23], v[210:213], v[194:197], v[20:23]
	v_mfma_f32_16x16x32_bf16 v[16:19], v[222:225], v[194:197], v[16:19]
	v_mfma_f32_16x16x32_bf16 v[16:19], v[218:221], v[190:193], v[16:19]
	v_mfma_f32_16x16x32_bf16 v[0:3], v[218:221], v[198:201], v[0:3]
	v_mfma_f32_16x16x32_bf16 v[0:3], v[222:225], v[202:205], v[0:3]
	v_mfma_f32_16x16x32_bf16 v[4:7], v[210:213], v[202:205], v[4:7]
	v_mfma_f32_16x16x32_bf16 v[4:7], v[206:209], v[198:201], v[4:7]
	s_setprio 0
	s_add_i32 s65, 16, 0x18000
	v_add_u32_e32 v140, s65, v173
	s_barrier
	ds_read_b128 v[128:131], v140
	ds_read_b128 v[132:135], v140 offset:1024
	ds_read_b128 v[136:139], v140 offset:2048
	ds_read_b128 v[140:143], v140 offset:3072
	s_add_u32 s2, s44, 0x80000
	s_addc_u32 s3, s45, 0
	s_mov_b32 m0, s31
	v_lshl_add_u64 v[206:207], s[2:3], 0, v[150:151]
	ds_read_b128 v[166:169], v176 offset:32768
	ds_read_b128 v[178:181], v176 offset:33792
	ds_read_b128 v[182:185], v176 offset:34816
	ds_read_b128 v[186:189], v176 offset:35840
	ds_read_b128 v[190:193], v176 offset:36864
	ds_read_b128 v[194:197], v176 offset:37888
	ds_read_b128 v[198:201], v176 offset:38912
	ds_read_b128 v[202:205], v176 offset:39936
	global_load_lds_dwordx4 v[206:207], off
	v_lshl_add_u64 v[206:207], s[2:3], 0, v[146:147]
	s_mov_b32 m0, s43
	s_nop 0
	global_load_lds_dwordx4 v[206:207], off
	s_waitcnt lgkmcnt(8)
	s_barrier
	s_waitcnt lgkmcnt(0)
	s_setprio 1
	s_waitcnt lgkmcnt(0)
	v_mfma_f32_16x16x32_bf16 v[124:127], v[128:131], v[166:169], v[124:127]
	v_mfma_f32_16x16x32_bf16 v[124:127], v[132:135], v[178:181], v[124:127]
	v_mfma_f32_16x16x32_bf16 v[120:123], v[140:143], v[178:181], v[120:123]
	v_mfma_f32_16x16x32_bf16 v[120:123], v[136:139], v[166:169], v[120:123]
	v_mfma_f32_16x16x32_bf16 v[104:107], v[136:139], v[182:185], v[104:107]
	v_mfma_f32_16x16x32_bf16 v[104:107], v[140:143], v[186:189], v[104:107]
	v_mfma_f32_16x16x32_bf16 v[108:111], v[132:135], v[186:189], v[108:111]
	v_mfma_f32_16x16x32_bf16 v[108:111], v[128:131], v[182:185], v[108:111]
	v_mfma_f32_16x16x32_bf16 v[92:95], v[128:131], v[190:193], v[92:95]
	v_mfma_f32_16x16x32_bf16 v[92:95], v[132:135], v[194:197], v[92:95]
	v_mfma_f32_16x16x32_bf16 v[88:91], v[140:143], v[194:197], v[88:91]
	v_mfma_f32_16x16x32_bf16 v[88:91], v[136:139], v[190:193], v[88:91]
	v_mfma_f32_16x16x32_bf16 v[72:75], v[136:139], v[198:201], v[72:75]
	v_mfma_f32_16x16x32_bf16 v[72:75], v[140:143], v[202:205], v[72:75]
	v_mfma_f32_16x16x32_bf16 v[76:79], v[132:135], v[202:205], v[76:79]
	v_mfma_f32_16x16x32_bf16 v[76:79], v[128:131], v[198:201], v[76:79]
	s_setprio 0
	s_barrier
	s_add_i32 s44, 16, 0x1c000
	s_add_i32 s2, s65, s26
	v_add_u32_e32 v152, s44, v173
	v_lshl_add_u64 v[170:171], v[170:171], 0, s[4:5]
	s_mov_b32 m0, s2
	ds_read_b128 v[206:209], v152
	ds_read_b128 v[210:213], v152 offset:1024
	ds_read_b128 v[218:221], v152 offset:2048
	ds_read_b128 v[222:225], v152 offset:3072
	global_load_lds_dwordx4 v[170:171], off
	v_lshl_add_u64 v[170:171], v[226:227], 0, s[4:5]
	s_add_i32 m0, s2, 0x2000
	s_nop 0
	global_load_lds_dwordx4 v[170:171], off
	s_barrier
; #define PG8_STAGE(bufoff, gbase, voff) do { _Pragma("unroll") for (int _i = 0; _i < 2; ++_i) \
;         __builtin_amdgcn_global_load_lds((const unsigned*)((const char*)(gbase) + (voff)[_i]), (LAS unsigned*)(lds + (bufoff) + ldsw + _i * 8192), 16, 0, 0); } while (0)
; #define PG8_LDA(dst, b, h) do { _Pragma("unroll") for (int m = 0; m < 4; ++m) _Pragma("unroll") for (int k = 0; k < 2; ++k) dst[m][k] = *(const LAS bf16x8*)(lds + PG8_SA(b, h) + aoff + m * 2048 + k * 1024); } while (0)
; #define PG8_MMA(ai, bj, At, Bt) do { __builtin_amdgcn_s_setprio(1); _Pragma("unroll") for (int m = 0; m < 4; ++m) _Pragma("unroll") for (int n = 0; n < 2; ++n) _Pragma("unroll") for (int k = 0; k < 2; ++k) \
;         acc[ai][bj][m][n] = __builtin_amdgcn_mfma_f32_16x16x32_bf16(Bt[n][k], At[m][k], acc[ai][bj][m][n], 0, 0, 0); __builtin_amdgcn_s_setprio(0); } while (0)
; #define PG8_WAIT_V(n) asm volatile("s_waitcnt vmcnt(" #n ")" ::: "memory")
; #define PG8_WAIT_L(n) asm volatile("s_waitcnt lgkmcnt(" #n ")" ::: "memory")
; #define PG8_BAR __builtin_amdgcn_s_barrier()
; #define PG8_SCHED __builtin_amdgcn_sched_barrier(0)
; template <class Epi>
; DEVINL void gemm_phase(LAS unsigned char* lds, const Gemm g, const Order& S, const Epi& E) {
;     ...
;             PG8_BAR; PG8_WAIT_L(0); PG8_MMA(0, 1, At, B1); PG8_BAR;
;             PG8_LDA(At, 1, 1); PG8_STAGE(PG8_SA(1, 0), a3, voffA);
;             PG8_BAR; PG8_WAIT_L(0); PG8_MMA(1, 0, At, B0); PG8_BAR; PG8_SCHED;
;             PG8_STAGE(PG8_SB(1, 1), b3 + hstepB, voffB);
;             PG8_WAIT_V(6); PG8_BAR; PG8_MMA(1, 1, At, B1); PG8_BAR;
;         }
	s_waitcnt lgkmcnt(0)
	s_setprio 1
	s_waitcnt lgkmcnt(0)
	v_mfma_f32_16x16x32_bf16 v[116:119], v[206:209], v[166:169], v[116:119]
	v_mfma_f32_16x16x32_bf16 v[116:119], v[210:213], v[178:181], v[116:119]
	v_mfma_f32_16x16x32_bf16 v[112:115], v[222:225], v[178:181], v[112:115]
	v_mfma_f32_16x16x32_bf16 v[112:115], v[218:221], v[166:169], v[112:115]
	v_mfma_f32_16x16x32_bf16 v[96:99], v[218:221], v[182:185], v[96:99]
	v_mfma_f32_16x16x32_bf16 v[96:99], v[222:225], v[186:189], v[96:99]
	v_mfma_f32_16x16x32_bf16 v[100:103], v[210:213], v[186:189], v[100:103]
	v_mfma_f32_16x16x32_bf16 v[100:103], v[206:209], v[182:185], v[100:103]
	v_mfma_f32_16x16x32_bf16 v[84:87], v[206:209], v[190:193], v[84:87]
	v_mfma_f32_16x16x32_bf16 v[84:87], v[210:213], v[194:197], v[84:87]
	v_mfma_f32_16x16x32_bf16 v[80:83], v[222:225], v[194:197], v[80:83]
	v_mfma_f32_16x16x32_bf16 v[80:83], v[218:221], v[190:193], v[80:83]
	v_mfma_f32_16x16x32_bf16 v[64:67], v[218:221], v[198:201], v[64:67]
	v_mfma_f32_16x16x32_bf16 v[64:67], v[222:225], v[202:205], v[64:67]
	v_mfma_f32_16x16x32_bf16 v[68:71], v[210:213], v[202:205], v[68:71]
	v_mfma_f32_16x16x32_bf16 v[68:71], v[206:209], v[198:201], v[68:71]
	s_setprio 0
	s_mov_b32 m0, s47
	v_lshl_add_u64 v[170:171], v[228:229], 0, s[4:5]
	s_barrier
	ds_read_b128 v[166:169], v176 offset:49152
	ds_read_b128 v[178:181], v176 offset:50176
	ds_read_b128 v[182:185], v176 offset:51200
	ds_read_b128 v[186:189], v176 offset:52224
	ds_read_b128 v[190:193], v176 offset:53248
	ds_read_b128 v[194:197], v176 offset:54272
	ds_read_b128 v[198:201], v176 offset:55296
	ds_read_b128 v[202:205], v176 offset:56320
	global_load_lds_dwordx4 v[170:171], off
	v_lshl_add_u64 v[170:171], v[230:231], 0, s[4:5]
	s_mov_b32 m0, s48
	s_nop 0
	global_load_lds_dwordx4 v[170:171], off
	s_barrier
	s_waitcnt lgkmcnt(0)
	s_setprio 1
	s_waitcnt lgkmcnt(0)
	v_mfma_f32_16x16x32_bf16 v[60:63], v[128:131], v[166:169], v[60:63]
	v_mfma_f32_16x16x32_bf16 v[60:63], v[132:135], v[178:181], v[60:63]
	v_mfma_f32_16x16x32_bf16 v[56:59], v[140:143], v[178:181], v[56:59]
	v_mfma_f32_16x16x32_bf16 v[56:59], v[136:139], v[166:169], v[56:59]
	v_mfma_f32_16x16x32_bf16 v[40:43], v[136:139], v[182:185], v[40:43]
	v_mfma_f32_16x16x32_bf16 v[40:43], v[140:143], v[186:189], v[40:43]
	v_mfma_f32_16x16x32_bf16 v[44:47], v[132:135], v[186:189], v[44:47]
	v_mfma_f32_16x16x32_bf16 v[44:47], v[128:131], v[182:185], v[44:47]
	v_mfma_f32_16x16x32_bf16 v[28:31], v[128:131], v[190:193], v[28:31]
	v_mfma_f32_16x16x32_bf16 v[28:31], v[132:135], v[194:197], v[28:31]
	v_mfma_f32_16x16x32_bf16 v[24:27], v[140:143], v[194:197], v[24:27]
	v_mfma_f32_16x16x32_bf16 v[24:27], v[136:139], v[190:193], v[24:27]
	v_mfma_f32_16x16x32_bf16 v[8:11], v[136:139], v[198:201], v[8:11]
	v_mfma_f32_16x16x32_bf16 v[8:11], v[140:143], v[202:205], v[8:11]
	v_mfma_f32_16x16x32_bf16 v[12:15], v[132:135], v[202:205], v[12:15]
	v_mfma_f32_16x16x32_bf16 v[12:15], v[128:131], v[198:201], v[12:15]
	s_setprio 0
	s_barrier
	s_add_u32 s2, s14, 0x80080
	s_addc_u32 s3, s15, 0
	s_add_i32 s14, s44, s26
	v_lshl_add_u64 v[128:129], s[2:3], 0, v[148:149]
	s_mov_b32 m0, s14
	s_nop 0
	global_load_lds_dwordx4 v[128:129], off
	v_lshl_add_u64 v[128:129], s[2:3], 0, v[144:145]
	s_add_i32 m0, s14, 0x2000
	s_nop 0
	global_load_lds_dwordx4 v[128:129], off
	s_waitcnt vmcnt(6)
	s_barrier
	s_setprio 1
	v_mfma_f32_16x16x32_bf16 v[52:55], v[206:209], v[166:169], v[52:55]
	v_mfma_f32_16x16x32_bf16 v[52:55], v[210:213], v[178:181], v[52:55]
	v_mfma_f32_16x16x32_bf16 v[48:51], v[222:225], v[178:181], v[48:51]
	v_mfma_f32_16x16x32_bf16 v[48:51], v[218:221], v[166:169], v[48:51]
	v_mfma_f32_16x16x32_bf16 v[32:35], v[218:221], v[182:185], v[32:35]
	v_mfma_f32_16x16x32_bf16 v[32:35], v[222:225], v[186:189], v[32:35]
	v_mfma_f32_16x16x32_bf16 v[36:39], v[210:213], v[186:189], v[36:39]
	v_mfma_f32_16x16x32_bf16 v[36:39], v[206:209], v[182:185], v[36:39]
	v_mfma_f32_16x16x32_bf16 v[20:23], v[206:209], v[190:193], v[20:23]
	v_mfma_f32_16x16x32_bf16 v[20:23], v[210:213], v[194:197], v[20:23]
	v_mfma_f32_16x16x32_bf16 v[16:19], v[222:225], v[194:197], v[16:19]
	v_mfma_f32_16x16x32_bf16 v[16:19], v[218:221], v[190:193], v[16:19]
	v_mfma_f32_16x16x32_bf16 v[0:3], v[218:221], v[198:201], v[0:3]
	v_mfma_f32_16x16x32_bf16 v[0:3], v[222:225], v[202:205], v[0:3]
	v_mfma_f32_16x16x32_bf16 v[4:7], v[210:213], v[202:205], v[4:7]
	v_mfma_f32_16x16x32_bf16 v[4:7], v[206:209], v[198:201], v[4:7]
	s_setprio 0
	s_add_u32 s12, s12, 0x100
	s_addc_u32 s13, s13, 0
	s_add_u32 s58, s58, 0x100
	s_addc_u32 s59, s59, 0
	s_cmp_ge_i32 s64, s46
	s_mov_b32 s14, s64
	s_barrier
	s_cbranch_scc0 .LBB0_650

; #define PG8_STAGE(bufoff, gbase, voff) do { _Pragma("unroll") for (int _i = 0; _i < 2; ++_i) \
;         __builtin_amdgcn_global_load_lds((const unsigned*)((const char*)(gbase) + (voff)[_i]), (LAS unsigned*)(lds + (bufoff) + ldsw + _i * 8192), 16, 0, 0); } while (0)
; #define PG8_LDA(dst, b, h) do { _Pragma("unroll") for (int m = 0; m < 4; ++m) _Pragma("unroll") for (int k = 0; k < 2; ++k) dst[m][k] = *(const LAS bf16x8*)(lds + PG8_SA(b, h) + aoff + m * 2048 + k * 1024); } while (0)
; #define PG8_LDB(dst, b, h) do { _Pragma("unroll") for (int n = 0; n < 2; ++n) _Pragma("unroll") for (int k = 0; k < 2; ++k) dst[n][k] = *(const LAS bf16x8*)(lds + PG8_SB(b, h) + boff + n * 2048 + k * 1024); } while (0)
; #define PG8_MMA(ai, bj, At, Bt) do { __builtin_amdgcn_s_setprio(1); _Pragma("unroll") for (int m = 0; m < 4; ++m) _Pragma("unroll") for (int n = 0; n < 2; ++n) _Pragma("unroll") for (int k = 0; k < 2; ++k) \
;         acc[ai][bj][m][n] = __builtin_amdgcn_mfma_f32_16x16x32_bf16(Bt[n][k], At[m][k], acc[ai][bj][m][n], 0, 0, 0); __builtin_amdgcn_s_setprio(0); } while (0)
; #define PG8_WAIT_L(n) asm volatile("s_waitcnt lgkmcnt(" #n ")" ::: "memory")
; #define PG8_BAR __builtin_amdgcn_s_barrier()
; #define PG8_SCHED __builtin_amdgcn_sched_barrier(0)
; template <class Epi>
; DEVINL void gemm_phase(LAS unsigned char* lds, const Gemm g, const Order& S, const Epi& E) {
;     ...
;             const char* a1 = cA + (size_t)(t + 1) * kstep;
;             const char* a2 = last ? nA : cA + (size_t)(t + 2) * kstep; const char* b2 = last ? nB : cB + (size_t)(t + 2) * kstep;
;             const char* a3 = a2 + kstep; const char* b3 = b2 + kstep;
;             PG8_LDB(B0, 0, 0); PG8_SCHED; PG8_LDA(At, 0, 0); PG8_STAGE(PG8_SA(1, 1), a1 + hstepA, voffA);
;             PG8_WAIT_L(8); PG8_BAR; PG8_WAIT_L(0); PG8_MMA(0, 0, At, B0); PG8_BAR; PG8_SCHED;
;             PG8_LDB(B1, 0, 1); PG8_STAGE(PG8_SB(0, 0), b2, voffB);
;             PG8_BAR; PG8_WAIT_L(0); PG8_MMA(0, 1, At, B1); PG8_BAR;
;             PG8_LDA(At, 0, 1); PG8_STAGE(PG8_SA(0, 0), a2, voffA);
;             PG8_BAR; PG8_WAIT_L(0); PG8_MMA(1, 0, At, B0); PG8_BAR; PG8_SCHED;
.LBB0_802:
	ds_read_b128 v[150:153], v147
	ds_read_b128 v[154:157], v147 offset:1024
	ds_read_b128 v[158:161], v147 offset:2048
	ds_read_b128 v[162:165], v147 offset:3072
	s_add_i32 s65, s38, 2
	s_add_u32 s4, s16, 0x100
	s_addc_u32 s5, s17, 0
	s_cmp_eq_u32 s49, s38
	s_cselect_b32 s38, s58, s59
	s_cselect_b32 s41, s13, s5
	s_cselect_b32 s40, s12, s4
	s_cselect_b32 s39, s11, s64
	v_lshl_add_u64 v[198:199], s[16:17], 0, v[136:137]
	s_add_i32 m0, s31, 0xc000
	ds_read_b128 v[166:169], v148
	ds_read_b128 v[170:173], v148 offset:1024
	ds_read_b128 v[174:177], v148 offset:2048
	ds_read_b128 v[178:181], v148 offset:3072
	ds_read_b128 v[182:185], v148 offset:4096
	ds_read_b128 v[186:189], v148 offset:5120
	ds_read_b128 v[190:193], v148 offset:6144
	ds_read_b128 v[194:197], v148 offset:7168
	global_load_lds_dwordx4 v[198:199], off
	v_lshl_add_u64 v[198:199], s[16:17], 0, v[138:139]
	s_add_i32 m0, s31, 0xe000
	s_nop 0
	global_load_lds_dwordx4 v[198:199], off
	s_waitcnt lgkmcnt(8)
	s_barrier
	s_waitcnt lgkmcnt(0)
	s_setprio 1
	s_waitcnt lgkmcnt(0)
	v_mfma_f32_16x16x32_bf16 v[120:123], v[150:153], v[166:169], v[120:123]
	v_mfma_f32_16x16x32_bf16 v[120:123], v[154:157], v[170:173], v[120:123]
	v_mfma_f32_16x16x32_bf16 v[124:127], v[162:165], v[170:173], v[124:127]
	v_mfma_f32_16x16x32_bf16 v[124:127], v[158:161], v[166:169], v[124:127]
	v_mfma_f32_16x16x32_bf16 v[104:107], v[158:161], v[174:177], v[104:107]
	v_mfma_f32_16x16x32_bf16 v[104:107], v[162:165], v[178:181], v[104:107]
	v_mfma_f32_16x16x32_bf16 v[108:111], v[154:157], v[178:181], v[108:111]
	v_mfma_f32_16x16x32_bf16 v[108:111], v[150:153], v[174:177], v[108:111]
	v_mfma_f32_16x16x32_bf16 v[92:95], v[150:153], v[182:185], v[92:95]
	v_mfma_f32_16x16x32_bf16 v[92:95], v[154:157], v[186:189], v[92:95]
	v_mfma_f32_16x16x32_bf16 v[88:91], v[162:165], v[186:189], v[88:91]
	v_mfma_f32_16x16x32_bf16 v[88:91], v[158:161], v[182:185], v[88:91]
	v_mfma_f32_16x16x32_bf16 v[72:75], v[158:161], v[190:193], v[72:75]
	v_mfma_f32_16x16x32_bf16 v[72:75], v[162:165], v[194:197], v[72:75]
	v_mfma_f32_16x16x32_bf16 v[76:79], v[154:157], v[194:197], v[76:79]
	v_mfma_f32_16x16x32_bf16 v[76:79], v[150:153], v[190:193], v[76:79]
	s_setprio 0
	s_barrier
	s_add_i32 s2, s52, s28
	v_lshl_add_u64 v[218:219], s[38:39], 0, v[132:133]
	s_mov_b32 m0, s2
	ds_read_b128 v[198:201], v149
	ds_read_b128 v[202:205], v149 offset:1024
	ds_read_b128 v[206:209], v149 offset:2048
	ds_read_b128 v[210:213], v149 offset:3072
	global_load_lds_dwordx4 v[218:219], off
	v_lshl_add_u64 v[220:221], s[38:39], 0, v[128:129]
	s_add_i32 m0, s2, 0x2000
	s_nop 0
	global_load_lds_dwordx4 v[220:221], off
	s_barrier
	s_waitcnt lgkmcnt(0)
	s_setprio 1
	s_waitcnt lgkmcnt(0)
	v_mfma_f32_16x16x32_bf16 v[116:119], v[198:201], v[166:169], v[116:119]
	v_mfma_f32_16x16x32_bf16 v[116:119], v[202:205], v[170:173], v[116:119]
	v_mfma_f32_16x16x32_bf16 v[112:115], v[210:213], v[170:173], v[112:115]
	v_mfma_f32_16x16x32_bf16 v[112:115], v[206:209], v[166:169], v[112:115]
	v_mfma_f32_16x16x32_bf16 v[96:99], v[206:209], v[174:177], v[96:99]
	v_mfma_f32_16x16x32_bf16 v[96:99], v[210:213], v[178:181], v[96:99]
	v_mfma_f32_16x16x32_bf16 v[100:103], v[202:205], v[178:181], v[100:103]
	v_mfma_f32_16x16x32_bf16 v[100:103], v[198:201], v[174:177], v[100:103]
	v_mfma_f32_16x16x32_bf16 v[84:87], v[198:201], v[182:185], v[84:87]
	v_mfma_f32_16x16x32_bf16 v[84:87], v[202:205], v[186:189], v[84:87]
	v_mfma_f32_16x16x32_bf16 v[80:83], v[210:213], v[186:189], v[80:83]
	v_mfma_f32_16x16x32_bf16 v[80:83], v[206:209], v[182:185], v[80:83]
	v_mfma_f32_16x16x32_bf16 v[64:67], v[206:209], v[190:193], v[64:67]
	v_mfma_f32_16x16x32_bf16 v[64:67], v[210:213], v[194:197], v[64:67]
	v_mfma_f32_16x16x32_bf16 v[68:71], v[202:205], v[194:197], v[68:71]
	v_mfma_f32_16x16x32_bf16 v[68:71], v[198:201], v[190:193], v[68:71]
	s_setprio 0
	s_mov_b32 m0, s31
	v_lshl_add_u64 v[222:223], s[40:41], 0, v[134:135]
	s_barrier
	ds_read_b128 v[166:169], v148 offset:16384
	ds_read_b128 v[170:173], v148 offset:17408
	ds_read_b128 v[174:177], v148 offset:18432
	ds_read_b128 v[178:181], v148 offset:19456
	ds_read_b128 v[182:185], v148 offset:20480
	ds_read_b128 v[186:189], v148 offset:21504
	ds_read_b128 v[190:193], v148 offset:22528
	ds_read_b128 v[194:197], v148 offset:23552
	global_load_lds_dwordx4 v[222:223], off
	v_lshl_add_u64 v[224:225], s[40:41], 0, v[130:131]
	s_mov_b32 m0, s42
	s_nop 0
	global_load_lds_dwordx4 v[224:225], off
	s_barrier
	s_waitcnt lgkmcnt(0)
	s_setprio 1
	s_waitcnt lgkmcnt(0)
	v_mfma_f32_16x16x32_bf16 v[60:63], v[150:153], v[166:169], v[60:63]
	v_mfma_f32_16x16x32_bf16 v[60:63], v[154:157], v[170:173], v[60:63]
	v_mfma_f32_16x16x32_bf16 v[56:59], v[162:165], v[170:173], v[56:59]
	v_mfma_f32_16x16x32_bf16 v[56:59], v[158:161], v[166:169], v[56:59]
	v_mfma_f32_16x16x32_bf16 v[40:43], v[158:161], v[174:177], v[40:43]
	v_mfma_f32_16x16x32_bf16 v[40:43], v[162:165], v[178:181], v[40:43]
	v_mfma_f32_16x16x32_bf16 v[44:47], v[154:157], v[178:181], v[44:47]
	v_mfma_f32_16x16x32_bf16 v[44:47], v[150:153], v[174:177], v[44:47]
	v_mfma_f32_16x16x32_bf16 v[28:31], v[150:153], v[182:185], v[28:31]
	v_mfma_f32_16x16x32_bf16 v[28:31], v[154:157], v[186:189], v[28:31]
	v_mfma_f32_16x16x32_bf16 v[24:27], v[162:165], v[186:189], v[24:27]
	v_mfma_f32_16x16x32_bf16 v[24:27], v[158:161], v[182:185], v[24:27]
	v_mfma_f32_16x16x32_bf16 v[8:11], v[158:161], v[190:193], v[8:11]
	v_mfma_f32_16x16x32_bf16 v[8:11], v[162:165], v[194:197], v[8:11]
	v_mfma_f32_16x16x32_bf16 v[12:15], v[154:157], v[194:197], v[12:15]
	v_mfma_f32_16x16x32_bf16 v[12:15], v[150:153], v[190:193], v[12:15]
	s_setprio 0
	s_barrier
; #define PG8_STAGE(bufoff, gbase, voff) do { _Pragma("unroll") for (int _i = 0; _i < 2; ++_i) \
;         __builtin_amdgcn_global_load_lds((const unsigned*)((const char*)(gbase) + (voff)[_i]), (LAS unsigned*)(lds + (bufoff) + ldsw + _i * 8192), 16, 0, 0); } while (0)
; #define PG8_LDA(dst, b, h) do { _Pragma("unroll") for (int m = 0; m < 4; ++m) _Pragma("unroll") for (int k = 0; k < 2; ++k) dst[m][k] = *(const LAS bf16x8*)(lds + PG8_SA(b, h) + aoff + m * 2048 + k * 1024); } while (0)
; #define PG8_LDB(dst, b, h) do { _Pragma("unroll") for (int n = 0; n < 2; ++n) _Pragma("unroll") for (int k = 0; k < 2; ++k) dst[n][k] = *(const LAS bf16x8*)(lds + PG8_SB(b, h) + boff + n * 2048 + k * 1024); } while (0)
; #define PG8_MMA(ai, bj, At, Bt) do { __builtin_amdgcn_s_setprio(1); _Pragma("unroll") for (int m = 0; m < 4; ++m) _Pragma("unroll") for (int n = 0; n < 2; ++n) _Pragma("unroll") for (int k = 0; k < 2; ++k) \
;         acc[ai][bj][m][n] = __builtin_amdgcn_mfma_f32_16x16x32_bf16(Bt[n][k], At[m][k], acc[ai][bj][m][n], 0, 0, 0); __builtin_amdgcn_s_setprio(0); } while (0)
; #define PG8_WAIT_V(n) asm volatile("s_waitcnt vmcnt(" #n ")" ::: "memory")
; #define PG8_WAIT_L(n) asm volatile("s_waitcnt lgkmcnt(" #n ")" ::: "memory")
; #define PG8_BAR __builtin_amdgcn_s_barrier()
; #define PG8_SCHED __builtin_amdgcn_sched_barrier(0)
; template <class Epi>
; DEVINL void gemm_phase(LAS unsigned char* lds, const Gemm g, const Order& S, const Epi& E) {
;     ...
;             PG8_STAGE(PG8_SB(0, 1), b2 + hstepB, voffB);
;             PG8_WAIT_V(6); PG8_BAR; PG8_MMA(1, 1, At, B1); PG8_BAR;
;             PG8_LDB(B0, 1, 0); PG8_SCHED; PG8_LDA(At, 1, 0); PG8_STAGE(PG8_SA(0, 1), a2 + hstepA, voffA);
;             PG8_WAIT_L(8); PG8_BAR; PG8_WAIT_L(0); PG8_MMA(0, 0, At, B0); PG8_BAR; PG8_SCHED;
;             PG8_LDB(B1, 1, 1); PG8_STAGE(PG8_SB(1, 0), b3, voffB);
	s_add_u32 s2, s38, 0x20000
	s_addc_u32 s3, s39, 0
	s_add_i32 s16, s53, s28
	v_lshl_add_u64 v[150:151], s[2:3], 0, v[132:133]
	s_mov_b32 m0, s16
	s_nop 0
	global_load_lds_dwordx4 v[150:151], off
	v_lshl_add_u64 v[150:151], s[2:3], 0, v[128:129]
	s_add_i32 m0, s16, 0x2000
	s_nop 0
	global_load_lds_dwordx4 v[150:151], off
	s_waitcnt vmcnt(6)
	s_barrier
	s_setprio 1
	v_mfma_f32_16x16x32_bf16 v[52:55], v[198:201], v[166:169], v[52:55]
	v_mfma_f32_16x16x32_bf16 v[52:55], v[202:205], v[170:173], v[52:55]
	v_mfma_f32_16x16x32_bf16 v[48:51], v[210:213], v[170:173], v[48:51]
	v_mfma_f32_16x16x32_bf16 v[48:51], v[206:209], v[166:169], v[48:51]
	v_mfma_f32_16x16x32_bf16 v[32:35], v[206:209], v[174:177], v[32:35]
	v_mfma_f32_16x16x32_bf16 v[32:35], v[210:213], v[178:181], v[32:35]
	v_mfma_f32_16x16x32_bf16 v[36:39], v[202:205], v[178:181], v[36:39]
	v_mfma_f32_16x16x32_bf16 v[36:39], v[198:201], v[174:177], v[36:39]
	v_mfma_f32_16x16x32_bf16 v[20:23], v[198:201], v[182:185], v[20:23]
	v_mfma_f32_16x16x32_bf16 v[20:23], v[202:205], v[186:189], v[20:23]
	v_mfma_f32_16x16x32_bf16 v[16:19], v[210:213], v[186:189], v[16:19]
	v_mfma_f32_16x16x32_bf16 v[16:19], v[206:209], v[182:185], v[16:19]
	v_mfma_f32_16x16x32_bf16 v[0:3], v[206:209], v[190:193], v[0:3]
	v_mfma_f32_16x16x32_bf16 v[0:3], v[210:213], v[194:197], v[0:3]
	v_mfma_f32_16x16x32_bf16 v[4:7], v[202:205], v[194:197], v[4:7]
	v_mfma_f32_16x16x32_bf16 v[4:7], v[198:201], v[190:193], v[4:7]
	s_setprio 0
	s_add_i32 s16, 16, 0x18000
	v_add_u32_e32 v162, s16, v145
	s_barrier
	ds_read_b128 v[150:153], v162
	ds_read_b128 v[154:157], v162 offset:1024
	ds_read_b128 v[158:161], v162 offset:2048
	ds_read_b128 v[162:165], v162 offset:3072
	s_add_u32 s2, s40, 0x30000
	s_addc_u32 s3, s41, 0
	s_mov_b32 m0, s43
	v_lshl_add_u64 v[198:199], s[2:3], 0, v[134:135]
	ds_read_b128 v[166:169], v148 offset:32768
	ds_read_b128 v[170:173], v148 offset:33792
	ds_read_b128 v[174:177], v148 offset:34816
	ds_read_b128 v[178:181], v148 offset:35840
	ds_read_b128 v[182:185], v148 offset:36864
	ds_read_b128 v[186:189], v148 offset:37888
	ds_read_b128 v[190:193], v148 offset:38912
	ds_read_b128 v[194:197], v148 offset:39936
	global_load_lds_dwordx4 v[198:199], off
	v_lshl_add_u64 v[198:199], s[2:3], 0, v[130:131]
	s_mov_b32 m0, s44
	s_nop 0
	global_load_lds_dwordx4 v[198:199], off
	s_waitcnt lgkmcnt(8)
	s_barrier
	s_waitcnt lgkmcnt(0)
	s_setprio 1
	s_waitcnt lgkmcnt(0)
	v_mfma_f32_16x16x32_bf16 v[120:123], v[150:153], v[166:169], v[120:123]
	v_mfma_f32_16x16x32_bf16 v[120:123], v[154:157], v[170:173], v[120:123]
	v_mfma_f32_16x16x32_bf16 v[124:127], v[162:165], v[170:173], v[124:127]
	v_mfma_f32_16x16x32_bf16 v[124:127], v[158:161], v[166:169], v[124:127]
	v_mfma_f32_16x16x32_bf16 v[104:107], v[158:161], v[174:177], v[104:107]
	v_mfma_f32_16x16x32_bf16 v[104:107], v[162:165], v[178:181], v[104:107]
	v_mfma_f32_16x16x32_bf16 v[108:111], v[154:157], v[178:181], v[108:111]
	v_mfma_f32_16x16x32_bf16 v[108:111], v[150:153], v[174:177], v[108:111]
	v_mfma_f32_16x16x32_bf16 v[92:95], v[150:153], v[182:185], v[92:95]
	v_mfma_f32_16x16x32_bf16 v[92:95], v[154:157], v[186:189], v[92:95]
	v_mfma_f32_16x16x32_bf16 v[88:91], v[162:165], v[186:189], v[88:91]
	v_mfma_f32_16x16x32_bf16 v[88:91], v[158:161], v[182:185], v[88:91]
	v_mfma_f32_16x16x32_bf16 v[72:75], v[158:161], v[190:193], v[72:75]
	v_mfma_f32_16x16x32_bf16 v[72:75], v[162:165], v[194:197], v[72:75]
	v_mfma_f32_16x16x32_bf16 v[76:79], v[154:157], v[194:197], v[76:79]
	v_mfma_f32_16x16x32_bf16 v[76:79], v[150:153], v[190:193], v[76:79]
	s_setprio 0
	s_barrier
	s_add_i32 s17, 16, 0x1c000
	s_add_i32 s2, s16, s28
	v_add_u32_e32 v210, s17, v145
	v_lshl_add_u64 v[218:219], v[218:219], 0, s[6:7]
	s_mov_b32 m0, s2
	ds_read_b128 v[198:201], v210
	ds_read_b128 v[202:205], v210 offset:1024
	ds_read_b128 v[206:209], v210 offset:2048
	ds_read_b128 v[210:213], v210 offset:3072
	global_load_lds_dwordx4 v[218:219], off
	v_lshl_add_u64 v[218:219], v[220:221], 0, s[6:7]
	s_add_i32 m0, s2, 0x2000
	s_nop 0
	global_load_lds_dwordx4 v[218:219], off
	s_barrier
; #define PG8_STAGE(bufoff, gbase, voff) do { _Pragma("unroll") for (int _i = 0; _i < 2; ++_i) \
;         __builtin_amdgcn_global_load_lds((const unsigned*)((const char*)(gbase) + (voff)[_i]), (LAS unsigned*)(lds + (bufoff) + ldsw + _i * 8192), 16, 0, 0); } while (0)
; #define PG8_LDA(dst, b, h) do { _Pragma("unroll") for (int m = 0; m < 4; ++m) _Pragma("unroll") for (int k = 0; k < 2; ++k) dst[m][k] = *(const LAS bf16x8*)(lds + PG8_SA(b, h) + aoff + m * 2048 + k * 1024); } while (0)
; #define PG8_MMA(ai, bj, At, Bt) do { __builtin_amdgcn_s_setprio(1); _Pragma("unroll") for (int m = 0; m < 4; ++m) _Pragma("unroll") for (int n = 0; n < 2; ++n) _Pragma("unroll") for (int k = 0; k < 2; ++k) \
;         acc[ai][bj][m][n] = __builtin_amdgcn_mfma_f32_16x16x32_bf16(Bt[n][k], At[m][k], acc[ai][bj][m][n], 0, 0, 0); __builtin_amdgcn_s_setprio(0); } while (0)
; #define PG8_WAIT_V(n) asm volatile("s_waitcnt vmcnt(" #n ")" ::: "memory")
; #define PG8_WAIT_L(n) asm volatile("s_waitcnt lgkmcnt(" #n ")" ::: "memory")
; #define PG8_BAR __builtin_amdgcn_s_barrier()
; #define PG8_SCHED __builtin_amdgcn_sched_barrier(0)
; template <class Epi>
; DEVINL void gemm_phase(LAS unsigned char* lds, const Gemm g, const Order& S, const Epi& E) {
;     ...
;             PG8_BAR; PG8_WAIT_L(0); PG8_MMA(0, 1, At, B1); PG8_BAR;
;             PG8_LDA(At, 1, 1); PG8_STAGE(PG8_SA(1, 0), a3, voffA);
;             PG8_BAR; PG8_WAIT_L(0); PG8_MMA(1, 0, At, B0); PG8_BAR; PG8_SCHED;
;             PG8_STAGE(PG8_SB(1, 1), b3 + hstepB, voffB);
;             PG8_WAIT_V(6); PG8_BAR; PG8_MMA(1, 1, At, B1); PG8_BAR;
;         }
	s_waitcnt lgkmcnt(0)
	s_setprio 1
	s_waitcnt lgkmcnt(0)
	v_mfma_f32_16x16x32_bf16 v[116:119], v[198:201], v[166:169], v[116:119]
	v_mfma_f32_16x16x32_bf16 v[116:119], v[202:205], v[170:173], v[116:119]
	v_mfma_f32_16x16x32_bf16 v[112:115], v[210:213], v[170:173], v[112:115]
	v_mfma_f32_16x16x32_bf16 v[112:115], v[206:209], v[166:169], v[112:115]
	v_mfma_f32_16x16x32_bf16 v[96:99], v[206:209], v[174:177], v[96:99]
	v_mfma_f32_16x16x32_bf16 v[96:99], v[210:213], v[178:181], v[96:99]
	v_mfma_f32_16x16x32_bf16 v[100:103], v[202:205], v[178:181], v[100:103]
	v_mfma_f32_16x16x32_bf16 v[100:103], v[198:201], v[174:177], v[100:103]
	v_mfma_f32_16x16x32_bf16 v[84:87], v[198:201], v[182:185], v[84:87]
	v_mfma_f32_16x16x32_bf16 v[84:87], v[202:205], v[186:189], v[84:87]
	v_mfma_f32_16x16x32_bf16 v[80:83], v[210:213], v[186:189], v[80:83]
	v_mfma_f32_16x16x32_bf16 v[80:83], v[206:209], v[182:185], v[80:83]
	v_mfma_f32_16x16x32_bf16 v[64:67], v[206:209], v[190:193], v[64:67]
	v_mfma_f32_16x16x32_bf16 v[64:67], v[210:213], v[194:197], v[64:67]
	v_mfma_f32_16x16x32_bf16 v[68:71], v[202:205], v[194:197], v[68:71]
	v_mfma_f32_16x16x32_bf16 v[68:71], v[198:201], v[190:193], v[68:71]
	s_setprio 0
	s_mov_b32 m0, s47
	v_lshl_add_u64 v[218:219], v[222:223], 0, s[6:7]
	s_barrier
	ds_read_b128 v[166:169], v148 offset:49152
	ds_read_b128 v[170:173], v148 offset:50176
	ds_read_b128 v[174:177], v148 offset:51200
	ds_read_b128 v[178:181], v148 offset:52224
	ds_read_b128 v[182:185], v148 offset:53248
	ds_read_b128 v[186:189], v148 offset:54272
	ds_read_b128 v[190:193], v148 offset:55296
	ds_read_b128 v[194:197], v148 offset:56320
	global_load_lds_dwordx4 v[218:219], off
	v_lshl_add_u64 v[218:219], v[224:225], 0, s[6:7]
	s_mov_b32 m0, s48
	s_nop 0
	global_load_lds_dwordx4 v[218:219], off
	s_barrier
	s_waitcnt lgkmcnt(0)
	s_setprio 1
	s_waitcnt lgkmcnt(0)
	v_mfma_f32_16x16x32_bf16 v[60:63], v[150:153], v[166:169], v[60:63]
	v_mfma_f32_16x16x32_bf16 v[60:63], v[154:157], v[170:173], v[60:63]
	v_mfma_f32_16x16x32_bf16 v[56:59], v[162:165], v[170:173], v[56:59]
	v_mfma_f32_16x16x32_bf16 v[56:59], v[158:161], v[166:169], v[56:59]
	v_mfma_f32_16x16x32_bf16 v[40:43], v[158:161], v[174:177], v[40:43]
	v_mfma_f32_16x16x32_bf16 v[40:43], v[162:165], v[178:181], v[40:43]
	v_mfma_f32_16x16x32_bf16 v[44:47], v[154:157], v[178:181], v[44:47]
	v_mfma_f32_16x16x32_bf16 v[44:47], v[150:153], v[174:177], v[44:47]
	v_mfma_f32_16x16x32_bf16 v[28:31], v[150:153], v[182:185], v[28:31]
	v_mfma_f32_16x16x32_bf16 v[28:31], v[154:157], v[186:189], v[28:31]
	v_mfma_f32_16x16x32_bf16 v[24:27], v[162:165], v[186:189], v[24:27]
	v_mfma_f32_16x16x32_bf16 v[24:27], v[158:161], v[182:185], v[24:27]
	v_mfma_f32_16x16x32_bf16 v[8:11], v[158:161], v[190:193], v[8:11]
	v_mfma_f32_16x16x32_bf16 v[8:11], v[162:165], v[194:197], v[8:11]
	v_mfma_f32_16x16x32_bf16 v[12:15], v[154:157], v[194:197], v[12:15]
	v_mfma_f32_16x16x32_bf16 v[12:15], v[150:153], v[190:193], v[12:15]
	s_setprio 0
	s_barrier
	s_add_u32 s2, s38, 0x20080
	s_addc_u32 s3, s39, 0
	s_add_i32 s16, s17, s28
	v_lshl_add_u64 v[150:151], s[2:3], 0, v[132:133]
	s_mov_b32 m0, s16
	s_nop 0
	global_load_lds_dwordx4 v[150:151], off
	v_lshl_add_u64 v[150:151], s[2:3], 0, v[128:129]
	s_add_i32 m0, s16, 0x2000
	s_nop 0
	global_load_lds_dwordx4 v[150:151], off
	s_waitcnt vmcnt(6)
	s_barrier
	s_setprio 1
	v_mfma_f32_16x16x32_bf16 v[52:55], v[198:201], v[166:169], v[52:55]
	v_mfma_f32_16x16x32_bf16 v[52:55], v[202:205], v[170:173], v[52:55]
	v_mfma_f32_16x16x32_bf16 v[48:51], v[210:213], v[170:173], v[48:51]
	v_mfma_f32_16x16x32_bf16 v[48:51], v[206:209], v[166:169], v[48:51]
	v_mfma_f32_16x16x32_bf16 v[32:35], v[206:209], v[174:177], v[32:35]
	v_mfma_f32_16x16x32_bf16 v[32:35], v[210:213], v[178:181], v[32:35]
	v_mfma_f32_16x16x32_bf16 v[36:39], v[202:205], v[178:181], v[36:39]
	v_mfma_f32_16x16x32_bf16 v[36:39], v[198:201], v[174:177], v[36:39]
	v_mfma_f32_16x16x32_bf16 v[20:23], v[198:201], v[182:185], v[20:23]
	v_mfma_f32_16x16x32_bf16 v[20:23], v[202:205], v[186:189], v[20:23]
	v_mfma_f32_16x16x32_bf16 v[16:19], v[210:213], v[186:189], v[16:19]
	v_mfma_f32_16x16x32_bf16 v[16:19], v[206:209], v[182:185], v[16:19]
	v_mfma_f32_16x16x32_bf16 v[0:3], v[206:209], v[190:193], v[0:3]
	v_mfma_f32_16x16x32_bf16 v[0:3], v[210:213], v[194:197], v[0:3]
	v_mfma_f32_16x16x32_bf16 v[4:7], v[202:205], v[194:197], v[4:7]
	v_mfma_f32_16x16x32_bf16 v[4:7], v[198:201], v[190:193], v[4:7]
	s_setprio 0
	s_add_u32 s59, s59, 0x100
	s_addc_u32 s64, s64, 0
	s_cmp_ge_i32 s65, s46
	s_mov_b64 s[16:17], s[4:5]
	s_mov_b32 s38, s65
	s_barrier
	s_cbranch_scc0 .LBB0_802
	s_branch .LBB0_795

; #define PG8_STAGE(bufoff, gbase, voff) do { _Pragma("unroll") for (int _i = 0; _i < 2; ++_i) \
;         __builtin_amdgcn_global_load_lds((const unsigned*)((const char*)(gbase) + (voff)[_i]), (LAS unsigned*)(lds + (bufoff) + ldsw + _i * 8192), 16, 0, 0); } while (0)
; #define PG8_LDA(dst, b, h) do { _Pragma("unroll") for (int m = 0; m < 4; ++m) _Pragma("unroll") for (int k = 0; k < 2; ++k) dst[m][k] = *(const LAS bf16x8*)(lds + PG8_SA(b, h) + aoff + m * 2048 + k * 1024); } while (0)
; #define PG8_LDB(dst, b, h) do { _Pragma("unroll") for (int n = 0; n < 2; ++n) _Pragma("unroll") for (int k = 0; k < 2; ++k) dst[n][k] = *(const LAS bf16x8*)(lds + PG8_SB(b, h) + boff + n * 2048 + k * 1024); } while (0)
; #define PG8_MMA(ai, bj, At, Bt) do { __builtin_amdgcn_s_setprio(1); _Pragma("unroll") for (int m = 0; m < 4; ++m) _Pragma("unroll") for (int n = 0; n < 2; ++n) _Pragma("unroll") for (int k = 0; k < 2; ++k) \
;         acc[ai][bj][m][n] = __builtin_amdgcn_mfma_f32_16x16x32_bf16(Bt[n][k], At[m][k], acc[ai][bj][m][n], 0, 0, 0); __builtin_amdgcn_s_setprio(0); } while (0)
; #define PG8_WAIT_L(n) asm volatile("s_waitcnt lgkmcnt(" #n ")" ::: "memory")
; #define PG8_BAR __builtin_amdgcn_s_barrier()
; #define PG8_SCHED __builtin_amdgcn_sched_barrier(0)
; template <class Epi>
; DEVINL void gemm_phase(LAS unsigned char* lds, const Gemm g, const Order& S, const Epi& E) {
;     ...
;             const char* a1 = cA + (size_t)(t + 1) * kstep;
;             const char* a2 = last ? nA : cA + (size_t)(t + 2) * kstep; const char* b2 = last ? nB : cB + (size_t)(t + 2) * kstep;
;             const char* a3 = a2 + kstep; const char* b3 = b2 + kstep;
;             PG8_LDB(B0, 0, 0); PG8_SCHED; PG8_LDA(At, 0, 0); PG8_STAGE(PG8_SA(1, 1), a1 + hstepA, voffA);
;             PG8_WAIT_L(8); PG8_BAR; PG8_WAIT_L(0); PG8_MMA(0, 0, At, B0); PG8_BAR; PG8_SCHED;
;             PG8_LDB(B1, 0, 1); PG8_STAGE(PG8_SB(0, 0), b2, voffB);
;             PG8_BAR; PG8_WAIT_L(0); PG8_MMA(0, 1, At, B1); PG8_BAR;
;             PG8_LDA(At, 0, 1); PG8_STAGE(PG8_SA(0, 0), a2, voffA);
;             PG8_BAR; PG8_WAIT_L(0); PG8_MMA(1, 0, At, B0); PG8_BAR; PG8_SCHED;
.LBB0_825:
	ds_read_b128 v[150:153], v147
	ds_read_b128 v[154:157], v147 offset:1024
	ds_read_b128 v[158:161], v147 offset:2048
	ds_read_b128 v[162:165], v147 offset:3072
	s_add_i32 s68, s42, 2
	s_add_u32 s4, s38, 0x100
	s_addc_u32 s5, s39, 0
	s_cmp_eq_u32 s53, s42
	s_cselect_b32 s42, s65, s66
	s_cselect_b32 s45, s15, s5
	s_cselect_b32 s44, s14, s4
	s_cselect_b32 s43, s13, s67
	v_lshl_add_u64 v[198:199], s[38:39], 0, v[136:137]
	s_add_i32 m0, s31, 0xc000
	ds_read_b128 v[166:169], v148
	ds_read_b128 v[170:173], v148 offset:1024
	ds_read_b128 v[174:177], v148 offset:2048
	ds_read_b128 v[178:181], v148 offset:3072
	ds_read_b128 v[182:185], v148 offset:4096
	ds_read_b128 v[186:189], v148 offset:5120
	ds_read_b128 v[190:193], v148 offset:6144
	ds_read_b128 v[194:197], v148 offset:7168
	global_load_lds_dwordx4 v[198:199], off
	v_lshl_add_u64 v[198:199], s[38:39], 0, v[138:139]
	s_add_i32 m0, s31, 0xe000
	s_nop 0
	global_load_lds_dwordx4 v[198:199], off
	s_waitcnt lgkmcnt(8)
	s_barrier
	s_waitcnt lgkmcnt(0)
	s_setprio 1
	s_waitcnt lgkmcnt(0)
	v_mfma_f32_16x16x32_bf16 v[120:123], v[150:153], v[166:169], v[120:123]
	v_mfma_f32_16x16x32_bf16 v[120:123], v[154:157], v[170:173], v[120:123]
	v_mfma_f32_16x16x32_bf16 v[124:127], v[162:165], v[170:173], v[124:127]
	v_mfma_f32_16x16x32_bf16 v[124:127], v[158:161], v[166:169], v[124:127]
	v_mfma_f32_16x16x32_bf16 v[104:107], v[158:161], v[174:177], v[104:107]
	v_mfma_f32_16x16x32_bf16 v[104:107], v[162:165], v[178:181], v[104:107]
	v_mfma_f32_16x16x32_bf16 v[108:111], v[154:157], v[178:181], v[108:111]
	v_mfma_f32_16x16x32_bf16 v[108:111], v[150:153], v[174:177], v[108:111]
	v_mfma_f32_16x16x32_bf16 v[92:95], v[150:153], v[182:185], v[92:95]
	v_mfma_f32_16x16x32_bf16 v[92:95], v[154:157], v[186:189], v[92:95]
	v_mfma_f32_16x16x32_bf16 v[88:91], v[162:165], v[186:189], v[88:91]
	v_mfma_f32_16x16x32_bf16 v[88:91], v[158:161], v[182:185], v[88:91]
	v_mfma_f32_16x16x32_bf16 v[72:75], v[158:161], v[190:193], v[72:75]
	v_mfma_f32_16x16x32_bf16 v[72:75], v[162:165], v[194:197], v[72:75]
	v_mfma_f32_16x16x32_bf16 v[76:79], v[154:157], v[194:197], v[76:79]
	v_mfma_f32_16x16x32_bf16 v[76:79], v[150:153], v[190:193], v[76:79]
	s_setprio 0
	s_barrier
	s_add_i32 s2, s57, s30
	v_lshl_add_u64 v[218:219], s[42:43], 0, v[130:131]
	s_mov_b32 m0, s2
	ds_read_b128 v[198:201], v149
	ds_read_b128 v[202:205], v149 offset:1024
	ds_read_b128 v[206:209], v149 offset:2048
	ds_read_b128 v[210:213], v149 offset:3072
	global_load_lds_dwordx4 v[218:219], off
	v_lshl_add_u64 v[220:221], s[42:43], 0, v[134:135]
	s_add_i32 m0, s2, 0x2000
	s_nop 0
	global_load_lds_dwordx4 v[220:221], off
	s_barrier
	s_waitcnt lgkmcnt(0)
	s_setprio 1
	s_waitcnt lgkmcnt(0)
	v_mfma_f32_16x16x32_bf16 v[116:119], v[198:201], v[166:169], v[116:119]
	v_mfma_f32_16x16x32_bf16 v[116:119], v[202:205], v[170:173], v[116:119]
	v_mfma_f32_16x16x32_bf16 v[112:115], v[210:213], v[170:173], v[112:115]
	v_mfma_f32_16x16x32_bf16 v[112:115], v[206:209], v[166:169], v[112:115]
	v_mfma_f32_16x16x32_bf16 v[96:99], v[206:209], v[174:177], v[96:99]
	v_mfma_f32_16x16x32_bf16 v[96:99], v[210:213], v[178:181], v[96:99]
	v_mfma_f32_16x16x32_bf16 v[100:103], v[202:205], v[178:181], v[100:103]
	v_mfma_f32_16x16x32_bf16 v[100:103], v[198:201], v[174:177], v[100:103]
	v_mfma_f32_16x16x32_bf16 v[84:87], v[198:201], v[182:185], v[84:87]
	v_mfma_f32_16x16x32_bf16 v[84:87], v[202:205], v[186:189], v[84:87]
	v_mfma_f32_16x16x32_bf16 v[80:83], v[210:213], v[186:189], v[80:83]
	v_mfma_f32_16x16x32_bf16 v[80:83], v[206:209], v[182:185], v[80:83]
	v_mfma_f32_16x16x32_bf16 v[64:67], v[206:209], v[190:193], v[64:67]
	v_mfma_f32_16x16x32_bf16 v[64:67], v[210:213], v[194:197], v[64:67]
	v_mfma_f32_16x16x32_bf16 v[68:71], v[202:205], v[194:197], v[68:71]
	v_mfma_f32_16x16x32_bf16 v[68:71], v[198:201], v[190:193], v[68:71]
	s_setprio 0
	s_mov_b32 m0, s31
	v_lshl_add_u64 v[222:223], s[44:45], 0, v[128:129]
	s_barrier
	ds_read_b128 v[166:169], v148 offset:16384
	ds_read_b128 v[170:173], v148 offset:17408
	ds_read_b128 v[174:177], v148 offset:18432
	ds_read_b128 v[178:181], v148 offset:19456
	ds_read_b128 v[182:185], v148 offset:20480
	ds_read_b128 v[186:189], v148 offset:21504
	ds_read_b128 v[190:193], v148 offset:22528
	ds_read_b128 v[194:197], v148 offset:23552
	global_load_lds_dwordx4 v[222:223], off
	v_lshl_add_u64 v[224:225], s[44:45], 0, v[132:133]
	s_mov_b32 m0, s46
	s_nop 0
	global_load_lds_dwordx4 v[224:225], off
	s_barrier
	s_waitcnt lgkmcnt(0)
	s_setprio 1
	s_waitcnt lgkmcnt(0)
	v_mfma_f32_16x16x32_bf16 v[60:63], v[150:153], v[166:169], v[60:63]
	v_mfma_f32_16x16x32_bf16 v[60:63], v[154:157], v[170:173], v[60:63]
	v_mfma_f32_16x16x32_bf16 v[56:59], v[162:165], v[170:173], v[56:59]
	v_mfma_f32_16x16x32_bf16 v[56:59], v[158:161], v[166:169], v[56:59]
	v_mfma_f32_16x16x32_bf16 v[40:43], v[158:161], v[174:177], v[40:43]
	v_mfma_f32_16x16x32_bf16 v[40:43], v[162:165], v[178:181], v[40:43]
	v_mfma_f32_16x16x32_bf16 v[44:47], v[154:157], v[178:181], v[44:47]
	v_mfma_f32_16x16x32_bf16 v[44:47], v[150:153], v[174:177], v[44:47]
	v_mfma_f32_16x16x32_bf16 v[28:31], v[150:153], v[182:185], v[28:31]
	v_mfma_f32_16x16x32_bf16 v[28:31], v[154:157], v[186:189], v[28:31]
	v_mfma_f32_16x16x32_bf16 v[24:27], v[162:165], v[186:189], v[24:27]
	v_mfma_f32_16x16x32_bf16 v[24:27], v[158:161], v[182:185], v[24:27]
	v_mfma_f32_16x16x32_bf16 v[8:11], v[158:161], v[190:193], v[8:11]
	v_mfma_f32_16x16x32_bf16 v[8:11], v[162:165], v[194:197], v[8:11]
	v_mfma_f32_16x16x32_bf16 v[12:15], v[154:157], v[194:197], v[12:15]
	v_mfma_f32_16x16x32_bf16 v[12:15], v[150:153], v[190:193], v[12:15]
	s_setprio 0
	s_barrier
; #define PG8_STAGE(bufoff, gbase, voff) do { _Pragma("unroll") for (int _i = 0; _i < 2; ++_i) \
;         __builtin_amdgcn_global_load_lds((const unsigned*)((const char*)(gbase) + (voff)[_i]), (LAS unsigned*)(lds + (bufoff) + ldsw + _i * 8192), 16, 0, 0); } while (0)
; #define PG8_LDA(dst, b, h) do { _Pragma("unroll") for (int m = 0; m < 4; ++m) _Pragma("unroll") for (int k = 0; k < 2; ++k) dst[m][k] = *(const LAS bf16x8*)(lds + PG8_SA(b, h) + aoff + m * 2048 + k * 1024); } while (0)
; #define PG8_LDB(dst, b, h) do { _Pragma("unroll") for (int n = 0; n < 2; ++n) _Pragma("unroll") for (int k = 0; k < 2; ++k) dst[n][k] = *(const LAS bf16x8*)(lds + PG8_SB(b, h) + boff + n * 2048 + k * 1024); } while (0)
; #define PG8_MMA(ai, bj, At, Bt) do { __builtin_amdgcn_s_setprio(1); _Pragma("unroll") for (int m = 0; m < 4; ++m) _Pragma("unroll") for (int n = 0; n < 2; ++n) _Pragma("unroll") for (int k = 0; k < 2; ++k) \
;         acc[ai][bj][m][n] = __builtin_amdgcn_mfma_f32_16x16x32_bf16(Bt[n][k], At[m][k], acc[ai][bj][m][n], 0, 0, 0); __builtin_amdgcn_s_setprio(0); } while (0)
; #define PG8_WAIT_V(n) asm volatile("s_waitcnt vmcnt(" #n ")" ::: "memory")
; #define PG8_WAIT_L(n) asm volatile("s_waitcnt lgkmcnt(" #n ")" ::: "memory")
; #define PG8_BAR __builtin_amdgcn_s_barrier()
; #define PG8_SCHED __builtin_amdgcn_sched_barrier(0)
; template <class Epi>
; DEVINL void gemm_phase(LAS unsigned char* lds, const Gemm g, const Order& S, const Epi& E) {
;     ...
;             PG8_STAGE(PG8_SB(0, 1), b2 + hstepB, voffB);
;             PG8_WAIT_V(6); PG8_BAR; PG8_MMA(1, 1, At, B1); PG8_BAR;
;             PG8_LDB(B0, 1, 0); PG8_SCHED; PG8_LDA(At, 1, 0); PG8_STAGE(PG8_SA(0, 1), a2 + hstepA, voffA);
;             PG8_WAIT_L(8); PG8_BAR; PG8_WAIT_L(0); PG8_MMA(0, 0, At, B0); PG8_BAR; PG8_SCHED;
;             PG8_LDB(B1, 1, 1); PG8_STAGE(PG8_SB(1, 0), b3, voffB);
	s_add_u32 s2, s42, 0x10000
	s_addc_u32 s3, s43, 0
	s_add_i32 s38, s58, s30
	v_lshl_add_u64 v[150:151], s[2:3], 0, v[130:131]
	s_mov_b32 m0, s38
	s_nop 0
	global_load_lds_dwordx4 v[150:151], off
	v_lshl_add_u64 v[150:151], s[2:3], 0, v[134:135]
	s_add_i32 m0, s38, 0x2000
	s_nop 0
	global_load_lds_dwordx4 v[150:151], off
	s_waitcnt vmcnt(6)
	s_barrier
	s_setprio 1
	v_mfma_f32_16x16x32_bf16 v[52:55], v[198:201], v[166:169], v[52:55]
	v_mfma_f32_16x16x32_bf16 v[52:55], v[202:205], v[170:173], v[52:55]
	v_mfma_f32_16x16x32_bf16 v[48:51], v[210:213], v[170:173], v[48:51]
	v_mfma_f32_16x16x32_bf16 v[48:51], v[206:209], v[166:169], v[48:51]
	v_mfma_f32_16x16x32_bf16 v[32:35], v[206:209], v[174:177], v[32:35]
	v_mfma_f32_16x16x32_bf16 v[32:35], v[210:213], v[178:181], v[32:35]
	v_mfma_f32_16x16x32_bf16 v[36:39], v[202:205], v[178:181], v[36:39]
	v_mfma_f32_16x16x32_bf16 v[36:39], v[198:201], v[174:177], v[36:39]
	v_mfma_f32_16x16x32_bf16 v[20:23], v[198:201], v[182:185], v[20:23]
	v_mfma_f32_16x16x32_bf16 v[20:23], v[202:205], v[186:189], v[20:23]
	v_mfma_f32_16x16x32_bf16 v[16:19], v[210:213], v[186:189], v[16:19]
	v_mfma_f32_16x16x32_bf16 v[16:19], v[206:209], v[182:185], v[16:19]
	v_mfma_f32_16x16x32_bf16 v[0:3], v[206:209], v[190:193], v[0:3]
	v_mfma_f32_16x16x32_bf16 v[0:3], v[210:213], v[194:197], v[0:3]
	v_mfma_f32_16x16x32_bf16 v[4:7], v[202:205], v[194:197], v[4:7]
	v_mfma_f32_16x16x32_bf16 v[4:7], v[198:201], v[190:193], v[4:7]
	s_setprio 0
	s_add_i32 s38, 16, 0x18000
	v_add_u32_e32 v162, s38, v145
	s_barrier
	ds_read_b128 v[150:153], v162
	ds_read_b128 v[154:157], v162 offset:1024
	ds_read_b128 v[158:161], v162 offset:2048
	ds_read_b128 v[162:165], v162 offset:3072
	s_add_u32 s2, s44, 0x30000
	s_addc_u32 s3, s45, 0
	s_mov_b32 m0, s47
	v_lshl_add_u64 v[198:199], s[2:3], 0, v[128:129]
	ds_read_b128 v[166:169], v148 offset:32768
	ds_read_b128 v[170:173], v148 offset:33792
	ds_read_b128 v[174:177], v148 offset:34816
	ds_read_b128 v[178:181], v148 offset:35840
	ds_read_b128 v[182:185], v148 offset:36864
	ds_read_b128 v[186:189], v148 offset:37888
	ds_read_b128 v[190:193], v148 offset:38912
	ds_read_b128 v[194:197], v148 offset:39936
	global_load_lds_dwordx4 v[198:199], off
	v_lshl_add_u64 v[198:199], s[2:3], 0, v[132:133]
	s_mov_b32 m0, s48
	s_nop 0
	global_load_lds_dwordx4 v[198:199], off
	s_waitcnt lgkmcnt(8)
	s_barrier
	s_waitcnt lgkmcnt(0)
	s_setprio 1
	s_waitcnt lgkmcnt(0)
	v_mfma_f32_16x16x32_bf16 v[120:123], v[150:153], v[166:169], v[120:123]
	v_mfma_f32_16x16x32_bf16 v[120:123], v[154:157], v[170:173], v[120:123]
	v_mfma_f32_16x16x32_bf16 v[124:127], v[162:165], v[170:173], v[124:127]
	v_mfma_f32_16x16x32_bf16 v[124:127], v[158:161], v[166:169], v[124:127]
	v_mfma_f32_16x16x32_bf16 v[104:107], v[158:161], v[174:177], v[104:107]
	v_mfma_f32_16x16x32_bf16 v[104:107], v[162:165], v[178:181], v[104:107]
	v_mfma_f32_16x16x32_bf16 v[108:111], v[154:157], v[178:181], v[108:111]
	v_mfma_f32_16x16x32_bf16 v[108:111], v[150:153], v[174:177], v[108:111]
	v_mfma_f32_16x16x32_bf16 v[92:95], v[150:153], v[182:185], v[92:95]
	v_mfma_f32_16x16x32_bf16 v[92:95], v[154:157], v[186:189], v[92:95]
	v_mfma_f32_16x16x32_bf16 v[88:91], v[162:165], v[186:189], v[88:91]
	v_mfma_f32_16x16x32_bf16 v[88:91], v[158:161], v[182:185], v[88:91]
	v_mfma_f32_16x16x32_bf16 v[72:75], v[158:161], v[190:193], v[72:75]
	v_mfma_f32_16x16x32_bf16 v[72:75], v[162:165], v[194:197], v[72:75]
	v_mfma_f32_16x16x32_bf16 v[76:79], v[154:157], v[194:197], v[76:79]
	v_mfma_f32_16x16x32_bf16 v[76:79], v[150:153], v[190:193], v[76:79]
	s_setprio 0
	s_barrier
	s_add_i32 s39, 16, 0x1c000
	s_add_i32 s2, s38, s30
	v_add_u32_e32 v210, s39, v145
	v_lshl_add_u64 v[218:219], v[218:219], 0, s[8:9]
	s_mov_b32 m0, s2
	ds_read_b128 v[198:201], v210
	ds_read_b128 v[202:205], v210 offset:1024
	ds_read_b128 v[206:209], v210 offset:2048
	ds_read_b128 v[210:213], v210 offset:3072
	global_load_lds_dwordx4 v[218:219], off
	v_lshl_add_u64 v[218:219], v[220:221], 0, s[8:9]
	s_add_i32 m0, s2, 0x2000
	s_nop 0
	global_load_lds_dwordx4 v[218:219], off
	s_barrier
; #define PG8_STAGE(bufoff, gbase, voff) do { _Pragma("unroll") for (int _i = 0; _i < 2; ++_i) \
;         __builtin_amdgcn_global_load_lds((const unsigned*)((const char*)(gbase) + (voff)[_i]), (LAS unsigned*)(lds + (bufoff) + ldsw + _i * 8192), 16, 0, 0); } while (0)
; #define PG8_LDA(dst, b, h) do { _Pragma("unroll") for (int m = 0; m < 4; ++m) _Pragma("unroll") for (int k = 0; k < 2; ++k) dst[m][k] = *(const LAS bf16x8*)(lds + PG8_SA(b, h) + aoff + m * 2048 + k * 1024); } while (0)
; #define PG8_MMA(ai, bj, At, Bt) do { __builtin_amdgcn_s_setprio(1); _Pragma("unroll") for (int m = 0; m < 4; ++m) _Pragma("unroll") for (int n = 0; n < 2; ++n) _Pragma("unroll") for (int k = 0; k < 2; ++k) \
;         acc[ai][bj][m][n] = __builtin_amdgcn_mfma_f32_16x16x32_bf16(Bt[n][k], At[m][k], acc[ai][bj][m][n], 0, 0, 0); __builtin_amdgcn_s_setprio(0); } while (0)
; #define PG8_WAIT_V(n) asm volatile("s_waitcnt vmcnt(" #n ")" ::: "memory")
; #define PG8_WAIT_L(n) asm volatile("s_waitcnt lgkmcnt(" #n ")" ::: "memory")
; #define PG8_BAR __builtin_amdgcn_s_barrier()
; #define PG8_SCHED __builtin_amdgcn_sched_barrier(0)
; template <class Epi>
; DEVINL void gemm_phase(LAS unsigned char* lds, const Gemm g, const Order& S, const Epi& E) {
;     ...
;             PG8_BAR; PG8_WAIT_L(0); PG8_MMA(0, 1, At, B1); PG8_BAR;
;             PG8_LDA(At, 1, 1); PG8_STAGE(PG8_SA(1, 0), a3, voffA);
;             PG8_BAR; PG8_WAIT_L(0); PG8_MMA(1, 0, At, B0); PG8_BAR; PG8_SCHED;
;             PG8_STAGE(PG8_SB(1, 1), b3 + hstepB, voffB);
;             PG8_WAIT_V(6); PG8_BAR; PG8_MMA(1, 1, At, B1); PG8_BAR;
;         }
	s_waitcnt lgkmcnt(0)
	s_setprio 1
	s_waitcnt lgkmcnt(0)
	v_mfma_f32_16x16x32_bf16 v[116:119], v[198:201], v[166:169], v[116:119]
	v_mfma_f32_16x16x32_bf16 v[116:119], v[202:205], v[170:173], v[116:119]
	v_mfma_f32_16x16x32_bf16 v[112:115], v[210:213], v[170:173], v[112:115]
	v_mfma_f32_16x16x32_bf16 v[112:115], v[206:209], v[166:169], v[112:115]
	v_mfma_f32_16x16x32_bf16 v[96:99], v[206:209], v[174:177], v[96:99]
	v_mfma_f32_16x16x32_bf16 v[96:99], v[210:213], v[178:181], v[96:99]
	v_mfma_f32_16x16x32_bf16 v[100:103], v[202:205], v[178:181], v[100:103]
	v_mfma_f32_16x16x32_bf16 v[100:103], v[198:201], v[174:177], v[100:103]
	v_mfma_f32_16x16x32_bf16 v[84:87], v[198:201], v[182:185], v[84:87]
	v_mfma_f32_16x16x32_bf16 v[84:87], v[202:205], v[186:189], v[84:87]
	v_mfma_f32_16x16x32_bf16 v[80:83], v[210:213], v[186:189], v[80:83]
	v_mfma_f32_16x16x32_bf16 v[80:83], v[206:209], v[182:185], v[80:83]
	v_mfma_f32_16x16x32_bf16 v[64:67], v[206:209], v[190:193], v[64:67]
	v_mfma_f32_16x16x32_bf16 v[64:67], v[210:213], v[194:197], v[64:67]
	v_mfma_f32_16x16x32_bf16 v[68:71], v[202:205], v[194:197], v[68:71]
	v_mfma_f32_16x16x32_bf16 v[68:71], v[198:201], v[190:193], v[68:71]
	s_setprio 0
	s_mov_b32 m0, s50
	v_lshl_add_u64 v[218:219], v[222:223], 0, s[8:9]
	s_barrier
	ds_read_b128 v[166:169], v148 offset:49152
	ds_read_b128 v[170:173], v148 offset:50176
	ds_read_b128 v[174:177], v148 offset:51200
	ds_read_b128 v[178:181], v148 offset:52224
	ds_read_b128 v[182:185], v148 offset:53248
	ds_read_b128 v[186:189], v148 offset:54272
	ds_read_b128 v[190:193], v148 offset:55296
	ds_read_b128 v[194:197], v148 offset:56320
	global_load_lds_dwordx4 v[218:219], off
	v_lshl_add_u64 v[218:219], v[224:225], 0, s[8:9]
	s_mov_b32 m0, s51
	s_nop 0
	global_load_lds_dwordx4 v[218:219], off
	s_barrier
	s_waitcnt lgkmcnt(0)
	s_setprio 1
	s_waitcnt lgkmcnt(0)
	v_mfma_f32_16x16x32_bf16 v[60:63], v[150:153], v[166:169], v[60:63]
	v_mfma_f32_16x16x32_bf16 v[60:63], v[154:157], v[170:173], v[60:63]
	v_mfma_f32_16x16x32_bf16 v[56:59], v[162:165], v[170:173], v[56:59]
	v_mfma_f32_16x16x32_bf16 v[56:59], v[158:161], v[166:169], v[56:59]
	v_mfma_f32_16x16x32_bf16 v[40:43], v[158:161], v[174:177], v[40:43]
	v_mfma_f32_16x16x32_bf16 v[40:43], v[162:165], v[178:181], v[40:43]
	v_mfma_f32_16x16x32_bf16 v[44:47], v[154:157], v[178:181], v[44:47]
	v_mfma_f32_16x16x32_bf16 v[44:47], v[150:153], v[174:177], v[44:47]
	v_mfma_f32_16x16x32_bf16 v[28:31], v[150:153], v[182:185], v[28:31]
	v_mfma_f32_16x16x32_bf16 v[28:31], v[154:157], v[186:189], v[28:31]
	v_mfma_f32_16x16x32_bf16 v[24:27], v[162:165], v[186:189], v[24:27]
	v_mfma_f32_16x16x32_bf16 v[24:27], v[158:161], v[182:185], v[24:27]
	v_mfma_f32_16x16x32_bf16 v[8:11], v[158:161], v[190:193], v[8:11]
	v_mfma_f32_16x16x32_bf16 v[8:11], v[162:165], v[194:197], v[8:11]
	v_mfma_f32_16x16x32_bf16 v[12:15], v[154:157], v[194:197], v[12:15]
	v_mfma_f32_16x16x32_bf16 v[12:15], v[150:153], v[190:193], v[12:15]
	s_setprio 0
	s_barrier
	s_add_u32 s2, s42, 0x10080
	s_addc_u32 s3, s43, 0
	s_add_i32 s38, s39, s30
	v_lshl_add_u64 v[150:151], s[2:3], 0, v[130:131]
	s_mov_b32 m0, s38
	s_nop 0
	global_load_lds_dwordx4 v[150:151], off
	v_lshl_add_u64 v[150:151], s[2:3], 0, v[134:135]
	s_add_i32 m0, s38, 0x2000
	s_nop 0
	global_load_lds_dwordx4 v[150:151], off
	s_waitcnt vmcnt(6)
	s_barrier
	s_setprio 1
	v_mfma_f32_16x16x32_bf16 v[52:55], v[198:201], v[166:169], v[52:55]
	v_mfma_f32_16x16x32_bf16 v[52:55], v[202:205], v[170:173], v[52:55]
	v_mfma_f32_16x16x32_bf16 v[48:51], v[210:213], v[170:173], v[48:51]
	v_mfma_f32_16x16x32_bf16 v[48:51], v[206:209], v[166:169], v[48:51]
	v_mfma_f32_16x16x32_bf16 v[32:35], v[206:209], v[174:177], v[32:35]
	v_mfma_f32_16x16x32_bf16 v[32:35], v[210:213], v[178:181], v[32:35]
	v_mfma_f32_16x16x32_bf16 v[36:39], v[202:205], v[178:181], v[36:39]
	v_mfma_f32_16x16x32_bf16 v[36:39], v[198:201], v[174:177], v[36:39]
	v_mfma_f32_16x16x32_bf16 v[20:23], v[198:201], v[182:185], v[20:23]
	v_mfma_f32_16x16x32_bf16 v[20:23], v[202:205], v[186:189], v[20:23]
	v_mfma_f32_16x16x32_bf16 v[16:19], v[210:213], v[186:189], v[16:19]
	v_mfma_f32_16x16x32_bf16 v[16:19], v[206:209], v[182:185], v[16:19]
	v_mfma_f32_16x16x32_bf16 v[0:3], v[206:209], v[190:193], v[0:3]
	v_mfma_f32_16x16x32_bf16 v[0:3], v[210:213], v[194:197], v[0:3]
	v_mfma_f32_16x16x32_bf16 v[4:7], v[202:205], v[194:197], v[4:7]
	v_mfma_f32_16x16x32_bf16 v[4:7], v[198:201], v[190:193], v[4:7]
	s_setprio 0
	s_add_u32 s66, s66, 0x100
	s_addc_u32 s67, s67, 0
	s_cmp_ge_i32 s68, s49
	s_mov_b64 s[38:39], s[4:5]
	s_mov_b32 s42, s68
	s_barrier
	s_cbranch_scc0 .LBB0_825
	s_branch .LBB0_814

; #define PG8_STAGE(bufoff, gbase, voff) do { _Pragma("unroll") for (int _i = 0; _i < 2; ++_i) \
;         __builtin_amdgcn_global_load_lds((const unsigned*)((const char*)(gbase) + (voff)[_i]), (LAS unsigned*)(lds + (bufoff) + ldsw + _i * 8192), 16, 0, 0); } while (0)
; #define PG8_LDA(dst, b, h) do { _Pragma("unroll") for (int m = 0; m < 4; ++m) _Pragma("unroll") for (int k = 0; k < 2; ++k) dst[m][k] = *(const LAS bf16x8*)(lds + PG8_SA(b, h) + aoff + m * 2048 + k * 1024); } while (0)
; #define PG8_LDB(dst, b, h) do { _Pragma("unroll") for (int n = 0; n < 2; ++n) _Pragma("unroll") for (int k = 0; k < 2; ++k) dst[n][k] = *(const LAS bf16x8*)(lds + PG8_SB(b, h) + boff + n * 2048 + k * 1024); } while (0)
; #define PG8_MMA(ai, bj, At, Bt) do { __builtin_amdgcn_s_setprio(1); _Pragma("unroll") for (int m = 0; m < 4; ++m) _Pragma("unroll") for (int n = 0; n < 2; ++n) _Pragma("unroll") for (int k = 0; k < 2; ++k) \
;         acc[ai][bj][m][n] = __builtin_amdgcn_mfma_f32_16x16x32_bf16(Bt[n][k], At[m][k], acc[ai][bj][m][n], 0, 0, 0); __builtin_amdgcn_s_setprio(0); } while (0)
; #define PG8_WAIT_L(n) asm volatile("s_waitcnt lgkmcnt(" #n ")" ::: "memory")
; #define PG8_BAR __builtin_amdgcn_s_barrier()
; #define PG8_SCHED __builtin_amdgcn_sched_barrier(0)
; template <class Epi>
; DEVINL void gemm_phase(LAS unsigned char* lds, const Gemm g, const Order& S, const Epi& E) {
;     ...
;             const char* a1 = cA + (size_t)(t + 1) * kstep;
;             const char* a2 = last ? nA : cA + (size_t)(t + 2) * kstep; const char* b2 = last ? nB : cB + (size_t)(t + 2) * kstep;
;             const char* a3 = a2 + kstep; const char* b3 = b2 + kstep;
;             PG8_LDB(B0, 0, 0); PG8_SCHED; PG8_LDA(At, 0, 0); PG8_STAGE(PG8_SA(1, 1), a1 + hstepA, voffA);
;             PG8_WAIT_L(8); PG8_BAR; PG8_WAIT_L(0); PG8_MMA(0, 0, At, B0); PG8_BAR; PG8_SCHED;
;             PG8_LDB(B1, 0, 1); PG8_STAGE(PG8_SB(0, 0), b2, voffB);
;             PG8_BAR; PG8_WAIT_L(0); PG8_MMA(0, 1, At, B1); PG8_BAR;
;             PG8_LDA(At, 0, 1); PG8_STAGE(PG8_SA(0, 0), a2, voffA);
;             PG8_BAR; PG8_WAIT_L(0); PG8_MMA(1, 0, At, B0); PG8_BAR; PG8_SCHED;
.LBB0_848:
	ds_read_b128 v[150:153], v147
	ds_read_b128 v[154:157], v147 offset:1024
	ds_read_b128 v[158:161], v147 offset:2048
	ds_read_b128 v[162:165], v147 offset:3072
	s_add_i32 s67, s44, 2
	s_add_u32 s2, s4, 0xffff0080
	s_addc_u32 s3, s5, -1
	s_cmp_eq_u32 s25, s44
	s_cselect_b32 s44, s16, s65
	s_cselect_b32 s47, s13, s3
	s_cselect_b32 s46, s64, s2
	s_cselect_b32 s45, s17, s66
	v_lshl_add_u64 v[198:199], s[4:5], 0, v[136:137]
	s_add_i32 m0, s9, 0xc000
	ds_read_b128 v[166:169], v148
	ds_read_b128 v[170:173], v148 offset:1024
	ds_read_b128 v[174:177], v148 offset:2048
	ds_read_b128 v[178:181], v148 offset:3072
	ds_read_b128 v[182:185], v148 offset:4096
	ds_read_b128 v[186:189], v148 offset:5120
	ds_read_b128 v[190:193], v148 offset:6144
	ds_read_b128 v[194:197], v148 offset:7168
	global_load_lds_dwordx4 v[198:199], off
	v_lshl_add_u64 v[198:199], s[4:5], 0, v[138:139]
	s_add_i32 m0, s9, 0xe000
	s_nop 0
	global_load_lds_dwordx4 v[198:199], off
	s_waitcnt lgkmcnt(8)
	s_barrier
	s_waitcnt lgkmcnt(0)
	s_setprio 1
	s_waitcnt lgkmcnt(0)
	v_mfma_f32_16x16x32_bf16 v[120:123], v[150:153], v[166:169], v[120:123]
	v_mfma_f32_16x16x32_bf16 v[120:123], v[154:157], v[170:173], v[120:123]
	v_mfma_f32_16x16x32_bf16 v[124:127], v[162:165], v[170:173], v[124:127]
	v_mfma_f32_16x16x32_bf16 v[124:127], v[158:161], v[166:169], v[124:127]
	v_mfma_f32_16x16x32_bf16 v[104:107], v[158:161], v[174:177], v[104:107]
	v_mfma_f32_16x16x32_bf16 v[104:107], v[162:165], v[178:181], v[104:107]
	v_mfma_f32_16x16x32_bf16 v[108:111], v[154:157], v[178:181], v[108:111]
	v_mfma_f32_16x16x32_bf16 v[108:111], v[150:153], v[174:177], v[108:111]
	v_mfma_f32_16x16x32_bf16 v[92:95], v[150:153], v[182:185], v[92:95]
	v_mfma_f32_16x16x32_bf16 v[92:95], v[154:157], v[186:189], v[92:95]
	v_mfma_f32_16x16x32_bf16 v[88:91], v[162:165], v[186:189], v[88:91]
	v_mfma_f32_16x16x32_bf16 v[88:91], v[158:161], v[182:185], v[88:91]
	v_mfma_f32_16x16x32_bf16 v[72:75], v[158:161], v[190:193], v[72:75]
	v_mfma_f32_16x16x32_bf16 v[72:75], v[162:165], v[194:197], v[72:75]
	v_mfma_f32_16x16x32_bf16 v[76:79], v[154:157], v[194:197], v[76:79]
	v_mfma_f32_16x16x32_bf16 v[76:79], v[150:153], v[190:193], v[76:79]
	s_setprio 0
	s_barrier
	s_add_i32 s2, s56, s30
	v_lshl_add_u64 v[218:219], s[44:45], 0, v[130:131]
	s_mov_b32 m0, s2
	ds_read_b128 v[198:201], v149
	ds_read_b128 v[202:205], v149 offset:1024
	ds_read_b128 v[206:209], v149 offset:2048
	ds_read_b128 v[210:213], v149 offset:3072
	global_load_lds_dwordx4 v[218:219], off
	v_lshl_add_u64 v[220:221], s[44:45], 0, v[134:135]
	s_add_i32 m0, s2, 0x2000
	s_nop 0
	global_load_lds_dwordx4 v[220:221], off
	s_barrier
	s_waitcnt lgkmcnt(0)
	s_setprio 1
	s_waitcnt lgkmcnt(0)
	v_mfma_f32_16x16x32_bf16 v[116:119], v[198:201], v[166:169], v[116:119]
	v_mfma_f32_16x16x32_bf16 v[116:119], v[202:205], v[170:173], v[116:119]
	v_mfma_f32_16x16x32_bf16 v[112:115], v[210:213], v[170:173], v[112:115]
	v_mfma_f32_16x16x32_bf16 v[112:115], v[206:209], v[166:169], v[112:115]
	v_mfma_f32_16x16x32_bf16 v[96:99], v[206:209], v[174:177], v[96:99]
	v_mfma_f32_16x16x32_bf16 v[96:99], v[210:213], v[178:181], v[96:99]
	v_mfma_f32_16x16x32_bf16 v[100:103], v[202:205], v[178:181], v[100:103]
	v_mfma_f32_16x16x32_bf16 v[100:103], v[198:201], v[174:177], v[100:103]
	v_mfma_f32_16x16x32_bf16 v[84:87], v[198:201], v[182:185], v[84:87]
	v_mfma_f32_16x16x32_bf16 v[84:87], v[202:205], v[186:189], v[84:87]
	v_mfma_f32_16x16x32_bf16 v[80:83], v[210:213], v[186:189], v[80:83]
	v_mfma_f32_16x16x32_bf16 v[80:83], v[206:209], v[182:185], v[80:83]
	v_mfma_f32_16x16x32_bf16 v[64:67], v[206:209], v[190:193], v[64:67]
	v_mfma_f32_16x16x32_bf16 v[64:67], v[210:213], v[194:197], v[64:67]
	v_mfma_f32_16x16x32_bf16 v[68:71], v[202:205], v[194:197], v[68:71]
	v_mfma_f32_16x16x32_bf16 v[68:71], v[198:201], v[190:193], v[68:71]
	s_setprio 0
	s_mov_b32 m0, s9
	v_lshl_add_u64 v[222:223], s[46:47], 0, v[128:129]
	s_barrier
	ds_read_b128 v[166:169], v148 offset:16384
	ds_read_b128 v[170:173], v148 offset:17408
	ds_read_b128 v[174:177], v148 offset:18432
	ds_read_b128 v[178:181], v148 offset:19456
	ds_read_b128 v[182:185], v148 offset:20480
	ds_read_b128 v[186:189], v148 offset:21504
	ds_read_b128 v[190:193], v148 offset:22528
	ds_read_b128 v[194:197], v148 offset:23552
	global_load_lds_dwordx4 v[222:223], off
	v_lshl_add_u64 v[224:225], s[46:47], 0, v[132:133]
	s_mov_b32 m0, s31
	s_nop 0
	global_load_lds_dwordx4 v[224:225], off
	s_barrier
	s_waitcnt lgkmcnt(0)
	s_setprio 1
	s_waitcnt lgkmcnt(0)
	v_mfma_f32_16x16x32_bf16 v[60:63], v[150:153], v[166:169], v[60:63]
	v_mfma_f32_16x16x32_bf16 v[60:63], v[154:157], v[170:173], v[60:63]
	v_mfma_f32_16x16x32_bf16 v[56:59], v[162:165], v[170:173], v[56:59]
	v_mfma_f32_16x16x32_bf16 v[56:59], v[158:161], v[166:169], v[56:59]
	v_mfma_f32_16x16x32_bf16 v[40:43], v[158:161], v[174:177], v[40:43]
	v_mfma_f32_16x16x32_bf16 v[40:43], v[162:165], v[178:181], v[40:43]
	v_mfma_f32_16x16x32_bf16 v[44:47], v[154:157], v[178:181], v[44:47]
	v_mfma_f32_16x16x32_bf16 v[44:47], v[150:153], v[174:177], v[44:47]
	v_mfma_f32_16x16x32_bf16 v[28:31], v[150:153], v[182:185], v[28:31]
	v_mfma_f32_16x16x32_bf16 v[28:31], v[154:157], v[186:189], v[28:31]
	v_mfma_f32_16x16x32_bf16 v[24:27], v[162:165], v[186:189], v[24:27]
	v_mfma_f32_16x16x32_bf16 v[24:27], v[158:161], v[182:185], v[24:27]
	v_mfma_f32_16x16x32_bf16 v[8:11], v[158:161], v[190:193], v[8:11]
	v_mfma_f32_16x16x32_bf16 v[8:11], v[162:165], v[194:197], v[8:11]
	v_mfma_f32_16x16x32_bf16 v[12:15], v[154:157], v[194:197], v[12:15]
	v_mfma_f32_16x16x32_bf16 v[12:15], v[150:153], v[190:193], v[12:15]
	s_setprio 0
	s_barrier
; #define PG8_STAGE(bufoff, gbase, voff) do { _Pragma("unroll") for (int _i = 0; _i < 2; ++_i) \
;         __builtin_amdgcn_global_load_lds((const unsigned*)((const char*)(gbase) + (voff)[_i]), (LAS unsigned*)(lds + (bufoff) + ldsw + _i * 8192), 16, 0, 0); } while (0)
; #define PG8_LDA(dst, b, h) do { _Pragma("unroll") for (int m = 0; m < 4; ++m) _Pragma("unroll") for (int k = 0; k < 2; ++k) dst[m][k] = *(const LAS bf16x8*)(lds + PG8_SA(b, h) + aoff + m * 2048 + k * 1024); } while (0)
; #define PG8_LDB(dst, b, h) do { _Pragma("unroll") for (int n = 0; n < 2; ++n) _Pragma("unroll") for (int k = 0; k < 2; ++k) dst[n][k] = *(const LAS bf16x8*)(lds + PG8_SB(b, h) + boff + n * 2048 + k * 1024); } while (0)
; #define PG8_MMA(ai, bj, At, Bt) do { __builtin_amdgcn_s_setprio(1); _Pragma("unroll") for (int m = 0; m < 4; ++m) _Pragma("unroll") for (int n = 0; n < 2; ++n) _Pragma("unroll") for (int k = 0; k < 2; ++k) \
;         acc[ai][bj][m][n] = __builtin_amdgcn_mfma_f32_16x16x32_bf16(Bt[n][k], At[m][k], acc[ai][bj][m][n], 0, 0, 0); __builtin_amdgcn_s_setprio(0); } while (0)
; #define PG8_WAIT_V(n) asm volatile("s_waitcnt vmcnt(" #n ")" ::: "memory")
; #define PG8_WAIT_L(n) asm volatile("s_waitcnt lgkmcnt(" #n ")" ::: "memory")
; #define PG8_BAR __builtin_amdgcn_s_barrier()
; #define PG8_SCHED __builtin_amdgcn_sched_barrier(0)
; template <class Epi>
; DEVINL void gemm_phase(LAS unsigned char* lds, const Gemm g, const Order& S, const Epi& E) {
;     ...
;             PG8_STAGE(PG8_SB(0, 1), b2 + hstepB, voffB);
;             PG8_WAIT_V(6); PG8_BAR; PG8_MMA(1, 1, At, B1); PG8_BAR;
;             PG8_LDB(B0, 1, 0); PG8_SCHED; PG8_LDA(At, 1, 0); PG8_STAGE(PG8_SA(0, 1), a2 + hstepA, voffA);
;             PG8_WAIT_L(8); PG8_BAR; PG8_WAIT_L(0); PG8_MMA(0, 0, At, B0); PG8_BAR; PG8_SCHED;
;             PG8_LDB(B1, 1, 1); PG8_STAGE(PG8_SB(1, 0), b3, voffB);
	s_add_u32 s2, s44, 0x30000
	s_addc_u32 s3, s45, 0
	s_add_i32 s68, s57, s30
	v_lshl_add_u64 v[150:151], s[2:3], 0, v[130:131]
	s_mov_b32 m0, s68
	s_nop 0
	global_load_lds_dwordx4 v[150:151], off
	v_lshl_add_u64 v[150:151], s[2:3], 0, v[134:135]
	s_add_i32 m0, s68, 0x2000
	s_nop 0
	global_load_lds_dwordx4 v[150:151], off
	s_waitcnt vmcnt(6)
	s_barrier
	s_setprio 1
	v_mfma_f32_16x16x32_bf16 v[52:55], v[198:201], v[166:169], v[52:55]
	v_mfma_f32_16x16x32_bf16 v[52:55], v[202:205], v[170:173], v[52:55]
	v_mfma_f32_16x16x32_bf16 v[48:51], v[210:213], v[170:173], v[48:51]
	v_mfma_f32_16x16x32_bf16 v[48:51], v[206:209], v[166:169], v[48:51]
	v_mfma_f32_16x16x32_bf16 v[32:35], v[206:209], v[174:177], v[32:35]
	v_mfma_f32_16x16x32_bf16 v[32:35], v[210:213], v[178:181], v[32:35]
	v_mfma_f32_16x16x32_bf16 v[36:39], v[202:205], v[178:181], v[36:39]
	v_mfma_f32_16x16x32_bf16 v[36:39], v[198:201], v[174:177], v[36:39]
	v_mfma_f32_16x16x32_bf16 v[20:23], v[198:201], v[182:185], v[20:23]
	v_mfma_f32_16x16x32_bf16 v[20:23], v[202:205], v[186:189], v[20:23]
	v_mfma_f32_16x16x32_bf16 v[16:19], v[210:213], v[186:189], v[16:19]
	v_mfma_f32_16x16x32_bf16 v[16:19], v[206:209], v[182:185], v[16:19]
	v_mfma_f32_16x16x32_bf16 v[0:3], v[206:209], v[190:193], v[0:3]
	v_mfma_f32_16x16x32_bf16 v[0:3], v[210:213], v[194:197], v[0:3]
	v_mfma_f32_16x16x32_bf16 v[4:7], v[202:205], v[194:197], v[4:7]
	v_mfma_f32_16x16x32_bf16 v[4:7], v[198:201], v[190:193], v[4:7]
	s_setprio 0
	s_add_i32 s68, 16, 0x18000
	v_add_u32_e32 v162, s68, v145
	s_barrier
	ds_read_b128 v[150:153], v162
	ds_read_b128 v[154:157], v162 offset:1024
	ds_read_b128 v[158:161], v162 offset:2048
	ds_read_b128 v[162:165], v162 offset:3072
	s_add_u32 s2, s46, 0x10000
	s_addc_u32 s3, s47, 0
	s_mov_b32 m0, s48
	v_lshl_add_u64 v[198:199], s[2:3], 0, v[128:129]
	ds_read_b128 v[166:169], v148 offset:32768
	ds_read_b128 v[170:173], v148 offset:33792
	ds_read_b128 v[174:177], v148 offset:34816
	ds_read_b128 v[178:181], v148 offset:35840
	ds_read_b128 v[182:185], v148 offset:36864
	ds_read_b128 v[186:189], v148 offset:37888
	ds_read_b128 v[190:193], v148 offset:38912
	ds_read_b128 v[194:197], v148 offset:39936
	global_load_lds_dwordx4 v[198:199], off
	v_lshl_add_u64 v[198:199], s[2:3], 0, v[132:133]
	s_mov_b32 m0, s49
	s_nop 0
	global_load_lds_dwordx4 v[198:199], off
	s_waitcnt lgkmcnt(8)
	s_barrier
	s_waitcnt lgkmcnt(0)
	s_setprio 1
	s_waitcnt lgkmcnt(0)
	v_mfma_f32_16x16x32_bf16 v[120:123], v[150:153], v[166:169], v[120:123]
	v_mfma_f32_16x16x32_bf16 v[120:123], v[154:157], v[170:173], v[120:123]
	v_mfma_f32_16x16x32_bf16 v[124:127], v[162:165], v[170:173], v[124:127]
	v_mfma_f32_16x16x32_bf16 v[124:127], v[158:161], v[166:169], v[124:127]
	v_mfma_f32_16x16x32_bf16 v[104:107], v[158:161], v[174:177], v[104:107]
	v_mfma_f32_16x16x32_bf16 v[104:107], v[162:165], v[178:181], v[104:107]
	v_mfma_f32_16x16x32_bf16 v[108:111], v[154:157], v[178:181], v[108:111]
	v_mfma_f32_16x16x32_bf16 v[108:111], v[150:153], v[174:177], v[108:111]
	v_mfma_f32_16x16x32_bf16 v[92:95], v[150:153], v[182:185], v[92:95]
	v_mfma_f32_16x16x32_bf16 v[92:95], v[154:157], v[186:189], v[92:95]
	v_mfma_f32_16x16x32_bf16 v[88:91], v[162:165], v[186:189], v[88:91]
	v_mfma_f32_16x16x32_bf16 v[88:91], v[158:161], v[182:185], v[88:91]
	v_mfma_f32_16x16x32_bf16 v[72:75], v[158:161], v[190:193], v[72:75]
	v_mfma_f32_16x16x32_bf16 v[72:75], v[162:165], v[194:197], v[72:75]
	v_mfma_f32_16x16x32_bf16 v[76:79], v[154:157], v[194:197], v[76:79]
	v_mfma_f32_16x16x32_bf16 v[76:79], v[150:153], v[190:193], v[76:79]
	s_setprio 0
	s_barrier
	s_add_i32 s46, 16, 0x1c000
	s_add_i32 s2, s68, s30
	v_add_u32_e32 v210, s46, v145
	v_lshl_add_u64 v[218:219], v[218:219], 0, s[6:7]
	s_mov_b32 m0, s2
	ds_read_b128 v[198:201], v210
	ds_read_b128 v[202:205], v210 offset:1024
	ds_read_b128 v[206:209], v210 offset:2048
	ds_read_b128 v[210:213], v210 offset:3072
	global_load_lds_dwordx4 v[218:219], off
	v_lshl_add_u64 v[218:219], v[220:221], 0, s[6:7]
	s_add_i32 m0, s2, 0x2000
	s_nop 0
	global_load_lds_dwordx4 v[218:219], off
	s_barrier
; #define PG8_STAGE(bufoff, gbase, voff) do { _Pragma("unroll") for (int _i = 0; _i < 2; ++_i) \
;         __builtin_amdgcn_global_load_lds((const unsigned*)((const char*)(gbase) + (voff)[_i]), (LAS unsigned*)(lds + (bufoff) + ldsw + _i * 8192), 16, 0, 0); } while (0)
; #define PG8_LDA(dst, b, h) do { _Pragma("unroll") for (int m = 0; m < 4; ++m) _Pragma("unroll") for (int k = 0; k < 2; ++k) dst[m][k] = *(const LAS bf16x8*)(lds + PG8_SA(b, h) + aoff + m * 2048 + k * 1024); } while (0)
; #define PG8_MMA(ai, bj, At, Bt) do { __builtin_amdgcn_s_setprio(1); _Pragma("unroll") for (int m = 0; m < 4; ++m) _Pragma("unroll") for (int n = 0; n < 2; ++n) _Pragma("unroll") for (int k = 0; k < 2; ++k) \
;         acc[ai][bj][m][n] = __builtin_amdgcn_mfma_f32_16x16x32_bf16(Bt[n][k], At[m][k], acc[ai][bj][m][n], 0, 0, 0); __builtin_amdgcn_s_setprio(0); } while (0)
; #define PG8_WAIT_V(n) asm volatile("s_waitcnt vmcnt(" #n ")" ::: "memory")
; #define PG8_WAIT_L(n) asm volatile("s_waitcnt lgkmcnt(" #n ")" ::: "memory")
; #define PG8_BAR __builtin_amdgcn_s_barrier()
; #define PG8_SCHED __builtin_amdgcn_sched_barrier(0)
; template <class Epi>
; DEVINL void gemm_phase(LAS unsigned char* lds, const Gemm g, const Order& S, const Epi& E) {
;     ...
;             PG8_BAR; PG8_WAIT_L(0); PG8_MMA(0, 1, At, B1); PG8_BAR;
;             PG8_LDA(At, 1, 1); PG8_STAGE(PG8_SA(1, 0), a3, voffA);
;             PG8_BAR; PG8_WAIT_L(0); PG8_MMA(1, 0, At, B0); PG8_BAR; PG8_SCHED;
;             PG8_STAGE(PG8_SB(1, 1), b3 + hstepB, voffB);
;             PG8_WAIT_V(6); PG8_BAR; PG8_MMA(1, 1, At, B1); PG8_BAR;
;         }
	s_waitcnt lgkmcnt(0)
	s_setprio 1
	s_waitcnt lgkmcnt(0)
	v_mfma_f32_16x16x32_bf16 v[116:119], v[198:201], v[166:169], v[116:119]
	v_mfma_f32_16x16x32_bf16 v[116:119], v[202:205], v[170:173], v[116:119]
	v_mfma_f32_16x16x32_bf16 v[112:115], v[210:213], v[170:173], v[112:115]
	v_mfma_f32_16x16x32_bf16 v[112:115], v[206:209], v[166:169], v[112:115]
	v_mfma_f32_16x16x32_bf16 v[96:99], v[206:209], v[174:177], v[96:99]
	v_mfma_f32_16x16x32_bf16 v[96:99], v[210:213], v[178:181], v[96:99]
	v_mfma_f32_16x16x32_bf16 v[100:103], v[202:205], v[178:181], v[100:103]
	v_mfma_f32_16x16x32_bf16 v[100:103], v[198:201], v[174:177], v[100:103]
	v_mfma_f32_16x16x32_bf16 v[84:87], v[198:201], v[182:185], v[84:87]
	v_mfma_f32_16x16x32_bf16 v[84:87], v[202:205], v[186:189], v[84:87]
	v_mfma_f32_16x16x32_bf16 v[80:83], v[210:213], v[186:189], v[80:83]
	v_mfma_f32_16x16x32_bf16 v[80:83], v[206:209], v[182:185], v[80:83]
	v_mfma_f32_16x16x32_bf16 v[64:67], v[206:209], v[190:193], v[64:67]
	v_mfma_f32_16x16x32_bf16 v[64:67], v[210:213], v[194:197], v[64:67]
	v_mfma_f32_16x16x32_bf16 v[68:71], v[202:205], v[194:197], v[68:71]
	v_mfma_f32_16x16x32_bf16 v[68:71], v[198:201], v[190:193], v[68:71]
	s_setprio 0
	s_mov_b32 m0, s52
	v_lshl_add_u64 v[218:219], v[222:223], 0, s[6:7]
	s_barrier
	ds_read_b128 v[166:169], v148 offset:49152
	ds_read_b128 v[170:173], v148 offset:50176
	ds_read_b128 v[174:177], v148 offset:51200
	ds_read_b128 v[178:181], v148 offset:52224
	ds_read_b128 v[182:185], v148 offset:53248
	ds_read_b128 v[186:189], v148 offset:54272
	ds_read_b128 v[190:193], v148 offset:55296
	ds_read_b128 v[194:197], v148 offset:56320
	global_load_lds_dwordx4 v[218:219], off
	v_lshl_add_u64 v[218:219], v[224:225], 0, s[6:7]
	s_mov_b32 m0, s53
	s_nop 0
	global_load_lds_dwordx4 v[218:219], off
	s_barrier
	s_waitcnt lgkmcnt(0)
	s_setprio 1
	s_waitcnt lgkmcnt(0)
	v_mfma_f32_16x16x32_bf16 v[60:63], v[150:153], v[166:169], v[60:63]
	v_mfma_f32_16x16x32_bf16 v[60:63], v[154:157], v[170:173], v[60:63]
	v_mfma_f32_16x16x32_bf16 v[56:59], v[162:165], v[170:173], v[56:59]
	v_mfma_f32_16x16x32_bf16 v[56:59], v[158:161], v[166:169], v[56:59]
	v_mfma_f32_16x16x32_bf16 v[40:43], v[158:161], v[174:177], v[40:43]
	v_mfma_f32_16x16x32_bf16 v[40:43], v[162:165], v[178:181], v[40:43]
	v_mfma_f32_16x16x32_bf16 v[44:47], v[154:157], v[178:181], v[44:47]
	v_mfma_f32_16x16x32_bf16 v[44:47], v[150:153], v[174:177], v[44:47]
	v_mfma_f32_16x16x32_bf16 v[28:31], v[150:153], v[182:185], v[28:31]
	v_mfma_f32_16x16x32_bf16 v[28:31], v[154:157], v[186:189], v[28:31]
	v_mfma_f32_16x16x32_bf16 v[24:27], v[162:165], v[186:189], v[24:27]
	v_mfma_f32_16x16x32_bf16 v[24:27], v[158:161], v[182:185], v[24:27]
	v_mfma_f32_16x16x32_bf16 v[8:11], v[158:161], v[190:193], v[8:11]
	v_mfma_f32_16x16x32_bf16 v[8:11], v[162:165], v[194:197], v[8:11]
	v_mfma_f32_16x16x32_bf16 v[12:15], v[154:157], v[194:197], v[12:15]
	v_mfma_f32_16x16x32_bf16 v[12:15], v[150:153], v[190:193], v[12:15]
	s_setprio 0
	s_barrier
	s_add_u32 s2, s44, 0x30080
	s_addc_u32 s3, s45, 0
	s_add_i32 s44, s46, s30
	v_lshl_add_u64 v[150:151], s[2:3], 0, v[130:131]
	s_mov_b32 m0, s44
	s_nop 0
	global_load_lds_dwordx4 v[150:151], off
	v_lshl_add_u64 v[150:151], s[2:3], 0, v[134:135]
	s_add_i32 m0, s44, 0x2000
	s_nop 0
	global_load_lds_dwordx4 v[150:151], off
	s_waitcnt vmcnt(6)
	s_barrier
	s_setprio 1
	v_mfma_f32_16x16x32_bf16 v[52:55], v[198:201], v[166:169], v[52:55]
	v_mfma_f32_16x16x32_bf16 v[52:55], v[202:205], v[170:173], v[52:55]
	v_mfma_f32_16x16x32_bf16 v[48:51], v[210:213], v[170:173], v[48:51]
	v_mfma_f32_16x16x32_bf16 v[48:51], v[206:209], v[166:169], v[48:51]
	v_mfma_f32_16x16x32_bf16 v[32:35], v[206:209], v[174:177], v[32:35]
	v_mfma_f32_16x16x32_bf16 v[32:35], v[210:213], v[178:181], v[32:35]
	v_mfma_f32_16x16x32_bf16 v[36:39], v[202:205], v[178:181], v[36:39]
	v_mfma_f32_16x16x32_bf16 v[36:39], v[198:201], v[174:177], v[36:39]
	v_mfma_f32_16x16x32_bf16 v[20:23], v[198:201], v[182:185], v[20:23]
	v_mfma_f32_16x16x32_bf16 v[20:23], v[202:205], v[186:189], v[20:23]
	v_mfma_f32_16x16x32_bf16 v[16:19], v[210:213], v[186:189], v[16:19]
	v_mfma_f32_16x16x32_bf16 v[16:19], v[206:209], v[182:185], v[16:19]
	v_mfma_f32_16x16x32_bf16 v[0:3], v[206:209], v[190:193], v[0:3]
	v_mfma_f32_16x16x32_bf16 v[0:3], v[210:213], v[194:197], v[0:3]
	v_mfma_f32_16x16x32_bf16 v[4:7], v[202:205], v[194:197], v[4:7]
	v_mfma_f32_16x16x32_bf16 v[4:7], v[198:201], v[190:193], v[4:7]
	s_setprio 0
	s_add_u32 s4, s4, 0x100
	s_addc_u32 s5, s5, 0
	s_add_u32 s65, s65, 0x100
	s_addc_u32 s66, s66, 0
	s_cmp_ge_i32 s67, s51
	s_mov_b32 s44, s67
	s_barrier
	s_cbranch_scc0 .LBB0_848
	s_branch .LBB0_837

; #define PG8_STAGE(bufoff, gbase, voff) do { _Pragma("unroll") for (int _i = 0; _i < 2; ++_i) \
;         __builtin_amdgcn_global_load_lds((const unsigned*)((const char*)(gbase) + (voff)[_i]), (LAS unsigned*)(lds + (bufoff) + ldsw + _i * 8192), 16, 0, 0); } while (0)
; #define PG8_LDA(dst, b, h) do { _Pragma("unroll") for (int m = 0; m < 4; ++m) _Pragma("unroll") for (int k = 0; k < 2; ++k) dst[m][k] = *(const LAS bf16x8*)(lds + PG8_SA(b, h) + aoff + m * 2048 + k * 1024); } while (0)
; #define PG8_LDB(dst, b, h) do { _Pragma("unroll") for (int n = 0; n < 2; ++n) _Pragma("unroll") for (int k = 0; k < 2; ++k) dst[n][k] = *(const LAS bf16x8*)(lds + PG8_SB(b, h) + boff + n * 2048 + k * 1024); } while (0)
; #define PG8_MMA(ai, bj, At, Bt) do { __builtin_amdgcn_s_setprio(1); _Pragma("unroll") for (int m = 0; m < 4; ++m) _Pragma("unroll") for (int n = 0; n < 2; ++n) _Pragma("unroll") for (int k = 0; k < 2; ++k) \
;         acc[ai][bj][m][n] = __builtin_amdgcn_mfma_f32_16x16x32_bf16(Bt[n][k], At[m][k], acc[ai][bj][m][n], 0, 0, 0); __builtin_amdgcn_s_setprio(0); } while (0)
; #define PG8_WAIT_L(n) asm volatile("s_waitcnt lgkmcnt(" #n ")" ::: "memory")
; #define PG8_BAR __builtin_amdgcn_s_barrier()
; #define PG8_SCHED __builtin_amdgcn_sched_barrier(0)
; template <class Epi>
; DEVINL void gemm_phase(LAS unsigned char* lds, const Gemm g, const Order& S, const Epi& E) {
;     ...
;             const char* a1 = cA + (size_t)(t + 1) * kstep;
;             const char* a2 = last ? nA : cA + (size_t)(t + 2) * kstep; const char* b2 = last ? nB : cB + (size_t)(t + 2) * kstep;
;             const char* a3 = a2 + kstep; const char* b3 = b2 + kstep;
;             PG8_LDB(B0, 0, 0); PG8_SCHED; PG8_LDA(At, 0, 0); PG8_STAGE(PG8_SA(1, 1), a1 + hstepA, voffA);
;             PG8_WAIT_L(8); PG8_BAR; PG8_WAIT_L(0); PG8_MMA(0, 0, At, B0); PG8_BAR; PG8_SCHED;
;             PG8_LDB(B1, 0, 1); PG8_STAGE(PG8_SB(0, 0), b2, voffB);
;             PG8_BAR; PG8_WAIT_L(0); PG8_MMA(0, 1, At, B1); PG8_BAR;
;             PG8_LDA(At, 0, 1); PG8_STAGE(PG8_SA(0, 0), a2, voffA);
;             PG8_BAR; PG8_WAIT_L(0); PG8_MMA(1, 0, At, B0); PG8_BAR; PG8_SCHED;
.LBB0_986:
	ds_read_b128 v[150:153], v147
	ds_read_b128 v[154:157], v147 offset:1024
	ds_read_b128 v[158:161], v147 offset:2048
	ds_read_b128 v[162:165], v147 offset:3072
	s_add_i32 s69, s46, 2
	s_add_u32 s2, s4, 0xffff0080
	s_addc_u32 s3, s5, -1
	s_cmp_eq_u32 s54, s46
	s_cselect_b32 s46, s66, s67
	s_cselect_b32 s49, s11, s3
	s_cselect_b32 s48, s13, s2
	s_cselect_b32 s47, s65, s68
	v_lshl_add_u64 v[198:199], s[4:5], 0, v[136:137]
	s_add_i32 m0, s30, 0xc000
	ds_read_b128 v[166:169], v148
	ds_read_b128 v[170:173], v148 offset:1024
	ds_read_b128 v[174:177], v148 offset:2048
	ds_read_b128 v[178:181], v148 offset:3072
	ds_read_b128 v[182:185], v148 offset:4096
	ds_read_b128 v[186:189], v148 offset:5120
	ds_read_b128 v[190:193], v148 offset:6144
	ds_read_b128 v[194:197], v148 offset:7168
	global_load_lds_dwordx4 v[198:199], off
	v_lshl_add_u64 v[198:199], s[4:5], 0, v[138:139]
	s_add_i32 m0, s30, 0xe000
	s_nop 0
	global_load_lds_dwordx4 v[198:199], off
	s_waitcnt lgkmcnt(8)
	s_barrier
	s_waitcnt lgkmcnt(0)
	s_setprio 1
	s_waitcnt lgkmcnt(0)
	v_mfma_f32_16x16x32_bf16 v[124:127], v[150:153], v[166:169], v[124:127]
	v_mfma_f32_16x16x32_bf16 v[124:127], v[154:157], v[170:173], v[124:127]
	v_mfma_f32_16x16x32_bf16 v[120:123], v[162:165], v[170:173], v[120:123]
	v_mfma_f32_16x16x32_bf16 v[120:123], v[158:161], v[166:169], v[120:123]
	v_mfma_f32_16x16x32_bf16 v[112:115], v[158:161], v[174:177], v[112:115]
	v_mfma_f32_16x16x32_bf16 v[112:115], v[162:165], v[178:181], v[112:115]
	v_mfma_f32_16x16x32_bf16 v[116:119], v[154:157], v[178:181], v[116:119]
	v_mfma_f32_16x16x32_bf16 v[116:119], v[150:153], v[174:177], v[116:119]
	v_mfma_f32_16x16x32_bf16 v[108:111], v[150:153], v[182:185], v[108:111]
	v_mfma_f32_16x16x32_bf16 v[108:111], v[154:157], v[186:189], v[108:111]
	v_mfma_f32_16x16x32_bf16 v[104:107], v[162:165], v[186:189], v[104:107]
	v_mfma_f32_16x16x32_bf16 v[104:107], v[158:161], v[182:185], v[104:107]
	v_mfma_f32_16x16x32_bf16 v[96:99], v[158:161], v[190:193], v[96:99]
	v_mfma_f32_16x16x32_bf16 v[96:99], v[162:165], v[194:197], v[96:99]
	v_mfma_f32_16x16x32_bf16 v[100:103], v[154:157], v[194:197], v[100:103]
	v_mfma_f32_16x16x32_bf16 v[100:103], v[150:153], v[190:193], v[100:103]
	s_setprio 0
	s_barrier
	s_add_i32 s2, s58, s29
	v_lshl_add_u64 v[218:219], s[46:47], 0, v[130:131]
	s_mov_b32 m0, s2
	ds_read_b128 v[198:201], v149
	ds_read_b128 v[202:205], v149 offset:1024
	ds_read_b128 v[206:209], v149 offset:2048
	ds_read_b128 v[210:213], v149 offset:3072
	global_load_lds_dwordx4 v[218:219], off
	v_lshl_add_u64 v[220:221], s[46:47], 0, v[134:135]
	s_add_i32 m0, s2, 0x2000
	s_nop 0
	global_load_lds_dwordx4 v[220:221], off
	s_barrier
	s_waitcnt lgkmcnt(0)
	s_setprio 1
	s_waitcnt lgkmcnt(0)
	v_mfma_f32_16x16x32_bf16 v[60:63], v[198:201], v[166:169], v[60:63]
	v_mfma_f32_16x16x32_bf16 v[60:63], v[202:205], v[170:173], v[60:63]
	v_mfma_f32_16x16x32_bf16 v[56:59], v[210:213], v[170:173], v[56:59]
	v_mfma_f32_16x16x32_bf16 v[56:59], v[206:209], v[166:169], v[56:59]
	v_mfma_f32_16x16x32_bf16 v[48:51], v[206:209], v[174:177], v[48:51]
	v_mfma_f32_16x16x32_bf16 v[48:51], v[210:213], v[178:181], v[48:51]
	v_mfma_f32_16x16x32_bf16 v[52:55], v[202:205], v[178:181], v[52:55]
	v_mfma_f32_16x16x32_bf16 v[52:55], v[198:201], v[174:177], v[52:55]
	v_mfma_f32_16x16x32_bf16 v[44:47], v[198:201], v[182:185], v[44:47]
	v_mfma_f32_16x16x32_bf16 v[44:47], v[202:205], v[186:189], v[44:47]
	v_mfma_f32_16x16x32_bf16 v[40:43], v[210:213], v[186:189], v[40:43]
	v_mfma_f32_16x16x32_bf16 v[40:43], v[206:209], v[182:185], v[40:43]
	v_mfma_f32_16x16x32_bf16 v[32:35], v[206:209], v[190:193], v[32:35]
	v_mfma_f32_16x16x32_bf16 v[32:35], v[210:213], v[194:197], v[32:35]
	v_mfma_f32_16x16x32_bf16 v[36:39], v[202:205], v[194:197], v[36:39]
	v_mfma_f32_16x16x32_bf16 v[36:39], v[198:201], v[190:193], v[36:39]
	s_setprio 0
	s_mov_b32 m0, s30
	v_lshl_add_u64 v[222:223], s[48:49], 0, v[128:129]
	s_barrier
	ds_read_b128 v[166:169], v148 offset:16384
	ds_read_b128 v[170:173], v148 offset:17408
	ds_read_b128 v[174:177], v148 offset:18432
	ds_read_b128 v[178:181], v148 offset:19456
	ds_read_b128 v[182:185], v148 offset:20480
	ds_read_b128 v[186:189], v148 offset:21504
	ds_read_b128 v[190:193], v148 offset:22528
	ds_read_b128 v[194:197], v148 offset:23552
	global_load_lds_dwordx4 v[222:223], off
	v_lshl_add_u64 v[224:225], s[48:49], 0, v[132:133]
	s_mov_b32 m0, s31
	s_nop 0
	global_load_lds_dwordx4 v[224:225], off
	s_barrier
	s_waitcnt lgkmcnt(0)
	s_setprio 1
	s_waitcnt lgkmcnt(0)
	v_mfma_f32_16x16x32_bf16 v[92:95], v[150:153], v[166:169], v[92:95]
	v_mfma_f32_16x16x32_bf16 v[92:95], v[154:157], v[170:173], v[92:95]
	v_mfma_f32_16x16x32_bf16 v[88:91], v[162:165], v[170:173], v[88:91]
	v_mfma_f32_16x16x32_bf16 v[88:91], v[158:161], v[166:169], v[88:91]
	v_mfma_f32_16x16x32_bf16 v[80:83], v[158:161], v[174:177], v[80:83]
	v_mfma_f32_16x16x32_bf16 v[80:83], v[162:165], v[178:181], v[80:83]
	v_mfma_f32_16x16x32_bf16 v[84:87], v[154:157], v[178:181], v[84:87]
	v_mfma_f32_16x16x32_bf16 v[84:87], v[150:153], v[174:177], v[84:87]
	v_mfma_f32_16x16x32_bf16 v[76:79], v[150:153], v[182:185], v[76:79]
	v_mfma_f32_16x16x32_bf16 v[76:79], v[154:157], v[186:189], v[76:79]
	v_mfma_f32_16x16x32_bf16 v[72:75], v[162:165], v[186:189], v[72:75]
	v_mfma_f32_16x16x32_bf16 v[72:75], v[158:161], v[182:185], v[72:75]
	v_mfma_f32_16x16x32_bf16 v[64:67], v[158:161], v[190:193], v[64:67]
	v_mfma_f32_16x16x32_bf16 v[64:67], v[162:165], v[194:197], v[64:67]
	v_mfma_f32_16x16x32_bf16 v[68:71], v[154:157], v[194:197], v[68:71]
	v_mfma_f32_16x16x32_bf16 v[68:71], v[150:153], v[190:193], v[68:71]
	s_setprio 0
	s_barrier
; #define PG8_STAGE(bufoff, gbase, voff) do { _Pragma("unroll") for (int _i = 0; _i < 2; ++_i) \
;         __builtin_amdgcn_global_load_lds((const unsigned*)((const char*)(gbase) + (voff)[_i]), (LAS unsigned*)(lds + (bufoff) + ldsw + _i * 8192), 16, 0, 0); } while (0)
; #define PG8_LDA(dst, b, h) do { _Pragma("unroll") for (int m = 0; m < 4; ++m) _Pragma("unroll") for (int k = 0; k < 2; ++k) dst[m][k] = *(const LAS bf16x8*)(lds + PG8_SA(b, h) + aoff + m * 2048 + k * 1024); } while (0)
; #define PG8_LDB(dst, b, h) do { _Pragma("unroll") for (int n = 0; n < 2; ++n) _Pragma("unroll") for (int k = 0; k < 2; ++k) dst[n][k] = *(const LAS bf16x8*)(lds + PG8_SB(b, h) + boff + n * 2048 + k * 1024); } while (0)
; #define PG8_MMA(ai, bj, At, Bt) do { __builtin_amdgcn_s_setprio(1); _Pragma("unroll") for (int m = 0; m < 4; ++m) _Pragma("unroll") for (int n = 0; n < 2; ++n) _Pragma("unroll") for (int k = 0; k < 2; ++k) \
;         acc[ai][bj][m][n] = __builtin_amdgcn_mfma_f32_16x16x32_bf16(Bt[n][k], At[m][k], acc[ai][bj][m][n], 0, 0, 0); __builtin_amdgcn_s_setprio(0); } while (0)
; #define PG8_WAIT_V(n) asm volatile("s_waitcnt vmcnt(" #n ")" ::: "memory")
; #define PG8_WAIT_L(n) asm volatile("s_waitcnt lgkmcnt(" #n ")" ::: "memory")
; #define PG8_BAR __builtin_amdgcn_s_barrier()
; #define PG8_SCHED __builtin_amdgcn_sched_barrier(0)
; template <class Epi>
; DEVINL void gemm_phase(LAS unsigned char* lds, const Gemm g, const Order& S, const Epi& E) {
;     ...
;             PG8_STAGE(PG8_SB(0, 1), b2 + hstepB, voffB);
;             PG8_WAIT_V(6); PG8_BAR; PG8_MMA(1, 1, At, B1); PG8_BAR;
;             PG8_LDB(B0, 1, 0); PG8_SCHED; PG8_LDA(At, 1, 0); PG8_STAGE(PG8_SA(0, 1), a2 + hstepA, voffA);
;             PG8_WAIT_L(8); PG8_BAR; PG8_WAIT_L(0); PG8_MMA(0, 0, At, B0); PG8_BAR; PG8_SCHED;
;             PG8_LDB(B1, 1, 1); PG8_STAGE(PG8_SB(1, 0), b3, voffB);
	s_add_u32 s2, s46, 0x10000
	s_addc_u32 s3, s47, 0
	s_add_i32 s70, s59, s29
	v_lshl_add_u64 v[150:151], s[2:3], 0, v[130:131]
	s_mov_b32 m0, s70
	s_nop 0
	global_load_lds_dwordx4 v[150:151], off
	v_lshl_add_u64 v[150:151], s[2:3], 0, v[134:135]
	s_add_i32 m0, s70, 0x2000
	s_nop 0
	global_load_lds_dwordx4 v[150:151], off
	s_waitcnt vmcnt(6)
	s_barrier
	s_setprio 1
	v_mfma_f32_16x16x32_bf16 v[28:31], v[198:201], v[166:169], v[28:31]
	v_mfma_f32_16x16x32_bf16 v[28:31], v[202:205], v[170:173], v[28:31]
	v_mfma_f32_16x16x32_bf16 v[24:27], v[210:213], v[170:173], v[24:27]
	v_mfma_f32_16x16x32_bf16 v[24:27], v[206:209], v[166:169], v[24:27]
	v_mfma_f32_16x16x32_bf16 v[16:19], v[206:209], v[174:177], v[16:19]
	v_mfma_f32_16x16x32_bf16 v[16:19], v[210:213], v[178:181], v[16:19]
	v_mfma_f32_16x16x32_bf16 v[20:23], v[202:205], v[178:181], v[20:23]
	v_mfma_f32_16x16x32_bf16 v[20:23], v[198:201], v[174:177], v[20:23]
	v_mfma_f32_16x16x32_bf16 v[12:15], v[198:201], v[182:185], v[12:15]
	v_mfma_f32_16x16x32_bf16 v[12:15], v[202:205], v[186:189], v[12:15]
	v_mfma_f32_16x16x32_bf16 v[8:11], v[210:213], v[186:189], v[8:11]
	v_mfma_f32_16x16x32_bf16 v[8:11], v[206:209], v[182:185], v[8:11]
	v_mfma_f32_16x16x32_bf16 v[0:3], v[206:209], v[190:193], v[0:3]
	v_mfma_f32_16x16x32_bf16 v[0:3], v[210:213], v[194:197], v[0:3]
	v_mfma_f32_16x16x32_bf16 v[4:7], v[202:205], v[194:197], v[4:7]
	v_mfma_f32_16x16x32_bf16 v[4:7], v[198:201], v[190:193], v[4:7]
	s_setprio 0
	s_add_i32 s70, 16, 0x18000
	v_add_u32_e32 v162, s70, v145
	s_barrier
	ds_read_b128 v[150:153], v162
	ds_read_b128 v[154:157], v162 offset:1024
	ds_read_b128 v[158:161], v162 offset:2048
	ds_read_b128 v[162:165], v162 offset:3072
	s_add_u32 s2, s48, 0x10000
	s_addc_u32 s3, s49, 0
	s_mov_b32 m0, s45
	v_lshl_add_u64 v[198:199], s[2:3], 0, v[128:129]
	ds_read_b128 v[166:169], v148 offset:32768
	ds_read_b128 v[170:173], v148 offset:33792
	ds_read_b128 v[174:177], v148 offset:34816
	ds_read_b128 v[178:181], v148 offset:35840
	ds_read_b128 v[182:185], v148 offset:36864
	ds_read_b128 v[186:189], v148 offset:37888
	ds_read_b128 v[190:193], v148 offset:38912
	ds_read_b128 v[194:197], v148 offset:39936
	global_load_lds_dwordx4 v[198:199], off
	v_lshl_add_u64 v[198:199], s[2:3], 0, v[132:133]
	s_mov_b32 m0, s50
	s_nop 0
	global_load_lds_dwordx4 v[198:199], off
	s_waitcnt lgkmcnt(8)
	s_barrier
	s_waitcnt lgkmcnt(0)
	s_setprio 1
	s_waitcnt lgkmcnt(0)
	v_mfma_f32_16x16x32_bf16 v[124:127], v[150:153], v[166:169], v[124:127]
	v_mfma_f32_16x16x32_bf16 v[124:127], v[154:157], v[170:173], v[124:127]
	v_mfma_f32_16x16x32_bf16 v[120:123], v[162:165], v[170:173], v[120:123]
	v_mfma_f32_16x16x32_bf16 v[120:123], v[158:161], v[166:169], v[120:123]
	v_mfma_f32_16x16x32_bf16 v[112:115], v[158:161], v[174:177], v[112:115]
	v_mfma_f32_16x16x32_bf16 v[112:115], v[162:165], v[178:181], v[112:115]
	v_mfma_f32_16x16x32_bf16 v[116:119], v[154:157], v[178:181], v[116:119]
	v_mfma_f32_16x16x32_bf16 v[116:119], v[150:153], v[174:177], v[116:119]
	v_mfma_f32_16x16x32_bf16 v[108:111], v[150:153], v[182:185], v[108:111]
	v_mfma_f32_16x16x32_bf16 v[108:111], v[154:157], v[186:189], v[108:111]
	v_mfma_f32_16x16x32_bf16 v[104:107], v[162:165], v[186:189], v[104:107]
	v_mfma_f32_16x16x32_bf16 v[104:107], v[158:161], v[182:185], v[104:107]
	v_mfma_f32_16x16x32_bf16 v[96:99], v[158:161], v[190:193], v[96:99]
	v_mfma_f32_16x16x32_bf16 v[96:99], v[162:165], v[194:197], v[96:99]
	v_mfma_f32_16x16x32_bf16 v[100:103], v[154:157], v[194:197], v[100:103]
	v_mfma_f32_16x16x32_bf16 v[100:103], v[150:153], v[190:193], v[100:103]
	s_setprio 0
	s_barrier
	s_add_i32 s48, 16, 0x1c000
	s_add_i32 s2, s70, s29
	v_add_u32_e32 v210, s48, v145
	v_lshl_add_u64 v[218:219], v[218:219], 0, s[6:7]
	s_mov_b32 m0, s2
	ds_read_b128 v[198:201], v210
	ds_read_b128 v[202:205], v210 offset:1024
	ds_read_b128 v[206:209], v210 offset:2048
	ds_read_b128 v[210:213], v210 offset:3072
	global_load_lds_dwordx4 v[218:219], off
	v_lshl_add_u64 v[218:219], v[220:221], 0, s[6:7]
	s_add_i32 m0, s2, 0x2000
	s_nop 0
	global_load_lds_dwordx4 v[218:219], off
	s_barrier
; #define PG8_STAGE(bufoff, gbase, voff) do { _Pragma("unroll") for (int _i = 0; _i < 2; ++_i) \
;         __builtin_amdgcn_global_load_lds((const unsigned*)((const char*)(gbase) + (voff)[_i]), (LAS unsigned*)(lds + (bufoff) + ldsw + _i * 8192), 16, 0, 0); } while (0)
; #define PG8_LDA(dst, b, h) do { _Pragma("unroll") for (int m = 0; m < 4; ++m) _Pragma("unroll") for (int k = 0; k < 2; ++k) dst[m][k] = *(const LAS bf16x8*)(lds + PG8_SA(b, h) + aoff + m * 2048 + k * 1024); } while (0)
; #define PG8_MMA(ai, bj, At, Bt) do { __builtin_amdgcn_s_setprio(1); _Pragma("unroll") for (int m = 0; m < 4; ++m) _Pragma("unroll") for (int n = 0; n < 2; ++n) _Pragma("unroll") for (int k = 0; k < 2; ++k) \
;         acc[ai][bj][m][n] = __builtin_amdgcn_mfma_f32_16x16x32_bf16(Bt[n][k], At[m][k], acc[ai][bj][m][n], 0, 0, 0); __builtin_amdgcn_s_setprio(0); } while (0)
; #define PG8_WAIT_V(n) asm volatile("s_waitcnt vmcnt(" #n ")" ::: "memory")
; #define PG8_WAIT_L(n) asm volatile("s_waitcnt lgkmcnt(" #n ")" ::: "memory")
; #define PG8_BAR __builtin_amdgcn_s_barrier()
; #define PG8_SCHED __builtin_amdgcn_sched_barrier(0)
; template <class Epi>
; DEVINL void gemm_phase(LAS unsigned char* lds, const Gemm g, const Order& S, const Epi& E) {
;     ...
;             PG8_BAR; PG8_WAIT_L(0); PG8_MMA(0, 1, At, B1); PG8_BAR;
;             PG8_LDA(At, 1, 1); PG8_STAGE(PG8_SA(1, 0), a3, voffA);
;             PG8_BAR; PG8_WAIT_L(0); PG8_MMA(1, 0, At, B0); PG8_BAR; PG8_SCHED;
;             PG8_STAGE(PG8_SB(1, 1), b3 + hstepB, voffB);
;             PG8_WAIT_V(6); PG8_BAR; PG8_MMA(1, 1, At, B1); PG8_BAR;
;         }
;         E(acc, cur, wr, wc, fr, fq);
	s_waitcnt lgkmcnt(0)
	s_setprio 1
	s_waitcnt lgkmcnt(0)
	v_mfma_f32_16x16x32_bf16 v[60:63], v[198:201], v[166:169], v[60:63]
	v_mfma_f32_16x16x32_bf16 v[60:63], v[202:205], v[170:173], v[60:63]
	v_mfma_f32_16x16x32_bf16 v[56:59], v[210:213], v[170:173], v[56:59]
	v_mfma_f32_16x16x32_bf16 v[56:59], v[206:209], v[166:169], v[56:59]
	v_mfma_f32_16x16x32_bf16 v[48:51], v[206:209], v[174:177], v[48:51]
	v_mfma_f32_16x16x32_bf16 v[48:51], v[210:213], v[178:181], v[48:51]
	v_mfma_f32_16x16x32_bf16 v[52:55], v[202:205], v[178:181], v[52:55]
	v_mfma_f32_16x16x32_bf16 v[52:55], v[198:201], v[174:177], v[52:55]
	v_mfma_f32_16x16x32_bf16 v[44:47], v[198:201], v[182:185], v[44:47]
	v_mfma_f32_16x16x32_bf16 v[44:47], v[202:205], v[186:189], v[44:47]
	v_mfma_f32_16x16x32_bf16 v[40:43], v[210:213], v[186:189], v[40:43]
	v_mfma_f32_16x16x32_bf16 v[40:43], v[206:209], v[182:185], v[40:43]
	v_mfma_f32_16x16x32_bf16 v[32:35], v[206:209], v[190:193], v[32:35]
	v_mfma_f32_16x16x32_bf16 v[32:35], v[210:213], v[194:197], v[32:35]
	v_mfma_f32_16x16x32_bf16 v[36:39], v[202:205], v[194:197], v[36:39]
	v_mfma_f32_16x16x32_bf16 v[36:39], v[198:201], v[190:193], v[36:39]
	s_setprio 0
	s_mov_b32 m0, s52
	v_lshl_add_u64 v[218:219], v[222:223], 0, s[6:7]
	s_barrier
	ds_read_b128 v[166:169], v148 offset:49152
	ds_read_b128 v[170:173], v148 offset:50176
	ds_read_b128 v[174:177], v148 offset:51200
	ds_read_b128 v[178:181], v148 offset:52224
	ds_read_b128 v[182:185], v148 offset:53248
	ds_read_b128 v[186:189], v148 offset:54272
	ds_read_b128 v[190:193], v148 offset:55296
	ds_read_b128 v[194:197], v148 offset:56320
	global_load_lds_dwordx4 v[218:219], off
	v_lshl_add_u64 v[218:219], v[224:225], 0, s[6:7]
	s_mov_b32 m0, s53
	s_nop 0
	global_load_lds_dwordx4 v[218:219], off
	s_barrier
	s_waitcnt lgkmcnt(0)
	s_setprio 1
	s_waitcnt lgkmcnt(0)
	v_mfma_f32_16x16x32_bf16 v[92:95], v[150:153], v[166:169], v[92:95]
	v_mfma_f32_16x16x32_bf16 v[92:95], v[154:157], v[170:173], v[92:95]
	v_mfma_f32_16x16x32_bf16 v[88:91], v[162:165], v[170:173], v[88:91]
	v_mfma_f32_16x16x32_bf16 v[88:91], v[158:161], v[166:169], v[88:91]
	v_mfma_f32_16x16x32_bf16 v[80:83], v[158:161], v[174:177], v[80:83]
	v_mfma_f32_16x16x32_bf16 v[80:83], v[162:165], v[178:181], v[80:83]
	v_mfma_f32_16x16x32_bf16 v[84:87], v[154:157], v[178:181], v[84:87]
	v_mfma_f32_16x16x32_bf16 v[84:87], v[150:153], v[174:177], v[84:87]
	v_mfma_f32_16x16x32_bf16 v[76:79], v[150:153], v[182:185], v[76:79]
	v_mfma_f32_16x16x32_bf16 v[76:79], v[154:157], v[186:189], v[76:79]
	v_mfma_f32_16x16x32_bf16 v[72:75], v[162:165], v[186:189], v[72:75]
	v_mfma_f32_16x16x32_bf16 v[72:75], v[158:161], v[182:185], v[72:75]
	v_mfma_f32_16x16x32_bf16 v[64:67], v[158:161], v[190:193], v[64:67]
	v_mfma_f32_16x16x32_bf16 v[64:67], v[162:165], v[194:197], v[64:67]
	v_mfma_f32_16x16x32_bf16 v[68:71], v[154:157], v[194:197], v[68:71]
	v_mfma_f32_16x16x32_bf16 v[68:71], v[150:153], v[190:193], v[68:71]
	s_setprio 0
	s_barrier
	s_add_u32 s2, s46, 0x10080
	s_addc_u32 s3, s47, 0
	s_add_i32 s46, s48, s29
	v_lshl_add_u64 v[150:151], s[2:3], 0, v[130:131]
	s_mov_b32 m0, s46
	s_nop 0
	global_load_lds_dwordx4 v[150:151], off
	v_lshl_add_u64 v[150:151], s[2:3], 0, v[134:135]
	s_add_i32 m0, s46, 0x2000
	s_nop 0
	global_load_lds_dwordx4 v[150:151], off
	s_waitcnt vmcnt(6)
	s_barrier
	s_setprio 1
	v_mfma_f32_16x16x32_bf16 v[28:31], v[198:201], v[166:169], v[28:31]
	v_mfma_f32_16x16x32_bf16 v[28:31], v[202:205], v[170:173], v[28:31]
	v_mfma_f32_16x16x32_bf16 v[24:27], v[210:213], v[170:173], v[24:27]
	v_mfma_f32_16x16x32_bf16 v[24:27], v[206:209], v[166:169], v[24:27]
	v_mfma_f32_16x16x32_bf16 v[16:19], v[206:209], v[174:177], v[16:19]
	v_mfma_f32_16x16x32_bf16 v[16:19], v[210:213], v[178:181], v[16:19]
	v_mfma_f32_16x16x32_bf16 v[20:23], v[202:205], v[178:181], v[20:23]
	v_mfma_f32_16x16x32_bf16 v[20:23], v[198:201], v[174:177], v[20:23]
	v_mfma_f32_16x16x32_bf16 v[12:15], v[198:201], v[182:185], v[12:15]
	v_mfma_f32_16x16x32_bf16 v[12:15], v[202:205], v[186:189], v[12:15]
	v_mfma_f32_16x16x32_bf16 v[8:11], v[210:213], v[186:189], v[8:11]
	v_mfma_f32_16x16x32_bf16 v[8:11], v[206:209], v[182:185], v[8:11]
	v_mfma_f32_16x16x32_bf16 v[0:3], v[206:209], v[190:193], v[0:3]
	v_mfma_f32_16x16x32_bf16 v[0:3], v[210:213], v[194:197], v[0:3]
	v_mfma_f32_16x16x32_bf16 v[4:7], v[202:205], v[194:197], v[4:7]
	v_mfma_f32_16x16x32_bf16 v[4:7], v[198:201], v[190:193], v[4:7]
	s_setprio 0
	s_add_u32 s4, s4, 0x100
	s_addc_u32 s5, s5, 0
	s_add_u32 s67, s67, 0x100
	s_addc_u32 s68, s68, 0
	s_cmp_ge_i32 s69, s51
	s_mov_b32 s46, s69
	s_barrier
	s_cbranch_scc0 .LBB0_986
	v_readlane_b32 s66, v251, 56
	v_readlane_b32 s67, v251, 57
	s_branch .LBB0_977

; #define PG8_STAGE(bufoff, gbase, voff) do { _Pragma("unroll") for (int _i = 0; _i < 2; ++_i) \
;         __builtin_amdgcn_global_load_lds((const unsigned*)((const char*)(gbase) + (voff)[_i]), (LAS unsigned*)(lds + (bufoff) + ldsw + _i * 8192), 16, 0, 0); } while (0)
; #define PG8_LDA(dst, b, h) do { _Pragma("unroll") for (int m = 0; m < 4; ++m) _Pragma("unroll") for (int k = 0; k < 2; ++k) dst[m][k] = *(const LAS bf16x8*)(lds + PG8_SA(b, h) + aoff + m * 2048 + k * 1024); } while (0)
; #define PG8_LDB(dst, b, h) do { _Pragma("unroll") for (int n = 0; n < 2; ++n) _Pragma("unroll") for (int k = 0; k < 2; ++k) dst[n][k] = *(const LAS bf16x8*)(lds + PG8_SB(b, h) + boff + n * 2048 + k * 1024); } while (0)
; #define PG8_MMA(ai, bj, At, Bt) do { __builtin_amdgcn_s_setprio(1); _Pragma("unroll") for (int m = 0; m < 4; ++m) _Pragma("unroll") for (int n = 0; n < 2; ++n) _Pragma("unroll") for (int k = 0; k < 2; ++k) \
;         acc[ai][bj][m][n] = __builtin_amdgcn_mfma_f32_16x16x32_bf16(Bt[n][k], At[m][k], acc[ai][bj][m][n], 0, 0, 0); __builtin_amdgcn_s_setprio(0); } while (0)
; #define PG8_WAIT_L(n) asm volatile("s_waitcnt lgkmcnt(" #n ")" ::: "memory")
; #define PG8_BAR __builtin_amdgcn_s_barrier()
; #define PG8_SCHED __builtin_amdgcn_sched_barrier(0)
; template <class Epi>
; DEVINL void gemm_phase(LAS unsigned char* lds, const Gemm g, const Order& S, const Epi& E) {
;     ...
;             const char* a1 = cA + (size_t)(t + 1) * kstep;
;             const char* a2 = last ? nA : cA + (size_t)(t + 2) * kstep; const char* b2 = last ? nB : cB + (size_t)(t + 2) * kstep;
;             const char* a3 = a2 + kstep; const char* b3 = b2 + kstep;
;             PG8_LDB(B0, 0, 0); PG8_SCHED; PG8_LDA(At, 0, 0); PG8_STAGE(PG8_SA(1, 1), a1 + hstepA, voffA);
;             PG8_WAIT_L(8); PG8_BAR; PG8_WAIT_L(0); PG8_MMA(0, 0, At, B0); PG8_BAR; PG8_SCHED;
;             PG8_LDB(B1, 0, 1); PG8_STAGE(PG8_SB(0, 0), b2, voffB);
;             PG8_BAR; PG8_WAIT_L(0); PG8_MMA(0, 1, At, B1); PG8_BAR;
;             PG8_LDA(At, 0, 1); PG8_STAGE(PG8_SA(0, 0), a2, voffA);
;             PG8_BAR; PG8_WAIT_L(0); PG8_MMA(1, 0, At, B0); PG8_BAR; PG8_SCHED;
.LBB0_1008:
	ds_read_b128 v[150:153], v147
	ds_read_b128 v[154:157], v147 offset:1024
	ds_read_b128 v[158:161], v147 offset:2048
	ds_read_b128 v[162:165], v147 offset:3072
	s_add_i32 s68, s46, 2
	s_add_u32 s47, s4, 0xffff0080
	s_addc_u32 s48, s5, -1
	s_cmp_eq_u32 s26, s46
	s_cselect_b32 s46, s13, s66
	s_cselect_b32 s49, s2, s48
	s_cselect_b32 s48, s3, s47
	s_cselect_b32 s47, s11, s67
	v_lshl_add_u64 v[198:199], s[4:5], 0, v[136:137]
	s_add_i32 m0, s45, 0xc000
	ds_read_b128 v[166:169], v148
	ds_read_b128 v[170:173], v148 offset:1024
	ds_read_b128 v[174:177], v148 offset:2048
	ds_read_b128 v[178:181], v148 offset:3072
	ds_read_b128 v[182:185], v148 offset:4096
	ds_read_b128 v[186:189], v148 offset:5120
	ds_read_b128 v[190:193], v148 offset:6144
	ds_read_b128 v[194:197], v148 offset:7168
	global_load_lds_dwordx4 v[198:199], off
	v_lshl_add_u64 v[198:199], s[4:5], 0, v[138:139]
	s_add_i32 m0, s45, 0xe000
	s_nop 0
	global_load_lds_dwordx4 v[198:199], off
	s_waitcnt lgkmcnt(8)
	s_barrier
	s_waitcnt lgkmcnt(0)
	s_setprio 1
	s_waitcnt lgkmcnt(0)
	v_mfma_f32_16x16x32_bf16 v[124:127], v[150:153], v[166:169], v[124:127]
	v_mfma_f32_16x16x32_bf16 v[124:127], v[154:157], v[170:173], v[124:127]
	v_mfma_f32_16x16x32_bf16 v[120:123], v[162:165], v[170:173], v[120:123]
	v_mfma_f32_16x16x32_bf16 v[120:123], v[158:161], v[166:169], v[120:123]
	v_mfma_f32_16x16x32_bf16 v[112:115], v[158:161], v[174:177], v[112:115]
	v_mfma_f32_16x16x32_bf16 v[112:115], v[162:165], v[178:181], v[112:115]
	v_mfma_f32_16x16x32_bf16 v[116:119], v[154:157], v[178:181], v[116:119]
	v_mfma_f32_16x16x32_bf16 v[116:119], v[150:153], v[174:177], v[116:119]
	v_mfma_f32_16x16x32_bf16 v[108:111], v[150:153], v[182:185], v[108:111]
	v_mfma_f32_16x16x32_bf16 v[108:111], v[154:157], v[186:189], v[108:111]
	v_mfma_f32_16x16x32_bf16 v[104:107], v[162:165], v[186:189], v[104:107]
	v_mfma_f32_16x16x32_bf16 v[104:107], v[158:161], v[182:185], v[104:107]
	v_mfma_f32_16x16x32_bf16 v[96:99], v[158:161], v[190:193], v[96:99]
	v_mfma_f32_16x16x32_bf16 v[96:99], v[162:165], v[194:197], v[96:99]
	v_mfma_f32_16x16x32_bf16 v[100:103], v[154:157], v[194:197], v[100:103]
	v_mfma_f32_16x16x32_bf16 v[100:103], v[150:153], v[190:193], v[100:103]
	s_setprio 0
	s_barrier
	s_add_i32 s69, s59, s31
	v_lshl_add_u64 v[218:219], s[46:47], 0, v[130:131]
	s_mov_b32 m0, s69
	ds_read_b128 v[198:201], v149
	ds_read_b128 v[202:205], v149 offset:1024
	ds_read_b128 v[206:209], v149 offset:2048
	ds_read_b128 v[210:213], v149 offset:3072
	global_load_lds_dwordx4 v[218:219], off
	v_lshl_add_u64 v[220:221], s[46:47], 0, v[134:135]
	s_add_i32 m0, s69, 0x2000
	s_nop 0
	global_load_lds_dwordx4 v[220:221], off
	s_barrier
	s_waitcnt lgkmcnt(0)
	s_setprio 1
	s_waitcnt lgkmcnt(0)
	v_mfma_f32_16x16x32_bf16 v[60:63], v[198:201], v[166:169], v[60:63]
	v_mfma_f32_16x16x32_bf16 v[60:63], v[202:205], v[170:173], v[60:63]
	v_mfma_f32_16x16x32_bf16 v[56:59], v[210:213], v[170:173], v[56:59]
	v_mfma_f32_16x16x32_bf16 v[56:59], v[206:209], v[166:169], v[56:59]
	v_mfma_f32_16x16x32_bf16 v[48:51], v[206:209], v[174:177], v[48:51]
	v_mfma_f32_16x16x32_bf16 v[48:51], v[210:213], v[178:181], v[48:51]
	v_mfma_f32_16x16x32_bf16 v[52:55], v[202:205], v[178:181], v[52:55]
	v_mfma_f32_16x16x32_bf16 v[52:55], v[198:201], v[174:177], v[52:55]
	v_mfma_f32_16x16x32_bf16 v[44:47], v[198:201], v[182:185], v[44:47]
	v_mfma_f32_16x16x32_bf16 v[44:47], v[202:205], v[186:189], v[44:47]
	v_mfma_f32_16x16x32_bf16 v[40:43], v[210:213], v[186:189], v[40:43]
	v_mfma_f32_16x16x32_bf16 v[40:43], v[206:209], v[182:185], v[40:43]
	v_mfma_f32_16x16x32_bf16 v[32:35], v[206:209], v[190:193], v[32:35]
	v_mfma_f32_16x16x32_bf16 v[32:35], v[210:213], v[194:197], v[32:35]
	v_mfma_f32_16x16x32_bf16 v[36:39], v[202:205], v[194:197], v[36:39]
	v_mfma_f32_16x16x32_bf16 v[36:39], v[198:201], v[190:193], v[36:39]
	s_setprio 0
	s_mov_b32 m0, s45
	v_lshl_add_u64 v[222:223], s[48:49], 0, v[128:129]
	s_barrier
	ds_read_b128 v[166:169], v148 offset:16384
	ds_read_b128 v[170:173], v148 offset:17408
	ds_read_b128 v[174:177], v148 offset:18432
	ds_read_b128 v[178:181], v148 offset:19456
	ds_read_b128 v[182:185], v148 offset:20480
	ds_read_b128 v[186:189], v148 offset:21504
	ds_read_b128 v[190:193], v148 offset:22528
	ds_read_b128 v[194:197], v148 offset:23552
	global_load_lds_dwordx4 v[222:223], off
	v_lshl_add_u64 v[224:225], s[48:49], 0, v[132:133]
	s_mov_b32 m0, s50
	s_nop 0
	global_load_lds_dwordx4 v[224:225], off
	s_barrier
	s_waitcnt lgkmcnt(0)
	s_setprio 1
	s_waitcnt lgkmcnt(0)
	v_mfma_f32_16x16x32_bf16 v[92:95], v[150:153], v[166:169], v[92:95]
	v_mfma_f32_16x16x32_bf16 v[92:95], v[154:157], v[170:173], v[92:95]
	v_mfma_f32_16x16x32_bf16 v[88:91], v[162:165], v[170:173], v[88:91]
	v_mfma_f32_16x16x32_bf16 v[88:91], v[158:161], v[166:169], v[88:91]
	v_mfma_f32_16x16x32_bf16 v[80:83], v[158:161], v[174:177], v[80:83]
	v_mfma_f32_16x16x32_bf16 v[80:83], v[162:165], v[178:181], v[80:83]
	v_mfma_f32_16x16x32_bf16 v[84:87], v[154:157], v[178:181], v[84:87]
	v_mfma_f32_16x16x32_bf16 v[84:87], v[150:153], v[174:177], v[84:87]
	v_mfma_f32_16x16x32_bf16 v[76:79], v[150:153], v[182:185], v[76:79]
	v_mfma_f32_16x16x32_bf16 v[76:79], v[154:157], v[186:189], v[76:79]
	v_mfma_f32_16x16x32_bf16 v[72:75], v[162:165], v[186:189], v[72:75]
	v_mfma_f32_16x16x32_bf16 v[72:75], v[158:161], v[182:185], v[72:75]
	v_mfma_f32_16x16x32_bf16 v[64:67], v[158:161], v[190:193], v[64:67]
	v_mfma_f32_16x16x32_bf16 v[64:67], v[162:165], v[194:197], v[64:67]
	v_mfma_f32_16x16x32_bf16 v[68:71], v[154:157], v[194:197], v[68:71]
	v_mfma_f32_16x16x32_bf16 v[68:71], v[150:153], v[190:193], v[68:71]
	s_setprio 0
	s_barrier
; #define PG8_STAGE(bufoff, gbase, voff) do { _Pragma("unroll") for (int _i = 0; _i < 2; ++_i) \
;         __builtin_amdgcn_global_load_lds((const unsigned*)((const char*)(gbase) + (voff)[_i]), (LAS unsigned*)(lds + (bufoff) + ldsw + _i * 8192), 16, 0, 0); } while (0)
; #define PG8_LDA(dst, b, h) do { _Pragma("unroll") for (int m = 0; m < 4; ++m) _Pragma("unroll") for (int k = 0; k < 2; ++k) dst[m][k] = *(const LAS bf16x8*)(lds + PG8_SA(b, h) + aoff + m * 2048 + k * 1024); } while (0)
; #define PG8_LDB(dst, b, h) do { _Pragma("unroll") for (int n = 0; n < 2; ++n) _Pragma("unroll") for (int k = 0; k < 2; ++k) dst[n][k] = *(const LAS bf16x8*)(lds + PG8_SB(b, h) + boff + n * 2048 + k * 1024); } while (0)
; #define PG8_MMA(ai, bj, At, Bt) do { __builtin_amdgcn_s_setprio(1); _Pragma("unroll") for (int m = 0; m < 4; ++m) _Pragma("unroll") for (int n = 0; n < 2; ++n) _Pragma("unroll") for (int k = 0; k < 2; ++k) \
;         acc[ai][bj][m][n] = __builtin_amdgcn_mfma_f32_16x16x32_bf16(Bt[n][k], At[m][k], acc[ai][bj][m][n], 0, 0, 0); __builtin_amdgcn_s_setprio(0); } while (0)
; #define PG8_WAIT_V(n) asm volatile("s_waitcnt vmcnt(" #n ")" ::: "memory")
; #define PG8_WAIT_L(n) asm volatile("s_waitcnt lgkmcnt(" #n ")" ::: "memory")
; #define PG8_BAR __builtin_amdgcn_s_barrier()
; #define PG8_SCHED __builtin_amdgcn_sched_barrier(0)
; template <class Epi>
; DEVINL void gemm_phase(LAS unsigned char* lds, const Gemm g, const Order& S, const Epi& E) {
;     ...
;             PG8_STAGE(PG8_SB(0, 1), b2 + hstepB, voffB);
;             PG8_WAIT_V(6); PG8_BAR; PG8_MMA(1, 1, At, B1); PG8_BAR;
;             PG8_LDB(B0, 1, 0); PG8_SCHED; PG8_LDA(At, 1, 0); PG8_STAGE(PG8_SA(0, 1), a2 + hstepA, voffA);
;             PG8_WAIT_L(8); PG8_BAR; PG8_WAIT_L(0); PG8_MMA(0, 0, At, B0); PG8_BAR; PG8_SCHED;
;             PG8_LDB(B1, 1, 1); PG8_STAGE(PG8_SB(1, 0), b3, voffB);
	s_add_u32 s70, s46, 0x10000
	s_addc_u32 s71, s47, 0
	s_add_i32 s69, s64, s31
	v_lshl_add_u64 v[150:151], s[70:71], 0, v[130:131]
	s_mov_b32 m0, s69
	s_nop 0
	global_load_lds_dwordx4 v[150:151], off
	v_lshl_add_u64 v[150:151], s[70:71], 0, v[134:135]
	s_add_i32 m0, s69, 0x2000
	s_nop 0
	global_load_lds_dwordx4 v[150:151], off
	s_waitcnt vmcnt(6)
	s_barrier
	s_setprio 1
	v_mfma_f32_16x16x32_bf16 v[28:31], v[198:201], v[166:169], v[28:31]
	v_mfma_f32_16x16x32_bf16 v[28:31], v[202:205], v[170:173], v[28:31]
	v_mfma_f32_16x16x32_bf16 v[24:27], v[210:213], v[170:173], v[24:27]
	v_mfma_f32_16x16x32_bf16 v[24:27], v[206:209], v[166:169], v[24:27]
	v_mfma_f32_16x16x32_bf16 v[16:19], v[206:209], v[174:177], v[16:19]
	v_mfma_f32_16x16x32_bf16 v[16:19], v[210:213], v[178:181], v[16:19]
	v_mfma_f32_16x16x32_bf16 v[20:23], v[202:205], v[178:181], v[20:23]
	v_mfma_f32_16x16x32_bf16 v[20:23], v[198:201], v[174:177], v[20:23]
	v_mfma_f32_16x16x32_bf16 v[12:15], v[198:201], v[182:185], v[12:15]
	v_mfma_f32_16x16x32_bf16 v[12:15], v[202:205], v[186:189], v[12:15]
	v_mfma_f32_16x16x32_bf16 v[8:11], v[210:213], v[186:189], v[8:11]
	v_mfma_f32_16x16x32_bf16 v[8:11], v[206:209], v[182:185], v[8:11]
	v_mfma_f32_16x16x32_bf16 v[0:3], v[206:209], v[190:193], v[0:3]
	v_mfma_f32_16x16x32_bf16 v[0:3], v[210:213], v[194:197], v[0:3]
	v_mfma_f32_16x16x32_bf16 v[4:7], v[202:205], v[194:197], v[4:7]
	v_mfma_f32_16x16x32_bf16 v[4:7], v[198:201], v[190:193], v[4:7]
	s_setprio 0
	s_add_i32 s69, 16, 0x18000
	v_add_u32_e32 v162, s69, v145
	s_barrier
	ds_read_b128 v[150:153], v162
	ds_read_b128 v[154:157], v162 offset:1024
	ds_read_b128 v[158:161], v162 offset:2048
	ds_read_b128 v[162:165], v162 offset:3072
	s_add_u32 s48, s48, 0x10000
	s_addc_u32 s49, s49, 0
	s_mov_b32 m0, s51
	v_lshl_add_u64 v[198:199], s[48:49], 0, v[128:129]
	ds_read_b128 v[166:169], v148 offset:32768
	ds_read_b128 v[170:173], v148 offset:33792
	ds_read_b128 v[174:177], v148 offset:34816
	ds_read_b128 v[178:181], v148 offset:35840
	ds_read_b128 v[182:185], v148 offset:36864
	ds_read_b128 v[186:189], v148 offset:37888
	ds_read_b128 v[190:193], v148 offset:38912
	ds_read_b128 v[194:197], v148 offset:39936
	global_load_lds_dwordx4 v[198:199], off
	v_lshl_add_u64 v[198:199], s[48:49], 0, v[132:133]
	s_mov_b32 m0, s52
	s_nop 0
	global_load_lds_dwordx4 v[198:199], off
	s_waitcnt lgkmcnt(8)
	s_barrier
	s_waitcnt lgkmcnt(0)
	s_setprio 1
	s_waitcnt lgkmcnt(0)
	v_mfma_f32_16x16x32_bf16 v[124:127], v[150:153], v[166:169], v[124:127]
	v_mfma_f32_16x16x32_bf16 v[124:127], v[154:157], v[170:173], v[124:127]
	v_mfma_f32_16x16x32_bf16 v[120:123], v[162:165], v[170:173], v[120:123]
	v_mfma_f32_16x16x32_bf16 v[120:123], v[158:161], v[166:169], v[120:123]
	v_mfma_f32_16x16x32_bf16 v[112:115], v[158:161], v[174:177], v[112:115]
	v_mfma_f32_16x16x32_bf16 v[112:115], v[162:165], v[178:181], v[112:115]
	v_mfma_f32_16x16x32_bf16 v[116:119], v[154:157], v[178:181], v[116:119]
	v_mfma_f32_16x16x32_bf16 v[116:119], v[150:153], v[174:177], v[116:119]
	v_mfma_f32_16x16x32_bf16 v[108:111], v[150:153], v[182:185], v[108:111]
	v_mfma_f32_16x16x32_bf16 v[108:111], v[154:157], v[186:189], v[108:111]
	v_mfma_f32_16x16x32_bf16 v[104:107], v[162:165], v[186:189], v[104:107]
	v_mfma_f32_16x16x32_bf16 v[104:107], v[158:161], v[182:185], v[104:107]
	v_mfma_f32_16x16x32_bf16 v[96:99], v[158:161], v[190:193], v[96:99]
	v_mfma_f32_16x16x32_bf16 v[96:99], v[162:165], v[194:197], v[96:99]
	v_mfma_f32_16x16x32_bf16 v[100:103], v[154:157], v[194:197], v[100:103]
	v_mfma_f32_16x16x32_bf16 v[100:103], v[150:153], v[190:193], v[100:103]
	s_setprio 0
	s_barrier
	s_add_i32 s48, 16, 0x1c000
	s_add_i32 s49, s69, s31
	v_add_u32_e32 v210, s48, v145
	v_lshl_add_u64 v[218:219], v[218:219], 0, s[6:7]
	s_mov_b32 m0, s49
	ds_read_b128 v[198:201], v210
	ds_read_b128 v[202:205], v210 offset:1024
	ds_read_b128 v[206:209], v210 offset:2048
	ds_read_b128 v[210:213], v210 offset:3072
	global_load_lds_dwordx4 v[218:219], off
	v_lshl_add_u64 v[218:219], v[220:221], 0, s[6:7]
	s_add_i32 m0, s49, 0x2000
	s_nop 0
	global_load_lds_dwordx4 v[218:219], off
	s_barrier
; #define PG8_STAGE(bufoff, gbase, voff) do { _Pragma("unroll") for (int _i = 0; _i < 2; ++_i) \
;         __builtin_amdgcn_global_load_lds((const unsigned*)((const char*)(gbase) + (voff)[_i]), (LAS unsigned*)(lds + (bufoff) + ldsw + _i * 8192), 16, 0, 0); } while (0)
; #define PG8_LDA(dst, b, h) do { _Pragma("unroll") for (int m = 0; m < 4; ++m) _Pragma("unroll") for (int k = 0; k < 2; ++k) dst[m][k] = *(const LAS bf16x8*)(lds + PG8_SA(b, h) + aoff + m * 2048 + k * 1024); } while (0)
; #define PG8_MMA(ai, bj, At, Bt) do { __builtin_amdgcn_s_setprio(1); _Pragma("unroll") for (int m = 0; m < 4; ++m) _Pragma("unroll") for (int n = 0; n < 2; ++n) _Pragma("unroll") for (int k = 0; k < 2; ++k) \
;         acc[ai][bj][m][n] = __builtin_amdgcn_mfma_f32_16x16x32_bf16(Bt[n][k], At[m][k], acc[ai][bj][m][n], 0, 0, 0); __builtin_amdgcn_s_setprio(0); } while (0)
; #define PG8_WAIT_V(n) asm volatile("s_waitcnt vmcnt(" #n ")" ::: "memory")
; #define PG8_WAIT_L(n) asm volatile("s_waitcnt lgkmcnt(" #n ")" ::: "memory")
; #define PG8_BAR __builtin_amdgcn_s_barrier()
; #define PG8_SCHED __builtin_amdgcn_sched_barrier(0)
; template <class Epi>
; DEVINL void gemm_phase(LAS unsigned char* lds, const Gemm g, const Order& S, const Epi& E) {
;     ...
;             PG8_BAR; PG8_WAIT_L(0); PG8_MMA(0, 1, At, B1); PG8_BAR;
;             PG8_LDA(At, 1, 1); PG8_STAGE(PG8_SA(1, 0), a3, voffA);
;             PG8_BAR; PG8_WAIT_L(0); PG8_MMA(1, 0, At, B0); PG8_BAR; PG8_SCHED;
;             PG8_STAGE(PG8_SB(1, 1), b3 + hstepB, voffB);
;             PG8_WAIT_V(6); PG8_BAR; PG8_MMA(1, 1, At, B1); PG8_BAR;
;         }
	s_waitcnt lgkmcnt(0)
	s_setprio 1
	s_waitcnt lgkmcnt(0)
	v_mfma_f32_16x16x32_bf16 v[60:63], v[198:201], v[166:169], v[60:63]
	v_mfma_f32_16x16x32_bf16 v[60:63], v[202:205], v[170:173], v[60:63]
	v_mfma_f32_16x16x32_bf16 v[56:59], v[210:213], v[170:173], v[56:59]
	v_mfma_f32_16x16x32_bf16 v[56:59], v[206:209], v[166:169], v[56:59]
	v_mfma_f32_16x16x32_bf16 v[48:51], v[206:209], v[174:177], v[48:51]
	v_mfma_f32_16x16x32_bf16 v[48:51], v[210:213], v[178:181], v[48:51]
	v_mfma_f32_16x16x32_bf16 v[52:55], v[202:205], v[178:181], v[52:55]
	v_mfma_f32_16x16x32_bf16 v[52:55], v[198:201], v[174:177], v[52:55]
	v_mfma_f32_16x16x32_bf16 v[44:47], v[198:201], v[182:185], v[44:47]
	v_mfma_f32_16x16x32_bf16 v[44:47], v[202:205], v[186:189], v[44:47]
	v_mfma_f32_16x16x32_bf16 v[40:43], v[210:213], v[186:189], v[40:43]
	v_mfma_f32_16x16x32_bf16 v[40:43], v[206:209], v[182:185], v[40:43]
	v_mfma_f32_16x16x32_bf16 v[32:35], v[206:209], v[190:193], v[32:35]
	v_mfma_f32_16x16x32_bf16 v[32:35], v[210:213], v[194:197], v[32:35]
	v_mfma_f32_16x16x32_bf16 v[36:39], v[202:205], v[194:197], v[36:39]
	v_mfma_f32_16x16x32_bf16 v[36:39], v[198:201], v[190:193], v[36:39]
	s_setprio 0
	s_mov_b32 m0, s54
	v_lshl_add_u64 v[218:219], v[222:223], 0, s[6:7]
	s_barrier
	ds_read_b128 v[166:169], v148 offset:49152
	ds_read_b128 v[170:173], v148 offset:50176
	ds_read_b128 v[174:177], v148 offset:51200
	ds_read_b128 v[178:181], v148 offset:52224
	ds_read_b128 v[182:185], v148 offset:53248
	ds_read_b128 v[186:189], v148 offset:54272
	ds_read_b128 v[190:193], v148 offset:55296
	ds_read_b128 v[194:197], v148 offset:56320
	global_load_lds_dwordx4 v[218:219], off
	v_lshl_add_u64 v[218:219], v[224:225], 0, s[6:7]
	s_mov_b32 m0, s55
	s_nop 0
	global_load_lds_dwordx4 v[218:219], off
	s_barrier
	s_waitcnt lgkmcnt(0)
	s_setprio 1
	s_waitcnt lgkmcnt(0)
	v_mfma_f32_16x16x32_bf16 v[92:95], v[150:153], v[166:169], v[92:95]
	v_mfma_f32_16x16x32_bf16 v[92:95], v[154:157], v[170:173], v[92:95]
	v_mfma_f32_16x16x32_bf16 v[88:91], v[162:165], v[170:173], v[88:91]
	v_mfma_f32_16x16x32_bf16 v[88:91], v[158:161], v[166:169], v[88:91]
	v_mfma_f32_16x16x32_bf16 v[80:83], v[158:161], v[174:177], v[80:83]
	v_mfma_f32_16x16x32_bf16 v[80:83], v[162:165], v[178:181], v[80:83]
	v_mfma_f32_16x16x32_bf16 v[84:87], v[154:157], v[178:181], v[84:87]
	v_mfma_f32_16x16x32_bf16 v[84:87], v[150:153], v[174:177], v[84:87]
	v_mfma_f32_16x16x32_bf16 v[76:79], v[150:153], v[182:185], v[76:79]
	v_mfma_f32_16x16x32_bf16 v[76:79], v[154:157], v[186:189], v[76:79]
	v_mfma_f32_16x16x32_bf16 v[72:75], v[162:165], v[186:189], v[72:75]
	v_mfma_f32_16x16x32_bf16 v[72:75], v[158:161], v[182:185], v[72:75]
	v_mfma_f32_16x16x32_bf16 v[64:67], v[158:161], v[190:193], v[64:67]
	v_mfma_f32_16x16x32_bf16 v[64:67], v[162:165], v[194:197], v[64:67]
	v_mfma_f32_16x16x32_bf16 v[68:71], v[154:157], v[194:197], v[68:71]
	v_mfma_f32_16x16x32_bf16 v[68:71], v[150:153], v[190:193], v[68:71]
	s_setprio 0
	s_barrier
	s_add_u32 s46, s46, 0x10080
	s_addc_u32 s47, s47, 0
	s_add_i32 s48, s48, s31
	v_lshl_add_u64 v[150:151], s[46:47], 0, v[130:131]
	s_mov_b32 m0, s48
	s_nop 0
	global_load_lds_dwordx4 v[150:151], off
	v_lshl_add_u64 v[150:151], s[46:47], 0, v[134:135]
	s_add_i32 m0, s48, 0x2000
	s_nop 0
	global_load_lds_dwordx4 v[150:151], off
	s_waitcnt vmcnt(6)
	s_barrier
	s_setprio 1
	v_mfma_f32_16x16x32_bf16 v[28:31], v[198:201], v[166:169], v[28:31]
	v_mfma_f32_16x16x32_bf16 v[28:31], v[202:205], v[170:173], v[28:31]
	v_mfma_f32_16x16x32_bf16 v[24:27], v[210:213], v[170:173], v[24:27]
	v_mfma_f32_16x16x32_bf16 v[24:27], v[206:209], v[166:169], v[24:27]
	v_mfma_f32_16x16x32_bf16 v[16:19], v[206:209], v[174:177], v[16:19]
	v_mfma_f32_16x16x32_bf16 v[16:19], v[210:213], v[178:181], v[16:19]
	v_mfma_f32_16x16x32_bf16 v[20:23], v[202:205], v[178:181], v[20:23]
	v_mfma_f32_16x16x32_bf16 v[20:23], v[198:201], v[174:177], v[20:23]
	v_mfma_f32_16x16x32_bf16 v[12:15], v[198:201], v[182:185], v[12:15]
	v_mfma_f32_16x16x32_bf16 v[12:15], v[202:205], v[186:189], v[12:15]
	v_mfma_f32_16x16x32_bf16 v[8:11], v[210:213], v[186:189], v[8:11]
	v_mfma_f32_16x16x32_bf16 v[8:11], v[206:209], v[182:185], v[8:11]
	v_mfma_f32_16x16x32_bf16 v[0:3], v[206:209], v[190:193], v[0:3]
	v_mfma_f32_16x16x32_bf16 v[0:3], v[210:213], v[194:197], v[0:3]
	v_mfma_f32_16x16x32_bf16 v[4:7], v[202:205], v[194:197], v[4:7]
	v_mfma_f32_16x16x32_bf16 v[4:7], v[198:201], v[190:193], v[4:7]
	s_setprio 0
	s_add_u32 s4, s4, 0x100
	s_addc_u32 s5, s5, 0
	s_add_u32 s66, s66, 0x100
	s_addc_u32 s67, s67, 0
	s_cmp_ge_i32 s68, s53
	s_mov_b32 s46, s68
	s_barrier
	s_cbranch_scc0 .LBB0_1008
	s_branch .LBB0_999

; #define PG8_STAGE(bufoff, gbase, voff) do { _Pragma("unroll") for (int _i = 0; _i < 2; ++_i) \
;         __builtin_amdgcn_global_load_lds((const unsigned*)((const char*)(gbase) + (voff)[_i]), (LAS unsigned*)(lds + (bufoff) + ldsw + _i * 8192), 16, 0, 0); } while (0)
; #define PG8_LDA(dst, b, h) do { _Pragma("unroll") for (int m = 0; m < 4; ++m) _Pragma("unroll") for (int k = 0; k < 2; ++k) dst[m][k] = *(const LAS bf16x8*)(lds + PG8_SA(b, h) + aoff + m * 2048 + k * 1024); } while (0)
; #define PG8_LDB(dst, b, h) do { _Pragma("unroll") for (int n = 0; n < 2; ++n) _Pragma("unroll") for (int k = 0; k < 2; ++k) dst[n][k] = *(const LAS bf16x8*)(lds + PG8_SB(b, h) + boff + n * 2048 + k * 1024); } while (0)
; #define PG8_MMA(ai, bj, At, Bt) do { __builtin_amdgcn_s_setprio(1); _Pragma("unroll") for (int m = 0; m < 4; ++m) _Pragma("unroll") for (int n = 0; n < 2; ++n) _Pragma("unroll") for (int k = 0; k < 2; ++k) \
;         acc[ai][bj][m][n] = __builtin_amdgcn_mfma_f32_16x16x32_bf16(Bt[n][k], At[m][k], acc[ai][bj][m][n], 0, 0, 0); __builtin_amdgcn_s_setprio(0); } while (0)
; #define PG8_WAIT_L(n) asm volatile("s_waitcnt lgkmcnt(" #n ")" ::: "memory")
; #define PG8_BAR __builtin_amdgcn_s_barrier()
; #define PG8_SCHED __builtin_amdgcn_sched_barrier(0)
; template <class Epi>
; DEVINL void gemm_phase(LAS unsigned char* lds, const Gemm g, const Order& S, const Epi& E) {
;     ...
;             const char* a1 = cA + (size_t)(t + 1) * kstep;
;             const char* a2 = last ? nA : cA + (size_t)(t + 2) * kstep; const char* b2 = last ? nB : cB + (size_t)(t + 2) * kstep;
;             const char* a3 = a2 + kstep; const char* b3 = b2 + kstep;
;             PG8_LDB(B0, 0, 0); PG8_SCHED; PG8_LDA(At, 0, 0); PG8_STAGE(PG8_SA(1, 1), a1 + hstepA, voffA);
;             PG8_WAIT_L(8); PG8_BAR; PG8_WAIT_L(0); PG8_MMA(0, 0, At, B0); PG8_BAR; PG8_SCHED;
;             PG8_LDB(B1, 0, 1); PG8_STAGE(PG8_SB(0, 0), b2, voffB);
;             PG8_BAR; PG8_WAIT_L(0); PG8_MMA(0, 1, At, B1); PG8_BAR;
;             PG8_LDA(At, 0, 1); PG8_STAGE(PG8_SA(0, 0), a2, voffA);
;             PG8_BAR; PG8_WAIT_L(0); PG8_MMA(1, 0, At, B0); PG8_BAR; PG8_SCHED;
.LBB0_1029:
	ds_read_b128 v[150:153], v147
	ds_read_b128 v[154:157], v147 offset:1024
	ds_read_b128 v[158:161], v147 offset:2048
	ds_read_b128 v[162:165], v147 offset:3072
	s_add_i32 s70, s48, 2
	s_add_u32 s49, s4, 0xffff0080
	s_addc_u32 s50, s5, -1
	s_cmp_eq_u32 s57, s48
	s_cselect_b32 s48, s13, s68
	s_cselect_b32 s51, s2, s50
	s_cselect_b32 s50, s3, s49
	s_cselect_b32 s49, s11, s69
	v_lshl_add_u64 v[198:199], s[4:5], 0, v[136:137]
	s_add_i32 m0, s31, 0xc000
	ds_read_b128 v[166:169], v148
	ds_read_b128 v[170:173], v148 offset:1024
	ds_read_b128 v[174:177], v148 offset:2048
	ds_read_b128 v[178:181], v148 offset:3072
	ds_read_b128 v[182:185], v148 offset:4096
	ds_read_b128 v[186:189], v148 offset:5120
	ds_read_b128 v[190:193], v148 offset:6144
	ds_read_b128 v[194:197], v148 offset:7168
	global_load_lds_dwordx4 v[198:199], off
	v_lshl_add_u64 v[198:199], s[4:5], 0, v[138:139]
	s_add_i32 m0, s31, 0xe000
	s_nop 0
	global_load_lds_dwordx4 v[198:199], off
	s_waitcnt lgkmcnt(8)
	s_barrier
	s_waitcnt lgkmcnt(0)
	s_setprio 1
	s_waitcnt lgkmcnt(0)
	v_mfma_f32_16x16x32_bf16 v[124:127], v[150:153], v[166:169], v[124:127]
	v_mfma_f32_16x16x32_bf16 v[124:127], v[154:157], v[170:173], v[124:127]
	v_mfma_f32_16x16x32_bf16 v[120:123], v[162:165], v[170:173], v[120:123]
	v_mfma_f32_16x16x32_bf16 v[120:123], v[158:161], v[166:169], v[120:123]
	v_mfma_f32_16x16x32_bf16 v[112:115], v[158:161], v[174:177], v[112:115]
	v_mfma_f32_16x16x32_bf16 v[112:115], v[162:165], v[178:181], v[112:115]
	v_mfma_f32_16x16x32_bf16 v[116:119], v[154:157], v[178:181], v[116:119]
	v_mfma_f32_16x16x32_bf16 v[116:119], v[150:153], v[174:177], v[116:119]
	v_mfma_f32_16x16x32_bf16 v[108:111], v[150:153], v[182:185], v[108:111]
	v_mfma_f32_16x16x32_bf16 v[108:111], v[154:157], v[186:189], v[108:111]
	v_mfma_f32_16x16x32_bf16 v[104:107], v[162:165], v[186:189], v[104:107]
	v_mfma_f32_16x16x32_bf16 v[104:107], v[158:161], v[182:185], v[104:107]
	v_mfma_f32_16x16x32_bf16 v[96:99], v[158:161], v[190:193], v[96:99]
	v_mfma_f32_16x16x32_bf16 v[96:99], v[162:165], v[194:197], v[96:99]
	v_mfma_f32_16x16x32_bf16 v[100:103], v[154:157], v[194:197], v[100:103]
	v_mfma_f32_16x16x32_bf16 v[100:103], v[150:153], v[190:193], v[100:103]
	s_setprio 0
	s_barrier
	s_add_i32 s71, s65, s30
	v_lshl_add_u64 v[218:219], s[48:49], 0, v[130:131]
	s_mov_b32 m0, s71
	ds_read_b128 v[198:201], v149
	ds_read_b128 v[202:205], v149 offset:1024
	ds_read_b128 v[206:209], v149 offset:2048
	ds_read_b128 v[210:213], v149 offset:3072
	global_load_lds_dwordx4 v[218:219], off
	v_lshl_add_u64 v[220:221], s[48:49], 0, v[134:135]
	s_add_i32 m0, s71, 0x2000
	s_nop 0
	global_load_lds_dwordx4 v[220:221], off
	s_barrier
	s_waitcnt lgkmcnt(0)
	s_setprio 1
	s_waitcnt lgkmcnt(0)
	v_mfma_f32_16x16x32_bf16 v[60:63], v[198:201], v[166:169], v[60:63]
	v_mfma_f32_16x16x32_bf16 v[60:63], v[202:205], v[170:173], v[60:63]
	v_mfma_f32_16x16x32_bf16 v[56:59], v[210:213], v[170:173], v[56:59]
	v_mfma_f32_16x16x32_bf16 v[56:59], v[206:209], v[166:169], v[56:59]
	v_mfma_f32_16x16x32_bf16 v[48:51], v[206:209], v[174:177], v[48:51]
	v_mfma_f32_16x16x32_bf16 v[48:51], v[210:213], v[178:181], v[48:51]
	v_mfma_f32_16x16x32_bf16 v[52:55], v[202:205], v[178:181], v[52:55]
	v_mfma_f32_16x16x32_bf16 v[52:55], v[198:201], v[174:177], v[52:55]
	v_mfma_f32_16x16x32_bf16 v[44:47], v[198:201], v[182:185], v[44:47]
	v_mfma_f32_16x16x32_bf16 v[44:47], v[202:205], v[186:189], v[44:47]
	v_mfma_f32_16x16x32_bf16 v[40:43], v[210:213], v[186:189], v[40:43]
	v_mfma_f32_16x16x32_bf16 v[40:43], v[206:209], v[182:185], v[40:43]
	v_mfma_f32_16x16x32_bf16 v[32:35], v[206:209], v[190:193], v[32:35]
	v_mfma_f32_16x16x32_bf16 v[32:35], v[210:213], v[194:197], v[32:35]
	v_mfma_f32_16x16x32_bf16 v[36:39], v[202:205], v[194:197], v[36:39]
	v_mfma_f32_16x16x32_bf16 v[36:39], v[198:201], v[190:193], v[36:39]
	s_setprio 0
	s_mov_b32 m0, s31
	v_lshl_add_u64 v[222:223], s[50:51], 0, v[128:129]
	s_barrier
	ds_read_b128 v[166:169], v148 offset:16384
	ds_read_b128 v[170:173], v148 offset:17408
	ds_read_b128 v[174:177], v148 offset:18432
	ds_read_b128 v[178:181], v148 offset:19456
	ds_read_b128 v[182:185], v148 offset:20480
	ds_read_b128 v[186:189], v148 offset:21504
	ds_read_b128 v[190:193], v148 offset:22528
	ds_read_b128 v[194:197], v148 offset:23552
	global_load_lds_dwordx4 v[222:223], off
	v_lshl_add_u64 v[224:225], s[50:51], 0, v[132:133]
	s_mov_b32 m0, s47
	s_nop 0
	global_load_lds_dwordx4 v[224:225], off
	s_barrier
	s_waitcnt lgkmcnt(0)
	s_setprio 1
	s_waitcnt lgkmcnt(0)
	v_mfma_f32_16x16x32_bf16 v[92:95], v[150:153], v[166:169], v[92:95]
	v_mfma_f32_16x16x32_bf16 v[92:95], v[154:157], v[170:173], v[92:95]
	v_mfma_f32_16x16x32_bf16 v[88:91], v[162:165], v[170:173], v[88:91]
	v_mfma_f32_16x16x32_bf16 v[88:91], v[158:161], v[166:169], v[88:91]
	v_mfma_f32_16x16x32_bf16 v[80:83], v[158:161], v[174:177], v[80:83]
	v_mfma_f32_16x16x32_bf16 v[80:83], v[162:165], v[178:181], v[80:83]
	v_mfma_f32_16x16x32_bf16 v[84:87], v[154:157], v[178:181], v[84:87]
	v_mfma_f32_16x16x32_bf16 v[84:87], v[150:153], v[174:177], v[84:87]
	v_mfma_f32_16x16x32_bf16 v[76:79], v[150:153], v[182:185], v[76:79]
	v_mfma_f32_16x16x32_bf16 v[76:79], v[154:157], v[186:189], v[76:79]
	v_mfma_f32_16x16x32_bf16 v[72:75], v[162:165], v[186:189], v[72:75]
	v_mfma_f32_16x16x32_bf16 v[72:75], v[158:161], v[182:185], v[72:75]
	v_mfma_f32_16x16x32_bf16 v[64:67], v[158:161], v[190:193], v[64:67]
	v_mfma_f32_16x16x32_bf16 v[64:67], v[162:165], v[194:197], v[64:67]
	v_mfma_f32_16x16x32_bf16 v[68:71], v[154:157], v[194:197], v[68:71]
	v_mfma_f32_16x16x32_bf16 v[68:71], v[150:153], v[190:193], v[68:71]
	s_setprio 0
	s_barrier
; #define PG8_STAGE(bufoff, gbase, voff) do { _Pragma("unroll") for (int _i = 0; _i < 2; ++_i) \
;         __builtin_amdgcn_global_load_lds((const unsigned*)((const char*)(gbase) + (voff)[_i]), (LAS unsigned*)(lds + (bufoff) + ldsw + _i * 8192), 16, 0, 0); } while (0)
; #define PG8_LDA(dst, b, h) do { _Pragma("unroll") for (int m = 0; m < 4; ++m) _Pragma("unroll") for (int k = 0; k < 2; ++k) dst[m][k] = *(const LAS bf16x8*)(lds + PG8_SA(b, h) + aoff + m * 2048 + k * 1024); } while (0)
; #define PG8_LDB(dst, b, h) do { _Pragma("unroll") for (int n = 0; n < 2; ++n) _Pragma("unroll") for (int k = 0; k < 2; ++k) dst[n][k] = *(const LAS bf16x8*)(lds + PG8_SB(b, h) + boff + n * 2048 + k * 1024); } while (0)
; #define PG8_MMA(ai, bj, At, Bt) do { __builtin_amdgcn_s_setprio(1); _Pragma("unroll") for (int m = 0; m < 4; ++m) _Pragma("unroll") for (int n = 0; n < 2; ++n) _Pragma("unroll") for (int k = 0; k < 2; ++k) \
;         acc[ai][bj][m][n] = __builtin_amdgcn_mfma_f32_16x16x32_bf16(Bt[n][k], At[m][k], acc[ai][bj][m][n], 0, 0, 0); __builtin_amdgcn_s_setprio(0); } while (0)
; #define PG8_WAIT_V(n) asm volatile("s_waitcnt vmcnt(" #n ")" ::: "memory")
; #define PG8_WAIT_L(n) asm volatile("s_waitcnt lgkmcnt(" #n ")" ::: "memory")
; #define PG8_BAR __builtin_amdgcn_s_barrier()
; #define PG8_SCHED __builtin_amdgcn_sched_barrier(0)
; template <class Epi>
; DEVINL void gemm_phase(LAS unsigned char* lds, const Gemm g, const Order& S, const Epi& E) {
;     ...
;             PG8_STAGE(PG8_SB(0, 1), b2 + hstepB, voffB);
;             PG8_WAIT_V(6); PG8_BAR; PG8_MMA(1, 1, At, B1); PG8_BAR;
;             PG8_LDB(B0, 1, 0); PG8_SCHED; PG8_LDA(At, 1, 0); PG8_STAGE(PG8_SA(0, 1), a2 + hstepA, voffA);
;             PG8_WAIT_L(8); PG8_BAR; PG8_WAIT_L(0); PG8_MMA(0, 0, At, B0); PG8_BAR; PG8_SCHED;
;             PG8_LDB(B1, 1, 1); PG8_STAGE(PG8_SB(1, 0), b3, voffB);
	s_add_u32 s72, s48, 0x10000
	s_addc_u32 s73, s49, 0
	s_add_i32 s71, s66, s30
	v_lshl_add_u64 v[150:151], s[72:73], 0, v[130:131]
	s_mov_b32 m0, s71
	s_nop 0
	global_load_lds_dwordx4 v[150:151], off
	v_lshl_add_u64 v[150:151], s[72:73], 0, v[134:135]
	s_add_i32 m0, s71, 0x2000
	s_nop 0
	global_load_lds_dwordx4 v[150:151], off
	s_waitcnt vmcnt(6)
	s_barrier
	s_setprio 1
	v_mfma_f32_16x16x32_bf16 v[28:31], v[198:201], v[166:169], v[28:31]
	v_mfma_f32_16x16x32_bf16 v[28:31], v[202:205], v[170:173], v[28:31]
	v_mfma_f32_16x16x32_bf16 v[24:27], v[210:213], v[170:173], v[24:27]
	v_mfma_f32_16x16x32_bf16 v[24:27], v[206:209], v[166:169], v[24:27]
	v_mfma_f32_16x16x32_bf16 v[16:19], v[206:209], v[174:177], v[16:19]
	v_mfma_f32_16x16x32_bf16 v[16:19], v[210:213], v[178:181], v[16:19]
	v_mfma_f32_16x16x32_bf16 v[20:23], v[202:205], v[178:181], v[20:23]
	v_mfma_f32_16x16x32_bf16 v[20:23], v[198:201], v[174:177], v[20:23]
	v_mfma_f32_16x16x32_bf16 v[12:15], v[198:201], v[182:185], v[12:15]
	v_mfma_f32_16x16x32_bf16 v[12:15], v[202:205], v[186:189], v[12:15]
	v_mfma_f32_16x16x32_bf16 v[8:11], v[210:213], v[186:189], v[8:11]
	v_mfma_f32_16x16x32_bf16 v[8:11], v[206:209], v[182:185], v[8:11]
	v_mfma_f32_16x16x32_bf16 v[0:3], v[206:209], v[190:193], v[0:3]
	v_mfma_f32_16x16x32_bf16 v[0:3], v[210:213], v[194:197], v[0:3]
	v_mfma_f32_16x16x32_bf16 v[4:7], v[202:205], v[194:197], v[4:7]
	v_mfma_f32_16x16x32_bf16 v[4:7], v[198:201], v[190:193], v[4:7]
	s_setprio 0
	s_add_i32 s71, 16, 0x18000
	v_add_u32_e32 v162, s71, v145
	s_barrier
	ds_read_b128 v[150:153], v162
	ds_read_b128 v[154:157], v162 offset:1024
	ds_read_b128 v[158:161], v162 offset:2048
	ds_read_b128 v[162:165], v162 offset:3072
	s_add_u32 s50, s50, 0x10000
	s_addc_u32 s51, s51, 0
	s_mov_b32 m0, s52
	v_lshl_add_u64 v[198:199], s[50:51], 0, v[128:129]
	ds_read_b128 v[166:169], v148 offset:32768
	ds_read_b128 v[170:173], v148 offset:33792
	ds_read_b128 v[174:177], v148 offset:34816
	ds_read_b128 v[178:181], v148 offset:35840
	ds_read_b128 v[182:185], v148 offset:36864
	ds_read_b128 v[186:189], v148 offset:37888
	ds_read_b128 v[190:193], v148 offset:38912
	ds_read_b128 v[194:197], v148 offset:39936
	global_load_lds_dwordx4 v[198:199], off
	v_lshl_add_u64 v[198:199], s[50:51], 0, v[132:133]
	s_mov_b32 m0, s53
	s_nop 0
	global_load_lds_dwordx4 v[198:199], off
	s_waitcnt lgkmcnt(8)
	s_barrier
	s_waitcnt lgkmcnt(0)
	s_setprio 1
	s_waitcnt lgkmcnt(0)
	v_mfma_f32_16x16x32_bf16 v[124:127], v[150:153], v[166:169], v[124:127]
	v_mfma_f32_16x16x32_bf16 v[124:127], v[154:157], v[170:173], v[124:127]
	v_mfma_f32_16x16x32_bf16 v[120:123], v[162:165], v[170:173], v[120:123]
	v_mfma_f32_16x16x32_bf16 v[120:123], v[158:161], v[166:169], v[120:123]
	v_mfma_f32_16x16x32_bf16 v[112:115], v[158:161], v[174:177], v[112:115]
	v_mfma_f32_16x16x32_bf16 v[112:115], v[162:165], v[178:181], v[112:115]
	v_mfma_f32_16x16x32_bf16 v[116:119], v[154:157], v[178:181], v[116:119]
	v_mfma_f32_16x16x32_bf16 v[116:119], v[150:153], v[174:177], v[116:119]
	v_mfma_f32_16x16x32_bf16 v[108:111], v[150:153], v[182:185], v[108:111]
	v_mfma_f32_16x16x32_bf16 v[108:111], v[154:157], v[186:189], v[108:111]
	v_mfma_f32_16x16x32_bf16 v[104:107], v[162:165], v[186:189], v[104:107]
	v_mfma_f32_16x16x32_bf16 v[104:107], v[158:161], v[182:185], v[104:107]
	v_mfma_f32_16x16x32_bf16 v[96:99], v[158:161], v[190:193], v[96:99]
	v_mfma_f32_16x16x32_bf16 v[96:99], v[162:165], v[194:197], v[96:99]
	v_mfma_f32_16x16x32_bf16 v[100:103], v[154:157], v[194:197], v[100:103]
	v_mfma_f32_16x16x32_bf16 v[100:103], v[150:153], v[190:193], v[100:103]
	s_setprio 0
	s_barrier
	s_add_i32 s50, 16, 0x1c000
	s_add_i32 s51, s71, s30
	v_add_u32_e32 v210, s50, v145
	v_lshl_add_u64 v[218:219], v[218:219], 0, s[6:7]
	s_mov_b32 m0, s51
	ds_read_b128 v[198:201], v210
	ds_read_b128 v[202:205], v210 offset:1024
	ds_read_b128 v[206:209], v210 offset:2048
	ds_read_b128 v[210:213], v210 offset:3072
	global_load_lds_dwordx4 v[218:219], off
	v_lshl_add_u64 v[218:219], v[220:221], 0, s[6:7]
	s_add_i32 m0, s51, 0x2000
	s_nop 0
	global_load_lds_dwordx4 v[218:219], off
	s_barrier
; #define PG8_STAGE(bufoff, gbase, voff) do { _Pragma("unroll") for (int _i = 0; _i < 2; ++_i) \
;         __builtin_amdgcn_global_load_lds((const unsigned*)((const char*)(gbase) + (voff)[_i]), (LAS unsigned*)(lds + (bufoff) + ldsw + _i * 8192), 16, 0, 0); } while (0)
; #define PG8_LDA(dst, b, h) do { _Pragma("unroll") for (int m = 0; m < 4; ++m) _Pragma("unroll") for (int k = 0; k < 2; ++k) dst[m][k] = *(const LAS bf16x8*)(lds + PG8_SA(b, h) + aoff + m * 2048 + k * 1024); } while (0)
; #define PG8_MMA(ai, bj, At, Bt) do { __builtin_amdgcn_s_setprio(1); _Pragma("unroll") for (int m = 0; m < 4; ++m) _Pragma("unroll") for (int n = 0; n < 2; ++n) _Pragma("unroll") for (int k = 0; k < 2; ++k) \
;         acc[ai][bj][m][n] = __builtin_amdgcn_mfma_f32_16x16x32_bf16(Bt[n][k], At[m][k], acc[ai][bj][m][n], 0, 0, 0); __builtin_amdgcn_s_setprio(0); } while (0)
; #define PG8_WAIT_V(n) asm volatile("s_waitcnt vmcnt(" #n ")" ::: "memory")
; #define PG8_WAIT_L(n) asm volatile("s_waitcnt lgkmcnt(" #n ")" ::: "memory")
; #define PG8_BAR __builtin_amdgcn_s_barrier()
; #define PG8_SCHED __builtin_amdgcn_sched_barrier(0)
; template <class Epi>
; DEVINL void gemm_phase(LAS unsigned char* lds, const Gemm g, const Order& S, const Epi& E) {
;     ...
;             PG8_BAR; PG8_WAIT_L(0); PG8_MMA(0, 1, At, B1); PG8_BAR;
;             PG8_LDA(At, 1, 1); PG8_STAGE(PG8_SA(1, 0), a3, voffA);
;             PG8_BAR; PG8_WAIT_L(0); PG8_MMA(1, 0, At, B0); PG8_BAR; PG8_SCHED;
;             PG8_STAGE(PG8_SB(1, 1), b3 + hstepB, voffB);
;             PG8_WAIT_V(6); PG8_BAR; PG8_MMA(1, 1, At, B1); PG8_BAR;
;         }
	s_waitcnt lgkmcnt(0)
	s_setprio 1
	s_waitcnt lgkmcnt(0)
	v_mfma_f32_16x16x32_bf16 v[60:63], v[198:201], v[166:169], v[60:63]
	v_mfma_f32_16x16x32_bf16 v[60:63], v[202:205], v[170:173], v[60:63]
	v_mfma_f32_16x16x32_bf16 v[56:59], v[210:213], v[170:173], v[56:59]
	v_mfma_f32_16x16x32_bf16 v[56:59], v[206:209], v[166:169], v[56:59]
	v_mfma_f32_16x16x32_bf16 v[48:51], v[206:209], v[174:177], v[48:51]
	v_mfma_f32_16x16x32_bf16 v[48:51], v[210:213], v[178:181], v[48:51]
	v_mfma_f32_16x16x32_bf16 v[52:55], v[202:205], v[178:181], v[52:55]
	v_mfma_f32_16x16x32_bf16 v[52:55], v[198:201], v[174:177], v[52:55]
	v_mfma_f32_16x16x32_bf16 v[44:47], v[198:201], v[182:185], v[44:47]
	v_mfma_f32_16x16x32_bf16 v[44:47], v[202:205], v[186:189], v[44:47]
	v_mfma_f32_16x16x32_bf16 v[40:43], v[210:213], v[186:189], v[40:43]
	v_mfma_f32_16x16x32_bf16 v[40:43], v[206:209], v[182:185], v[40:43]
	v_mfma_f32_16x16x32_bf16 v[32:35], v[206:209], v[190:193], v[32:35]
	v_mfma_f32_16x16x32_bf16 v[32:35], v[210:213], v[194:197], v[32:35]
	v_mfma_f32_16x16x32_bf16 v[36:39], v[202:205], v[194:197], v[36:39]
	v_mfma_f32_16x16x32_bf16 v[36:39], v[198:201], v[190:193], v[36:39]
	s_setprio 0
	s_mov_b32 m0, s55
	v_lshl_add_u64 v[218:219], v[222:223], 0, s[6:7]
	s_barrier
	ds_read_b128 v[166:169], v148 offset:49152
	ds_read_b128 v[170:173], v148 offset:50176
	ds_read_b128 v[174:177], v148 offset:51200
	ds_read_b128 v[178:181], v148 offset:52224
	ds_read_b128 v[182:185], v148 offset:53248
	ds_read_b128 v[186:189], v148 offset:54272
	ds_read_b128 v[190:193], v148 offset:55296
	ds_read_b128 v[194:197], v148 offset:56320
	global_load_lds_dwordx4 v[218:219], off
	v_lshl_add_u64 v[218:219], v[224:225], 0, s[6:7]
	s_mov_b32 m0, s56
	s_nop 0
	global_load_lds_dwordx4 v[218:219], off
	s_barrier
	s_waitcnt lgkmcnt(0)
	s_setprio 1
	s_waitcnt lgkmcnt(0)
	v_mfma_f32_16x16x32_bf16 v[92:95], v[150:153], v[166:169], v[92:95]
	v_mfma_f32_16x16x32_bf16 v[92:95], v[154:157], v[170:173], v[92:95]
	v_mfma_f32_16x16x32_bf16 v[88:91], v[162:165], v[170:173], v[88:91]
	v_mfma_f32_16x16x32_bf16 v[88:91], v[158:161], v[166:169], v[88:91]
	v_mfma_f32_16x16x32_bf16 v[80:83], v[158:161], v[174:177], v[80:83]
	v_mfma_f32_16x16x32_bf16 v[80:83], v[162:165], v[178:181], v[80:83]
	v_mfma_f32_16x16x32_bf16 v[84:87], v[154:157], v[178:181], v[84:87]
	v_mfma_f32_16x16x32_bf16 v[84:87], v[150:153], v[174:177], v[84:87]
	v_mfma_f32_16x16x32_bf16 v[76:79], v[150:153], v[182:185], v[76:79]
	v_mfma_f32_16x16x32_bf16 v[76:79], v[154:157], v[186:189], v[76:79]
	v_mfma_f32_16x16x32_bf16 v[72:75], v[162:165], v[186:189], v[72:75]
	v_mfma_f32_16x16x32_bf16 v[72:75], v[158:161], v[182:185], v[72:75]
	v_mfma_f32_16x16x32_bf16 v[64:67], v[158:161], v[190:193], v[64:67]
	v_mfma_f32_16x16x32_bf16 v[64:67], v[162:165], v[194:197], v[64:67]
	v_mfma_f32_16x16x32_bf16 v[68:71], v[154:157], v[194:197], v[68:71]
	v_mfma_f32_16x16x32_bf16 v[68:71], v[150:153], v[190:193], v[68:71]
	s_setprio 0
	s_barrier
	s_add_u32 s48, s48, 0x10080
	s_addc_u32 s49, s49, 0
	s_add_i32 s50, s50, s30
	v_lshl_add_u64 v[150:151], s[48:49], 0, v[130:131]
	s_mov_b32 m0, s50
	s_nop 0
	global_load_lds_dwordx4 v[150:151], off
	v_lshl_add_u64 v[150:151], s[48:49], 0, v[134:135]
	s_add_i32 m0, s50, 0x2000
	s_nop 0
	global_load_lds_dwordx4 v[150:151], off
	s_waitcnt vmcnt(6)
	s_barrier
	s_setprio 1
	v_mfma_f32_16x16x32_bf16 v[28:31], v[198:201], v[166:169], v[28:31]
	v_mfma_f32_16x16x32_bf16 v[28:31], v[202:205], v[170:173], v[28:31]
	v_mfma_f32_16x16x32_bf16 v[24:27], v[210:213], v[170:173], v[24:27]
	v_mfma_f32_16x16x32_bf16 v[24:27], v[206:209], v[166:169], v[24:27]
	v_mfma_f32_16x16x32_bf16 v[16:19], v[206:209], v[174:177], v[16:19]
	v_mfma_f32_16x16x32_bf16 v[16:19], v[210:213], v[178:181], v[16:19]
	v_mfma_f32_16x16x32_bf16 v[20:23], v[202:205], v[178:181], v[20:23]
	v_mfma_f32_16x16x32_bf16 v[20:23], v[198:201], v[174:177], v[20:23]
	v_mfma_f32_16x16x32_bf16 v[12:15], v[198:201], v[182:185], v[12:15]
	v_mfma_f32_16x16x32_bf16 v[12:15], v[202:205], v[186:189], v[12:15]
	v_mfma_f32_16x16x32_bf16 v[8:11], v[210:213], v[186:189], v[8:11]
	v_mfma_f32_16x16x32_bf16 v[8:11], v[206:209], v[182:185], v[8:11]
	v_mfma_f32_16x16x32_bf16 v[0:3], v[206:209], v[190:193], v[0:3]
	v_mfma_f32_16x16x32_bf16 v[0:3], v[210:213], v[194:197], v[0:3]
	v_mfma_f32_16x16x32_bf16 v[4:7], v[202:205], v[194:197], v[4:7]
	v_mfma_f32_16x16x32_bf16 v[4:7], v[198:201], v[190:193], v[4:7]
	s_setprio 0
	s_add_u32 s4, s4, 0x100
	s_addc_u32 s5, s5, 0
	s_add_u32 s68, s68, 0x100
	s_addc_u32 s69, s69, 0
	s_cmp_ge_i32 s70, s54
	s_mov_b32 s48, s70
	s_barrier
	s_cbranch_scc0 .LBB0_1029
	s_branch .LBB0_1020

; #define PG8_STAGE(bufoff, gbase, voff) do { _Pragma("unroll") for (int _i = 0; _i < 2; ++_i) \
;         __builtin_amdgcn_global_load_lds((const unsigned*)((const char*)(gbase) + (voff)[_i]), (LAS unsigned*)(lds + (bufoff) + ldsw + _i * 8192), 16, 0, 0); } while (0)
; #define PG8_LDA(dst, b, h) do { _Pragma("unroll") for (int m = 0; m < 4; ++m) _Pragma("unroll") for (int k = 0; k < 2; ++k) dst[m][k] = *(const LAS bf16x8*)(lds + PG8_SA(b, h) + aoff + m * 2048 + k * 1024); } while (0)
; #define PG8_LDB(dst, b, h) do { _Pragma("unroll") for (int n = 0; n < 2; ++n) _Pragma("unroll") for (int k = 0; k < 2; ++k) dst[n][k] = *(const LAS bf16x8*)(lds + PG8_SB(b, h) + boff + n * 2048 + k * 1024); } while (0)
; #define PG8_MMA(ai, bj, At, Bt) do { __builtin_amdgcn_s_setprio(1); _Pragma("unroll") for (int m = 0; m < 4; ++m) _Pragma("unroll") for (int n = 0; n < 2; ++n) _Pragma("unroll") for (int k = 0; k < 2; ++k) \
;         acc[ai][bj][m][n] = __builtin_amdgcn_mfma_f32_16x16x32_bf16(Bt[n][k], At[m][k], acc[ai][bj][m][n], 0, 0, 0); __builtin_amdgcn_s_setprio(0); } while (0)
; #define PG8_WAIT_L(n) asm volatile("s_waitcnt lgkmcnt(" #n ")" ::: "memory")
; #define PG8_BAR __builtin_amdgcn_s_barrier()
; #define PG8_SCHED __builtin_amdgcn_sched_barrier(0)
; template <class Epi>
; DEVINL void gemm_phase(LAS unsigned char* lds, const Gemm g, const Order& S, const Epi& E) {
;     ...
;             const char* a1 = cA + (size_t)(t + 1) * kstep;
;             const char* a2 = last ? nA : cA + (size_t)(t + 2) * kstep; const char* b2 = last ? nB : cB + (size_t)(t + 2) * kstep;
;             const char* a3 = a2 + kstep; const char* b3 = b2 + kstep;
;             PG8_LDB(B0, 0, 0); PG8_SCHED; PG8_LDA(At, 0, 0); PG8_STAGE(PG8_SA(1, 1), a1 + hstepA, voffA);
;             PG8_WAIT_L(8); PG8_BAR; PG8_WAIT_L(0); PG8_MMA(0, 0, At, B0); PG8_BAR; PG8_SCHED;
;             PG8_LDB(B1, 0, 1); PG8_STAGE(PG8_SB(0, 0), b2, voffB);
;             PG8_BAR; PG8_WAIT_L(0); PG8_MMA(0, 1, At, B1); PG8_BAR;
;             PG8_LDA(At, 0, 1); PG8_STAGE(PG8_SA(0, 0), a2, voffA);
;             PG8_BAR; PG8_WAIT_L(0); PG8_MMA(1, 0, At, B0); PG8_BAR; PG8_SCHED;
.LBB0_1186:
	ds_read_b128 v[128:131], v159
	ds_read_b128 v[148:151], v159 offset:1024
	ds_read_b128 v[152:155], v159 offset:2048
	ds_read_b128 v[162:165], v159 offset:3072
	s_add_i32 s66, s30, 2
	s_add_u32 s31, s10, 0xfffc0080
	s_addc_u32 s40, s11, -1
	s_cmp_eq_u32 s53, s30
	s_cselect_b32 s30, s17, s64
	s_cselect_b32 s41, s2, s40
	s_cselect_b32 s40, s3, s31
	s_cselect_b32 s31, s13, s65
	v_lshl_add_u64 v[198:199], s[10:11], 0, v[140:141]
	s_add_i32 m0, s29, 0xc000
	ds_read_b128 v[166:169], v160
	ds_read_b128 v[170:173], v160 offset:1024
	ds_read_b128 v[174:177], v160 offset:2048
	ds_read_b128 v[178:181], v160 offset:3072
	ds_read_b128 v[182:185], v160 offset:4096
	ds_read_b128 v[186:189], v160 offset:5120
	ds_read_b128 v[190:193], v160 offset:6144
	ds_read_b128 v[194:197], v160 offset:7168
	global_load_lds_dwordx4 v[198:199], off
	v_lshl_add_u64 v[198:199], s[10:11], 0, v[142:143]
	s_add_i32 m0, s29, 0xe000
	s_nop 0
	global_load_lds_dwordx4 v[198:199], off
	s_waitcnt lgkmcnt(8)
	s_barrier
	s_waitcnt lgkmcnt(0)
	s_setprio 1
	s_waitcnt lgkmcnt(0)
	v_mfma_f32_16x16x32_bf16 v[124:127], v[128:131], v[166:169], v[124:127]
	v_mfma_f32_16x16x32_bf16 v[124:127], v[148:151], v[170:173], v[124:127]
	v_mfma_f32_16x16x32_bf16 v[120:123], v[162:165], v[170:173], v[120:123]
	v_mfma_f32_16x16x32_bf16 v[120:123], v[152:155], v[166:169], v[120:123]
	v_mfma_f32_16x16x32_bf16 v[104:107], v[152:155], v[174:177], v[104:107]
	v_mfma_f32_16x16x32_bf16 v[104:107], v[162:165], v[178:181], v[104:107]
	v_mfma_f32_16x16x32_bf16 v[108:111], v[148:151], v[178:181], v[108:111]
	v_mfma_f32_16x16x32_bf16 v[108:111], v[128:131], v[174:177], v[108:111]
	v_mfma_f32_16x16x32_bf16 v[92:95], v[128:131], v[182:185], v[92:95]
	v_mfma_f32_16x16x32_bf16 v[92:95], v[148:151], v[186:189], v[92:95]
	v_mfma_f32_16x16x32_bf16 v[88:91], v[162:165], v[186:189], v[88:91]
	v_mfma_f32_16x16x32_bf16 v[88:91], v[152:155], v[182:185], v[88:91]
	v_mfma_f32_16x16x32_bf16 v[72:75], v[152:155], v[190:193], v[72:75]
	v_mfma_f32_16x16x32_bf16 v[72:75], v[162:165], v[194:197], v[72:75]
	v_mfma_f32_16x16x32_bf16 v[76:79], v[148:151], v[194:197], v[76:79]
	v_mfma_f32_16x16x32_bf16 v[76:79], v[128:131], v[190:193], v[76:79]
	s_setprio 0
	s_barrier
	s_add_i32 s67, s57, s46
	v_lshl_add_u64 v[218:219], s[30:31], 0, v[134:135]
	s_mov_b32 m0, s67
	ds_read_b128 v[198:201], v161
	ds_read_b128 v[202:205], v161 offset:1024
	ds_read_b128 v[206:209], v161 offset:2048
	ds_read_b128 v[210:213], v161 offset:3072
	global_load_lds_dwordx4 v[218:219], off
	v_lshl_add_u64 v[220:221], s[30:31], 0, v[138:139]
	s_add_i32 m0, s67, 0x2000
	s_nop 0
	global_load_lds_dwordx4 v[220:221], off
	s_barrier
	s_waitcnt lgkmcnt(0)
	s_setprio 1
	s_waitcnt lgkmcnt(0)
	v_mfma_f32_16x16x32_bf16 v[116:119], v[198:201], v[166:169], v[116:119]
	v_mfma_f32_16x16x32_bf16 v[116:119], v[202:205], v[170:173], v[116:119]
	v_mfma_f32_16x16x32_bf16 v[112:115], v[210:213], v[170:173], v[112:115]
	v_mfma_f32_16x16x32_bf16 v[112:115], v[206:209], v[166:169], v[112:115]
	v_mfma_f32_16x16x32_bf16 v[96:99], v[206:209], v[174:177], v[96:99]
	v_mfma_f32_16x16x32_bf16 v[96:99], v[210:213], v[178:181], v[96:99]
	v_mfma_f32_16x16x32_bf16 v[100:103], v[202:205], v[178:181], v[100:103]
	v_mfma_f32_16x16x32_bf16 v[100:103], v[198:201], v[174:177], v[100:103]
	v_mfma_f32_16x16x32_bf16 v[84:87], v[198:201], v[182:185], v[84:87]
	v_mfma_f32_16x16x32_bf16 v[84:87], v[202:205], v[186:189], v[84:87]
	v_mfma_f32_16x16x32_bf16 v[80:83], v[210:213], v[186:189], v[80:83]
	v_mfma_f32_16x16x32_bf16 v[80:83], v[206:209], v[182:185], v[80:83]
	v_mfma_f32_16x16x32_bf16 v[64:67], v[206:209], v[190:193], v[64:67]
	v_mfma_f32_16x16x32_bf16 v[64:67], v[210:213], v[194:197], v[64:67]
	v_mfma_f32_16x16x32_bf16 v[68:71], v[202:205], v[194:197], v[68:71]
	v_mfma_f32_16x16x32_bf16 v[68:71], v[198:201], v[190:193], v[68:71]
	s_setprio 0
	s_mov_b32 m0, s29
	v_lshl_add_u64 v[222:223], s[40:41], 0, v[132:133]
	s_barrier
	ds_read_b128 v[166:169], v160 offset:16384
	ds_read_b128 v[170:173], v160 offset:17408
	ds_read_b128 v[174:177], v160 offset:18432
	ds_read_b128 v[178:181], v160 offset:19456
	ds_read_b128 v[182:185], v160 offset:20480
	ds_read_b128 v[186:189], v160 offset:21504
	ds_read_b128 v[190:193], v160 offset:22528
	ds_read_b128 v[194:197], v160 offset:23552
	global_load_lds_dwordx4 v[222:223], off
	v_lshl_add_u64 v[224:225], s[40:41], 0, v[136:137]
	s_mov_b32 m0, s47
	s_nop 0
	global_load_lds_dwordx4 v[224:225], off
	s_barrier
	s_waitcnt lgkmcnt(0)
	s_setprio 1
	s_waitcnt lgkmcnt(0)
	v_mfma_f32_16x16x32_bf16 v[60:63], v[128:131], v[166:169], v[60:63]
	v_mfma_f32_16x16x32_bf16 v[60:63], v[148:151], v[170:173], v[60:63]
	v_mfma_f32_16x16x32_bf16 v[56:59], v[162:165], v[170:173], v[56:59]
	v_mfma_f32_16x16x32_bf16 v[56:59], v[152:155], v[166:169], v[56:59]
	v_mfma_f32_16x16x32_bf16 v[40:43], v[152:155], v[174:177], v[40:43]
	v_mfma_f32_16x16x32_bf16 v[40:43], v[162:165], v[178:181], v[40:43]
	v_mfma_f32_16x16x32_bf16 v[44:47], v[148:151], v[178:181], v[44:47]
	v_mfma_f32_16x16x32_bf16 v[44:47], v[128:131], v[174:177], v[44:47]
	v_mfma_f32_16x16x32_bf16 v[28:31], v[128:131], v[182:185], v[28:31]
	v_mfma_f32_16x16x32_bf16 v[28:31], v[148:151], v[186:189], v[28:31]
	v_mfma_f32_16x16x32_bf16 v[24:27], v[162:165], v[186:189], v[24:27]
	v_mfma_f32_16x16x32_bf16 v[24:27], v[152:155], v[182:185], v[24:27]
	v_mfma_f32_16x16x32_bf16 v[8:11], v[152:155], v[190:193], v[8:11]
	v_mfma_f32_16x16x32_bf16 v[8:11], v[162:165], v[194:197], v[8:11]
	v_mfma_f32_16x16x32_bf16 v[12:15], v[148:151], v[194:197], v[12:15]
	v_mfma_f32_16x16x32_bf16 v[12:15], v[128:131], v[190:193], v[12:15]
	s_setprio 0
	s_barrier
; #define PG8_STAGE(bufoff, gbase, voff) do { _Pragma("unroll") for (int _i = 0; _i < 2; ++_i) \
;         __builtin_amdgcn_global_load_lds((const unsigned*)((const char*)(gbase) + (voff)[_i]), (LAS unsigned*)(lds + (bufoff) + ldsw + _i * 8192), 16, 0, 0); } while (0)
; #define PG8_LDA(dst, b, h) do { _Pragma("unroll") for (int m = 0; m < 4; ++m) _Pragma("unroll") for (int k = 0; k < 2; ++k) dst[m][k] = *(const LAS bf16x8*)(lds + PG8_SA(b, h) + aoff + m * 2048 + k * 1024); } while (0)
; #define PG8_LDB(dst, b, h) do { _Pragma("unroll") for (int n = 0; n < 2; ++n) _Pragma("unroll") for (int k = 0; k < 2; ++k) dst[n][k] = *(const LAS bf16x8*)(lds + PG8_SB(b, h) + boff + n * 2048 + k * 1024); } while (0)
; #define PG8_MMA(ai, bj, At, Bt) do { __builtin_amdgcn_s_setprio(1); _Pragma("unroll") for (int m = 0; m < 4; ++m) _Pragma("unroll") for (int n = 0; n < 2; ++n) _Pragma("unroll") for (int k = 0; k < 2; ++k) \
;         acc[ai][bj][m][n] = __builtin_amdgcn_mfma_f32_16x16x32_bf16(Bt[n][k], At[m][k], acc[ai][bj][m][n], 0, 0, 0); __builtin_amdgcn_s_setprio(0); } while (0)
; #define PG8_WAIT_V(n) asm volatile("s_waitcnt vmcnt(" #n ")" ::: "memory")
; #define PG8_WAIT_L(n) asm volatile("s_waitcnt lgkmcnt(" #n ")" ::: "memory")
; #define PG8_BAR __builtin_amdgcn_s_barrier()
; #define PG8_SCHED __builtin_amdgcn_sched_barrier(0)
; template <class Epi>
; DEVINL void gemm_phase(LAS unsigned char* lds, const Gemm g, const Order& S, const Epi& E) {
;     ...
;             PG8_STAGE(PG8_SB(0, 1), b2 + hstepB, voffB);
;             PG8_WAIT_V(6); PG8_BAR; PG8_MMA(1, 1, At, B1); PG8_BAR;
;             PG8_LDB(B0, 1, 0); PG8_SCHED; PG8_LDA(At, 1, 0); PG8_STAGE(PG8_SA(0, 1), a2 + hstepA, voffA);
;             PG8_WAIT_L(8); PG8_BAR; PG8_WAIT_L(0); PG8_MMA(0, 0, At, B0); PG8_BAR; PG8_SCHED;
;             PG8_LDB(B1, 1, 1); PG8_STAGE(PG8_SB(1, 0), b3, voffB);
	s_add_u32 s68, s30, 0x40000
	s_addc_u32 s69, s31, 0
	s_add_i32 s67, s58, s46
	v_lshl_add_u64 v[128:129], s[68:69], 0, v[134:135]
	s_mov_b32 m0, s67
	s_nop 0
	global_load_lds_dwordx4 v[128:129], off
	v_lshl_add_u64 v[128:129], s[68:69], 0, v[138:139]
	s_add_i32 m0, s67, 0x2000
	s_nop 0
	global_load_lds_dwordx4 v[128:129], off
	s_waitcnt vmcnt(6)
	s_barrier
	s_setprio 1
	v_mfma_f32_16x16x32_bf16 v[52:55], v[198:201], v[166:169], v[52:55]
	v_mfma_f32_16x16x32_bf16 v[52:55], v[202:205], v[170:173], v[52:55]
	v_mfma_f32_16x16x32_bf16 v[48:51], v[210:213], v[170:173], v[48:51]
	v_mfma_f32_16x16x32_bf16 v[48:51], v[206:209], v[166:169], v[48:51]
	v_mfma_f32_16x16x32_bf16 v[32:35], v[206:209], v[174:177], v[32:35]
	v_mfma_f32_16x16x32_bf16 v[32:35], v[210:213], v[178:181], v[32:35]
	v_mfma_f32_16x16x32_bf16 v[36:39], v[202:205], v[178:181], v[36:39]
	v_mfma_f32_16x16x32_bf16 v[36:39], v[198:201], v[174:177], v[36:39]
	v_mfma_f32_16x16x32_bf16 v[20:23], v[198:201], v[182:185], v[20:23]
	v_mfma_f32_16x16x32_bf16 v[20:23], v[202:205], v[186:189], v[20:23]
	v_mfma_f32_16x16x32_bf16 v[16:19], v[210:213], v[186:189], v[16:19]
	v_mfma_f32_16x16x32_bf16 v[16:19], v[206:209], v[182:185], v[16:19]
	v_mfma_f32_16x16x32_bf16 v[0:3], v[206:209], v[190:193], v[0:3]
	v_mfma_f32_16x16x32_bf16 v[0:3], v[210:213], v[194:197], v[0:3]
	v_mfma_f32_16x16x32_bf16 v[4:7], v[202:205], v[194:197], v[4:7]
	v_mfma_f32_16x16x32_bf16 v[4:7], v[198:201], v[190:193], v[4:7]
	s_setprio 0
	s_add_i32 s67, 16, 0x18000
	v_add_u32_e32 v162, s67, v157
	s_barrier
	ds_read_b128 v[128:131], v162
	ds_read_b128 v[148:151], v162 offset:1024
	ds_read_b128 v[152:155], v162 offset:2048
	ds_read_b128 v[162:165], v162 offset:3072
	s_add_u32 s40, s40, 0x40000
	s_addc_u32 s41, s41, 0
	s_mov_b32 m0, s48
	v_lshl_add_u64 v[198:199], s[40:41], 0, v[132:133]
	ds_read_b128 v[166:169], v160 offset:32768
	ds_read_b128 v[170:173], v160 offset:33792
	ds_read_b128 v[174:177], v160 offset:34816
	ds_read_b128 v[178:181], v160 offset:35840
	ds_read_b128 v[182:185], v160 offset:36864
	ds_read_b128 v[186:189], v160 offset:37888
	ds_read_b128 v[190:193], v160 offset:38912
	ds_read_b128 v[194:197], v160 offset:39936
	global_load_lds_dwordx4 v[198:199], off
	v_lshl_add_u64 v[198:199], s[40:41], 0, v[136:137]
	s_mov_b32 m0, s49
	s_nop 0
	global_load_lds_dwordx4 v[198:199], off
	s_waitcnt lgkmcnt(8)
	s_barrier
	s_waitcnt lgkmcnt(0)
	s_setprio 1
	s_waitcnt lgkmcnt(0)
	v_mfma_f32_16x16x32_bf16 v[124:127], v[128:131], v[166:169], v[124:127]
	v_mfma_f32_16x16x32_bf16 v[124:127], v[148:151], v[170:173], v[124:127]
	v_mfma_f32_16x16x32_bf16 v[120:123], v[162:165], v[170:173], v[120:123]
	v_mfma_f32_16x16x32_bf16 v[120:123], v[152:155], v[166:169], v[120:123]
	v_mfma_f32_16x16x32_bf16 v[104:107], v[152:155], v[174:177], v[104:107]
	v_mfma_f32_16x16x32_bf16 v[104:107], v[162:165], v[178:181], v[104:107]
	v_mfma_f32_16x16x32_bf16 v[108:111], v[148:151], v[178:181], v[108:111]
	v_mfma_f32_16x16x32_bf16 v[108:111], v[128:131], v[174:177], v[108:111]
	v_mfma_f32_16x16x32_bf16 v[92:95], v[128:131], v[182:185], v[92:95]
	v_mfma_f32_16x16x32_bf16 v[92:95], v[148:151], v[186:189], v[92:95]
	v_mfma_f32_16x16x32_bf16 v[88:91], v[162:165], v[186:189], v[88:91]
	v_mfma_f32_16x16x32_bf16 v[88:91], v[152:155], v[182:185], v[88:91]
	v_mfma_f32_16x16x32_bf16 v[72:75], v[152:155], v[190:193], v[72:75]
	v_mfma_f32_16x16x32_bf16 v[72:75], v[162:165], v[194:197], v[72:75]
	v_mfma_f32_16x16x32_bf16 v[76:79], v[148:151], v[194:197], v[76:79]
	v_mfma_f32_16x16x32_bf16 v[76:79], v[128:131], v[190:193], v[76:79]
	s_setprio 0
	s_barrier
	s_add_i32 s40, 16, 0x1c000
	s_add_i32 s41, s67, s46
	v_add_u32_e32 v210, s40, v157
	v_lshl_add_u64 v[218:219], v[218:219], 0, s[6:7]
	s_mov_b32 m0, s41
	ds_read_b128 v[198:201], v210
	ds_read_b128 v[202:205], v210 offset:1024
	ds_read_b128 v[206:209], v210 offset:2048
	ds_read_b128 v[210:213], v210 offset:3072
	global_load_lds_dwordx4 v[218:219], off
	v_lshl_add_u64 v[218:219], v[220:221], 0, s[6:7]
	s_add_i32 m0, s41, 0x2000
	s_nop 0
	global_load_lds_dwordx4 v[218:219], off
	s_barrier
; #define PG8_STAGE(bufoff, gbase, voff) do { _Pragma("unroll") for (int _i = 0; _i < 2; ++_i) \
;         __builtin_amdgcn_global_load_lds((const unsigned*)((const char*)(gbase) + (voff)[_i]), (LAS unsigned*)(lds + (bufoff) + ldsw + _i * 8192), 16, 0, 0); } while (0)
; #define PG8_LDA(dst, b, h) do { _Pragma("unroll") for (int m = 0; m < 4; ++m) _Pragma("unroll") for (int k = 0; k < 2; ++k) dst[m][k] = *(const LAS bf16x8*)(lds + PG8_SA(b, h) + aoff + m * 2048 + k * 1024); } while (0)
; #define PG8_MMA(ai, bj, At, Bt) do { __builtin_amdgcn_s_setprio(1); _Pragma("unroll") for (int m = 0; m < 4; ++m) _Pragma("unroll") for (int n = 0; n < 2; ++n) _Pragma("unroll") for (int k = 0; k < 2; ++k) \
;         acc[ai][bj][m][n] = __builtin_amdgcn_mfma_f32_16x16x32_bf16(Bt[n][k], At[m][k], acc[ai][bj][m][n], 0, 0, 0); __builtin_amdgcn_s_setprio(0); } while (0)
; #define PG8_WAIT_V(n) asm volatile("s_waitcnt vmcnt(" #n ")" ::: "memory")
; #define PG8_WAIT_L(n) asm volatile("s_waitcnt lgkmcnt(" #n ")" ::: "memory")
; #define PG8_BAR __builtin_amdgcn_s_barrier()
; #define PG8_SCHED __builtin_amdgcn_sched_barrier(0)
; template <class Epi>
; DEVINL void gemm_phase(LAS unsigned char* lds, const Gemm g, const Order& S, const Epi& E) {
;     ...
;             PG8_BAR; PG8_WAIT_L(0); PG8_MMA(0, 1, At, B1); PG8_BAR;
;             PG8_LDA(At, 1, 1); PG8_STAGE(PG8_SA(1, 0), a3, voffA);
;             PG8_BAR; PG8_WAIT_L(0); PG8_MMA(1, 0, At, B0); PG8_BAR; PG8_SCHED;
;             PG8_STAGE(PG8_SB(1, 1), b3 + hstepB, voffB);
;             PG8_WAIT_V(6); PG8_BAR; PG8_MMA(1, 1, At, B1); PG8_BAR;
;         }
	s_waitcnt lgkmcnt(0)
	s_setprio 1
	s_waitcnt lgkmcnt(0)
	v_mfma_f32_16x16x32_bf16 v[116:119], v[198:201], v[166:169], v[116:119]
	v_mfma_f32_16x16x32_bf16 v[116:119], v[202:205], v[170:173], v[116:119]
	v_mfma_f32_16x16x32_bf16 v[112:115], v[210:213], v[170:173], v[112:115]
	v_mfma_f32_16x16x32_bf16 v[112:115], v[206:209], v[166:169], v[112:115]
	v_mfma_f32_16x16x32_bf16 v[96:99], v[206:209], v[174:177], v[96:99]
	v_mfma_f32_16x16x32_bf16 v[96:99], v[210:213], v[178:181], v[96:99]
	v_mfma_f32_16x16x32_bf16 v[100:103], v[202:205], v[178:181], v[100:103]
	v_mfma_f32_16x16x32_bf16 v[100:103], v[198:201], v[174:177], v[100:103]
	v_mfma_f32_16x16x32_bf16 v[84:87], v[198:201], v[182:185], v[84:87]
	v_mfma_f32_16x16x32_bf16 v[84:87], v[202:205], v[186:189], v[84:87]
	v_mfma_f32_16x16x32_bf16 v[80:83], v[210:213], v[186:189], v[80:83]
	v_mfma_f32_16x16x32_bf16 v[80:83], v[206:209], v[182:185], v[80:83]
	v_mfma_f32_16x16x32_bf16 v[64:67], v[206:209], v[190:193], v[64:67]
	v_mfma_f32_16x16x32_bf16 v[64:67], v[210:213], v[194:197], v[64:67]
	v_mfma_f32_16x16x32_bf16 v[68:71], v[202:205], v[194:197], v[68:71]
	v_mfma_f32_16x16x32_bf16 v[68:71], v[198:201], v[190:193], v[68:71]
	s_setprio 0
	s_mov_b32 m0, s51
	v_lshl_add_u64 v[218:219], v[222:223], 0, s[6:7]
	s_barrier
	ds_read_b128 v[166:169], v160 offset:49152
	ds_read_b128 v[170:173], v160 offset:50176
	ds_read_b128 v[174:177], v160 offset:51200
	ds_read_b128 v[178:181], v160 offset:52224
	ds_read_b128 v[182:185], v160 offset:53248
	ds_read_b128 v[186:189], v160 offset:54272
	ds_read_b128 v[190:193], v160 offset:55296
	ds_read_b128 v[194:197], v160 offset:56320
	global_load_lds_dwordx4 v[218:219], off
	v_lshl_add_u64 v[218:219], v[224:225], 0, s[6:7]
	s_mov_b32 m0, s52
	s_nop 0
	global_load_lds_dwordx4 v[218:219], off
	s_barrier
	s_waitcnt lgkmcnt(0)
	s_setprio 1
	s_waitcnt lgkmcnt(0)
	v_mfma_f32_16x16x32_bf16 v[60:63], v[128:131], v[166:169], v[60:63]
	v_mfma_f32_16x16x32_bf16 v[60:63], v[148:151], v[170:173], v[60:63]
	v_mfma_f32_16x16x32_bf16 v[56:59], v[162:165], v[170:173], v[56:59]
	v_mfma_f32_16x16x32_bf16 v[56:59], v[152:155], v[166:169], v[56:59]
	v_mfma_f32_16x16x32_bf16 v[40:43], v[152:155], v[174:177], v[40:43]
	v_mfma_f32_16x16x32_bf16 v[40:43], v[162:165], v[178:181], v[40:43]
	v_mfma_f32_16x16x32_bf16 v[44:47], v[148:151], v[178:181], v[44:47]
	v_mfma_f32_16x16x32_bf16 v[44:47], v[128:131], v[174:177], v[44:47]
	v_mfma_f32_16x16x32_bf16 v[28:31], v[128:131], v[182:185], v[28:31]
	v_mfma_f32_16x16x32_bf16 v[28:31], v[148:151], v[186:189], v[28:31]
	v_mfma_f32_16x16x32_bf16 v[24:27], v[162:165], v[186:189], v[24:27]
	v_mfma_f32_16x16x32_bf16 v[24:27], v[152:155], v[182:185], v[24:27]
	v_mfma_f32_16x16x32_bf16 v[8:11], v[152:155], v[190:193], v[8:11]
	v_mfma_f32_16x16x32_bf16 v[8:11], v[162:165], v[194:197], v[8:11]
	v_mfma_f32_16x16x32_bf16 v[12:15], v[148:151], v[194:197], v[12:15]
	v_mfma_f32_16x16x32_bf16 v[12:15], v[128:131], v[190:193], v[12:15]
	s_setprio 0
	s_barrier
	s_add_u32 s30, s30, 0x40080
	s_addc_u32 s31, s31, 0
	s_add_i32 s40, s40, s46
	v_lshl_add_u64 v[128:129], s[30:31], 0, v[134:135]
	s_mov_b32 m0, s40
	s_nop 0
	global_load_lds_dwordx4 v[128:129], off
	v_lshl_add_u64 v[128:129], s[30:31], 0, v[138:139]
	s_add_i32 m0, s40, 0x2000
	s_nop 0
	global_load_lds_dwordx4 v[128:129], off
	s_waitcnt vmcnt(6)
	s_barrier
	s_setprio 1
	v_mfma_f32_16x16x32_bf16 v[52:55], v[198:201], v[166:169], v[52:55]
	v_mfma_f32_16x16x32_bf16 v[52:55], v[202:205], v[170:173], v[52:55]
	v_mfma_f32_16x16x32_bf16 v[48:51], v[210:213], v[170:173], v[48:51]
	v_mfma_f32_16x16x32_bf16 v[48:51], v[206:209], v[166:169], v[48:51]
	v_mfma_f32_16x16x32_bf16 v[32:35], v[206:209], v[174:177], v[32:35]
	v_mfma_f32_16x16x32_bf16 v[32:35], v[210:213], v[178:181], v[32:35]
	v_mfma_f32_16x16x32_bf16 v[36:39], v[202:205], v[178:181], v[36:39]
	v_mfma_f32_16x16x32_bf16 v[36:39], v[198:201], v[174:177], v[36:39]
	v_mfma_f32_16x16x32_bf16 v[20:23], v[198:201], v[182:185], v[20:23]
	v_mfma_f32_16x16x32_bf16 v[20:23], v[202:205], v[186:189], v[20:23]
	v_mfma_f32_16x16x32_bf16 v[16:19], v[210:213], v[186:189], v[16:19]
	v_mfma_f32_16x16x32_bf16 v[16:19], v[206:209], v[182:185], v[16:19]
	v_mfma_f32_16x16x32_bf16 v[0:3], v[206:209], v[190:193], v[0:3]
	v_mfma_f32_16x16x32_bf16 v[0:3], v[210:213], v[194:197], v[0:3]
	v_mfma_f32_16x16x32_bf16 v[4:7], v[202:205], v[194:197], v[4:7]
	v_mfma_f32_16x16x32_bf16 v[4:7], v[198:201], v[190:193], v[4:7]
	s_setprio 0
	s_add_u32 s10, s10, 0x100
	s_addc_u32 s11, s11, 0
	s_add_u32 s64, s64, 0x100
	s_addc_u32 s65, s65, 0
	s_cmp_ge_i32 s66, s50
	s_mov_b32 s30, s66
	s_barrier
	s_cbranch_scc0 .LBB0_1186
	s_branch .LBB0_1177

; #define PG8_STAGE(bufoff, gbase, voff) do { _Pragma("unroll") for (int _i = 0; _i < 2; ++_i) \
;         __builtin_amdgcn_global_load_lds((const unsigned*)((const char*)(gbase) + (voff)[_i]), (LAS unsigned*)(lds + (bufoff) + ldsw + _i * 8192), 16, 0, 0); } while (0)
; #define PG8_LDA(dst, b, h) do { _Pragma("unroll") for (int m = 0; m < 4; ++m) _Pragma("unroll") for (int k = 0; k < 2; ++k) dst[m][k] = *(const LAS bf16x8*)(lds + PG8_SA(b, h) + aoff + m * 2048 + k * 1024); } while (0)
; #define PG8_LDB(dst, b, h) do { _Pragma("unroll") for (int n = 0; n < 2; ++n) _Pragma("unroll") for (int k = 0; k < 2; ++k) dst[n][k] = *(const LAS bf16x8*)(lds + PG8_SB(b, h) + boff + n * 2048 + k * 1024); } while (0)
; #define PG8_MMA(ai, bj, At, Bt) do { __builtin_amdgcn_s_setprio(1); _Pragma("unroll") for (int m = 0; m < 4; ++m) _Pragma("unroll") for (int n = 0; n < 2; ++n) _Pragma("unroll") for (int k = 0; k < 2; ++k) \
;         acc[ai][bj][m][n] = __builtin_amdgcn_mfma_f32_16x16x32_bf16(Bt[n][k], At[m][k], acc[ai][bj][m][n], 0, 0, 0); __builtin_amdgcn_s_setprio(0); } while (0)
; #define PG8_WAIT_L(n) asm volatile("s_waitcnt lgkmcnt(" #n ")" ::: "memory")
; #define PG8_BAR __builtin_amdgcn_s_barrier()
; #define PG8_SCHED __builtin_amdgcn_sched_barrier(0)
; template <class Epi>
; DEVINL void gemm_phase(LAS unsigned char* lds, const Gemm g, const Order& S, const Epi& E) {
;     ...
;             const char* a1 = cA + (size_t)(t + 1) * kstep;
;             const char* a2 = last ? nA : cA + (size_t)(t + 2) * kstep; const char* b2 = last ? nB : cB + (size_t)(t + 2) * kstep;
;             const char* a3 = a2 + kstep; const char* b3 = b2 + kstep;
;             PG8_LDB(B0, 0, 0); PG8_SCHED; PG8_LDA(At, 0, 0); PG8_STAGE(PG8_SA(1, 1), a1 + hstepA, voffA);
;             PG8_WAIT_L(8); PG8_BAR; PG8_WAIT_L(0); PG8_MMA(0, 0, At, B0); PG8_BAR; PG8_SCHED;
;             PG8_LDB(B1, 0, 1); PG8_STAGE(PG8_SB(0, 0), b2, voffB);
;             PG8_BAR; PG8_WAIT_L(0); PG8_MMA(0, 1, At, B1); PG8_BAR;
;             PG8_LDA(At, 0, 1); PG8_STAGE(PG8_SA(0, 0), a2, voffA);
;             PG8_BAR; PG8_WAIT_L(0); PG8_MMA(1, 0, At, B0); PG8_BAR; PG8_SCHED;
.LBB0_1259:
	ds_read_b128 v[128:131], v183
	ds_read_b128 v[132:135], v183 offset:1024
	ds_read_b128 v[136:139], v183 offset:2048
	ds_read_b128 v[140:143], v183 offset:3072
	s_add_i32 s68, s40, 2
	s_add_u32 s41, s8, 0xfffc0080
	s_addc_u32 s42, s9, -1
	s_cmp_eq_u32 s55, s40
	s_cselect_b32 s40, s25, s66
	s_cselect_b32 s43, s2, s42
	s_cselect_b32 s42, s3, s41
	s_cselect_b32 s41, s17, s67
	v_lshl_add_u64 v[198:199], s[8:9], 0, v[160:161]
	s_add_i32 m0, s31, 0xc000
	ds_read_b128 v[144:147], v184
	ds_read_b128 v[148:151], v184 offset:1024
	ds_read_b128 v[168:171], v184 offset:2048
	ds_read_b128 v[172:175], v184 offset:3072
	ds_read_b128 v[176:179], v184 offset:4096
	ds_read_b128 v[186:189], v184 offset:5120
	ds_read_b128 v[190:193], v184 offset:6144
	ds_read_b128 v[194:197], v184 offset:7168
	global_load_lds_dwordx4 v[198:199], off
	v_lshl_add_u64 v[198:199], s[8:9], 0, v[162:163]
	s_add_i32 m0, s31, 0xe000
	s_nop 0
	global_load_lds_dwordx4 v[198:199], off
	s_waitcnt lgkmcnt(8)
	s_barrier
	s_waitcnt lgkmcnt(0)
	s_setprio 1
	s_waitcnt lgkmcnt(0)
	v_mfma_f32_16x16x32_bf16 v[116:119], v[128:131], v[144:147], v[116:119]
	v_mfma_f32_16x16x32_bf16 v[116:119], v[132:135], v[148:151], v[116:119]
	v_mfma_f32_16x16x32_bf16 v[124:127], v[140:143], v[148:151], v[124:127]
	v_mfma_f32_16x16x32_bf16 v[124:127], v[136:139], v[144:147], v[124:127]
	v_mfma_f32_16x16x32_bf16 v[104:107], v[136:139], v[168:171], v[104:107]
	v_mfma_f32_16x16x32_bf16 v[104:107], v[140:143], v[172:175], v[104:107]
	v_mfma_f32_16x16x32_bf16 v[108:111], v[132:135], v[172:175], v[108:111]
	v_mfma_f32_16x16x32_bf16 v[108:111], v[128:131], v[168:171], v[108:111]
	v_mfma_f32_16x16x32_bf16 v[92:95], v[128:131], v[176:179], v[92:95]
	v_mfma_f32_16x16x32_bf16 v[92:95], v[132:135], v[186:189], v[92:95]
	v_mfma_f32_16x16x32_bf16 v[88:91], v[140:143], v[186:189], v[88:91]
	v_mfma_f32_16x16x32_bf16 v[88:91], v[136:139], v[176:179], v[88:91]
	v_mfma_f32_16x16x32_bf16 v[72:75], v[136:139], v[190:193], v[72:75]
	v_mfma_f32_16x16x32_bf16 v[72:75], v[140:143], v[194:197], v[72:75]
	v_mfma_f32_16x16x32_bf16 v[76:79], v[132:135], v[194:197], v[76:79]
	v_mfma_f32_16x16x32_bf16 v[76:79], v[128:131], v[190:193], v[76:79]
	s_setprio 0
	s_barrier
	s_add_i32 s69, s59, s48
	v_lshl_add_u64 v[218:219], s[40:41], 0, v[154:155]
	s_mov_b32 m0, s69
	ds_read_b128 v[198:201], v185
	ds_read_b128 v[202:205], v185 offset:1024
	ds_read_b128 v[206:209], v185 offset:2048
	ds_read_b128 v[210:213], v185 offset:3072
	global_load_lds_dwordx4 v[218:219], off
	v_lshl_add_u64 v[220:221], s[40:41], 0, v[158:159]
	s_add_i32 m0, s69, 0x2000
	s_nop 0
	global_load_lds_dwordx4 v[220:221], off
	s_barrier
	s_waitcnt lgkmcnt(0)
	s_setprio 1
	s_waitcnt lgkmcnt(0)
	v_mfma_f32_16x16x32_bf16 v[120:123], v[198:201], v[144:147], v[120:123]
	v_mfma_f32_16x16x32_bf16 v[120:123], v[202:205], v[148:151], v[120:123]
	v_mfma_f32_16x16x32_bf16 v[112:115], v[210:213], v[148:151], v[112:115]
	v_mfma_f32_16x16x32_bf16 v[112:115], v[206:209], v[144:147], v[112:115]
	v_mfma_f32_16x16x32_bf16 v[96:99], v[206:209], v[168:171], v[96:99]
	v_mfma_f32_16x16x32_bf16 v[96:99], v[210:213], v[172:175], v[96:99]
	v_mfma_f32_16x16x32_bf16 v[100:103], v[202:205], v[172:175], v[100:103]
	v_mfma_f32_16x16x32_bf16 v[100:103], v[198:201], v[168:171], v[100:103]
	v_mfma_f32_16x16x32_bf16 v[84:87], v[198:201], v[176:179], v[84:87]
	v_mfma_f32_16x16x32_bf16 v[84:87], v[202:205], v[186:189], v[84:87]
	v_mfma_f32_16x16x32_bf16 v[80:83], v[210:213], v[186:189], v[80:83]
	v_mfma_f32_16x16x32_bf16 v[80:83], v[206:209], v[176:179], v[80:83]
	v_mfma_f32_16x16x32_bf16 v[64:67], v[206:209], v[190:193], v[64:67]
	v_mfma_f32_16x16x32_bf16 v[64:67], v[210:213], v[194:197], v[64:67]
	v_mfma_f32_16x16x32_bf16 v[68:71], v[202:205], v[194:197], v[68:71]
	v_mfma_f32_16x16x32_bf16 v[68:71], v[198:201], v[190:193], v[68:71]
	s_setprio 0
	s_mov_b32 m0, s31
	v_lshl_add_u64 v[222:223], s[42:43], 0, v[152:153]
	s_barrier
	ds_read_b128 v[144:147], v184 offset:16384
	ds_read_b128 v[148:151], v184 offset:17408
	ds_read_b128 v[168:171], v184 offset:18432
	ds_read_b128 v[172:175], v184 offset:19456
	ds_read_b128 v[176:179], v184 offset:20480
	ds_read_b128 v[186:189], v184 offset:21504
	ds_read_b128 v[190:193], v184 offset:22528
	ds_read_b128 v[194:197], v184 offset:23552
	global_load_lds_dwordx4 v[222:223], off
	v_lshl_add_u64 v[224:225], s[42:43], 0, v[156:157]
	s_mov_b32 m0, s49
	s_nop 0
	global_load_lds_dwordx4 v[224:225], off
	s_barrier
	s_waitcnt lgkmcnt(0)
	s_setprio 1
	s_waitcnt lgkmcnt(0)
	v_mfma_f32_16x16x32_bf16 v[60:63], v[128:131], v[144:147], v[60:63]
	v_mfma_f32_16x16x32_bf16 v[60:63], v[132:135], v[148:151], v[60:63]
	v_mfma_f32_16x16x32_bf16 v[56:59], v[140:143], v[148:151], v[56:59]
	v_mfma_f32_16x16x32_bf16 v[56:59], v[136:139], v[144:147], v[56:59]
	v_mfma_f32_16x16x32_bf16 v[40:43], v[136:139], v[168:171], v[40:43]
	v_mfma_f32_16x16x32_bf16 v[40:43], v[140:143], v[172:175], v[40:43]
	v_mfma_f32_16x16x32_bf16 v[44:47], v[132:135], v[172:175], v[44:47]
	v_mfma_f32_16x16x32_bf16 v[44:47], v[128:131], v[168:171], v[44:47]
	v_mfma_f32_16x16x32_bf16 v[28:31], v[128:131], v[176:179], v[28:31]
	v_mfma_f32_16x16x32_bf16 v[28:31], v[132:135], v[186:189], v[28:31]
	v_mfma_f32_16x16x32_bf16 v[24:27], v[140:143], v[186:189], v[24:27]
	v_mfma_f32_16x16x32_bf16 v[24:27], v[136:139], v[176:179], v[24:27]
	v_mfma_f32_16x16x32_bf16 v[8:11], v[136:139], v[190:193], v[8:11]
	v_mfma_f32_16x16x32_bf16 v[8:11], v[140:143], v[194:197], v[8:11]
	v_mfma_f32_16x16x32_bf16 v[12:15], v[132:135], v[194:197], v[12:15]
	v_mfma_f32_16x16x32_bf16 v[12:15], v[128:131], v[190:193], v[12:15]
	s_setprio 0
	s_barrier
; #define PG8_STAGE(bufoff, gbase, voff) do { _Pragma("unroll") for (int _i = 0; _i < 2; ++_i) \
;         __builtin_amdgcn_global_load_lds((const unsigned*)((const char*)(gbase) + (voff)[_i]), (LAS unsigned*)(lds + (bufoff) + ldsw + _i * 8192), 16, 0, 0); } while (0)
; #define PG8_LDA(dst, b, h) do { _Pragma("unroll") for (int m = 0; m < 4; ++m) _Pragma("unroll") for (int k = 0; k < 2; ++k) dst[m][k] = *(const LAS bf16x8*)(lds + PG8_SA(b, h) + aoff + m * 2048 + k * 1024); } while (0)
; #define PG8_LDB(dst, b, h) do { _Pragma("unroll") for (int n = 0; n < 2; ++n) _Pragma("unroll") for (int k = 0; k < 2; ++k) dst[n][k] = *(const LAS bf16x8*)(lds + PG8_SB(b, h) + boff + n * 2048 + k * 1024); } while (0)
; #define PG8_MMA(ai, bj, At, Bt) do { __builtin_amdgcn_s_setprio(1); _Pragma("unroll") for (int m = 0; m < 4; ++m) _Pragma("unroll") for (int n = 0; n < 2; ++n) _Pragma("unroll") for (int k = 0; k < 2; ++k) \
;         acc[ai][bj][m][n] = __builtin_amdgcn_mfma_f32_16x16x32_bf16(Bt[n][k], At[m][k], acc[ai][bj][m][n], 0, 0, 0); __builtin_amdgcn_s_setprio(0); } while (0)
; #define PG8_WAIT_V(n) asm volatile("s_waitcnt vmcnt(" #n ")" ::: "memory")
; #define PG8_WAIT_L(n) asm volatile("s_waitcnt lgkmcnt(" #n ")" ::: "memory")
; #define PG8_BAR __builtin_amdgcn_s_barrier()
; #define PG8_SCHED __builtin_amdgcn_sched_barrier(0)
; template <class Epi>
; DEVINL void gemm_phase(LAS unsigned char* lds, const Gemm g, const Order& S, const Epi& E) {
;     ...
;             PG8_STAGE(PG8_SB(0, 1), b2 + hstepB, voffB);
;             PG8_WAIT_V(6); PG8_BAR; PG8_MMA(1, 1, At, B1); PG8_BAR;
;             PG8_LDB(B0, 1, 0); PG8_SCHED; PG8_LDA(At, 1, 0); PG8_STAGE(PG8_SA(0, 1), a2 + hstepA, voffA);
;             PG8_WAIT_L(8); PG8_BAR; PG8_WAIT_L(0); PG8_MMA(0, 0, At, B0); PG8_BAR; PG8_SCHED;
;             PG8_LDB(B1, 1, 1); PG8_STAGE(PG8_SB(1, 0), b3, voffB);
	s_add_u32 s70, s40, 0x40000
	s_addc_u32 s71, s41, 0
	s_add_i32 s69, s64, s48
	v_lshl_add_u64 v[128:129], s[70:71], 0, v[154:155]
	s_mov_b32 m0, s69
	s_nop 0
	global_load_lds_dwordx4 v[128:129], off
	v_lshl_add_u64 v[128:129], s[70:71], 0, v[158:159]
	s_add_i32 m0, s69, 0x2000
	s_nop 0
	global_load_lds_dwordx4 v[128:129], off
	s_waitcnt vmcnt(6)
	s_barrier
	s_setprio 1
	v_mfma_f32_16x16x32_bf16 v[52:55], v[198:201], v[144:147], v[52:55]
	v_mfma_f32_16x16x32_bf16 v[52:55], v[202:205], v[148:151], v[52:55]
	v_mfma_f32_16x16x32_bf16 v[48:51], v[210:213], v[148:151], v[48:51]
	v_mfma_f32_16x16x32_bf16 v[48:51], v[206:209], v[144:147], v[48:51]
	v_mfma_f32_16x16x32_bf16 v[32:35], v[206:209], v[168:171], v[32:35]
	v_mfma_f32_16x16x32_bf16 v[32:35], v[210:213], v[172:175], v[32:35]
	v_mfma_f32_16x16x32_bf16 v[36:39], v[202:205], v[172:175], v[36:39]
	v_mfma_f32_16x16x32_bf16 v[36:39], v[198:201], v[168:171], v[36:39]
	v_mfma_f32_16x16x32_bf16 v[20:23], v[198:201], v[176:179], v[20:23]
	v_mfma_f32_16x16x32_bf16 v[20:23], v[202:205], v[186:189], v[20:23]
	v_mfma_f32_16x16x32_bf16 v[16:19], v[210:213], v[186:189], v[16:19]
	v_mfma_f32_16x16x32_bf16 v[16:19], v[206:209], v[176:179], v[16:19]
	v_mfma_f32_16x16x32_bf16 v[0:3], v[206:209], v[190:193], v[0:3]
	v_mfma_f32_16x16x32_bf16 v[0:3], v[210:213], v[194:197], v[0:3]
	v_mfma_f32_16x16x32_bf16 v[4:7], v[202:205], v[194:197], v[4:7]
	v_mfma_f32_16x16x32_bf16 v[4:7], v[198:201], v[190:193], v[4:7]
	s_setprio 0
	s_add_i32 s69, 16, 0x18000
	v_add_u32_e32 v140, s69, v181
	s_barrier
	ds_read_b128 v[128:131], v140
	ds_read_b128 v[132:135], v140 offset:1024
	ds_read_b128 v[136:139], v140 offset:2048
	ds_read_b128 v[140:143], v140 offset:3072
	s_add_u32 s42, s42, 0x40000
	s_addc_u32 s43, s43, 0
	s_mov_b32 m0, s50
	v_lshl_add_u64 v[198:199], s[42:43], 0, v[152:153]
	ds_read_b128 v[144:147], v184 offset:32768
	ds_read_b128 v[148:151], v184 offset:33792
	ds_read_b128 v[168:171], v184 offset:34816
	ds_read_b128 v[172:175], v184 offset:35840
	ds_read_b128 v[176:179], v184 offset:36864
	ds_read_b128 v[186:189], v184 offset:37888
	ds_read_b128 v[190:193], v184 offset:38912
	ds_read_b128 v[194:197], v184 offset:39936
	global_load_lds_dwordx4 v[198:199], off
	v_lshl_add_u64 v[198:199], s[42:43], 0, v[156:157]
	s_mov_b32 m0, s51
	s_nop 0
	global_load_lds_dwordx4 v[198:199], off
	s_waitcnt lgkmcnt(8)
	s_barrier
	s_waitcnt lgkmcnt(0)
	s_setprio 1
	s_waitcnt lgkmcnt(0)
	v_mfma_f32_16x16x32_bf16 v[116:119], v[128:131], v[144:147], v[116:119]
	v_mfma_f32_16x16x32_bf16 v[116:119], v[132:135], v[148:151], v[116:119]
	v_mfma_f32_16x16x32_bf16 v[124:127], v[140:143], v[148:151], v[124:127]
	v_mfma_f32_16x16x32_bf16 v[124:127], v[136:139], v[144:147], v[124:127]
	v_mfma_f32_16x16x32_bf16 v[104:107], v[136:139], v[168:171], v[104:107]
	v_mfma_f32_16x16x32_bf16 v[104:107], v[140:143], v[172:175], v[104:107]
	v_mfma_f32_16x16x32_bf16 v[108:111], v[132:135], v[172:175], v[108:111]
	v_mfma_f32_16x16x32_bf16 v[108:111], v[128:131], v[168:171], v[108:111]
	v_mfma_f32_16x16x32_bf16 v[92:95], v[128:131], v[176:179], v[92:95]
	v_mfma_f32_16x16x32_bf16 v[92:95], v[132:135], v[186:189], v[92:95]
	v_mfma_f32_16x16x32_bf16 v[88:91], v[140:143], v[186:189], v[88:91]
	v_mfma_f32_16x16x32_bf16 v[88:91], v[136:139], v[176:179], v[88:91]
	v_mfma_f32_16x16x32_bf16 v[72:75], v[136:139], v[190:193], v[72:75]
	v_mfma_f32_16x16x32_bf16 v[72:75], v[140:143], v[194:197], v[72:75]
	v_mfma_f32_16x16x32_bf16 v[76:79], v[132:135], v[194:197], v[76:79]
	v_mfma_f32_16x16x32_bf16 v[76:79], v[128:131], v[190:193], v[76:79]
	s_setprio 0
	s_barrier
	s_add_i32 s42, 16, 0x1c000
	s_add_i32 s43, s69, s48
	v_add_u32_e32 v210, s42, v181
	v_lshl_add_u64 v[218:219], v[218:219], 0, s[10:11]
	s_mov_b32 m0, s43
	ds_read_b128 v[198:201], v210
	ds_read_b128 v[202:205], v210 offset:1024
	ds_read_b128 v[206:209], v210 offset:2048
	ds_read_b128 v[210:213], v210 offset:3072
	global_load_lds_dwordx4 v[218:219], off
	v_lshl_add_u64 v[218:219], v[220:221], 0, s[10:11]
	s_add_i32 m0, s43, 0x2000
	s_nop 0
	global_load_lds_dwordx4 v[218:219], off
	s_barrier
; #define PG8_STAGE(bufoff, gbase, voff) do { _Pragma("unroll") for (int _i = 0; _i < 2; ++_i) \
;         __builtin_amdgcn_global_load_lds((const unsigned*)((const char*)(gbase) + (voff)[_i]), (LAS unsigned*)(lds + (bufoff) + ldsw + _i * 8192), 16, 0, 0); } while (0)
; #define PG8_LDA(dst, b, h) do { _Pragma("unroll") for (int m = 0; m < 4; ++m) _Pragma("unroll") for (int k = 0; k < 2; ++k) dst[m][k] = *(const LAS bf16x8*)(lds + PG8_SA(b, h) + aoff + m * 2048 + k * 1024); } while (0)
; #define PG8_MMA(ai, bj, At, Bt) do { __builtin_amdgcn_s_setprio(1); _Pragma("unroll") for (int m = 0; m < 4; ++m) _Pragma("unroll") for (int n = 0; n < 2; ++n) _Pragma("unroll") for (int k = 0; k < 2; ++k) \
;         acc[ai][bj][m][n] = __builtin_amdgcn_mfma_f32_16x16x32_bf16(Bt[n][k], At[m][k], acc[ai][bj][m][n], 0, 0, 0); __builtin_amdgcn_s_setprio(0); } while (0)
; #define PG8_WAIT_V(n) asm volatile("s_waitcnt vmcnt(" #n ")" ::: "memory")
; #define PG8_WAIT_L(n) asm volatile("s_waitcnt lgkmcnt(" #n ")" ::: "memory")
; #define PG8_BAR __builtin_amdgcn_s_barrier()
; #define PG8_SCHED __builtin_amdgcn_sched_barrier(0)
; template <class Epi>
; DEVINL void gemm_phase(LAS unsigned char* lds, const Gemm g, const Order& S, const Epi& E) {
;     ...
;             PG8_BAR; PG8_WAIT_L(0); PG8_MMA(0, 1, At, B1); PG8_BAR;
;             PG8_LDA(At, 1, 1); PG8_STAGE(PG8_SA(1, 0), a3, voffA);
;             PG8_BAR; PG8_WAIT_L(0); PG8_MMA(1, 0, At, B0); PG8_BAR; PG8_SCHED;
;             PG8_STAGE(PG8_SB(1, 1), b3 + hstepB, voffB);
;             PG8_WAIT_V(6); PG8_BAR; PG8_MMA(1, 1, At, B1); PG8_BAR;
;         }
	s_waitcnt lgkmcnt(0)
	s_setprio 1
	s_waitcnt lgkmcnt(0)
	v_mfma_f32_16x16x32_bf16 v[120:123], v[198:201], v[144:147], v[120:123]
	v_mfma_f32_16x16x32_bf16 v[120:123], v[202:205], v[148:151], v[120:123]
	v_mfma_f32_16x16x32_bf16 v[112:115], v[210:213], v[148:151], v[112:115]
	v_mfma_f32_16x16x32_bf16 v[112:115], v[206:209], v[144:147], v[112:115]
	v_mfma_f32_16x16x32_bf16 v[96:99], v[206:209], v[168:171], v[96:99]
	v_mfma_f32_16x16x32_bf16 v[96:99], v[210:213], v[172:175], v[96:99]
	v_mfma_f32_16x16x32_bf16 v[100:103], v[202:205], v[172:175], v[100:103]
	v_mfma_f32_16x16x32_bf16 v[100:103], v[198:201], v[168:171], v[100:103]
	v_mfma_f32_16x16x32_bf16 v[84:87], v[198:201], v[176:179], v[84:87]
	v_mfma_f32_16x16x32_bf16 v[84:87], v[202:205], v[186:189], v[84:87]
	v_mfma_f32_16x16x32_bf16 v[80:83], v[210:213], v[186:189], v[80:83]
	v_mfma_f32_16x16x32_bf16 v[80:83], v[206:209], v[176:179], v[80:83]
	v_mfma_f32_16x16x32_bf16 v[64:67], v[206:209], v[190:193], v[64:67]
	v_mfma_f32_16x16x32_bf16 v[64:67], v[210:213], v[194:197], v[64:67]
	v_mfma_f32_16x16x32_bf16 v[68:71], v[202:205], v[194:197], v[68:71]
	v_mfma_f32_16x16x32_bf16 v[68:71], v[198:201], v[190:193], v[68:71]
	s_setprio 0
	s_mov_b32 m0, s53
	v_lshl_add_u64 v[218:219], v[222:223], 0, s[10:11]
	s_barrier
	ds_read_b128 v[144:147], v184 offset:49152
	ds_read_b128 v[148:151], v184 offset:50176
	ds_read_b128 v[168:171], v184 offset:51200
	ds_read_b128 v[172:175], v184 offset:52224
	ds_read_b128 v[176:179], v184 offset:53248
	ds_read_b128 v[186:189], v184 offset:54272
	ds_read_b128 v[190:193], v184 offset:55296
	ds_read_b128 v[194:197], v184 offset:56320
	global_load_lds_dwordx4 v[218:219], off
	v_lshl_add_u64 v[218:219], v[224:225], 0, s[10:11]
	s_mov_b32 m0, s54
	s_nop 0
	global_load_lds_dwordx4 v[218:219], off
	s_barrier
	s_waitcnt lgkmcnt(0)
	s_setprio 1
	s_waitcnt lgkmcnt(0)
	v_mfma_f32_16x16x32_bf16 v[60:63], v[128:131], v[144:147], v[60:63]
	v_mfma_f32_16x16x32_bf16 v[60:63], v[132:135], v[148:151], v[60:63]
	v_mfma_f32_16x16x32_bf16 v[56:59], v[140:143], v[148:151], v[56:59]
	v_mfma_f32_16x16x32_bf16 v[56:59], v[136:139], v[144:147], v[56:59]
	v_mfma_f32_16x16x32_bf16 v[40:43], v[136:139], v[168:171], v[40:43]
	v_mfma_f32_16x16x32_bf16 v[40:43], v[140:143], v[172:175], v[40:43]
	v_mfma_f32_16x16x32_bf16 v[44:47], v[132:135], v[172:175], v[44:47]
	v_mfma_f32_16x16x32_bf16 v[44:47], v[128:131], v[168:171], v[44:47]
	v_mfma_f32_16x16x32_bf16 v[28:31], v[128:131], v[176:179], v[28:31]
	v_mfma_f32_16x16x32_bf16 v[28:31], v[132:135], v[186:189], v[28:31]
	v_mfma_f32_16x16x32_bf16 v[24:27], v[140:143], v[186:189], v[24:27]
	v_mfma_f32_16x16x32_bf16 v[24:27], v[136:139], v[176:179], v[24:27]
	v_mfma_f32_16x16x32_bf16 v[8:11], v[136:139], v[190:193], v[8:11]
	v_mfma_f32_16x16x32_bf16 v[8:11], v[140:143], v[194:197], v[8:11]
	v_mfma_f32_16x16x32_bf16 v[12:15], v[132:135], v[194:197], v[12:15]
	v_mfma_f32_16x16x32_bf16 v[12:15], v[128:131], v[190:193], v[12:15]
	s_setprio 0
	s_barrier
	s_add_u32 s40, s40, 0x40080
	s_addc_u32 s41, s41, 0
	s_add_i32 s42, s42, s48
	v_lshl_add_u64 v[128:129], s[40:41], 0, v[154:155]
	s_mov_b32 m0, s42
	s_nop 0
	global_load_lds_dwordx4 v[128:129], off
	v_lshl_add_u64 v[128:129], s[40:41], 0, v[158:159]
	s_add_i32 m0, s42, 0x2000
	s_nop 0
	global_load_lds_dwordx4 v[128:129], off
	s_waitcnt vmcnt(6)
	s_barrier
	s_setprio 1
	v_mfma_f32_16x16x32_bf16 v[52:55], v[198:201], v[144:147], v[52:55]
	v_mfma_f32_16x16x32_bf16 v[52:55], v[202:205], v[148:151], v[52:55]
	v_mfma_f32_16x16x32_bf16 v[48:51], v[210:213], v[148:151], v[48:51]
	v_mfma_f32_16x16x32_bf16 v[48:51], v[206:209], v[144:147], v[48:51]
	v_mfma_f32_16x16x32_bf16 v[32:35], v[206:209], v[168:171], v[32:35]
	v_mfma_f32_16x16x32_bf16 v[32:35], v[210:213], v[172:175], v[32:35]
	v_mfma_f32_16x16x32_bf16 v[36:39], v[202:205], v[172:175], v[36:39]
	v_mfma_f32_16x16x32_bf16 v[36:39], v[198:201], v[168:171], v[36:39]
	v_mfma_f32_16x16x32_bf16 v[20:23], v[198:201], v[176:179], v[20:23]
	v_mfma_f32_16x16x32_bf16 v[20:23], v[202:205], v[186:189], v[20:23]
	v_mfma_f32_16x16x32_bf16 v[16:19], v[210:213], v[186:189], v[16:19]
	v_mfma_f32_16x16x32_bf16 v[16:19], v[206:209], v[176:179], v[16:19]
	v_mfma_f32_16x16x32_bf16 v[0:3], v[206:209], v[190:193], v[0:3]
	v_mfma_f32_16x16x32_bf16 v[0:3], v[210:213], v[194:197], v[0:3]
	v_mfma_f32_16x16x32_bf16 v[4:7], v[202:205], v[194:197], v[4:7]
	v_mfma_f32_16x16x32_bf16 v[4:7], v[198:201], v[190:193], v[4:7]
	s_setprio 0
	s_add_u32 s8, s8, 0x100
	s_addc_u32 s9, s9, 0
	s_add_u32 s66, s66, 0x100
	s_addc_u32 s67, s67, 0
	s_cmp_ge_i32 s68, s52
	s_mov_b32 s40, s68
	s_barrier
	s_cbranch_scc0 .LBB0_1259
	s_branch .LBB0_1250

; #define PG8_STAGE(bufoff, gbase, voff) do { _Pragma("unroll") for (int _i = 0; _i < 2; ++_i) \
;         __builtin_amdgcn_global_load_lds((const unsigned*)((const char*)(gbase) + (voff)[_i]), (LAS unsigned*)(lds + (bufoff) + ldsw + _i * 8192), 16, 0, 0); } while (0)
; #define PG8_LDA(dst, b, h) do { _Pragma("unroll") for (int m = 0; m < 4; ++m) _Pragma("unroll") for (int k = 0; k < 2; ++k) dst[m][k] = *(const LAS bf16x8*)(lds + PG8_SA(b, h) + aoff + m * 2048 + k * 1024); } while (0)
; #define PG8_LDB(dst, b, h) do { _Pragma("unroll") for (int n = 0; n < 2; ++n) _Pragma("unroll") for (int k = 0; k < 2; ++k) dst[n][k] = *(const LAS bf16x8*)(lds + PG8_SB(b, h) + boff + n * 2048 + k * 1024); } while (0)
; #define PG8_MMA(ai, bj, At, Bt) do { __builtin_amdgcn_s_setprio(1); _Pragma("unroll") for (int m = 0; m < 4; ++m) _Pragma("unroll") for (int n = 0; n < 2; ++n) _Pragma("unroll") for (int k = 0; k < 2; ++k) \
;         acc[ai][bj][m][n] = __builtin_amdgcn_mfma_f32_16x16x32_bf16(Bt[n][k], At[m][k], acc[ai][bj][m][n], 0, 0, 0); __builtin_amdgcn_s_setprio(0); } while (0)
; #define PG8_WAIT_L(n) asm volatile("s_waitcnt lgkmcnt(" #n ")" ::: "memory")
; #define PG8_BAR __builtin_amdgcn_s_barrier()
; #define PG8_SCHED __builtin_amdgcn_sched_barrier(0)
; template <class Epi>
; DEVINL void gemm_phase(LAS unsigned char* lds, const Gemm g, const Order& S, const Epi& E) {
;     ...
;             const char* a1 = cA + (size_t)(t + 1) * kstep;
;             const char* a2 = last ? nA : cA + (size_t)(t + 2) * kstep; const char* b2 = last ? nB : cB + (size_t)(t + 2) * kstep;
;             const char* a3 = a2 + kstep; const char* b3 = b2 + kstep;
;             PG8_LDB(B0, 0, 0); PG8_SCHED; PG8_LDA(At, 0, 0); PG8_STAGE(PG8_SA(1, 1), a1 + hstepA, voffA);
;             PG8_WAIT_L(8); PG8_BAR; PG8_WAIT_L(0); PG8_MMA(0, 0, At, B0); PG8_BAR; PG8_SCHED;
;             PG8_LDB(B1, 0, 1); PG8_STAGE(PG8_SB(0, 0), b2, voffB);
;             PG8_BAR; PG8_WAIT_L(0); PG8_MMA(0, 1, At, B1); PG8_BAR;
;             PG8_LDA(At, 0, 1); PG8_STAGE(PG8_SA(0, 0), a2, voffA);
;             PG8_BAR; PG8_WAIT_L(0); PG8_MMA(1, 0, At, B0); PG8_BAR; PG8_SCHED;
.LBB0_1332:
	ds_read_b128 v[150:153], v147
	ds_read_b128 v[154:157], v147 offset:1024
	ds_read_b128 v[158:161], v147 offset:2048
	ds_read_b128 v[162:165], v147 offset:3072
	s_add_i32 s71, s40, 2
	s_add_u32 s41, s8, 0xfff80080
	s_addc_u32 s42, s9, -1
	s_cmp_eq_u32 s55, s40
	s_cselect_b32 s40, s29, s69
	s_cselect_b32 s43, s2, s42
	s_cselect_b32 s42, s3, s41
	s_cselect_b32 s41, s27, s70
	v_lshl_add_u64 v[198:199], s[8:9], 0, v[136:137]
	s_add_i32 m0, s25, 0xc000
	ds_read_b128 v[166:169], v148
	ds_read_b128 v[170:173], v148 offset:1024
	ds_read_b128 v[174:177], v148 offset:2048
	ds_read_b128 v[178:181], v148 offset:3072
	ds_read_b128 v[182:185], v148 offset:4096
	ds_read_b128 v[186:189], v148 offset:5120
	ds_read_b128 v[190:193], v148 offset:6144
	ds_read_b128 v[194:197], v148 offset:7168
	global_load_lds_dwordx4 v[198:199], off
	v_lshl_add_u64 v[198:199], s[8:9], 0, v[138:139]
	s_add_i32 m0, s25, 0xe000
	s_nop 0
	global_load_lds_dwordx4 v[198:199], off
	s_waitcnt lgkmcnt(8)
	s_barrier
	s_waitcnt lgkmcnt(0)
	s_setprio 1
	s_waitcnt lgkmcnt(0)
	v_mfma_f32_16x16x32_bf16 v[120:123], v[150:153], v[166:169], v[120:123]
	v_mfma_f32_16x16x32_bf16 v[120:123], v[154:157], v[170:173], v[120:123]
	v_mfma_f32_16x16x32_bf16 v[124:127], v[162:165], v[170:173], v[124:127]
	v_mfma_f32_16x16x32_bf16 v[124:127], v[158:161], v[166:169], v[124:127]
	v_mfma_f32_16x16x32_bf16 v[104:107], v[158:161], v[174:177], v[104:107]
	v_mfma_f32_16x16x32_bf16 v[104:107], v[162:165], v[178:181], v[104:107]
	v_mfma_f32_16x16x32_bf16 v[108:111], v[154:157], v[178:181], v[108:111]
	v_mfma_f32_16x16x32_bf16 v[108:111], v[150:153], v[174:177], v[108:111]
	v_mfma_f32_16x16x32_bf16 v[92:95], v[150:153], v[182:185], v[92:95]
	v_mfma_f32_16x16x32_bf16 v[92:95], v[154:157], v[186:189], v[92:95]
	v_mfma_f32_16x16x32_bf16 v[88:91], v[162:165], v[186:189], v[88:91]
	v_mfma_f32_16x16x32_bf16 v[88:91], v[158:161], v[182:185], v[88:91]
	v_mfma_f32_16x16x32_bf16 v[72:75], v[158:161], v[190:193], v[72:75]
	v_mfma_f32_16x16x32_bf16 v[72:75], v[162:165], v[194:197], v[72:75]
	v_mfma_f32_16x16x32_bf16 v[76:79], v[154:157], v[194:197], v[76:79]
	v_mfma_f32_16x16x32_bf16 v[76:79], v[150:153], v[190:193], v[76:79]
	s_setprio 0
	s_barrier
	s_add_i32 s72, s59, s48
	v_lshl_add_u64 v[218:219], s[40:41], 0, v[130:131]
	s_mov_b32 m0, s72
	ds_read_b128 v[198:201], v149
	ds_read_b128 v[202:205], v149 offset:1024
	ds_read_b128 v[206:209], v149 offset:2048
	ds_read_b128 v[210:213], v149 offset:3072
	global_load_lds_dwordx4 v[218:219], off
	v_lshl_add_u64 v[220:221], s[40:41], 0, v[134:135]
	s_add_i32 m0, s72, 0x2000
	s_nop 0
	global_load_lds_dwordx4 v[220:221], off
	s_barrier
	s_waitcnt lgkmcnt(0)
	s_setprio 1
	s_waitcnt lgkmcnt(0)
	v_mfma_f32_16x16x32_bf16 v[116:119], v[198:201], v[166:169], v[116:119]
	v_mfma_f32_16x16x32_bf16 v[116:119], v[202:205], v[170:173], v[116:119]
	v_mfma_f32_16x16x32_bf16 v[112:115], v[210:213], v[170:173], v[112:115]
	v_mfma_f32_16x16x32_bf16 v[112:115], v[206:209], v[166:169], v[112:115]
	v_mfma_f32_16x16x32_bf16 v[96:99], v[206:209], v[174:177], v[96:99]
	v_mfma_f32_16x16x32_bf16 v[96:99], v[210:213], v[178:181], v[96:99]
	v_mfma_f32_16x16x32_bf16 v[100:103], v[202:205], v[178:181], v[100:103]
	v_mfma_f32_16x16x32_bf16 v[100:103], v[198:201], v[174:177], v[100:103]
	v_mfma_f32_16x16x32_bf16 v[84:87], v[198:201], v[182:185], v[84:87]
	v_mfma_f32_16x16x32_bf16 v[84:87], v[202:205], v[186:189], v[84:87]
	v_mfma_f32_16x16x32_bf16 v[80:83], v[210:213], v[186:189], v[80:83]
	v_mfma_f32_16x16x32_bf16 v[80:83], v[206:209], v[182:185], v[80:83]
	v_mfma_f32_16x16x32_bf16 v[64:67], v[206:209], v[190:193], v[64:67]
	v_mfma_f32_16x16x32_bf16 v[64:67], v[210:213], v[194:197], v[64:67]
	v_mfma_f32_16x16x32_bf16 v[68:71], v[202:205], v[194:197], v[68:71]
	v_mfma_f32_16x16x32_bf16 v[68:71], v[198:201], v[190:193], v[68:71]
	s_setprio 0
	s_mov_b32 m0, s25
	v_lshl_add_u64 v[222:223], s[42:43], 0, v[128:129]
	s_barrier
	ds_read_b128 v[166:169], v148 offset:16384
	ds_read_b128 v[170:173], v148 offset:17408
	ds_read_b128 v[174:177], v148 offset:18432
	ds_read_b128 v[178:181], v148 offset:19456
	ds_read_b128 v[182:185], v148 offset:20480
	ds_read_b128 v[186:189], v148 offset:21504
	ds_read_b128 v[190:193], v148 offset:22528
	ds_read_b128 v[194:197], v148 offset:23552
	global_load_lds_dwordx4 v[222:223], off
	v_lshl_add_u64 v[224:225], s[42:43], 0, v[132:133]
	s_mov_b32 m0, s49
	s_nop 0
	global_load_lds_dwordx4 v[224:225], off
	s_barrier
	s_waitcnt lgkmcnt(0)
	s_setprio 1
	s_waitcnt lgkmcnt(0)
	v_mfma_f32_16x16x32_bf16 v[60:63], v[150:153], v[166:169], v[60:63]
	v_mfma_f32_16x16x32_bf16 v[60:63], v[154:157], v[170:173], v[60:63]
	v_mfma_f32_16x16x32_bf16 v[56:59], v[162:165], v[170:173], v[56:59]
	v_mfma_f32_16x16x32_bf16 v[56:59], v[158:161], v[166:169], v[56:59]
	v_mfma_f32_16x16x32_bf16 v[40:43], v[158:161], v[174:177], v[40:43]
	v_mfma_f32_16x16x32_bf16 v[40:43], v[162:165], v[178:181], v[40:43]
	v_mfma_f32_16x16x32_bf16 v[44:47], v[154:157], v[178:181], v[44:47]
	v_mfma_f32_16x16x32_bf16 v[44:47], v[150:153], v[174:177], v[44:47]
	v_mfma_f32_16x16x32_bf16 v[28:31], v[150:153], v[182:185], v[28:31]
	v_mfma_f32_16x16x32_bf16 v[28:31], v[154:157], v[186:189], v[28:31]
	v_mfma_f32_16x16x32_bf16 v[24:27], v[162:165], v[186:189], v[24:27]
	v_mfma_f32_16x16x32_bf16 v[24:27], v[158:161], v[182:185], v[24:27]
	v_mfma_f32_16x16x32_bf16 v[8:11], v[158:161], v[190:193], v[8:11]
	v_mfma_f32_16x16x32_bf16 v[8:11], v[162:165], v[194:197], v[8:11]
	v_mfma_f32_16x16x32_bf16 v[12:15], v[154:157], v[194:197], v[12:15]
	v_mfma_f32_16x16x32_bf16 v[12:15], v[150:153], v[190:193], v[12:15]
	s_setprio 0
	s_barrier
; #define PG8_STAGE(bufoff, gbase, voff) do { _Pragma("unroll") for (int _i = 0; _i < 2; ++_i) \
;         __builtin_amdgcn_global_load_lds((const unsigned*)((const char*)(gbase) + (voff)[_i]), (LAS unsigned*)(lds + (bufoff) + ldsw + _i * 8192), 16, 0, 0); } while (0)
; #define PG8_LDA(dst, b, h) do { _Pragma("unroll") for (int m = 0; m < 4; ++m) _Pragma("unroll") for (int k = 0; k < 2; ++k) dst[m][k] = *(const LAS bf16x8*)(lds + PG8_SA(b, h) + aoff + m * 2048 + k * 1024); } while (0)
; #define PG8_LDB(dst, b, h) do { _Pragma("unroll") for (int n = 0; n < 2; ++n) _Pragma("unroll") for (int k = 0; k < 2; ++k) dst[n][k] = *(const LAS bf16x8*)(lds + PG8_SB(b, h) + boff + n * 2048 + k * 1024); } while (0)
; #define PG8_MMA(ai, bj, At, Bt) do { __builtin_amdgcn_s_setprio(1); _Pragma("unroll") for (int m = 0; m < 4; ++m) _Pragma("unroll") for (int n = 0; n < 2; ++n) _Pragma("unroll") for (int k = 0; k < 2; ++k) \
;         acc[ai][bj][m][n] = __builtin_amdgcn_mfma_f32_16x16x32_bf16(Bt[n][k], At[m][k], acc[ai][bj][m][n], 0, 0, 0); __builtin_amdgcn_s_setprio(0); } while (0)
; #define PG8_WAIT_V(n) asm volatile("s_waitcnt vmcnt(" #n ")" ::: "memory")
; #define PG8_WAIT_L(n) asm volatile("s_waitcnt lgkmcnt(" #n ")" ::: "memory")
; #define PG8_BAR __builtin_amdgcn_s_barrier()
; #define PG8_SCHED __builtin_amdgcn_sched_barrier(0)
; template <class Epi>
; DEVINL void gemm_phase(LAS unsigned char* lds, const Gemm g, const Order& S, const Epi& E) {
;     ...
;             PG8_STAGE(PG8_SB(0, 1), b2 + hstepB, voffB);
;             PG8_WAIT_V(6); PG8_BAR; PG8_MMA(1, 1, At, B1); PG8_BAR;
;             PG8_LDB(B0, 1, 0); PG8_SCHED; PG8_LDA(At, 1, 0); PG8_STAGE(PG8_SA(0, 1), a2 + hstepA, voffA);
;             PG8_WAIT_L(8); PG8_BAR; PG8_WAIT_L(0); PG8_MMA(0, 0, At, B0); PG8_BAR; PG8_SCHED;
;             PG8_LDB(B1, 1, 1); PG8_STAGE(PG8_SB(1, 0), b3, voffB);
	s_add_u32 s72, s40, 0x80000
	s_addc_u32 s73, s41, 0
	s_add_i32 s74, s64, s48
	v_lshl_add_u64 v[150:151], s[72:73], 0, v[130:131]
	s_mov_b32 m0, s74
	s_nop 0
	global_load_lds_dwordx4 v[150:151], off
	v_lshl_add_u64 v[150:151], s[72:73], 0, v[134:135]
	s_add_i32 m0, s74, 0x2000
	s_nop 0
	global_load_lds_dwordx4 v[150:151], off
	s_waitcnt vmcnt(6)
	s_barrier
	s_setprio 1
	v_mfma_f32_16x16x32_bf16 v[52:55], v[198:201], v[166:169], v[52:55]
	v_mfma_f32_16x16x32_bf16 v[52:55], v[202:205], v[170:173], v[52:55]
	v_mfma_f32_16x16x32_bf16 v[48:51], v[210:213], v[170:173], v[48:51]
	v_mfma_f32_16x16x32_bf16 v[48:51], v[206:209], v[166:169], v[48:51]
	v_mfma_f32_16x16x32_bf16 v[32:35], v[206:209], v[174:177], v[32:35]
	v_mfma_f32_16x16x32_bf16 v[32:35], v[210:213], v[178:181], v[32:35]
	v_mfma_f32_16x16x32_bf16 v[36:39], v[202:205], v[178:181], v[36:39]
	v_mfma_f32_16x16x32_bf16 v[36:39], v[198:201], v[174:177], v[36:39]
	v_mfma_f32_16x16x32_bf16 v[20:23], v[198:201], v[182:185], v[20:23]
	v_mfma_f32_16x16x32_bf16 v[20:23], v[202:205], v[186:189], v[20:23]
	v_mfma_f32_16x16x32_bf16 v[16:19], v[210:213], v[186:189], v[16:19]
	v_mfma_f32_16x16x32_bf16 v[16:19], v[206:209], v[182:185], v[16:19]
	v_mfma_f32_16x16x32_bf16 v[0:3], v[206:209], v[190:193], v[0:3]
	v_mfma_f32_16x16x32_bf16 v[0:3], v[210:213], v[194:197], v[0:3]
	v_mfma_f32_16x16x32_bf16 v[4:7], v[202:205], v[194:197], v[4:7]
	v_mfma_f32_16x16x32_bf16 v[4:7], v[198:201], v[190:193], v[4:7]
	s_setprio 0
	s_add_i32 s72, 16, 0x18000
	v_add_u32_e32 v162, s72, v145
	s_barrier
	ds_read_b128 v[150:153], v162
	ds_read_b128 v[154:157], v162 offset:1024
	ds_read_b128 v[158:161], v162 offset:2048
	ds_read_b128 v[162:165], v162 offset:3072
	s_add_u32 s42, s42, 0x80000
	s_addc_u32 s43, s43, 0
	s_mov_b32 m0, s50
	v_lshl_add_u64 v[198:199], s[42:43], 0, v[128:129]
	ds_read_b128 v[166:169], v148 offset:32768
	ds_read_b128 v[170:173], v148 offset:33792
	ds_read_b128 v[174:177], v148 offset:34816
	ds_read_b128 v[178:181], v148 offset:35840
	ds_read_b128 v[182:185], v148 offset:36864
	ds_read_b128 v[186:189], v148 offset:37888
	ds_read_b128 v[190:193], v148 offset:38912
	ds_read_b128 v[194:197], v148 offset:39936
	global_load_lds_dwordx4 v[198:199], off
	v_lshl_add_u64 v[198:199], s[42:43], 0, v[132:133]
	s_mov_b32 m0, s51
	s_nop 0
	global_load_lds_dwordx4 v[198:199], off
	s_waitcnt lgkmcnt(8)
	s_barrier
	s_waitcnt lgkmcnt(0)
	s_setprio 1
	s_waitcnt lgkmcnt(0)
	v_mfma_f32_16x16x32_bf16 v[120:123], v[150:153], v[166:169], v[120:123]
	v_mfma_f32_16x16x32_bf16 v[120:123], v[154:157], v[170:173], v[120:123]
	v_mfma_f32_16x16x32_bf16 v[124:127], v[162:165], v[170:173], v[124:127]
	v_mfma_f32_16x16x32_bf16 v[124:127], v[158:161], v[166:169], v[124:127]
	v_mfma_f32_16x16x32_bf16 v[104:107], v[158:161], v[174:177], v[104:107]
	v_mfma_f32_16x16x32_bf16 v[104:107], v[162:165], v[178:181], v[104:107]
	v_mfma_f32_16x16x32_bf16 v[108:111], v[154:157], v[178:181], v[108:111]
	v_mfma_f32_16x16x32_bf16 v[108:111], v[150:153], v[174:177], v[108:111]
	v_mfma_f32_16x16x32_bf16 v[92:95], v[150:153], v[182:185], v[92:95]
	v_mfma_f32_16x16x32_bf16 v[92:95], v[154:157], v[186:189], v[92:95]
	v_mfma_f32_16x16x32_bf16 v[88:91], v[162:165], v[186:189], v[88:91]
	v_mfma_f32_16x16x32_bf16 v[88:91], v[158:161], v[182:185], v[88:91]
	v_mfma_f32_16x16x32_bf16 v[72:75], v[158:161], v[190:193], v[72:75]
	v_mfma_f32_16x16x32_bf16 v[72:75], v[162:165], v[194:197], v[72:75]
	v_mfma_f32_16x16x32_bf16 v[76:79], v[154:157], v[194:197], v[76:79]
	v_mfma_f32_16x16x32_bf16 v[76:79], v[150:153], v[190:193], v[76:79]
	s_setprio 0
	s_barrier
	s_add_i32 s42, 16, 0x1c000
	s_add_i32 s43, s72, s48
	v_add_u32_e32 v210, s42, v145
	v_lshl_add_u64 v[218:219], v[218:219], 0, s[6:7]
	s_mov_b32 m0, s43
	ds_read_b128 v[198:201], v210
	ds_read_b128 v[202:205], v210 offset:1024
	ds_read_b128 v[206:209], v210 offset:2048
	ds_read_b128 v[210:213], v210 offset:3072
	global_load_lds_dwordx4 v[218:219], off
	v_lshl_add_u64 v[218:219], v[220:221], 0, s[6:7]
	s_add_i32 m0, s43, 0x2000
	s_nop 0
	global_load_lds_dwordx4 v[218:219], off
	s_barrier
; #define PG8_STAGE(bufoff, gbase, voff) do { _Pragma("unroll") for (int _i = 0; _i < 2; ++_i) \
;         __builtin_amdgcn_global_load_lds((const unsigned*)((const char*)(gbase) + (voff)[_i]), (LAS unsigned*)(lds + (bufoff) + ldsw + _i * 8192), 16, 0, 0); } while (0)
; #define PG8_LDA(dst, b, h) do { _Pragma("unroll") for (int m = 0; m < 4; ++m) _Pragma("unroll") for (int k = 0; k < 2; ++k) dst[m][k] = *(const LAS bf16x8*)(lds + PG8_SA(b, h) + aoff + m * 2048 + k * 1024); } while (0)
; #define PG8_MMA(ai, bj, At, Bt) do { __builtin_amdgcn_s_setprio(1); _Pragma("unroll") for (int m = 0; m < 4; ++m) _Pragma("unroll") for (int n = 0; n < 2; ++n) _Pragma("unroll") for (int k = 0; k < 2; ++k) \
;         acc[ai][bj][m][n] = __builtin_amdgcn_mfma_f32_16x16x32_bf16(Bt[n][k], At[m][k], acc[ai][bj][m][n], 0, 0, 0); __builtin_amdgcn_s_setprio(0); } while (0)
; #define PG8_WAIT_V(n) asm volatile("s_waitcnt vmcnt(" #n ")" ::: "memory")
; #define PG8_WAIT_L(n) asm volatile("s_waitcnt lgkmcnt(" #n ")" ::: "memory")
; #define PG8_BAR __builtin_amdgcn_s_barrier()
; #define PG8_SCHED __builtin_amdgcn_sched_barrier(0)
; template <class Epi>
; DEVINL void gemm_phase(LAS unsigned char* lds, const Gemm g, const Order& S, const Epi& E) {
;     ...
;             PG8_BAR; PG8_WAIT_L(0); PG8_MMA(0, 1, At, B1); PG8_BAR;
;             PG8_LDA(At, 1, 1); PG8_STAGE(PG8_SA(1, 0), a3, voffA);
;             PG8_BAR; PG8_WAIT_L(0); PG8_MMA(1, 0, At, B0); PG8_BAR; PG8_SCHED;
;             PG8_STAGE(PG8_SB(1, 1), b3 + hstepB, voffB);
;             PG8_WAIT_V(6); PG8_BAR; PG8_MMA(1, 1, At, B1); PG8_BAR;
;         }
	s_waitcnt lgkmcnt(0)
	s_setprio 1
	s_waitcnt lgkmcnt(0)
	v_mfma_f32_16x16x32_bf16 v[116:119], v[198:201], v[166:169], v[116:119]
	v_mfma_f32_16x16x32_bf16 v[116:119], v[202:205], v[170:173], v[116:119]
	v_mfma_f32_16x16x32_bf16 v[112:115], v[210:213], v[170:173], v[112:115]
	v_mfma_f32_16x16x32_bf16 v[112:115], v[206:209], v[166:169], v[112:115]
	v_mfma_f32_16x16x32_bf16 v[96:99], v[206:209], v[174:177], v[96:99]
	v_mfma_f32_16x16x32_bf16 v[96:99], v[210:213], v[178:181], v[96:99]
	v_mfma_f32_16x16x32_bf16 v[100:103], v[202:205], v[178:181], v[100:103]
	v_mfma_f32_16x16x32_bf16 v[100:103], v[198:201], v[174:177], v[100:103]
	v_mfma_f32_16x16x32_bf16 v[84:87], v[198:201], v[182:185], v[84:87]
	v_mfma_f32_16x16x32_bf16 v[84:87], v[202:205], v[186:189], v[84:87]
	v_mfma_f32_16x16x32_bf16 v[80:83], v[210:213], v[186:189], v[80:83]
	v_mfma_f32_16x16x32_bf16 v[80:83], v[206:209], v[182:185], v[80:83]
	v_mfma_f32_16x16x32_bf16 v[64:67], v[206:209], v[190:193], v[64:67]
	v_mfma_f32_16x16x32_bf16 v[64:67], v[210:213], v[194:197], v[64:67]
	v_mfma_f32_16x16x32_bf16 v[68:71], v[202:205], v[194:197], v[68:71]
	v_mfma_f32_16x16x32_bf16 v[68:71], v[198:201], v[190:193], v[68:71]
	s_setprio 0
	s_mov_b32 m0, s53
	v_lshl_add_u64 v[218:219], v[222:223], 0, s[6:7]
	s_barrier
	ds_read_b128 v[166:169], v148 offset:49152
	ds_read_b128 v[170:173], v148 offset:50176
	ds_read_b128 v[174:177], v148 offset:51200
	ds_read_b128 v[178:181], v148 offset:52224
	ds_read_b128 v[182:185], v148 offset:53248
	ds_read_b128 v[186:189], v148 offset:54272
	ds_read_b128 v[190:193], v148 offset:55296
	ds_read_b128 v[194:197], v148 offset:56320
	global_load_lds_dwordx4 v[218:219], off
	v_lshl_add_u64 v[218:219], v[224:225], 0, s[6:7]
	s_mov_b32 m0, s54
	s_nop 0
	global_load_lds_dwordx4 v[218:219], off
	s_barrier
	s_waitcnt lgkmcnt(0)
	s_setprio 1
	s_waitcnt lgkmcnt(0)
	v_mfma_f32_16x16x32_bf16 v[60:63], v[150:153], v[166:169], v[60:63]
	v_mfma_f32_16x16x32_bf16 v[60:63], v[154:157], v[170:173], v[60:63]
	v_mfma_f32_16x16x32_bf16 v[56:59], v[162:165], v[170:173], v[56:59]
	v_mfma_f32_16x16x32_bf16 v[56:59], v[158:161], v[166:169], v[56:59]
	v_mfma_f32_16x16x32_bf16 v[40:43], v[158:161], v[174:177], v[40:43]
	v_mfma_f32_16x16x32_bf16 v[40:43], v[162:165], v[178:181], v[40:43]
	v_mfma_f32_16x16x32_bf16 v[44:47], v[154:157], v[178:181], v[44:47]
	v_mfma_f32_16x16x32_bf16 v[44:47], v[150:153], v[174:177], v[44:47]
	v_mfma_f32_16x16x32_bf16 v[28:31], v[150:153], v[182:185], v[28:31]
	v_mfma_f32_16x16x32_bf16 v[28:31], v[154:157], v[186:189], v[28:31]
	v_mfma_f32_16x16x32_bf16 v[24:27], v[162:165], v[186:189], v[24:27]
	v_mfma_f32_16x16x32_bf16 v[24:27], v[158:161], v[182:185], v[24:27]
	v_mfma_f32_16x16x32_bf16 v[8:11], v[158:161], v[190:193], v[8:11]
	v_mfma_f32_16x16x32_bf16 v[8:11], v[162:165], v[194:197], v[8:11]
	v_mfma_f32_16x16x32_bf16 v[12:15], v[154:157], v[194:197], v[12:15]
	v_mfma_f32_16x16x32_bf16 v[12:15], v[150:153], v[190:193], v[12:15]
	s_setprio 0
	s_barrier
	s_add_u32 s40, s40, 0x80080
	s_addc_u32 s41, s41, 0
	s_add_i32 s42, s42, s48
	v_lshl_add_u64 v[150:151], s[40:41], 0, v[130:131]
	s_mov_b32 m0, s42
	s_nop 0
	global_load_lds_dwordx4 v[150:151], off
	v_lshl_add_u64 v[150:151], s[40:41], 0, v[134:135]
	s_add_i32 m0, s42, 0x2000
	s_nop 0
	global_load_lds_dwordx4 v[150:151], off
	s_waitcnt vmcnt(6)
	s_barrier
	s_setprio 1
	v_mfma_f32_16x16x32_bf16 v[52:55], v[198:201], v[166:169], v[52:55]
	v_mfma_f32_16x16x32_bf16 v[52:55], v[202:205], v[170:173], v[52:55]
	v_mfma_f32_16x16x32_bf16 v[48:51], v[210:213], v[170:173], v[48:51]
	v_mfma_f32_16x16x32_bf16 v[48:51], v[206:209], v[166:169], v[48:51]
	v_mfma_f32_16x16x32_bf16 v[32:35], v[206:209], v[174:177], v[32:35]
	v_mfma_f32_16x16x32_bf16 v[32:35], v[210:213], v[178:181], v[32:35]
	v_mfma_f32_16x16x32_bf16 v[36:39], v[202:205], v[178:181], v[36:39]
	v_mfma_f32_16x16x32_bf16 v[36:39], v[198:201], v[174:177], v[36:39]
	v_mfma_f32_16x16x32_bf16 v[20:23], v[198:201], v[182:185], v[20:23]
	v_mfma_f32_16x16x32_bf16 v[20:23], v[202:205], v[186:189], v[20:23]
	v_mfma_f32_16x16x32_bf16 v[16:19], v[210:213], v[186:189], v[16:19]
	v_mfma_f32_16x16x32_bf16 v[16:19], v[206:209], v[182:185], v[16:19]
	v_mfma_f32_16x16x32_bf16 v[0:3], v[206:209], v[190:193], v[0:3]
	v_mfma_f32_16x16x32_bf16 v[0:3], v[210:213], v[194:197], v[0:3]
	v_mfma_f32_16x16x32_bf16 v[4:7], v[202:205], v[194:197], v[4:7]
	v_mfma_f32_16x16x32_bf16 v[4:7], v[198:201], v[190:193], v[4:7]
	s_setprio 0
	s_add_u32 s8, s8, 0x100
	s_addc_u32 s9, s9, 0
	s_add_u32 s69, s69, 0x100
	s_addc_u32 s70, s70, 0
	s_cmp_ge_i32 s71, s52
	s_mov_b32 s40, s71
	s_barrier
	s_cbranch_scc0 .LBB0_1332
	s_branch .LBB0_1323

; #define PG8_STAGE(bufoff, gbase, voff) do { _Pragma("unroll") for (int _i = 0; _i < 2; ++_i) \
;         __builtin_amdgcn_global_load_lds((const unsigned*)((const char*)(gbase) + (voff)[_i]), (LAS unsigned*)(lds + (bufoff) + ldsw + _i * 8192), 16, 0, 0); } while (0)
; #define PG8_LDA(dst, b, h) do { _Pragma("unroll") for (int m = 0; m < 4; ++m) _Pragma("unroll") for (int k = 0; k < 2; ++k) dst[m][k] = *(const LAS bf16x8*)(lds + PG8_SA(b, h) + aoff + m * 2048 + k * 1024); } while (0)
; #define PG8_LDB(dst, b, h) do { _Pragma("unroll") for (int n = 0; n < 2; ++n) _Pragma("unroll") for (int k = 0; k < 2; ++k) dst[n][k] = *(const LAS bf16x8*)(lds + PG8_SB(b, h) + boff + n * 2048 + k * 1024); } while (0)
; #define PG8_MMA(ai, bj, At, Bt) do { __builtin_amdgcn_s_setprio(1); _Pragma("unroll") for (int m = 0; m < 4; ++m) _Pragma("unroll") for (int n = 0; n < 2; ++n) _Pragma("unroll") for (int k = 0; k < 2; ++k) \
;         acc[ai][bj][m][n] = __builtin_amdgcn_mfma_f32_16x16x32_bf16(Bt[n][k], At[m][k], acc[ai][bj][m][n], 0, 0, 0); __builtin_amdgcn_s_setprio(0); } while (0)
; #define PG8_WAIT_L(n) asm volatile("s_waitcnt lgkmcnt(" #n ")" ::: "memory")
; #define PG8_BAR __builtin_amdgcn_s_barrier()
; #define PG8_SCHED __builtin_amdgcn_sched_barrier(0)
; template <class Epi>
; DEVINL void gemm_phase(LAS unsigned char* lds, const Gemm g, const Order& S, const Epi& E) {
;     ...
;             const char* a1 = cA + (size_t)(t + 1) * kstep;
;             const char* a2 = last ? nA : cA + (size_t)(t + 2) * kstep; const char* b2 = last ? nB : cB + (size_t)(t + 2) * kstep;
;             const char* a3 = a2 + kstep; const char* b3 = b2 + kstep;
;             PG8_LDB(B0, 0, 0); PG8_SCHED; PG8_LDA(At, 0, 0); PG8_STAGE(PG8_SA(1, 1), a1 + hstepA, voffA);
;             PG8_WAIT_L(8); PG8_BAR; PG8_WAIT_L(0); PG8_MMA(0, 0, At, B0); PG8_BAR; PG8_SCHED;
;             PG8_LDB(B1, 0, 1); PG8_STAGE(PG8_SB(0, 0), b2, voffB);
;             PG8_BAR; PG8_WAIT_L(0); PG8_MMA(0, 1, At, B1); PG8_BAR;
;             PG8_LDA(At, 0, 1); PG8_STAGE(PG8_SA(0, 0), a2, voffA);
;             PG8_BAR; PG8_WAIT_L(0); PG8_MMA(1, 0, At, B0); PG8_BAR; PG8_SCHED;
.LBB0_1492:
	ds_read_b128 v[150:153], v147
	ds_read_b128 v[154:157], v147 offset:1024
	ds_read_b128 v[158:161], v147 offset:2048
	ds_read_b128 v[162:165], v147 offset:3072
	s_add_i32 s74, s42, 2
	s_add_u32 s43, s8, 0xfff80080
	s_addc_u32 s44, s9, -1
	s_cmp_eq_u32 s57, s42
	s_cselect_b32 s42, s37, s72
	s_cselect_b32 s45, s2, s44
	s_cselect_b32 s44, s3, s43
	s_cselect_b32 s43, s31, s73
	v_lshl_add_u64 v[198:199], s[8:9], 0, v[136:137]
	s_add_i32 m0, s29, 0xc000
	ds_read_b128 v[166:169], v148
	ds_read_b128 v[170:173], v148 offset:1024
	ds_read_b128 v[174:177], v148 offset:2048
	ds_read_b128 v[178:181], v148 offset:3072
	ds_read_b128 v[182:185], v148 offset:4096
	ds_read_b128 v[186:189], v148 offset:5120
	ds_read_b128 v[190:193], v148 offset:6144
	ds_read_b128 v[194:197], v148 offset:7168
	global_load_lds_dwordx4 v[198:199], off
	v_lshl_add_u64 v[198:199], s[8:9], 0, v[138:139]
	s_add_i32 m0, s29, 0xe000
	s_nop 0
	global_load_lds_dwordx4 v[198:199], off
	s_waitcnt lgkmcnt(8)
	s_barrier
	s_waitcnt lgkmcnt(0)
	s_setprio 1
	s_waitcnt lgkmcnt(0)
	v_mfma_f32_16x16x32_bf16 v[120:123], v[150:153], v[166:169], v[120:123]
	v_mfma_f32_16x16x32_bf16 v[120:123], v[154:157], v[170:173], v[120:123]
	v_mfma_f32_16x16x32_bf16 v[124:127], v[162:165], v[170:173], v[124:127]
	v_mfma_f32_16x16x32_bf16 v[124:127], v[158:161], v[166:169], v[124:127]
	v_mfma_f32_16x16x32_bf16 v[104:107], v[158:161], v[174:177], v[104:107]
	v_mfma_f32_16x16x32_bf16 v[104:107], v[162:165], v[178:181], v[104:107]
	v_mfma_f32_16x16x32_bf16 v[108:111], v[154:157], v[178:181], v[108:111]
	v_mfma_f32_16x16x32_bf16 v[108:111], v[150:153], v[174:177], v[108:111]
	v_mfma_f32_16x16x32_bf16 v[92:95], v[150:153], v[182:185], v[92:95]
	v_mfma_f32_16x16x32_bf16 v[92:95], v[154:157], v[186:189], v[92:95]
	v_mfma_f32_16x16x32_bf16 v[88:91], v[162:165], v[186:189], v[88:91]
	v_mfma_f32_16x16x32_bf16 v[88:91], v[158:161], v[182:185], v[88:91]
	v_mfma_f32_16x16x32_bf16 v[72:75], v[158:161], v[190:193], v[72:75]
	v_mfma_f32_16x16x32_bf16 v[72:75], v[162:165], v[194:197], v[72:75]
	v_mfma_f32_16x16x32_bf16 v[76:79], v[154:157], v[194:197], v[76:79]
	v_mfma_f32_16x16x32_bf16 v[76:79], v[150:153], v[190:193], v[76:79]
	s_setprio 0
	s_barrier
	s_add_i32 s75, s65, s50
	v_lshl_add_u64 v[218:219], s[42:43], 0, v[130:131]
	s_mov_b32 m0, s75
	ds_read_b128 v[198:201], v149
	ds_read_b128 v[202:205], v149 offset:1024
	ds_read_b128 v[206:209], v149 offset:2048
	ds_read_b128 v[210:213], v149 offset:3072
	global_load_lds_dwordx4 v[218:219], off
	v_lshl_add_u64 v[220:221], s[42:43], 0, v[134:135]
	s_add_i32 m0, s75, 0x2000
	s_nop 0
	global_load_lds_dwordx4 v[220:221], off
	s_barrier
	s_waitcnt lgkmcnt(0)
	s_setprio 1
	s_waitcnt lgkmcnt(0)
	v_mfma_f32_16x16x32_bf16 v[116:119], v[198:201], v[166:169], v[116:119]
	v_mfma_f32_16x16x32_bf16 v[116:119], v[202:205], v[170:173], v[116:119]
	v_mfma_f32_16x16x32_bf16 v[112:115], v[210:213], v[170:173], v[112:115]
	v_mfma_f32_16x16x32_bf16 v[112:115], v[206:209], v[166:169], v[112:115]
	v_mfma_f32_16x16x32_bf16 v[96:99], v[206:209], v[174:177], v[96:99]
	v_mfma_f32_16x16x32_bf16 v[96:99], v[210:213], v[178:181], v[96:99]
	v_mfma_f32_16x16x32_bf16 v[100:103], v[202:205], v[178:181], v[100:103]
	v_mfma_f32_16x16x32_bf16 v[100:103], v[198:201], v[174:177], v[100:103]
	v_mfma_f32_16x16x32_bf16 v[84:87], v[198:201], v[182:185], v[84:87]
	v_mfma_f32_16x16x32_bf16 v[84:87], v[202:205], v[186:189], v[84:87]
	v_mfma_f32_16x16x32_bf16 v[80:83], v[210:213], v[186:189], v[80:83]
	v_mfma_f32_16x16x32_bf16 v[80:83], v[206:209], v[182:185], v[80:83]
	v_mfma_f32_16x16x32_bf16 v[64:67], v[206:209], v[190:193], v[64:67]
	v_mfma_f32_16x16x32_bf16 v[64:67], v[210:213], v[194:197], v[64:67]
	v_mfma_f32_16x16x32_bf16 v[68:71], v[202:205], v[194:197], v[68:71]
	v_mfma_f32_16x16x32_bf16 v[68:71], v[198:201], v[190:193], v[68:71]
	s_setprio 0
	s_mov_b32 m0, s29
	v_lshl_add_u64 v[222:223], s[44:45], 0, v[128:129]
	s_barrier
	ds_read_b128 v[166:169], v148 offset:16384
	ds_read_b128 v[170:173], v148 offset:17408
	ds_read_b128 v[174:177], v148 offset:18432
	ds_read_b128 v[178:181], v148 offset:19456
	ds_read_b128 v[182:185], v148 offset:20480
	ds_read_b128 v[186:189], v148 offset:21504
	ds_read_b128 v[190:193], v148 offset:22528
	ds_read_b128 v[194:197], v148 offset:23552
	global_load_lds_dwordx4 v[222:223], off
	v_lshl_add_u64 v[224:225], s[44:45], 0, v[132:133]
	s_mov_b32 m0, s51
	s_nop 0
	global_load_lds_dwordx4 v[224:225], off
	s_barrier
	s_waitcnt lgkmcnt(0)
	s_setprio 1
	s_waitcnt lgkmcnt(0)
	v_mfma_f32_16x16x32_bf16 v[60:63], v[150:153], v[166:169], v[60:63]
	v_mfma_f32_16x16x32_bf16 v[60:63], v[154:157], v[170:173], v[60:63]
	v_mfma_f32_16x16x32_bf16 v[56:59], v[162:165], v[170:173], v[56:59]
	v_mfma_f32_16x16x32_bf16 v[56:59], v[158:161], v[166:169], v[56:59]
	v_mfma_f32_16x16x32_bf16 v[40:43], v[158:161], v[174:177], v[40:43]
	v_mfma_f32_16x16x32_bf16 v[40:43], v[162:165], v[178:181], v[40:43]
	v_mfma_f32_16x16x32_bf16 v[44:47], v[154:157], v[178:181], v[44:47]
	v_mfma_f32_16x16x32_bf16 v[44:47], v[150:153], v[174:177], v[44:47]
	v_mfma_f32_16x16x32_bf16 v[28:31], v[150:153], v[182:185], v[28:31]
	v_mfma_f32_16x16x32_bf16 v[28:31], v[154:157], v[186:189], v[28:31]
	v_mfma_f32_16x16x32_bf16 v[24:27], v[162:165], v[186:189], v[24:27]
	v_mfma_f32_16x16x32_bf16 v[24:27], v[158:161], v[182:185], v[24:27]
	v_mfma_f32_16x16x32_bf16 v[8:11], v[158:161], v[190:193], v[8:11]
	v_mfma_f32_16x16x32_bf16 v[8:11], v[162:165], v[194:197], v[8:11]
	v_mfma_f32_16x16x32_bf16 v[12:15], v[154:157], v[194:197], v[12:15]
	v_mfma_f32_16x16x32_bf16 v[12:15], v[150:153], v[190:193], v[12:15]
	s_setprio 0
	s_barrier
; #define PG8_STAGE(bufoff, gbase, voff) do { _Pragma("unroll") for (int _i = 0; _i < 2; ++_i) \
;         __builtin_amdgcn_global_load_lds((const unsigned*)((const char*)(gbase) + (voff)[_i]), (LAS unsigned*)(lds + (bufoff) + ldsw + _i * 8192), 16, 0, 0); } while (0)
; #define PG8_LDA(dst, b, h) do { _Pragma("unroll") for (int m = 0; m < 4; ++m) _Pragma("unroll") for (int k = 0; k < 2; ++k) dst[m][k] = *(const LAS bf16x8*)(lds + PG8_SA(b, h) + aoff + m * 2048 + k * 1024); } while (0)
; #define PG8_LDB(dst, b, h) do { _Pragma("unroll") for (int n = 0; n < 2; ++n) _Pragma("unroll") for (int k = 0; k < 2; ++k) dst[n][k] = *(const LAS bf16x8*)(lds + PG8_SB(b, h) + boff + n * 2048 + k * 1024); } while (0)
; #define PG8_MMA(ai, bj, At, Bt) do { __builtin_amdgcn_s_setprio(1); _Pragma("unroll") for (int m = 0; m < 4; ++m) _Pragma("unroll") for (int n = 0; n < 2; ++n) _Pragma("unroll") for (int k = 0; k < 2; ++k) \
;         acc[ai][bj][m][n] = __builtin_amdgcn_mfma_f32_16x16x32_bf16(Bt[n][k], At[m][k], acc[ai][bj][m][n], 0, 0, 0); __builtin_amdgcn_s_setprio(0); } while (0)
; #define PG8_WAIT_V(n) asm volatile("s_waitcnt vmcnt(" #n ")" ::: "memory")
; #define PG8_WAIT_L(n) asm volatile("s_waitcnt lgkmcnt(" #n ")" ::: "memory")
; #define PG8_BAR __builtin_amdgcn_s_barrier()
; #define PG8_SCHED __builtin_amdgcn_sched_barrier(0)
; template <class Epi>
; DEVINL void gemm_phase(LAS unsigned char* lds, const Gemm g, const Order& S, const Epi& E) {
;     ...
;             PG8_STAGE(PG8_SB(0, 1), b2 + hstepB, voffB);
;             PG8_WAIT_V(6); PG8_BAR; PG8_MMA(1, 1, At, B1); PG8_BAR;
;             PG8_LDB(B0, 1, 0); PG8_SCHED; PG8_LDA(At, 1, 0); PG8_STAGE(PG8_SA(0, 1), a2 + hstepA, voffA);
;             PG8_WAIT_L(8); PG8_BAR; PG8_WAIT_L(0); PG8_MMA(0, 0, At, B0); PG8_BAR; PG8_SCHED;
;             PG8_LDB(B1, 1, 1); PG8_STAGE(PG8_SB(1, 0), b3, voffB);
	s_add_u32 s76, s42, 0x80000
	s_addc_u32 s77, s43, 0
	s_add_i32 s75, s66, s50
	v_lshl_add_u64 v[150:151], s[76:77], 0, v[130:131]
	s_mov_b32 m0, s75
	s_nop 0
	global_load_lds_dwordx4 v[150:151], off
	v_lshl_add_u64 v[150:151], s[76:77], 0, v[134:135]
	s_add_i32 m0, s75, 0x2000
	s_nop 0
	global_load_lds_dwordx4 v[150:151], off
	s_waitcnt vmcnt(6)
	s_barrier
	s_setprio 1
	v_mfma_f32_16x16x32_bf16 v[52:55], v[198:201], v[166:169], v[52:55]
	v_mfma_f32_16x16x32_bf16 v[52:55], v[202:205], v[170:173], v[52:55]
	v_mfma_f32_16x16x32_bf16 v[48:51], v[210:213], v[170:173], v[48:51]
	v_mfma_f32_16x16x32_bf16 v[48:51], v[206:209], v[166:169], v[48:51]
	v_mfma_f32_16x16x32_bf16 v[32:35], v[206:209], v[174:177], v[32:35]
	v_mfma_f32_16x16x32_bf16 v[32:35], v[210:213], v[178:181], v[32:35]
	v_mfma_f32_16x16x32_bf16 v[36:39], v[202:205], v[178:181], v[36:39]
	v_mfma_f32_16x16x32_bf16 v[36:39], v[198:201], v[174:177], v[36:39]
	v_mfma_f32_16x16x32_bf16 v[20:23], v[198:201], v[182:185], v[20:23]
	v_mfma_f32_16x16x32_bf16 v[20:23], v[202:205], v[186:189], v[20:23]
	v_mfma_f32_16x16x32_bf16 v[16:19], v[210:213], v[186:189], v[16:19]
	v_mfma_f32_16x16x32_bf16 v[16:19], v[206:209], v[182:185], v[16:19]
	v_mfma_f32_16x16x32_bf16 v[0:3], v[206:209], v[190:193], v[0:3]
	v_mfma_f32_16x16x32_bf16 v[0:3], v[210:213], v[194:197], v[0:3]
	v_mfma_f32_16x16x32_bf16 v[4:7], v[202:205], v[194:197], v[4:7]
	v_mfma_f32_16x16x32_bf16 v[4:7], v[198:201], v[190:193], v[4:7]
	s_setprio 0
	s_add_i32 s75, 16, 0x18000
	v_add_u32_e32 v162, s75, v145
	s_barrier
	ds_read_b128 v[150:153], v162
	ds_read_b128 v[154:157], v162 offset:1024
	ds_read_b128 v[158:161], v162 offset:2048
	ds_read_b128 v[162:165], v162 offset:3072
	s_add_u32 s44, s44, 0x80000
	s_addc_u32 s45, s45, 0
	s_mov_b32 m0, s52
	v_lshl_add_u64 v[198:199], s[44:45], 0, v[128:129]
	ds_read_b128 v[166:169], v148 offset:32768
	ds_read_b128 v[170:173], v148 offset:33792
	ds_read_b128 v[174:177], v148 offset:34816
	ds_read_b128 v[178:181], v148 offset:35840
	ds_read_b128 v[182:185], v148 offset:36864
	ds_read_b128 v[186:189], v148 offset:37888
	ds_read_b128 v[190:193], v148 offset:38912
	ds_read_b128 v[194:197], v148 offset:39936
	global_load_lds_dwordx4 v[198:199], off
	v_lshl_add_u64 v[198:199], s[44:45], 0, v[132:133]
	s_mov_b32 m0, s53
	s_nop 0
	global_load_lds_dwordx4 v[198:199], off
	s_waitcnt lgkmcnt(8)
	s_barrier
	s_waitcnt lgkmcnt(0)
	s_setprio 1
	s_waitcnt lgkmcnt(0)
	v_mfma_f32_16x16x32_bf16 v[120:123], v[150:153], v[166:169], v[120:123]
	v_mfma_f32_16x16x32_bf16 v[120:123], v[154:157], v[170:173], v[120:123]
	v_mfma_f32_16x16x32_bf16 v[124:127], v[162:165], v[170:173], v[124:127]
	v_mfma_f32_16x16x32_bf16 v[124:127], v[158:161], v[166:169], v[124:127]
	v_mfma_f32_16x16x32_bf16 v[104:107], v[158:161], v[174:177], v[104:107]
	v_mfma_f32_16x16x32_bf16 v[104:107], v[162:165], v[178:181], v[104:107]
	v_mfma_f32_16x16x32_bf16 v[108:111], v[154:157], v[178:181], v[108:111]
	v_mfma_f32_16x16x32_bf16 v[108:111], v[150:153], v[174:177], v[108:111]
	v_mfma_f32_16x16x32_bf16 v[92:95], v[150:153], v[182:185], v[92:95]
	v_mfma_f32_16x16x32_bf16 v[92:95], v[154:157], v[186:189], v[92:95]
	v_mfma_f32_16x16x32_bf16 v[88:91], v[162:165], v[186:189], v[88:91]
	v_mfma_f32_16x16x32_bf16 v[88:91], v[158:161], v[182:185], v[88:91]
	v_mfma_f32_16x16x32_bf16 v[72:75], v[158:161], v[190:193], v[72:75]
	v_mfma_f32_16x16x32_bf16 v[72:75], v[162:165], v[194:197], v[72:75]
	v_mfma_f32_16x16x32_bf16 v[76:79], v[154:157], v[194:197], v[76:79]
	v_mfma_f32_16x16x32_bf16 v[76:79], v[150:153], v[190:193], v[76:79]
	s_setprio 0
	s_barrier
	s_add_i32 s44, 16, 0x1c000
	s_add_i32 s45, s75, s50
	v_add_u32_e32 v210, s44, v145
	v_lshl_add_u64 v[218:219], v[218:219], 0, s[6:7]
	s_mov_b32 m0, s45
	ds_read_b128 v[198:201], v210
	ds_read_b128 v[202:205], v210 offset:1024
	ds_read_b128 v[206:209], v210 offset:2048
	ds_read_b128 v[210:213], v210 offset:3072
	global_load_lds_dwordx4 v[218:219], off
	v_lshl_add_u64 v[218:219], v[220:221], 0, s[6:7]
	s_add_i32 m0, s45, 0x2000
	s_nop 0
	global_load_lds_dwordx4 v[218:219], off
	s_barrier
; #define PG8_STAGE(bufoff, gbase, voff) do { _Pragma("unroll") for (int _i = 0; _i < 2; ++_i) \
;         __builtin_amdgcn_global_load_lds((const unsigned*)((const char*)(gbase) + (voff)[_i]), (LAS unsigned*)(lds + (bufoff) + ldsw + _i * 8192), 16, 0, 0); } while (0)
; #define PG8_LDA(dst, b, h) do { _Pragma("unroll") for (int m = 0; m < 4; ++m) _Pragma("unroll") for (int k = 0; k < 2; ++k) dst[m][k] = *(const LAS bf16x8*)(lds + PG8_SA(b, h) + aoff + m * 2048 + k * 1024); } while (0)
; #define PG8_MMA(ai, bj, At, Bt) do { __builtin_amdgcn_s_setprio(1); _Pragma("unroll") for (int m = 0; m < 4; ++m) _Pragma("unroll") for (int n = 0; n < 2; ++n) _Pragma("unroll") for (int k = 0; k < 2; ++k) \
;         acc[ai][bj][m][n] = __builtin_amdgcn_mfma_f32_16x16x32_bf16(Bt[n][k], At[m][k], acc[ai][bj][m][n], 0, 0, 0); __builtin_amdgcn_s_setprio(0); } while (0)
; #define PG8_WAIT_V(n) asm volatile("s_waitcnt vmcnt(" #n ")" ::: "memory")
; #define PG8_WAIT_L(n) asm volatile("s_waitcnt lgkmcnt(" #n ")" ::: "memory")
; #define PG8_BAR __builtin_amdgcn_s_barrier()
; #define PG8_SCHED __builtin_amdgcn_sched_barrier(0)
; template <class Epi>
; DEVINL void gemm_phase(LAS unsigned char* lds, const Gemm g, const Order& S, const Epi& E) {
;     ...
;             PG8_BAR; PG8_WAIT_L(0); PG8_MMA(0, 1, At, B1); PG8_BAR;
;             PG8_LDA(At, 1, 1); PG8_STAGE(PG8_SA(1, 0), a3, voffA);
;             PG8_BAR; PG8_WAIT_L(0); PG8_MMA(1, 0, At, B0); PG8_BAR; PG8_SCHED;
;             PG8_STAGE(PG8_SB(1, 1), b3 + hstepB, voffB);
;             PG8_WAIT_V(6); PG8_BAR; PG8_MMA(1, 1, At, B1); PG8_BAR;
;         }
	s_waitcnt lgkmcnt(0)
	s_setprio 1
	s_waitcnt lgkmcnt(0)
	v_mfma_f32_16x16x32_bf16 v[116:119], v[198:201], v[166:169], v[116:119]
	v_mfma_f32_16x16x32_bf16 v[116:119], v[202:205], v[170:173], v[116:119]
	v_mfma_f32_16x16x32_bf16 v[112:115], v[210:213], v[170:173], v[112:115]
	v_mfma_f32_16x16x32_bf16 v[112:115], v[206:209], v[166:169], v[112:115]
	v_mfma_f32_16x16x32_bf16 v[96:99], v[206:209], v[174:177], v[96:99]
	v_mfma_f32_16x16x32_bf16 v[96:99], v[210:213], v[178:181], v[96:99]
	v_mfma_f32_16x16x32_bf16 v[100:103], v[202:205], v[178:181], v[100:103]
	v_mfma_f32_16x16x32_bf16 v[100:103], v[198:201], v[174:177], v[100:103]
	v_mfma_f32_16x16x32_bf16 v[84:87], v[198:201], v[182:185], v[84:87]
	v_mfma_f32_16x16x32_bf16 v[84:87], v[202:205], v[186:189], v[84:87]
	v_mfma_f32_16x16x32_bf16 v[80:83], v[210:213], v[186:189], v[80:83]
	v_mfma_f32_16x16x32_bf16 v[80:83], v[206:209], v[182:185], v[80:83]
	v_mfma_f32_16x16x32_bf16 v[64:67], v[206:209], v[190:193], v[64:67]
	v_mfma_f32_16x16x32_bf16 v[64:67], v[210:213], v[194:197], v[64:67]
	v_mfma_f32_16x16x32_bf16 v[68:71], v[202:205], v[194:197], v[68:71]
	v_mfma_f32_16x16x32_bf16 v[68:71], v[198:201], v[190:193], v[68:71]
	s_setprio 0
	s_mov_b32 m0, s55
	v_lshl_add_u64 v[218:219], v[222:223], 0, s[6:7]
	s_barrier
	ds_read_b128 v[166:169], v148 offset:49152
	ds_read_b128 v[170:173], v148 offset:50176
	ds_read_b128 v[174:177], v148 offset:51200
	ds_read_b128 v[178:181], v148 offset:52224
	ds_read_b128 v[182:185], v148 offset:53248
	ds_read_b128 v[186:189], v148 offset:54272
	ds_read_b128 v[190:193], v148 offset:55296
	ds_read_b128 v[194:197], v148 offset:56320
	global_load_lds_dwordx4 v[218:219], off
	v_lshl_add_u64 v[218:219], v[224:225], 0, s[6:7]
	s_mov_b32 m0, s56
	s_nop 0
	global_load_lds_dwordx4 v[218:219], off
	s_barrier
	s_waitcnt lgkmcnt(0)
	s_setprio 1
	s_waitcnt lgkmcnt(0)
	v_mfma_f32_16x16x32_bf16 v[60:63], v[150:153], v[166:169], v[60:63]
	v_mfma_f32_16x16x32_bf16 v[60:63], v[154:157], v[170:173], v[60:63]
	v_mfma_f32_16x16x32_bf16 v[56:59], v[162:165], v[170:173], v[56:59]
	v_mfma_f32_16x16x32_bf16 v[56:59], v[158:161], v[166:169], v[56:59]
	v_mfma_f32_16x16x32_bf16 v[40:43], v[158:161], v[174:177], v[40:43]
	v_mfma_f32_16x16x32_bf16 v[40:43], v[162:165], v[178:181], v[40:43]
	v_mfma_f32_16x16x32_bf16 v[44:47], v[154:157], v[178:181], v[44:47]
	v_mfma_f32_16x16x32_bf16 v[44:47], v[150:153], v[174:177], v[44:47]
	v_mfma_f32_16x16x32_bf16 v[28:31], v[150:153], v[182:185], v[28:31]
	v_mfma_f32_16x16x32_bf16 v[28:31], v[154:157], v[186:189], v[28:31]
	v_mfma_f32_16x16x32_bf16 v[24:27], v[162:165], v[186:189], v[24:27]
	v_mfma_f32_16x16x32_bf16 v[24:27], v[158:161], v[182:185], v[24:27]
	v_mfma_f32_16x16x32_bf16 v[8:11], v[158:161], v[190:193], v[8:11]
	v_mfma_f32_16x16x32_bf16 v[8:11], v[162:165], v[194:197], v[8:11]
	v_mfma_f32_16x16x32_bf16 v[12:15], v[154:157], v[194:197], v[12:15]
	v_mfma_f32_16x16x32_bf16 v[12:15], v[150:153], v[190:193], v[12:15]
	s_setprio 0
	s_barrier
	s_add_u32 s42, s42, 0x80080
	s_addc_u32 s43, s43, 0
	s_add_i32 s44, s44, s50
	v_lshl_add_u64 v[150:151], s[42:43], 0, v[130:131]
	s_mov_b32 m0, s44
	s_nop 0
	global_load_lds_dwordx4 v[150:151], off
	v_lshl_add_u64 v[150:151], s[42:43], 0, v[134:135]
	s_add_i32 m0, s44, 0x2000
	s_nop 0
	global_load_lds_dwordx4 v[150:151], off
	s_waitcnt vmcnt(6)
	s_barrier
	s_setprio 1
	v_mfma_f32_16x16x32_bf16 v[52:55], v[198:201], v[166:169], v[52:55]
	v_mfma_f32_16x16x32_bf16 v[52:55], v[202:205], v[170:173], v[52:55]
	v_mfma_f32_16x16x32_bf16 v[48:51], v[210:213], v[170:173], v[48:51]
	v_mfma_f32_16x16x32_bf16 v[48:51], v[206:209], v[166:169], v[48:51]
	v_mfma_f32_16x16x32_bf16 v[32:35], v[206:209], v[174:177], v[32:35]
	v_mfma_f32_16x16x32_bf16 v[32:35], v[210:213], v[178:181], v[32:35]
	v_mfma_f32_16x16x32_bf16 v[36:39], v[202:205], v[178:181], v[36:39]
	v_mfma_f32_16x16x32_bf16 v[36:39], v[198:201], v[174:177], v[36:39]
	v_mfma_f32_16x16x32_bf16 v[20:23], v[198:201], v[182:185], v[20:23]
	v_mfma_f32_16x16x32_bf16 v[20:23], v[202:205], v[186:189], v[20:23]
	v_mfma_f32_16x16x32_bf16 v[16:19], v[210:213], v[186:189], v[16:19]
	v_mfma_f32_16x16x32_bf16 v[16:19], v[206:209], v[182:185], v[16:19]
	v_mfma_f32_16x16x32_bf16 v[0:3], v[206:209], v[190:193], v[0:3]
	v_mfma_f32_16x16x32_bf16 v[0:3], v[210:213], v[194:197], v[0:3]
	v_mfma_f32_16x16x32_bf16 v[4:7], v[202:205], v[194:197], v[4:7]
	v_mfma_f32_16x16x32_bf16 v[4:7], v[198:201], v[190:193], v[4:7]
	s_setprio 0
	s_add_u32 s8, s8, 0x100
	s_addc_u32 s9, s9, 0
	s_add_u32 s72, s72, 0x100
	s_addc_u32 s73, s73, 0
	s_cmp_ge_i32 s74, s54
	s_mov_b32 s42, s74
	s_barrier
	s_cbranch_scc0 .LBB0_1492
	v_readlane_b32 s75, v250, 1
	s_branch .LBB0_1483

; #define PG8_STAGE(bufoff, gbase, voff) do { _Pragma("unroll") for (int _i = 0; _i < 2; ++_i) \
;         __builtin_amdgcn_global_load_lds((const unsigned*)((const char*)(gbase) + (voff)[_i]), (LAS unsigned*)(lds + (bufoff) + ldsw + _i * 8192), 16, 0, 0); } while (0)
; #define PG8_LDA(dst, b, h) do { _Pragma("unroll") for (int m = 0; m < 4; ++m) _Pragma("unroll") for (int k = 0; k < 2; ++k) dst[m][k] = *(const LAS bf16x8*)(lds + PG8_SA(b, h) + aoff + m * 2048 + k * 1024); } while (0)
; #define PG8_LDB(dst, b, h) do { _Pragma("unroll") for (int n = 0; n < 2; ++n) _Pragma("unroll") for (int k = 0; k < 2; ++k) dst[n][k] = *(const LAS bf16x8*)(lds + PG8_SB(b, h) + boff + n * 2048 + k * 1024); } while (0)
; #define PG8_MMA(ai, bj, At, Bt) do { __builtin_amdgcn_s_setprio(1); _Pragma("unroll") for (int m = 0; m < 4; ++m) _Pragma("unroll") for (int n = 0; n < 2; ++n) _Pragma("unroll") for (int k = 0; k < 2; ++k) \
;         acc[ai][bj][m][n] = __builtin_amdgcn_mfma_f32_16x16x32_bf16(Bt[n][k], At[m][k], acc[ai][bj][m][n], 0, 0, 0); __builtin_amdgcn_s_setprio(0); } while (0)
; #define PG8_WAIT_L(n) asm volatile("s_waitcnt lgkmcnt(" #n ")" ::: "memory")
; #define PG8_BAR __builtin_amdgcn_s_barrier()
; #define PG8_SCHED __builtin_amdgcn_sched_barrier(0)
; template <class Epi>
; DEVINL void gemm_phase(LAS unsigned char* lds, const Gemm g, const Order& S, const Epi& E) {
;     ...
;             const char* a1 = cA + (size_t)(t + 1) * kstep;
;             const char* a2 = last ? nA : cA + (size_t)(t + 2) * kstep; const char* b2 = last ? nB : cB + (size_t)(t + 2) * kstep;
;             const char* a3 = a2 + kstep; const char* b3 = b2 + kstep;
;             PG8_LDB(B0, 0, 0); PG8_SCHED; PG8_LDA(At, 0, 0); PG8_STAGE(PG8_SA(1, 1), a1 + hstepA, voffA);
;             PG8_WAIT_L(8); PG8_BAR; PG8_WAIT_L(0); PG8_MMA(0, 0, At, B0); PG8_BAR; PG8_SCHED;
;             PG8_LDB(B1, 0, 1); PG8_STAGE(PG8_SB(0, 0), b2, voffB);
;             PG8_BAR; PG8_WAIT_L(0); PG8_MMA(0, 1, At, B1); PG8_BAR;
;             PG8_LDA(At, 0, 1); PG8_STAGE(PG8_SA(0, 0), a2, voffA);
;             PG8_BAR; PG8_WAIT_L(0); PG8_MMA(1, 0, At, B0); PG8_BAR; PG8_SCHED;
.LBB0_1623:
	ds_read_b128 v[150:153], v147
	ds_read_b128 v[154:157], v147 offset:1024
	ds_read_b128 v[158:161], v147 offset:2048
	ds_read_b128 v[162:165], v147 offset:3072
	s_add_i32 s69, s38, 2
	s_add_u32 s39, s2, 0xfffc0080
	s_addc_u32 s40, s3, -1
	s_cmp_eq_u32 s52, s38
	s_cselect_b32 s38, s66, s67
	s_cselect_b32 s41, s27, s40
	s_cselect_b32 s40, s29, s39
	s_cselect_b32 s39, s65, s68
	v_lshl_add_u64 v[198:199], s[2:3], 0, v[136:137]
	s_add_i32 m0, s25, 0xc000
	ds_read_b128 v[166:169], v148
	ds_read_b128 v[170:173], v148 offset:1024
	ds_read_b128 v[174:177], v148 offset:2048
	ds_read_b128 v[178:181], v148 offset:3072
	ds_read_b128 v[182:185], v148 offset:4096
	ds_read_b128 v[186:189], v148 offset:5120
	ds_read_b128 v[190:193], v148 offset:6144
	ds_read_b128 v[194:197], v148 offset:7168
	global_load_lds_dwordx4 v[198:199], off
	v_lshl_add_u64 v[198:199], s[2:3], 0, v[138:139]
	s_add_i32 m0, s25, 0xe000
	s_nop 0
	global_load_lds_dwordx4 v[198:199], off
	s_waitcnt lgkmcnt(8)
	s_barrier
	s_waitcnt lgkmcnt(0)
	s_setprio 1
	s_waitcnt lgkmcnt(0)
	v_mfma_f32_16x16x32_bf16 v[120:123], v[150:153], v[166:169], v[120:123]
	v_mfma_f32_16x16x32_bf16 v[120:123], v[154:157], v[170:173], v[120:123]
	v_mfma_f32_16x16x32_bf16 v[124:127], v[162:165], v[170:173], v[124:127]
	v_mfma_f32_16x16x32_bf16 v[124:127], v[158:161], v[166:169], v[124:127]
	v_mfma_f32_16x16x32_bf16 v[104:107], v[158:161], v[174:177], v[104:107]
	v_mfma_f32_16x16x32_bf16 v[104:107], v[162:165], v[178:181], v[104:107]
	v_mfma_f32_16x16x32_bf16 v[108:111], v[154:157], v[178:181], v[108:111]
	v_mfma_f32_16x16x32_bf16 v[108:111], v[150:153], v[174:177], v[108:111]
	v_mfma_f32_16x16x32_bf16 v[92:95], v[150:153], v[182:185], v[92:95]
	v_mfma_f32_16x16x32_bf16 v[92:95], v[154:157], v[186:189], v[92:95]
	v_mfma_f32_16x16x32_bf16 v[88:91], v[162:165], v[186:189], v[88:91]
	v_mfma_f32_16x16x32_bf16 v[88:91], v[158:161], v[182:185], v[88:91]
	v_mfma_f32_16x16x32_bf16 v[72:75], v[158:161], v[190:193], v[72:75]
	v_mfma_f32_16x16x32_bf16 v[72:75], v[162:165], v[194:197], v[72:75]
	v_mfma_f32_16x16x32_bf16 v[76:79], v[154:157], v[194:197], v[76:79]
	v_mfma_f32_16x16x32_bf16 v[76:79], v[150:153], v[190:193], v[76:79]
	s_setprio 0
	s_barrier
	s_add_i32 s70, s58, s45
	v_lshl_add_u64 v[218:219], s[38:39], 0, v[130:131]
	s_mov_b32 m0, s70
	ds_read_b128 v[198:201], v149
	ds_read_b128 v[202:205], v149 offset:1024
	ds_read_b128 v[206:209], v149 offset:2048
	ds_read_b128 v[210:213], v149 offset:3072
	global_load_lds_dwordx4 v[218:219], off
	v_lshl_add_u64 v[220:221], s[38:39], 0, v[134:135]
	s_add_i32 m0, s70, 0x2000
	s_nop 0
	global_load_lds_dwordx4 v[220:221], off
	s_barrier
	s_waitcnt lgkmcnt(0)
	s_setprio 1
	s_waitcnt lgkmcnt(0)
	v_mfma_f32_16x16x32_bf16 v[116:119], v[198:201], v[166:169], v[116:119]
	v_mfma_f32_16x16x32_bf16 v[116:119], v[202:205], v[170:173], v[116:119]
	v_mfma_f32_16x16x32_bf16 v[112:115], v[210:213], v[170:173], v[112:115]
	v_mfma_f32_16x16x32_bf16 v[112:115], v[206:209], v[166:169], v[112:115]
	v_mfma_f32_16x16x32_bf16 v[96:99], v[206:209], v[174:177], v[96:99]
	v_mfma_f32_16x16x32_bf16 v[96:99], v[210:213], v[178:181], v[96:99]
	v_mfma_f32_16x16x32_bf16 v[100:103], v[202:205], v[178:181], v[100:103]
	v_mfma_f32_16x16x32_bf16 v[100:103], v[198:201], v[174:177], v[100:103]
	v_mfma_f32_16x16x32_bf16 v[84:87], v[198:201], v[182:185], v[84:87]
	v_mfma_f32_16x16x32_bf16 v[84:87], v[202:205], v[186:189], v[84:87]
	v_mfma_f32_16x16x32_bf16 v[80:83], v[210:213], v[186:189], v[80:83]
	v_mfma_f32_16x16x32_bf16 v[80:83], v[206:209], v[182:185], v[80:83]
	v_mfma_f32_16x16x32_bf16 v[64:67], v[206:209], v[190:193], v[64:67]
	v_mfma_f32_16x16x32_bf16 v[64:67], v[210:213], v[194:197], v[64:67]
	v_mfma_f32_16x16x32_bf16 v[68:71], v[202:205], v[194:197], v[68:71]
	v_mfma_f32_16x16x32_bf16 v[68:71], v[198:201], v[190:193], v[68:71]
	s_setprio 0
	s_mov_b32 m0, s25
	v_lshl_add_u64 v[222:223], s[40:41], 0, v[128:129]
	s_barrier
	ds_read_b128 v[166:169], v148 offset:16384
	ds_read_b128 v[170:173], v148 offset:17408
	ds_read_b128 v[174:177], v148 offset:18432
	ds_read_b128 v[178:181], v148 offset:19456
	ds_read_b128 v[182:185], v148 offset:20480
	ds_read_b128 v[186:189], v148 offset:21504
	ds_read_b128 v[190:193], v148 offset:22528
	ds_read_b128 v[194:197], v148 offset:23552
	global_load_lds_dwordx4 v[222:223], off
	v_lshl_add_u64 v[224:225], s[40:41], 0, v[132:133]
	s_mov_b32 m0, s46
	s_nop 0
	global_load_lds_dwordx4 v[224:225], off
	s_barrier
	s_waitcnt lgkmcnt(0)
	s_setprio 1
	s_waitcnt lgkmcnt(0)
	v_mfma_f32_16x16x32_bf16 v[60:63], v[150:153], v[166:169], v[60:63]
	v_mfma_f32_16x16x32_bf16 v[60:63], v[154:157], v[170:173], v[60:63]
	v_mfma_f32_16x16x32_bf16 v[56:59], v[162:165], v[170:173], v[56:59]
	v_mfma_f32_16x16x32_bf16 v[56:59], v[158:161], v[166:169], v[56:59]
	v_mfma_f32_16x16x32_bf16 v[40:43], v[158:161], v[174:177], v[40:43]
	v_mfma_f32_16x16x32_bf16 v[40:43], v[162:165], v[178:181], v[40:43]
	v_mfma_f32_16x16x32_bf16 v[44:47], v[154:157], v[178:181], v[44:47]
	v_mfma_f32_16x16x32_bf16 v[44:47], v[150:153], v[174:177], v[44:47]
	v_mfma_f32_16x16x32_bf16 v[28:31], v[150:153], v[182:185], v[28:31]
	v_mfma_f32_16x16x32_bf16 v[28:31], v[154:157], v[186:189], v[28:31]
	v_mfma_f32_16x16x32_bf16 v[24:27], v[162:165], v[186:189], v[24:27]
	v_mfma_f32_16x16x32_bf16 v[24:27], v[158:161], v[182:185], v[24:27]
	v_mfma_f32_16x16x32_bf16 v[8:11], v[158:161], v[190:193], v[8:11]
	v_mfma_f32_16x16x32_bf16 v[8:11], v[162:165], v[194:197], v[8:11]
	v_mfma_f32_16x16x32_bf16 v[12:15], v[154:157], v[194:197], v[12:15]
	v_mfma_f32_16x16x32_bf16 v[12:15], v[150:153], v[190:193], v[12:15]
	s_setprio 0
	s_barrier
; #define PG8_STAGE(bufoff, gbase, voff) do { _Pragma("unroll") for (int _i = 0; _i < 2; ++_i) \
;         __builtin_amdgcn_global_load_lds((const unsigned*)((const char*)(gbase) + (voff)[_i]), (LAS unsigned*)(lds + (bufoff) + ldsw + _i * 8192), 16, 0, 0); } while (0)
; #define PG8_LDA(dst, b, h) do { _Pragma("unroll") for (int m = 0; m < 4; ++m) _Pragma("unroll") for (int k = 0; k < 2; ++k) dst[m][k] = *(const LAS bf16x8*)(lds + PG8_SA(b, h) + aoff + m * 2048 + k * 1024); } while (0)
; #define PG8_LDB(dst, b, h) do { _Pragma("unroll") for (int n = 0; n < 2; ++n) _Pragma("unroll") for (int k = 0; k < 2; ++k) dst[n][k] = *(const LAS bf16x8*)(lds + PG8_SB(b, h) + boff + n * 2048 + k * 1024); } while (0)
; #define PG8_MMA(ai, bj, At, Bt) do { __builtin_amdgcn_s_setprio(1); _Pragma("unroll") for (int m = 0; m < 4; ++m) _Pragma("unroll") for (int n = 0; n < 2; ++n) _Pragma("unroll") for (int k = 0; k < 2; ++k) \
;         acc[ai][bj][m][n] = __builtin_amdgcn_mfma_f32_16x16x32_bf16(Bt[n][k], At[m][k], acc[ai][bj][m][n], 0, 0, 0); __builtin_amdgcn_s_setprio(0); } while (0)
; #define PG8_WAIT_V(n) asm volatile("s_waitcnt vmcnt(" #n ")" ::: "memory")
; #define PG8_WAIT_L(n) asm volatile("s_waitcnt lgkmcnt(" #n ")" ::: "memory")
; #define PG8_BAR __builtin_amdgcn_s_barrier()
; #define PG8_SCHED __builtin_amdgcn_sched_barrier(0)
; template <class Epi>
; DEVINL void gemm_phase(LAS unsigned char* lds, const Gemm g, const Order& S, const Epi& E) {
;     ...
;             PG8_STAGE(PG8_SB(0, 1), b2 + hstepB, voffB);
;             PG8_WAIT_V(6); PG8_BAR; PG8_MMA(1, 1, At, B1); PG8_BAR;
;             PG8_LDB(B0, 1, 0); PG8_SCHED; PG8_LDA(At, 1, 0); PG8_STAGE(PG8_SA(0, 1), a2 + hstepA, voffA);
;             PG8_WAIT_L(8); PG8_BAR; PG8_WAIT_L(0); PG8_MMA(0, 0, At, B0); PG8_BAR; PG8_SCHED;
;             PG8_LDB(B1, 1, 1); PG8_STAGE(PG8_SB(1, 0), b3, voffB);
	s_add_u32 s70, s38, 0x40000
	s_addc_u32 s71, s39, 0
	s_add_i32 s72, s59, s45
	v_lshl_add_u64 v[150:151], s[70:71], 0, v[130:131]
	s_mov_b32 m0, s72
	s_nop 0
	global_load_lds_dwordx4 v[150:151], off
	v_lshl_add_u64 v[150:151], s[70:71], 0, v[134:135]
	s_add_i32 m0, s72, 0x2000
	s_nop 0
	global_load_lds_dwordx4 v[150:151], off
	s_waitcnt vmcnt(6)
	s_barrier
	s_setprio 1
	v_mfma_f32_16x16x32_bf16 v[52:55], v[198:201], v[166:169], v[52:55]
	v_mfma_f32_16x16x32_bf16 v[52:55], v[202:205], v[170:173], v[52:55]
	v_mfma_f32_16x16x32_bf16 v[48:51], v[210:213], v[170:173], v[48:51]
	v_mfma_f32_16x16x32_bf16 v[48:51], v[206:209], v[166:169], v[48:51]
	v_mfma_f32_16x16x32_bf16 v[32:35], v[206:209], v[174:177], v[32:35]
	v_mfma_f32_16x16x32_bf16 v[32:35], v[210:213], v[178:181], v[32:35]
	v_mfma_f32_16x16x32_bf16 v[36:39], v[202:205], v[178:181], v[36:39]
	v_mfma_f32_16x16x32_bf16 v[36:39], v[198:201], v[174:177], v[36:39]
	v_mfma_f32_16x16x32_bf16 v[20:23], v[198:201], v[182:185], v[20:23]
	v_mfma_f32_16x16x32_bf16 v[20:23], v[202:205], v[186:189], v[20:23]
	v_mfma_f32_16x16x32_bf16 v[16:19], v[210:213], v[186:189], v[16:19]
	v_mfma_f32_16x16x32_bf16 v[16:19], v[206:209], v[182:185], v[16:19]
	v_mfma_f32_16x16x32_bf16 v[0:3], v[206:209], v[190:193], v[0:3]
	v_mfma_f32_16x16x32_bf16 v[0:3], v[210:213], v[194:197], v[0:3]
	v_mfma_f32_16x16x32_bf16 v[4:7], v[202:205], v[194:197], v[4:7]
	v_mfma_f32_16x16x32_bf16 v[4:7], v[198:201], v[190:193], v[4:7]
	s_setprio 0
	s_add_i32 s70, 16, 0x18000
	v_add_u32_e32 v162, s70, v145
	s_barrier
	ds_read_b128 v[150:153], v162
	ds_read_b128 v[154:157], v162 offset:1024
	ds_read_b128 v[158:161], v162 offset:2048
	ds_read_b128 v[162:165], v162 offset:3072
	s_add_u32 s40, s40, 0x40000
	s_addc_u32 s41, s41, 0
	s_mov_b32 m0, s47
	v_lshl_add_u64 v[198:199], s[40:41], 0, v[128:129]
	ds_read_b128 v[166:169], v148 offset:32768
	ds_read_b128 v[170:173], v148 offset:33792
	ds_read_b128 v[174:177], v148 offset:34816
	ds_read_b128 v[178:181], v148 offset:35840
	ds_read_b128 v[182:185], v148 offset:36864
	ds_read_b128 v[186:189], v148 offset:37888
	ds_read_b128 v[190:193], v148 offset:38912
	ds_read_b128 v[194:197], v148 offset:39936
	global_load_lds_dwordx4 v[198:199], off
	v_lshl_add_u64 v[198:199], s[40:41], 0, v[132:133]
	s_mov_b32 m0, s48
	s_nop 0
	global_load_lds_dwordx4 v[198:199], off
	s_waitcnt lgkmcnt(8)
	s_barrier
	s_waitcnt lgkmcnt(0)
	s_setprio 1
	s_waitcnt lgkmcnt(0)
	v_mfma_f32_16x16x32_bf16 v[120:123], v[150:153], v[166:169], v[120:123]
	v_mfma_f32_16x16x32_bf16 v[120:123], v[154:157], v[170:173], v[120:123]
	v_mfma_f32_16x16x32_bf16 v[124:127], v[162:165], v[170:173], v[124:127]
	v_mfma_f32_16x16x32_bf16 v[124:127], v[158:161], v[166:169], v[124:127]
	v_mfma_f32_16x16x32_bf16 v[104:107], v[158:161], v[174:177], v[104:107]
	v_mfma_f32_16x16x32_bf16 v[104:107], v[162:165], v[178:181], v[104:107]
	v_mfma_f32_16x16x32_bf16 v[108:111], v[154:157], v[178:181], v[108:111]
	v_mfma_f32_16x16x32_bf16 v[108:111], v[150:153], v[174:177], v[108:111]
	v_mfma_f32_16x16x32_bf16 v[92:95], v[150:153], v[182:185], v[92:95]
	v_mfma_f32_16x16x32_bf16 v[92:95], v[154:157], v[186:189], v[92:95]
	v_mfma_f32_16x16x32_bf16 v[88:91], v[162:165], v[186:189], v[88:91]
	v_mfma_f32_16x16x32_bf16 v[88:91], v[158:161], v[182:185], v[88:91]
	v_mfma_f32_16x16x32_bf16 v[72:75], v[158:161], v[190:193], v[72:75]
	v_mfma_f32_16x16x32_bf16 v[72:75], v[162:165], v[194:197], v[72:75]
	v_mfma_f32_16x16x32_bf16 v[76:79], v[154:157], v[194:197], v[76:79]
	v_mfma_f32_16x16x32_bf16 v[76:79], v[150:153], v[190:193], v[76:79]
	s_setprio 0
	s_barrier
	s_add_i32 s40, 16, 0x1c000
	s_add_i32 s41, s70, s45
	v_add_u32_e32 v210, s40, v145
	v_lshl_add_u64 v[218:219], v[218:219], 0, s[6:7]
	s_mov_b32 m0, s41
	ds_read_b128 v[198:201], v210
	ds_read_b128 v[202:205], v210 offset:1024
	ds_read_b128 v[206:209], v210 offset:2048
	ds_read_b128 v[210:213], v210 offset:3072
	global_load_lds_dwordx4 v[218:219], off
	v_lshl_add_u64 v[218:219], v[220:221], 0, s[6:7]
	s_add_i32 m0, s41, 0x2000
	s_nop 0
	global_load_lds_dwordx4 v[218:219], off
	s_barrier
; #define PG8_STAGE(bufoff, gbase, voff) do { _Pragma("unroll") for (int _i = 0; _i < 2; ++_i) \
;         __builtin_amdgcn_global_load_lds((const unsigned*)((const char*)(gbase) + (voff)[_i]), (LAS unsigned*)(lds + (bufoff) + ldsw + _i * 8192), 16, 0, 0); } while (0)
; #define PG8_LDA(dst, b, h) do { _Pragma("unroll") for (int m = 0; m < 4; ++m) _Pragma("unroll") for (int k = 0; k < 2; ++k) dst[m][k] = *(const LAS bf16x8*)(lds + PG8_SA(b, h) + aoff + m * 2048 + k * 1024); } while (0)
; #define PG8_LDB(dst, b, h) do { _Pragma("unroll") for (int n = 0; n < 2; ++n) _Pragma("unroll") for (int k = 0; k < 2; ++k) dst[n][k] = *(const LAS bf16x8*)(lds + PG8_SB(b, h) + boff + n * 2048 + k * 1024); } while (0)
; #define PG8_MMA(ai, bj, At, Bt) do { __builtin_amdgcn_s_setprio(1); _Pragma("unroll") for (int m = 0; m < 4; ++m) _Pragma("unroll") for (int n = 0; n < 2; ++n) _Pragma("unroll") for (int k = 0; k < 2; ++k) \
;         acc[ai][bj][m][n] = __builtin_amdgcn_mfma_f32_16x16x32_bf16(Bt[n][k], At[m][k], acc[ai][bj][m][n], 0, 0, 0); __builtin_amdgcn_s_setprio(0); } while (0)
; #define PG8_WAIT_V(n) asm volatile("s_waitcnt vmcnt(" #n ")" ::: "memory")
; #define PG8_WAIT_L(n) asm volatile("s_waitcnt lgkmcnt(" #n ")" ::: "memory")
; #define PG8_BAR __builtin_amdgcn_s_barrier()
; #define PG8_SCHED __builtin_amdgcn_sched_barrier(0)
; template <class Epi>
; DEVINL void gemm_phase(LAS unsigned char* lds, const Gemm g, const Order& S, const Epi& E) {
;     ...
;         for (int t = 0; t < nt; t += 2) {
;     ...
;             PG8_LDB(B1, 1, 1); PG8_STAGE(PG8_SB(1, 0), b3, voffB);
;             PG8_BAR; PG8_WAIT_L(0); PG8_MMA(0, 1, At, B1); PG8_BAR;
;             PG8_LDA(At, 1, 1); PG8_STAGE(PG8_SA(1, 0), a3, voffA);
;             PG8_BAR; PG8_WAIT_L(0); PG8_MMA(1, 0, At, B0); PG8_BAR; PG8_SCHED;
;             PG8_STAGE(PG8_SB(1, 1), b3 + hstepB, voffB);
;             PG8_WAIT_V(6); PG8_BAR; PG8_MMA(1, 1, At, B1); PG8_BAR;
	s_waitcnt lgkmcnt(0)
	s_setprio 1
	s_waitcnt lgkmcnt(0)
	v_mfma_f32_16x16x32_bf16 v[116:119], v[198:201], v[166:169], v[116:119]
	v_mfma_f32_16x16x32_bf16 v[116:119], v[202:205], v[170:173], v[116:119]
	v_mfma_f32_16x16x32_bf16 v[112:115], v[210:213], v[170:173], v[112:115]
	v_mfma_f32_16x16x32_bf16 v[112:115], v[206:209], v[166:169], v[112:115]
	v_mfma_f32_16x16x32_bf16 v[96:99], v[206:209], v[174:177], v[96:99]
	v_mfma_f32_16x16x32_bf16 v[96:99], v[210:213], v[178:181], v[96:99]
	v_mfma_f32_16x16x32_bf16 v[100:103], v[202:205], v[178:181], v[100:103]
	v_mfma_f32_16x16x32_bf16 v[100:103], v[198:201], v[174:177], v[100:103]
	v_mfma_f32_16x16x32_bf16 v[84:87], v[198:201], v[182:185], v[84:87]
	v_mfma_f32_16x16x32_bf16 v[84:87], v[202:205], v[186:189], v[84:87]
	v_mfma_f32_16x16x32_bf16 v[80:83], v[210:213], v[186:189], v[80:83]
	v_mfma_f32_16x16x32_bf16 v[80:83], v[206:209], v[182:185], v[80:83]
	v_mfma_f32_16x16x32_bf16 v[64:67], v[206:209], v[190:193], v[64:67]
	v_mfma_f32_16x16x32_bf16 v[64:67], v[210:213], v[194:197], v[64:67]
	v_mfma_f32_16x16x32_bf16 v[68:71], v[202:205], v[194:197], v[68:71]
	v_mfma_f32_16x16x32_bf16 v[68:71], v[198:201], v[190:193], v[68:71]
	s_setprio 0
	s_mov_b32 m0, s50
	v_lshl_add_u64 v[218:219], v[222:223], 0, s[6:7]
	s_barrier
	ds_read_b128 v[166:169], v148 offset:49152
	ds_read_b128 v[170:173], v148 offset:50176
	ds_read_b128 v[174:177], v148 offset:51200
	ds_read_b128 v[178:181], v148 offset:52224
	ds_read_b128 v[182:185], v148 offset:53248
	ds_read_b128 v[186:189], v148 offset:54272
	ds_read_b128 v[190:193], v148 offset:55296
	ds_read_b128 v[194:197], v148 offset:56320
	global_load_lds_dwordx4 v[218:219], off
	v_lshl_add_u64 v[218:219], v[224:225], 0, s[6:7]
	s_mov_b32 m0, s51
	s_nop 0
	global_load_lds_dwordx4 v[218:219], off
	s_barrier
	s_waitcnt lgkmcnt(0)
	s_setprio 1
	s_waitcnt lgkmcnt(0)
	v_mfma_f32_16x16x32_bf16 v[60:63], v[150:153], v[166:169], v[60:63]
	v_mfma_f32_16x16x32_bf16 v[60:63], v[154:157], v[170:173], v[60:63]
	v_mfma_f32_16x16x32_bf16 v[56:59], v[162:165], v[170:173], v[56:59]
	v_mfma_f32_16x16x32_bf16 v[56:59], v[158:161], v[166:169], v[56:59]
	v_mfma_f32_16x16x32_bf16 v[40:43], v[158:161], v[174:177], v[40:43]
	v_mfma_f32_16x16x32_bf16 v[40:43], v[162:165], v[178:181], v[40:43]
	v_mfma_f32_16x16x32_bf16 v[44:47], v[154:157], v[178:181], v[44:47]
	v_mfma_f32_16x16x32_bf16 v[44:47], v[150:153], v[174:177], v[44:47]
	v_mfma_f32_16x16x32_bf16 v[28:31], v[150:153], v[182:185], v[28:31]
	v_mfma_f32_16x16x32_bf16 v[28:31], v[154:157], v[186:189], v[28:31]
	v_mfma_f32_16x16x32_bf16 v[24:27], v[162:165], v[186:189], v[24:27]
	v_mfma_f32_16x16x32_bf16 v[24:27], v[158:161], v[182:185], v[24:27]
	v_mfma_f32_16x16x32_bf16 v[8:11], v[158:161], v[190:193], v[8:11]
	v_mfma_f32_16x16x32_bf16 v[8:11], v[162:165], v[194:197], v[8:11]
	v_mfma_f32_16x16x32_bf16 v[12:15], v[154:157], v[194:197], v[12:15]
	v_mfma_f32_16x16x32_bf16 v[12:15], v[150:153], v[190:193], v[12:15]
	s_setprio 0
	s_barrier
	s_add_u32 s38, s38, 0x40080
	s_addc_u32 s39, s39, 0
	s_add_i32 s40, s40, s45
	v_lshl_add_u64 v[150:151], s[38:39], 0, v[130:131]
	s_mov_b32 m0, s40
	s_nop 0
	global_load_lds_dwordx4 v[150:151], off
	v_lshl_add_u64 v[150:151], s[38:39], 0, v[134:135]
	s_add_i32 m0, s40, 0x2000
	s_nop 0
	global_load_lds_dwordx4 v[150:151], off
	s_waitcnt vmcnt(6)
	s_barrier
	s_setprio 1
	v_mfma_f32_16x16x32_bf16 v[52:55], v[198:201], v[166:169], v[52:55]
	v_mfma_f32_16x16x32_bf16 v[52:55], v[202:205], v[170:173], v[52:55]
	v_mfma_f32_16x16x32_bf16 v[48:51], v[210:213], v[170:173], v[48:51]
	v_mfma_f32_16x16x32_bf16 v[48:51], v[206:209], v[166:169], v[48:51]
	v_mfma_f32_16x16x32_bf16 v[32:35], v[206:209], v[174:177], v[32:35]
	v_mfma_f32_16x16x32_bf16 v[32:35], v[210:213], v[178:181], v[32:35]
	v_mfma_f32_16x16x32_bf16 v[36:39], v[202:205], v[178:181], v[36:39]
	v_mfma_f32_16x16x32_bf16 v[36:39], v[198:201], v[174:177], v[36:39]
	v_mfma_f32_16x16x32_bf16 v[20:23], v[198:201], v[182:185], v[20:23]
	v_mfma_f32_16x16x32_bf16 v[20:23], v[202:205], v[186:189], v[20:23]
	v_mfma_f32_16x16x32_bf16 v[16:19], v[210:213], v[186:189], v[16:19]
	v_mfma_f32_16x16x32_bf16 v[16:19], v[206:209], v[182:185], v[16:19]
	v_mfma_f32_16x16x32_bf16 v[0:3], v[206:209], v[190:193], v[0:3]
	v_mfma_f32_16x16x32_bf16 v[0:3], v[210:213], v[194:197], v[0:3]
	v_mfma_f32_16x16x32_bf16 v[4:7], v[202:205], v[194:197], v[4:7]
	v_mfma_f32_16x16x32_bf16 v[4:7], v[198:201], v[190:193], v[4:7]
	s_setprio 0
	s_add_u32 s2, s2, 0x100
	s_addc_u32 s3, s3, 0
	s_add_u32 s67, s67, 0x100
	s_addc_u32 s68, s68, 0
	s_cmp_ge_i32 s69, s49
	s_mov_b32 s38, s69
	s_barrier
	s_cbranch_scc0 .LBB0_1623
	s_branch .LBB0_1614

; #define PG8_STAGE(bufoff, gbase, voff) do { _Pragma("unroll") for (int _i = 0; _i < 2; ++_i) \
;         __builtin_amdgcn_global_load_lds((const unsigned*)((const char*)(gbase) + (voff)[_i]), (LAS unsigned*)(lds + (bufoff) + ldsw + _i * 8192), 16, 0, 0); } while (0)
; #define PG8_LDA(dst, b, h) do { _Pragma("unroll") for (int m = 0; m < 4; ++m) _Pragma("unroll") for (int k = 0; k < 2; ++k) dst[m][k] = *(const LAS bf16x8*)(lds + PG8_SA(b, h) + aoff + m * 2048 + k * 1024); } while (0)
; #define PG8_LDB(dst, b, h) do { _Pragma("unroll") for (int n = 0; n < 2; ++n) _Pragma("unroll") for (int k = 0; k < 2; ++k) dst[n][k] = *(const LAS bf16x8*)(lds + PG8_SB(b, h) + boff + n * 2048 + k * 1024); } while (0)
; #define PG8_MMA(ai, bj, At, Bt) do { __builtin_amdgcn_s_setprio(1); _Pragma("unroll") for (int m = 0; m < 4; ++m) _Pragma("unroll") for (int n = 0; n < 2; ++n) _Pragma("unroll") for (int k = 0; k < 2; ++k) \
;         acc[ai][bj][m][n] = __builtin_amdgcn_mfma_f32_16x16x32_bf16(Bt[n][k], At[m][k], acc[ai][bj][m][n], 0, 0, 0); __builtin_amdgcn_s_setprio(0); } while (0)
; #define PG8_WAIT_L(n) asm volatile("s_waitcnt lgkmcnt(" #n ")" ::: "memory")
; #define PG8_BAR __builtin_amdgcn_s_barrier()
; #define PG8_SCHED __builtin_amdgcn_sched_barrier(0)
; template <class Epi>
; DEVINL void gemm_phase(LAS unsigned char* lds, const Gemm g, const Order& S, const Epi& E) {
;     ...
;             const char* a1 = cA + (size_t)(t + 1) * kstep;
;             const char* a2 = last ? nA : cA + (size_t)(t + 2) * kstep; const char* b2 = last ? nB : cB + (size_t)(t + 2) * kstep;
;             const char* a3 = a2 + kstep; const char* b3 = b2 + kstep;
;             PG8_LDB(B0, 0, 0); PG8_SCHED; PG8_LDA(At, 0, 0); PG8_STAGE(PG8_SA(1, 1), a1 + hstepA, voffA);
;             PG8_WAIT_L(8); PG8_BAR; PG8_WAIT_L(0); PG8_MMA(0, 0, At, B0); PG8_BAR; PG8_SCHED;
;             PG8_LDB(B1, 0, 1); PG8_STAGE(PG8_SB(0, 0), b2, voffB);
;             PG8_BAR; PG8_WAIT_L(0); PG8_MMA(0, 1, At, B1); PG8_BAR;
;             PG8_LDA(At, 0, 1); PG8_STAGE(PG8_SA(0, 0), a2, voffA);
;             PG8_BAR; PG8_WAIT_L(0); PG8_MMA(1, 0, At, B0); PG8_BAR; PG8_SCHED;
.LBB0_1775:
	ds_read_b128 v[152:155], v149
	ds_read_b128 v[156:159], v149 offset:1024
	ds_read_b128 v[160:163], v149 offset:2048
	ds_read_b128 v[164:167], v149 offset:3072
	s_add_i32 s55, s26, 2
	s_add_u32 s27, s24, 0xfff80080
	s_addc_u32 s28, s25, -1
	s_cmp_eq_u32 s44, s26
	s_cselect_b32 s26, s52, s53
	s_cselect_b32 s29, s9, s28
	s_cselect_b32 s28, s11, s27
	s_cselect_b32 s27, s51, s54
	v_lshl_add_u64 v[144:145], s[24:25], 0, v[136:137]
	s_add_i32 m0, s17, 0xc000
	ds_read_b128 v[168:171], v150
	ds_read_b128 v[172:175], v150 offset:1024
	ds_read_b128 v[176:179], v150 offset:2048
	ds_read_b128 v[180:183], v150 offset:3072
	ds_read_b128 v[184:187], v150 offset:4096
	ds_read_b128 v[188:191], v150 offset:5120
	ds_read_b128 v[192:195], v150 offset:6144
	ds_read_b128 v[196:199], v150 offset:7168
	global_load_lds_dwordx4 v[144:145], off
	v_lshl_add_u64 v[144:145], s[24:25], 0, v[138:139]
	s_add_i32 m0, s17, 0xe000
	s_nop 0
	global_load_lds_dwordx4 v[144:145], off
	s_waitcnt lgkmcnt(8)
	s_barrier
	s_waitcnt lgkmcnt(0)
	s_setprio 1
	s_waitcnt lgkmcnt(0)
	v_mfma_f32_16x16x32_bf16 v[124:127], v[152:155], v[168:171], v[124:127]
	v_mfma_f32_16x16x32_bf16 v[124:127], v[156:159], v[172:175], v[124:127]
	v_mfma_f32_16x16x32_bf16 v[116:119], v[164:167], v[172:175], v[116:119]
	v_mfma_f32_16x16x32_bf16 v[116:119], v[160:163], v[168:171], v[116:119]
	v_mfma_f32_16x16x32_bf16 v[100:103], v[160:163], v[176:179], v[100:103]
	v_mfma_f32_16x16x32_bf16 v[100:103], v[164:167], v[180:183], v[100:103]
	v_mfma_f32_16x16x32_bf16 v[108:111], v[156:159], v[180:183], v[108:111]
	v_mfma_f32_16x16x32_bf16 v[108:111], v[152:155], v[176:179], v[108:111]
	v_mfma_f32_16x16x32_bf16 v[92:95], v[152:155], v[184:187], v[92:95]
	v_mfma_f32_16x16x32_bf16 v[92:95], v[156:159], v[188:191], v[92:95]
	v_mfma_f32_16x16x32_bf16 v[84:87], v[164:167], v[188:191], v[84:87]
	v_mfma_f32_16x16x32_bf16 v[84:87], v[160:163], v[184:187], v[84:87]
	v_mfma_f32_16x16x32_bf16 v[68:71], v[160:163], v[192:195], v[68:71]
	v_mfma_f32_16x16x32_bf16 v[68:71], v[164:167], v[196:199], v[68:71]
	v_mfma_f32_16x16x32_bf16 v[76:79], v[156:159], v[196:199], v[76:79]
	v_mfma_f32_16x16x32_bf16 v[76:79], v[152:155], v[192:195], v[76:79]
	s_setprio 0
	s_barrier
	s_add_i32 s56, s47, s30
	v_lshl_add_u64 v[144:145], s[26:27], 0, v[132:133]
	s_mov_b32 m0, s56
	ds_read_b128 v[200:203], v151
	ds_read_b128 v[204:207], v151 offset:1024
	ds_read_b128 v[208:211], v151 offset:2048
	ds_read_b128 v[218:221], v151 offset:3072
	global_load_lds_dwordx4 v[144:145], off
	v_lshl_add_u64 v[212:213], s[26:27], 0, v[128:129]
	s_add_i32 m0, s56, 0x2000
	s_nop 0
	global_load_lds_dwordx4 v[212:213], off
	s_barrier
	s_waitcnt lgkmcnt(0)
	s_setprio 1
	s_waitcnt lgkmcnt(0)
	v_mfma_f32_16x16x32_bf16 v[120:123], v[200:203], v[168:171], v[120:123]
	v_mfma_f32_16x16x32_bf16 v[120:123], v[204:207], v[172:175], v[120:123]
	v_mfma_f32_16x16x32_bf16 v[112:115], v[218:221], v[172:175], v[112:115]
	v_mfma_f32_16x16x32_bf16 v[112:115], v[208:211], v[168:171], v[112:115]
	v_mfma_f32_16x16x32_bf16 v[96:99], v[208:211], v[176:179], v[96:99]
	v_mfma_f32_16x16x32_bf16 v[96:99], v[218:221], v[180:183], v[96:99]
	v_mfma_f32_16x16x32_bf16 v[104:107], v[204:207], v[180:183], v[104:107]
	v_mfma_f32_16x16x32_bf16 v[104:107], v[200:203], v[176:179], v[104:107]
	v_mfma_f32_16x16x32_bf16 v[88:91], v[200:203], v[184:187], v[88:91]
	v_mfma_f32_16x16x32_bf16 v[88:91], v[204:207], v[188:191], v[88:91]
	v_mfma_f32_16x16x32_bf16 v[80:83], v[218:221], v[188:191], v[80:83]
	v_mfma_f32_16x16x32_bf16 v[80:83], v[208:211], v[184:187], v[80:83]
	v_mfma_f32_16x16x32_bf16 v[64:67], v[208:211], v[192:195], v[64:67]
	v_mfma_f32_16x16x32_bf16 v[64:67], v[218:221], v[196:199], v[64:67]
	v_mfma_f32_16x16x32_bf16 v[72:75], v[204:207], v[196:199], v[72:75]
	v_mfma_f32_16x16x32_bf16 v[72:75], v[200:203], v[192:195], v[72:75]
	s_setprio 0
	s_mov_b32 m0, s17
	v_lshl_add_u64 v[222:223], s[28:29], 0, v[134:135]
	s_barrier
	ds_read_b128 v[168:171], v150 offset:16384
	ds_read_b128 v[172:175], v150 offset:17408
	ds_read_b128 v[176:179], v150 offset:18432
	ds_read_b128 v[180:183], v150 offset:19456
	ds_read_b128 v[184:187], v150 offset:20480
	ds_read_b128 v[188:191], v150 offset:21504
	ds_read_b128 v[192:195], v150 offset:22528
	ds_read_b128 v[196:199], v150 offset:23552
	global_load_lds_dwordx4 v[222:223], off
	v_lshl_add_u64 v[224:225], s[28:29], 0, v[130:131]
	s_mov_b32 m0, s37
	s_nop 0
	global_load_lds_dwordx4 v[224:225], off
	s_barrier
	s_waitcnt lgkmcnt(0)
	s_setprio 1
	s_waitcnt lgkmcnt(0)
	v_mfma_f32_16x16x32_bf16 v[60:63], v[152:155], v[168:171], v[60:63]
	v_mfma_f32_16x16x32_bf16 v[60:63], v[156:159], v[172:175], v[60:63]
	v_mfma_f32_16x16x32_bf16 v[52:55], v[164:167], v[172:175], v[52:55]
	v_mfma_f32_16x16x32_bf16 v[52:55], v[160:163], v[168:171], v[52:55]
	v_mfma_f32_16x16x32_bf16 v[36:39], v[160:163], v[176:179], v[36:39]
	v_mfma_f32_16x16x32_bf16 v[36:39], v[164:167], v[180:183], v[36:39]
	v_mfma_f32_16x16x32_bf16 v[44:47], v[156:159], v[180:183], v[44:47]
	v_mfma_f32_16x16x32_bf16 v[44:47], v[152:155], v[176:179], v[44:47]
	v_mfma_f32_16x16x32_bf16 v[28:31], v[152:155], v[184:187], v[28:31]
	v_mfma_f32_16x16x32_bf16 v[28:31], v[156:159], v[188:191], v[28:31]
	v_mfma_f32_16x16x32_bf16 v[20:23], v[164:167], v[188:191], v[20:23]
	v_mfma_f32_16x16x32_bf16 v[20:23], v[160:163], v[184:187], v[20:23]
	v_mfma_f32_16x16x32_bf16 v[4:7], v[160:163], v[192:195], v[4:7]
	v_mfma_f32_16x16x32_bf16 v[4:7], v[164:167], v[196:199], v[4:7]
	v_mfma_f32_16x16x32_bf16 v[12:15], v[156:159], v[196:199], v[12:15]
	v_mfma_f32_16x16x32_bf16 v[12:15], v[152:155], v[192:195], v[12:15]
	s_setprio 0
	s_barrier
; #define PG8_STAGE(bufoff, gbase, voff) do { _Pragma("unroll") for (int _i = 0; _i < 2; ++_i) \
;         __builtin_amdgcn_global_load_lds((const unsigned*)((const char*)(gbase) + (voff)[_i]), (LAS unsigned*)(lds + (bufoff) + ldsw + _i * 8192), 16, 0, 0); } while (0)
; #define PG8_LDA(dst, b, h) do { _Pragma("unroll") for (int m = 0; m < 4; ++m) _Pragma("unroll") for (int k = 0; k < 2; ++k) dst[m][k] = *(const LAS bf16x8*)(lds + PG8_SA(b, h) + aoff + m * 2048 + k * 1024); } while (0)
; #define PG8_LDB(dst, b, h) do { _Pragma("unroll") for (int n = 0; n < 2; ++n) _Pragma("unroll") for (int k = 0; k < 2; ++k) dst[n][k] = *(const LAS bf16x8*)(lds + PG8_SB(b, h) + boff + n * 2048 + k * 1024); } while (0)
; #define PG8_MMA(ai, bj, At, Bt) do { __builtin_amdgcn_s_setprio(1); _Pragma("unroll") for (int m = 0; m < 4; ++m) _Pragma("unroll") for (int n = 0; n < 2; ++n) _Pragma("unroll") for (int k = 0; k < 2; ++k) \
;         acc[ai][bj][m][n] = __builtin_amdgcn_mfma_f32_16x16x32_bf16(Bt[n][k], At[m][k], acc[ai][bj][m][n], 0, 0, 0); __builtin_amdgcn_s_setprio(0); } while (0)
; #define PG8_WAIT_V(n) asm volatile("s_waitcnt vmcnt(" #n ")" ::: "memory")
; #define PG8_WAIT_L(n) asm volatile("s_waitcnt lgkmcnt(" #n ")" ::: "memory")
; #define PG8_BAR __builtin_amdgcn_s_barrier()
; #define PG8_SCHED __builtin_amdgcn_sched_barrier(0)
; template <class Epi>
; DEVINL void gemm_phase(LAS unsigned char* lds, const Gemm g, const Order& S, const Epi& E) {
;     ...
;             PG8_STAGE(PG8_SB(0, 1), b2 + hstepB, voffB);
;             PG8_WAIT_V(6); PG8_BAR; PG8_MMA(1, 1, At, B1); PG8_BAR;
;             PG8_LDB(B0, 1, 0); PG8_SCHED; PG8_LDA(At, 1, 0); PG8_STAGE(PG8_SA(0, 1), a2 + hstepA, voffA);
;             PG8_WAIT_L(8); PG8_BAR; PG8_WAIT_L(0); PG8_MMA(0, 0, At, B0); PG8_BAR; PG8_SCHED;
;             PG8_LDB(B1, 1, 1); PG8_STAGE(PG8_SB(1, 0), b3, voffB);
	s_add_u32 s56, s26, 0x80000
	s_addc_u32 s57, s27, 0
	s_add_i32 s58, s48, s30
	v_lshl_add_u64 v[152:153], s[56:57], 0, v[132:133]
	s_mov_b32 m0, s58
	s_nop 0
	global_load_lds_dwordx4 v[152:153], off
	v_lshl_add_u64 v[152:153], s[56:57], 0, v[128:129]
	s_add_i32 m0, s58, 0x2000
	s_nop 0
	global_load_lds_dwordx4 v[152:153], off
	s_waitcnt vmcnt(6)
	s_barrier
	s_setprio 1
	v_mfma_f32_16x16x32_bf16 v[56:59], v[200:203], v[168:171], v[56:59]
	v_mfma_f32_16x16x32_bf16 v[56:59], v[204:207], v[172:175], v[56:59]
	v_mfma_f32_16x16x32_bf16 v[48:51], v[218:221], v[172:175], v[48:51]
	v_mfma_f32_16x16x32_bf16 v[48:51], v[208:211], v[168:171], v[48:51]
	v_mfma_f32_16x16x32_bf16 v[32:35], v[208:211], v[176:179], v[32:35]
	v_mfma_f32_16x16x32_bf16 v[32:35], v[218:221], v[180:183], v[32:35]
	v_mfma_f32_16x16x32_bf16 v[40:43], v[204:207], v[180:183], v[40:43]
	v_mfma_f32_16x16x32_bf16 v[40:43], v[200:203], v[176:179], v[40:43]
	v_mfma_f32_16x16x32_bf16 v[24:27], v[200:203], v[184:187], v[24:27]
	v_mfma_f32_16x16x32_bf16 v[24:27], v[204:207], v[188:191], v[24:27]
	v_mfma_f32_16x16x32_bf16 v[16:19], v[218:221], v[188:191], v[16:19]
	v_mfma_f32_16x16x32_bf16 v[16:19], v[208:211], v[184:187], v[16:19]
	v_mfma_f32_16x16x32_bf16 v[0:3], v[208:211], v[192:195], v[0:3]
	v_mfma_f32_16x16x32_bf16 v[0:3], v[218:221], v[196:199], v[0:3]
	v_mfma_f32_16x16x32_bf16 v[8:11], v[204:207], v[196:199], v[8:11]
	v_mfma_f32_16x16x32_bf16 v[8:11], v[200:203], v[192:195], v[8:11]
	s_setprio 0
	s_add_i32 s56, 16, 0x18000
	v_add_u32_e32 v164, s56, v147
	s_barrier
	ds_read_b128 v[152:155], v164
	ds_read_b128 v[156:159], v164 offset:1024
	ds_read_b128 v[160:163], v164 offset:2048
	ds_read_b128 v[164:167], v164 offset:3072
	s_add_u32 s28, s28, 0x80000
	s_addc_u32 s29, s29, 0
	s_mov_b32 m0, s38
	v_lshl_add_u64 v[200:201], s[28:29], 0, v[134:135]
	ds_read_b128 v[168:171], v150 offset:32768
	ds_read_b128 v[172:175], v150 offset:33792
	ds_read_b128 v[176:179], v150 offset:34816
	ds_read_b128 v[180:183], v150 offset:35840
	ds_read_b128 v[184:187], v150 offset:36864
	ds_read_b128 v[188:191], v150 offset:37888
	ds_read_b128 v[192:195], v150 offset:38912
	ds_read_b128 v[196:199], v150 offset:39936
	global_load_lds_dwordx4 v[200:201], off
	v_lshl_add_u64 v[200:201], s[28:29], 0, v[130:131]
	s_mov_b32 m0, s39
	s_nop 0
	global_load_lds_dwordx4 v[200:201], off
	s_waitcnt lgkmcnt(8)
	s_barrier
	s_waitcnt lgkmcnt(0)
	s_setprio 1
	s_waitcnt lgkmcnt(0)
	v_mfma_f32_16x16x32_bf16 v[124:127], v[152:155], v[168:171], v[124:127]
	v_mfma_f32_16x16x32_bf16 v[124:127], v[156:159], v[172:175], v[124:127]
	v_mfma_f32_16x16x32_bf16 v[116:119], v[164:167], v[172:175], v[116:119]
	v_mfma_f32_16x16x32_bf16 v[116:119], v[160:163], v[168:171], v[116:119]
	v_mfma_f32_16x16x32_bf16 v[100:103], v[160:163], v[176:179], v[100:103]
	v_mfma_f32_16x16x32_bf16 v[100:103], v[164:167], v[180:183], v[100:103]
	v_mfma_f32_16x16x32_bf16 v[108:111], v[156:159], v[180:183], v[108:111]
	v_mfma_f32_16x16x32_bf16 v[108:111], v[152:155], v[176:179], v[108:111]
	v_mfma_f32_16x16x32_bf16 v[92:95], v[152:155], v[184:187], v[92:95]
	v_mfma_f32_16x16x32_bf16 v[92:95], v[156:159], v[188:191], v[92:95]
	v_mfma_f32_16x16x32_bf16 v[84:87], v[164:167], v[188:191], v[84:87]
	v_mfma_f32_16x16x32_bf16 v[84:87], v[160:163], v[184:187], v[84:87]
	v_mfma_f32_16x16x32_bf16 v[68:71], v[160:163], v[192:195], v[68:71]
	v_mfma_f32_16x16x32_bf16 v[68:71], v[164:167], v[196:199], v[68:71]
	v_mfma_f32_16x16x32_bf16 v[76:79], v[156:159], v[196:199], v[76:79]
	v_mfma_f32_16x16x32_bf16 v[76:79], v[152:155], v[192:195], v[76:79]
	s_setprio 0
	s_barrier
	s_add_i32 s28, 16, 0x1c000
	s_add_i32 s29, s56, s30
	v_add_u32_e32 v214, s28, v147
	v_lshl_add_u64 v[144:145], v[144:145], 0, s[6:7]
	s_mov_b32 m0, s29
	ds_read_b128 v[200:203], v214
	ds_read_b128 v[204:207], v214 offset:1024
	ds_read_b128 v[208:211], v214 offset:2048
	ds_read_b128 v[218:221], v214 offset:3072
	global_load_lds_dwordx4 v[144:145], off
	v_lshl_add_u64 v[144:145], v[212:213], 0, s[6:7]
	s_add_i32 m0, s29, 0x2000
	s_nop 0
	global_load_lds_dwordx4 v[144:145], off
	s_barrier
; #define PG8_STAGE(bufoff, gbase, voff) do { _Pragma("unroll") for (int _i = 0; _i < 2; ++_i) \
;         __builtin_amdgcn_global_load_lds((const unsigned*)((const char*)(gbase) + (voff)[_i]), (LAS unsigned*)(lds + (bufoff) + ldsw + _i * 8192), 16, 0, 0); } while (0)
; #define PG8_LDA(dst, b, h) do { _Pragma("unroll") for (int m = 0; m < 4; ++m) _Pragma("unroll") for (int k = 0; k < 2; ++k) dst[m][k] = *(const LAS bf16x8*)(lds + PG8_SA(b, h) + aoff + m * 2048 + k * 1024); } while (0)
; #define PG8_LDB(dst, b, h) do { _Pragma("unroll") for (int n = 0; n < 2; ++n) _Pragma("unroll") for (int k = 0; k < 2; ++k) dst[n][k] = *(const LAS bf16x8*)(lds + PG8_SB(b, h) + boff + n * 2048 + k * 1024); } while (0)
; #define PG8_MMA(ai, bj, At, Bt) do { __builtin_amdgcn_s_setprio(1); _Pragma("unroll") for (int m = 0; m < 4; ++m) _Pragma("unroll") for (int n = 0; n < 2; ++n) _Pragma("unroll") for (int k = 0; k < 2; ++k) \
;         acc[ai][bj][m][n] = __builtin_amdgcn_mfma_f32_16x16x32_bf16(Bt[n][k], At[m][k], acc[ai][bj][m][n], 0, 0, 0); __builtin_amdgcn_s_setprio(0); } while (0)
; #define PG8_WAIT_V(n) asm volatile("s_waitcnt vmcnt(" #n ")" ::: "memory")
; #define PG8_WAIT_L(n) asm volatile("s_waitcnt lgkmcnt(" #n ")" ::: "memory")
; #define PG8_BAR __builtin_amdgcn_s_barrier()
; #define PG8_SCHED __builtin_amdgcn_sched_barrier(0)
; template <class Epi>
; DEVINL void gemm_phase(LAS unsigned char* lds, const Gemm g, const Order& S, const Epi& E) {
;     ...
;         for (int t = 0; t < nt; t += 2) {
;     ...
;             PG8_LDB(B1, 1, 1); PG8_STAGE(PG8_SB(1, 0), b3, voffB);
;             PG8_BAR; PG8_WAIT_L(0); PG8_MMA(0, 1, At, B1); PG8_BAR;
;             PG8_LDA(At, 1, 1); PG8_STAGE(PG8_SA(1, 0), a3, voffA);
;             PG8_BAR; PG8_WAIT_L(0); PG8_MMA(1, 0, At, B0); PG8_BAR; PG8_SCHED;
;             PG8_STAGE(PG8_SB(1, 1), b3 + hstepB, voffB);
;             PG8_WAIT_V(6); PG8_BAR; PG8_MMA(1, 1, At, B1); PG8_BAR;
	s_waitcnt lgkmcnt(0)
	s_setprio 1
	s_waitcnt lgkmcnt(0)
	v_mfma_f32_16x16x32_bf16 v[120:123], v[200:203], v[168:171], v[120:123]
	v_mfma_f32_16x16x32_bf16 v[120:123], v[204:207], v[172:175], v[120:123]
	v_mfma_f32_16x16x32_bf16 v[112:115], v[218:221], v[172:175], v[112:115]
	v_mfma_f32_16x16x32_bf16 v[112:115], v[208:211], v[168:171], v[112:115]
	v_mfma_f32_16x16x32_bf16 v[96:99], v[208:211], v[176:179], v[96:99]
	v_mfma_f32_16x16x32_bf16 v[96:99], v[218:221], v[180:183], v[96:99]
	v_mfma_f32_16x16x32_bf16 v[104:107], v[204:207], v[180:183], v[104:107]
	v_mfma_f32_16x16x32_bf16 v[104:107], v[200:203], v[176:179], v[104:107]
	v_mfma_f32_16x16x32_bf16 v[88:91], v[200:203], v[184:187], v[88:91]
	v_mfma_f32_16x16x32_bf16 v[88:91], v[204:207], v[188:191], v[88:91]
	v_mfma_f32_16x16x32_bf16 v[80:83], v[218:221], v[188:191], v[80:83]
	v_mfma_f32_16x16x32_bf16 v[80:83], v[208:211], v[184:187], v[80:83]
	v_mfma_f32_16x16x32_bf16 v[64:67], v[208:211], v[192:195], v[64:67]
	v_mfma_f32_16x16x32_bf16 v[64:67], v[218:221], v[196:199], v[64:67]
	v_mfma_f32_16x16x32_bf16 v[72:75], v[204:207], v[196:199], v[72:75]
	v_mfma_f32_16x16x32_bf16 v[72:75], v[200:203], v[192:195], v[72:75]
	s_setprio 0
	s_mov_b32 m0, s42
	v_lshl_add_u64 v[144:145], v[222:223], 0, s[6:7]
	s_barrier
	ds_read_b128 v[168:171], v150 offset:49152
	ds_read_b128 v[172:175], v150 offset:50176
	ds_read_b128 v[176:179], v150 offset:51200
	ds_read_b128 v[180:183], v150 offset:52224
	ds_read_b128 v[184:187], v150 offset:53248
	ds_read_b128 v[188:191], v150 offset:54272
	ds_read_b128 v[192:195], v150 offset:55296
	ds_read_b128 v[196:199], v150 offset:56320
	global_load_lds_dwordx4 v[144:145], off
	v_lshl_add_u64 v[144:145], v[224:225], 0, s[6:7]
	s_mov_b32 m0, s43
	s_nop 0
	global_load_lds_dwordx4 v[144:145], off
	s_barrier
	s_waitcnt lgkmcnt(0)
	s_setprio 1
	s_waitcnt lgkmcnt(0)
	v_mfma_f32_16x16x32_bf16 v[60:63], v[152:155], v[168:171], v[60:63]
	v_mfma_f32_16x16x32_bf16 v[60:63], v[156:159], v[172:175], v[60:63]
	v_mfma_f32_16x16x32_bf16 v[52:55], v[164:167], v[172:175], v[52:55]
	v_mfma_f32_16x16x32_bf16 v[52:55], v[160:163], v[168:171], v[52:55]
	v_mfma_f32_16x16x32_bf16 v[36:39], v[160:163], v[176:179], v[36:39]
	v_mfma_f32_16x16x32_bf16 v[36:39], v[164:167], v[180:183], v[36:39]
	v_mfma_f32_16x16x32_bf16 v[44:47], v[156:159], v[180:183], v[44:47]
	v_mfma_f32_16x16x32_bf16 v[44:47], v[152:155], v[176:179], v[44:47]
	v_mfma_f32_16x16x32_bf16 v[28:31], v[152:155], v[184:187], v[28:31]
	v_mfma_f32_16x16x32_bf16 v[28:31], v[156:159], v[188:191], v[28:31]
	v_mfma_f32_16x16x32_bf16 v[20:23], v[164:167], v[188:191], v[20:23]
	v_mfma_f32_16x16x32_bf16 v[20:23], v[160:163], v[184:187], v[20:23]
	v_mfma_f32_16x16x32_bf16 v[4:7], v[160:163], v[192:195], v[4:7]
	v_mfma_f32_16x16x32_bf16 v[4:7], v[164:167], v[196:199], v[4:7]
	v_mfma_f32_16x16x32_bf16 v[12:15], v[156:159], v[196:199], v[12:15]
	v_mfma_f32_16x16x32_bf16 v[12:15], v[152:155], v[192:195], v[12:15]
	s_setprio 0
	s_barrier
	s_add_u32 s26, s26, 0x80080
	s_addc_u32 s27, s27, 0
	s_add_i32 s28, s28, s30
	v_lshl_add_u64 v[144:145], s[26:27], 0, v[132:133]
	s_mov_b32 m0, s28
	s_nop 0
	global_load_lds_dwordx4 v[144:145], off
	v_lshl_add_u64 v[144:145], s[26:27], 0, v[128:129]
	s_add_i32 m0, s28, 0x2000
	s_nop 0
	global_load_lds_dwordx4 v[144:145], off
	s_waitcnt vmcnt(6)
	s_barrier
	s_setprio 1
	v_mfma_f32_16x16x32_bf16 v[56:59], v[200:203], v[168:171], v[56:59]
	v_mfma_f32_16x16x32_bf16 v[56:59], v[204:207], v[172:175], v[56:59]
	v_mfma_f32_16x16x32_bf16 v[48:51], v[218:221], v[172:175], v[48:51]
	v_mfma_f32_16x16x32_bf16 v[48:51], v[208:211], v[168:171], v[48:51]
	v_mfma_f32_16x16x32_bf16 v[32:35], v[208:211], v[176:179], v[32:35]
	v_mfma_f32_16x16x32_bf16 v[32:35], v[218:221], v[180:183], v[32:35]
	v_mfma_f32_16x16x32_bf16 v[40:43], v[204:207], v[180:183], v[40:43]
	v_mfma_f32_16x16x32_bf16 v[40:43], v[200:203], v[176:179], v[40:43]
	v_mfma_f32_16x16x32_bf16 v[24:27], v[200:203], v[184:187], v[24:27]
	v_mfma_f32_16x16x32_bf16 v[24:27], v[204:207], v[188:191], v[24:27]
	v_mfma_f32_16x16x32_bf16 v[16:19], v[218:221], v[188:191], v[16:19]
	v_mfma_f32_16x16x32_bf16 v[16:19], v[208:211], v[184:187], v[16:19]
	v_mfma_f32_16x16x32_bf16 v[0:3], v[208:211], v[192:195], v[0:3]
	v_mfma_f32_16x16x32_bf16 v[0:3], v[218:221], v[196:199], v[0:3]
	v_mfma_f32_16x16x32_bf16 v[8:11], v[204:207], v[196:199], v[8:11]
	v_mfma_f32_16x16x32_bf16 v[8:11], v[200:203], v[192:195], v[8:11]
	s_setprio 0
	s_add_u32 s24, s24, 0x100
	s_addc_u32 s25, s25, 0
	s_add_u32 s53, s53, 0x100
	s_addc_u32 s54, s54, 0
	s_cmp_ge_i32 s55, s41
	s_mov_b32 s26, s55
	s_barrier
	s_cbranch_scc0 .LBB0_1775
	s_branch .LBB0_1770

; #define PG8_STAGE(bufoff, gbase, voff) do { _Pragma("unroll") for (int _i = 0; _i < 2; ++_i) \
;         __builtin_amdgcn_global_load_lds((const unsigned*)((const char*)(gbase) + (voff)[_i]), (LAS unsigned*)(lds + (bufoff) + ldsw + _i * 8192), 16, 0, 0); } while (0)
; #define PG8_LDA(dst, b, h) do { _Pragma("unroll") for (int m = 0; m < 4; ++m) _Pragma("unroll") for (int k = 0; k < 2; ++k) dst[m][k] = *(const LAS bf16x8*)(lds + PG8_SA(b, h) + aoff + m * 2048 + k * 1024); } while (0)
; #define PG8_LDB(dst, b, h) do { _Pragma("unroll") for (int n = 0; n < 2; ++n) _Pragma("unroll") for (int k = 0; k < 2; ++k) dst[n][k] = *(const LAS bf16x8*)(lds + PG8_SB(b, h) + boff + n * 2048 + k * 1024); } while (0)
; #define PG8_MMA(ai, bj, At, Bt) do { __builtin_amdgcn_s_setprio(1); _Pragma("unroll") for (int m = 0; m < 4; ++m) _Pragma("unroll") for (int n = 0; n < 2; ++n) _Pragma("unroll") for (int k = 0; k < 2; ++k) \
;         acc[ai][bj][m][n] = __builtin_amdgcn_mfma_f32_16x16x32_bf16(Bt[n][k], At[m][k], acc[ai][bj][m][n], 0, 0, 0); __builtin_amdgcn_s_setprio(0); } while (0)
; #define PG8_WAIT_L(n) asm volatile("s_waitcnt lgkmcnt(" #n ")" ::: "memory")
; #define PG8_BAR __builtin_amdgcn_s_barrier()
; #define PG8_SCHED __builtin_amdgcn_sched_barrier(0)
; template <class Epi>
; DEVINL void gemm_phase(LAS unsigned char* lds, const Gemm g, const Order& S, const Epi& E) {
;     ...
;             const char* a1 = cA + (size_t)(t + 1) * kstep;
;             const char* a2 = last ? nA : cA + (size_t)(t + 2) * kstep; const char* b2 = last ? nB : cB + (size_t)(t + 2) * kstep;
;             const char* a3 = a2 + kstep; const char* b3 = b2 + kstep;
;             PG8_LDB(B0, 0, 0); PG8_SCHED; PG8_LDA(At, 0, 0); PG8_STAGE(PG8_SA(1, 1), a1 + hstepA, voffA);
;             PG8_WAIT_L(8); PG8_BAR; PG8_WAIT_L(0); PG8_MMA(0, 0, At, B0); PG8_BAR; PG8_SCHED;
;             PG8_LDB(B1, 0, 1); PG8_STAGE(PG8_SB(0, 0), b2, voffB);
;             PG8_BAR; PG8_WAIT_L(0); PG8_MMA(0, 1, At, B1); PG8_BAR;
;             PG8_LDA(At, 0, 1); PG8_STAGE(PG8_SA(0, 0), a2, voffA);
;             PG8_BAR; PG8_WAIT_L(0); PG8_MMA(1, 0, At, B0); PG8_BAR; PG8_SCHED;
.LBB0_1852:
	ds_read_b128 v[150:153], v147
	ds_read_b128 v[154:157], v147 offset:1024
	ds_read_b128 v[158:161], v147 offset:2048
	ds_read_b128 v[162:165], v147 offset:3072
	s_add_i32 s61, s28, 2
	s_add_u32 s26, s24, 0x100
	s_addc_u32 s27, s25, 0
	s_cmp_eq_u32 s45, s28
	s_cselect_b32 s28, s4, s59
	s_cselect_b32 s31, s3, s27
	s_cselect_b32 s30, s2, s26
	s_cselect_b32 s29, s5, s60
	v_lshl_add_u64 v[198:199], s[24:25], 0, v[136:137]
	s_add_i32 m0, s38, 0xc000
	ds_read_b128 v[166:169], v148
	ds_read_b128 v[170:173], v148 offset:1024
	ds_read_b128 v[174:177], v148 offset:2048
	ds_read_b128 v[178:181], v148 offset:3072
	ds_read_b128 v[182:185], v148 offset:4096
	ds_read_b128 v[186:189], v148 offset:5120
	ds_read_b128 v[190:193], v148 offset:6144
	ds_read_b128 v[194:197], v148 offset:7168
	global_load_lds_dwordx4 v[198:199], off
	v_lshl_add_u64 v[198:199], s[24:25], 0, v[138:139]
	s_add_i32 m0, s38, 0xe000
	s_nop 0
	global_load_lds_dwordx4 v[198:199], off
	s_waitcnt lgkmcnt(8)
	s_barrier
	s_waitcnt lgkmcnt(0)
	s_setprio 1
	s_waitcnt lgkmcnt(0)
	v_mfma_f32_16x16x32_bf16 v[120:123], v[150:153], v[166:169], v[120:123]
	v_mfma_f32_16x16x32_bf16 v[120:123], v[154:157], v[170:173], v[120:123]
	v_mfma_f32_16x16x32_bf16 v[124:127], v[162:165], v[170:173], v[124:127]
	v_mfma_f32_16x16x32_bf16 v[124:127], v[158:161], v[166:169], v[124:127]
	v_mfma_f32_16x16x32_bf16 v[104:107], v[158:161], v[174:177], v[104:107]
	v_mfma_f32_16x16x32_bf16 v[104:107], v[162:165], v[178:181], v[104:107]
	v_mfma_f32_16x16x32_bf16 v[108:111], v[154:157], v[178:181], v[108:111]
	v_mfma_f32_16x16x32_bf16 v[108:111], v[150:153], v[174:177], v[108:111]
	v_mfma_f32_16x16x32_bf16 v[92:95], v[150:153], v[182:185], v[92:95]
	v_mfma_f32_16x16x32_bf16 v[92:95], v[154:157], v[186:189], v[92:95]
	v_mfma_f32_16x16x32_bf16 v[88:91], v[162:165], v[186:189], v[88:91]
	v_mfma_f32_16x16x32_bf16 v[88:91], v[158:161], v[182:185], v[88:91]
	v_mfma_f32_16x16x32_bf16 v[72:75], v[158:161], v[190:193], v[72:75]
	v_mfma_f32_16x16x32_bf16 v[72:75], v[162:165], v[194:197], v[72:75]
	v_mfma_f32_16x16x32_bf16 v[76:79], v[154:157], v[194:197], v[76:79]
	v_mfma_f32_16x16x32_bf16 v[76:79], v[150:153], v[190:193], v[76:79]
	s_setprio 0
	s_barrier
	s_add_i32 s24, s49, s37
	v_lshl_add_u64 v[218:219], s[28:29], 0, v[130:131]
	s_mov_b32 m0, s24
	ds_read_b128 v[198:201], v149
	ds_read_b128 v[202:205], v149 offset:1024
	ds_read_b128 v[206:209], v149 offset:2048
	ds_read_b128 v[210:213], v149 offset:3072
	global_load_lds_dwordx4 v[218:219], off
	v_lshl_add_u64 v[220:221], s[28:29], 0, v[134:135]
	s_add_i32 m0, s24, 0x2000
	s_nop 0
	global_load_lds_dwordx4 v[220:221], off
	s_barrier
	s_waitcnt lgkmcnt(0)
	s_setprio 1
	s_waitcnt lgkmcnt(0)
	v_mfma_f32_16x16x32_bf16 v[116:119], v[198:201], v[166:169], v[116:119]
	v_mfma_f32_16x16x32_bf16 v[116:119], v[202:205], v[170:173], v[116:119]
	v_mfma_f32_16x16x32_bf16 v[112:115], v[210:213], v[170:173], v[112:115]
	v_mfma_f32_16x16x32_bf16 v[112:115], v[206:209], v[166:169], v[112:115]
	v_mfma_f32_16x16x32_bf16 v[96:99], v[206:209], v[174:177], v[96:99]
	v_mfma_f32_16x16x32_bf16 v[96:99], v[210:213], v[178:181], v[96:99]
	v_mfma_f32_16x16x32_bf16 v[100:103], v[202:205], v[178:181], v[100:103]
	v_mfma_f32_16x16x32_bf16 v[100:103], v[198:201], v[174:177], v[100:103]
	v_mfma_f32_16x16x32_bf16 v[84:87], v[198:201], v[182:185], v[84:87]
	v_mfma_f32_16x16x32_bf16 v[84:87], v[202:205], v[186:189], v[84:87]
	v_mfma_f32_16x16x32_bf16 v[80:83], v[210:213], v[186:189], v[80:83]
	v_mfma_f32_16x16x32_bf16 v[80:83], v[206:209], v[182:185], v[80:83]
	v_mfma_f32_16x16x32_bf16 v[64:67], v[206:209], v[190:193], v[64:67]
	v_mfma_f32_16x16x32_bf16 v[64:67], v[210:213], v[194:197], v[64:67]
	v_mfma_f32_16x16x32_bf16 v[68:71], v[202:205], v[194:197], v[68:71]
	v_mfma_f32_16x16x32_bf16 v[68:71], v[198:201], v[190:193], v[68:71]
	s_setprio 0
	s_mov_b32 m0, s38
	v_lshl_add_u64 v[222:223], s[30:31], 0, v[128:129]
	s_barrier
	ds_read_b128 v[166:169], v148 offset:16384
	ds_read_b128 v[170:173], v148 offset:17408
	ds_read_b128 v[174:177], v148 offset:18432
	ds_read_b128 v[178:181], v148 offset:19456
	ds_read_b128 v[182:185], v148 offset:20480
	ds_read_b128 v[186:189], v148 offset:21504
	ds_read_b128 v[190:193], v148 offset:22528
	ds_read_b128 v[194:197], v148 offset:23552
	global_load_lds_dwordx4 v[222:223], off
	v_lshl_add_u64 v[224:225], s[30:31], 0, v[132:133]
	s_mov_b32 m0, s39
	s_nop 0
	global_load_lds_dwordx4 v[224:225], off
	s_barrier
	s_waitcnt lgkmcnt(0)
	s_setprio 1
	s_waitcnt lgkmcnt(0)
	v_mfma_f32_16x16x32_bf16 v[60:63], v[150:153], v[166:169], v[60:63]
	v_mfma_f32_16x16x32_bf16 v[60:63], v[154:157], v[170:173], v[60:63]
	v_mfma_f32_16x16x32_bf16 v[56:59], v[162:165], v[170:173], v[56:59]
	v_mfma_f32_16x16x32_bf16 v[56:59], v[158:161], v[166:169], v[56:59]
	v_mfma_f32_16x16x32_bf16 v[40:43], v[158:161], v[174:177], v[40:43]
	v_mfma_f32_16x16x32_bf16 v[40:43], v[162:165], v[178:181], v[40:43]
	v_mfma_f32_16x16x32_bf16 v[44:47], v[154:157], v[178:181], v[44:47]
	v_mfma_f32_16x16x32_bf16 v[44:47], v[150:153], v[174:177], v[44:47]
	v_mfma_f32_16x16x32_bf16 v[28:31], v[150:153], v[182:185], v[28:31]
	v_mfma_f32_16x16x32_bf16 v[28:31], v[154:157], v[186:189], v[28:31]
	v_mfma_f32_16x16x32_bf16 v[24:27], v[162:165], v[186:189], v[24:27]
	v_mfma_f32_16x16x32_bf16 v[24:27], v[158:161], v[182:185], v[24:27]
	v_mfma_f32_16x16x32_bf16 v[8:11], v[158:161], v[190:193], v[8:11]
	v_mfma_f32_16x16x32_bf16 v[8:11], v[162:165], v[194:197], v[8:11]
	v_mfma_f32_16x16x32_bf16 v[12:15], v[154:157], v[194:197], v[12:15]
	v_mfma_f32_16x16x32_bf16 v[12:15], v[150:153], v[190:193], v[12:15]
	s_setprio 0
	s_barrier
; #define PG8_STAGE(bufoff, gbase, voff) do { _Pragma("unroll") for (int _i = 0; _i < 2; ++_i) \
;         __builtin_amdgcn_global_load_lds((const unsigned*)((const char*)(gbase) + (voff)[_i]), (LAS unsigned*)(lds + (bufoff) + ldsw + _i * 8192), 16, 0, 0); } while (0)
; #define PG8_LDA(dst, b, h) do { _Pragma("unroll") for (int m = 0; m < 4; ++m) _Pragma("unroll") for (int k = 0; k < 2; ++k) dst[m][k] = *(const LAS bf16x8*)(lds + PG8_SA(b, h) + aoff + m * 2048 + k * 1024); } while (0)
; #define PG8_LDB(dst, b, h) do { _Pragma("unroll") for (int n = 0; n < 2; ++n) _Pragma("unroll") for (int k = 0; k < 2; ++k) dst[n][k] = *(const LAS bf16x8*)(lds + PG8_SB(b, h) + boff + n * 2048 + k * 1024); } while (0)
; #define PG8_MMA(ai, bj, At, Bt) do { __builtin_amdgcn_s_setprio(1); _Pragma("unroll") for (int m = 0; m < 4; ++m) _Pragma("unroll") for (int n = 0; n < 2; ++n) _Pragma("unroll") for (int k = 0; k < 2; ++k) \
;         acc[ai][bj][m][n] = __builtin_amdgcn_mfma_f32_16x16x32_bf16(Bt[n][k], At[m][k], acc[ai][bj][m][n], 0, 0, 0); __builtin_amdgcn_s_setprio(0); } while (0)
; #define PG8_WAIT_V(n) asm volatile("s_waitcnt vmcnt(" #n ")" ::: "memory")
; #define PG8_WAIT_L(n) asm volatile("s_waitcnt lgkmcnt(" #n ")" ::: "memory")
; #define PG8_BAR __builtin_amdgcn_s_barrier()
; #define PG8_SCHED __builtin_amdgcn_sched_barrier(0)
; template <class Epi>
; DEVINL void gemm_phase(LAS unsigned char* lds, const Gemm g, const Order& S, const Epi& E) {
;     ...
;             PG8_STAGE(PG8_SB(0, 1), b2 + hstepB, voffB);
;             PG8_WAIT_V(6); PG8_BAR; PG8_MMA(1, 1, At, B1); PG8_BAR;
;             PG8_LDB(B0, 1, 0); PG8_SCHED; PG8_LDA(At, 1, 0); PG8_STAGE(PG8_SA(0, 1), a2 + hstepA, voffA);
;             PG8_WAIT_L(8); PG8_BAR; PG8_WAIT_L(0); PG8_MMA(0, 0, At, B0); PG8_BAR; PG8_SCHED;
;             PG8_LDB(B1, 1, 1); PG8_STAGE(PG8_SB(1, 0), b3, voffB);
	s_add_u32 s24, s28, 0x158000
	s_addc_u32 s25, s29, 0
	s_add_i32 s62, s50, s37
	v_lshl_add_u64 v[150:151], s[24:25], 0, v[130:131]
	s_mov_b32 m0, s62
	s_nop 0
	global_load_lds_dwordx4 v[150:151], off
	v_lshl_add_u64 v[150:151], s[24:25], 0, v[134:135]
	s_add_i32 m0, s62, 0x2000
	s_nop 0
	global_load_lds_dwordx4 v[150:151], off
	s_waitcnt vmcnt(6)
	s_barrier
	s_setprio 1
	v_mfma_f32_16x16x32_bf16 v[52:55], v[198:201], v[166:169], v[52:55]
	v_mfma_f32_16x16x32_bf16 v[52:55], v[202:205], v[170:173], v[52:55]
	v_mfma_f32_16x16x32_bf16 v[48:51], v[210:213], v[170:173], v[48:51]
	v_mfma_f32_16x16x32_bf16 v[48:51], v[206:209], v[166:169], v[48:51]
	v_mfma_f32_16x16x32_bf16 v[32:35], v[206:209], v[174:177], v[32:35]
	v_mfma_f32_16x16x32_bf16 v[32:35], v[210:213], v[178:181], v[32:35]
	v_mfma_f32_16x16x32_bf16 v[36:39], v[202:205], v[178:181], v[36:39]
	v_mfma_f32_16x16x32_bf16 v[36:39], v[198:201], v[174:177], v[36:39]
	v_mfma_f32_16x16x32_bf16 v[20:23], v[198:201], v[182:185], v[20:23]
	v_mfma_f32_16x16x32_bf16 v[20:23], v[202:205], v[186:189], v[20:23]
	v_mfma_f32_16x16x32_bf16 v[16:19], v[210:213], v[186:189], v[16:19]
	v_mfma_f32_16x16x32_bf16 v[16:19], v[206:209], v[182:185], v[16:19]
	v_mfma_f32_16x16x32_bf16 v[0:3], v[206:209], v[190:193], v[0:3]
	v_mfma_f32_16x16x32_bf16 v[0:3], v[210:213], v[194:197], v[0:3]
	v_mfma_f32_16x16x32_bf16 v[4:7], v[202:205], v[194:197], v[4:7]
	v_mfma_f32_16x16x32_bf16 v[4:7], v[198:201], v[190:193], v[4:7]
	s_setprio 0
	s_add_i32 s62, 16, 0x18000
	v_add_u32_e32 v162, s62, v145
	s_barrier
	ds_read_b128 v[150:153], v162
	ds_read_b128 v[154:157], v162 offset:1024
	ds_read_b128 v[158:161], v162 offset:2048
	ds_read_b128 v[162:165], v162 offset:3072
	s_add_u32 s24, s30, 0x158000
	s_addc_u32 s25, s31, 0
	s_mov_b32 m0, s40
	v_lshl_add_u64 v[198:199], s[24:25], 0, v[128:129]
	ds_read_b128 v[166:169], v148 offset:32768
	ds_read_b128 v[170:173], v148 offset:33792
	ds_read_b128 v[174:177], v148 offset:34816
	ds_read_b128 v[178:181], v148 offset:35840
	ds_read_b128 v[182:185], v148 offset:36864
	ds_read_b128 v[186:189], v148 offset:37888
	ds_read_b128 v[190:193], v148 offset:38912
	ds_read_b128 v[194:197], v148 offset:39936
	global_load_lds_dwordx4 v[198:199], off
	v_lshl_add_u64 v[198:199], s[24:25], 0, v[132:133]
	s_mov_b32 m0, s41
	s_nop 0
	global_load_lds_dwordx4 v[198:199], off
	s_waitcnt lgkmcnt(8)
	s_barrier
	s_waitcnt lgkmcnt(0)
	s_setprio 1
	s_waitcnt lgkmcnt(0)
	v_mfma_f32_16x16x32_bf16 v[120:123], v[150:153], v[166:169], v[120:123]
	v_mfma_f32_16x16x32_bf16 v[120:123], v[154:157], v[170:173], v[120:123]
	v_mfma_f32_16x16x32_bf16 v[124:127], v[162:165], v[170:173], v[124:127]
	v_mfma_f32_16x16x32_bf16 v[124:127], v[158:161], v[166:169], v[124:127]
	v_mfma_f32_16x16x32_bf16 v[104:107], v[158:161], v[174:177], v[104:107]
	v_mfma_f32_16x16x32_bf16 v[104:107], v[162:165], v[178:181], v[104:107]
	v_mfma_f32_16x16x32_bf16 v[108:111], v[154:157], v[178:181], v[108:111]
	v_mfma_f32_16x16x32_bf16 v[108:111], v[150:153], v[174:177], v[108:111]
	v_mfma_f32_16x16x32_bf16 v[92:95], v[150:153], v[182:185], v[92:95]
	v_mfma_f32_16x16x32_bf16 v[92:95], v[154:157], v[186:189], v[92:95]
	v_mfma_f32_16x16x32_bf16 v[88:91], v[162:165], v[186:189], v[88:91]
	v_mfma_f32_16x16x32_bf16 v[88:91], v[158:161], v[182:185], v[88:91]
	v_mfma_f32_16x16x32_bf16 v[72:75], v[158:161], v[190:193], v[72:75]
	v_mfma_f32_16x16x32_bf16 v[72:75], v[162:165], v[194:197], v[72:75]
	v_mfma_f32_16x16x32_bf16 v[76:79], v[154:157], v[194:197], v[76:79]
	v_mfma_f32_16x16x32_bf16 v[76:79], v[150:153], v[190:193], v[76:79]
	s_setprio 0
	s_barrier
	s_add_i32 s30, 16, 0x1c000
	s_add_i32 s24, s62, s37
	v_add_u32_e32 v210, s30, v145
	v_lshl_add_u64 v[218:219], v[218:219], 0, s[6:7]
	s_mov_b32 m0, s24
	ds_read_b128 v[198:201], v210
	ds_read_b128 v[202:205], v210 offset:1024
	ds_read_b128 v[206:209], v210 offset:2048
	ds_read_b128 v[210:213], v210 offset:3072
	global_load_lds_dwordx4 v[218:219], off
	v_lshl_add_u64 v[218:219], v[220:221], 0, s[6:7]
	s_add_i32 m0, s24, 0x2000
	s_nop 0
	global_load_lds_dwordx4 v[218:219], off
	s_barrier
; #define PG8_STAGE(bufoff, gbase, voff) do { _Pragma("unroll") for (int _i = 0; _i < 2; ++_i) \
;         __builtin_amdgcn_global_load_lds((const unsigned*)((const char*)(gbase) + (voff)[_i]), (LAS unsigned*)(lds + (bufoff) + ldsw + _i * 8192), 16, 0, 0); } while (0)
; #define PG8_LDA(dst, b, h) do { _Pragma("unroll") for (int m = 0; m < 4; ++m) _Pragma("unroll") for (int k = 0; k < 2; ++k) dst[m][k] = *(const LAS bf16x8*)(lds + PG8_SA(b, h) + aoff + m * 2048 + k * 1024); } while (0)
; #define PG8_LDB(dst, b, h) do { _Pragma("unroll") for (int n = 0; n < 2; ++n) _Pragma("unroll") for (int k = 0; k < 2; ++k) dst[n][k] = *(const LAS bf16x8*)(lds + PG8_SB(b, h) + boff + n * 2048 + k * 1024); } while (0)
; #define PG8_MMA(ai, bj, At, Bt) do { __builtin_amdgcn_s_setprio(1); _Pragma("unroll") for (int m = 0; m < 4; ++m) _Pragma("unroll") for (int n = 0; n < 2; ++n) _Pragma("unroll") for (int k = 0; k < 2; ++k) \
;         acc[ai][bj][m][n] = __builtin_amdgcn_mfma_f32_16x16x32_bf16(Bt[n][k], At[m][k], acc[ai][bj][m][n], 0, 0, 0); __builtin_amdgcn_s_setprio(0); } while (0)
; #define PG8_WAIT_V(n) asm volatile("s_waitcnt vmcnt(" #n ")" ::: "memory")
; #define PG8_WAIT_L(n) asm volatile("s_waitcnt lgkmcnt(" #n ")" ::: "memory")
; #define PG8_BAR __builtin_amdgcn_s_barrier()
; #define PG8_SCHED __builtin_amdgcn_sched_barrier(0)
; template <class Epi>
; DEVINL void gemm_phase(LAS unsigned char* lds, const Gemm g, const Order& S, const Epi& E) {
;     ...
;         for (int t = 0; t < nt; t += 2) {
;     ...
;             PG8_LDB(B1, 1, 1); PG8_STAGE(PG8_SB(1, 0), b3, voffB);
;             PG8_BAR; PG8_WAIT_L(0); PG8_MMA(0, 1, At, B1); PG8_BAR;
;             PG8_LDA(At, 1, 1); PG8_STAGE(PG8_SA(1, 0), a3, voffA);
;             PG8_BAR; PG8_WAIT_L(0); PG8_MMA(1, 0, At, B0); PG8_BAR; PG8_SCHED;
;             PG8_STAGE(PG8_SB(1, 1), b3 + hstepB, voffB);
;             PG8_WAIT_V(6); PG8_BAR; PG8_MMA(1, 1, At, B1); PG8_BAR;
	s_waitcnt lgkmcnt(0)
	s_setprio 1
	s_waitcnt lgkmcnt(0)
	v_mfma_f32_16x16x32_bf16 v[116:119], v[198:201], v[166:169], v[116:119]
	v_mfma_f32_16x16x32_bf16 v[116:119], v[202:205], v[170:173], v[116:119]
	v_mfma_f32_16x16x32_bf16 v[112:115], v[210:213], v[170:173], v[112:115]
	v_mfma_f32_16x16x32_bf16 v[112:115], v[206:209], v[166:169], v[112:115]
	v_mfma_f32_16x16x32_bf16 v[96:99], v[206:209], v[174:177], v[96:99]
	v_mfma_f32_16x16x32_bf16 v[96:99], v[210:213], v[178:181], v[96:99]
	v_mfma_f32_16x16x32_bf16 v[100:103], v[202:205], v[178:181], v[100:103]
	v_mfma_f32_16x16x32_bf16 v[100:103], v[198:201], v[174:177], v[100:103]
	v_mfma_f32_16x16x32_bf16 v[84:87], v[198:201], v[182:185], v[84:87]
	v_mfma_f32_16x16x32_bf16 v[84:87], v[202:205], v[186:189], v[84:87]
	v_mfma_f32_16x16x32_bf16 v[80:83], v[210:213], v[186:189], v[80:83]
	v_mfma_f32_16x16x32_bf16 v[80:83], v[206:209], v[182:185], v[80:83]
	v_mfma_f32_16x16x32_bf16 v[64:67], v[206:209], v[190:193], v[64:67]
	v_mfma_f32_16x16x32_bf16 v[64:67], v[210:213], v[194:197], v[64:67]
	v_mfma_f32_16x16x32_bf16 v[68:71], v[202:205], v[194:197], v[68:71]
	v_mfma_f32_16x16x32_bf16 v[68:71], v[198:201], v[190:193], v[68:71]
	s_setprio 0
	s_mov_b32 m0, s43
	v_lshl_add_u64 v[218:219], v[222:223], 0, s[6:7]
	s_barrier
	ds_read_b128 v[166:169], v148 offset:49152
	ds_read_b128 v[170:173], v148 offset:50176
	ds_read_b128 v[174:177], v148 offset:51200
	ds_read_b128 v[178:181], v148 offset:52224
	ds_read_b128 v[182:185], v148 offset:53248
	ds_read_b128 v[186:189], v148 offset:54272
	ds_read_b128 v[190:193], v148 offset:55296
	ds_read_b128 v[194:197], v148 offset:56320
	global_load_lds_dwordx4 v[218:219], off
	v_lshl_add_u64 v[218:219], v[224:225], 0, s[6:7]
	s_mov_b32 m0, s44
	s_nop 0
	global_load_lds_dwordx4 v[218:219], off
	s_barrier
	s_waitcnt lgkmcnt(0)
	s_setprio 1
	s_waitcnt lgkmcnt(0)
	v_mfma_f32_16x16x32_bf16 v[60:63], v[150:153], v[166:169], v[60:63]
	v_mfma_f32_16x16x32_bf16 v[60:63], v[154:157], v[170:173], v[60:63]
	v_mfma_f32_16x16x32_bf16 v[56:59], v[162:165], v[170:173], v[56:59]
	v_mfma_f32_16x16x32_bf16 v[56:59], v[158:161], v[166:169], v[56:59]
	v_mfma_f32_16x16x32_bf16 v[40:43], v[158:161], v[174:177], v[40:43]
	v_mfma_f32_16x16x32_bf16 v[40:43], v[162:165], v[178:181], v[40:43]
	v_mfma_f32_16x16x32_bf16 v[44:47], v[154:157], v[178:181], v[44:47]
	v_mfma_f32_16x16x32_bf16 v[44:47], v[150:153], v[174:177], v[44:47]
	v_mfma_f32_16x16x32_bf16 v[28:31], v[150:153], v[182:185], v[28:31]
	v_mfma_f32_16x16x32_bf16 v[28:31], v[154:157], v[186:189], v[28:31]
	v_mfma_f32_16x16x32_bf16 v[24:27], v[162:165], v[186:189], v[24:27]
	v_mfma_f32_16x16x32_bf16 v[24:27], v[158:161], v[182:185], v[24:27]
	v_mfma_f32_16x16x32_bf16 v[8:11], v[158:161], v[190:193], v[8:11]
	v_mfma_f32_16x16x32_bf16 v[8:11], v[162:165], v[194:197], v[8:11]
	v_mfma_f32_16x16x32_bf16 v[12:15], v[154:157], v[194:197], v[12:15]
	v_mfma_f32_16x16x32_bf16 v[12:15], v[150:153], v[190:193], v[12:15]
	s_setprio 0
	s_barrier
	s_add_u32 s24, s28, 0x158080
	s_addc_u32 s25, s29, 0
	s_add_i32 s28, s30, s37
	v_lshl_add_u64 v[150:151], s[24:25], 0, v[130:131]
	s_mov_b32 m0, s28
	s_nop 0
	global_load_lds_dwordx4 v[150:151], off
	v_lshl_add_u64 v[150:151], s[24:25], 0, v[134:135]
	s_add_i32 m0, s28, 0x2000
	s_nop 0
	global_load_lds_dwordx4 v[150:151], off
	s_waitcnt vmcnt(6)
	s_barrier
	s_setprio 1
	v_mfma_f32_16x16x32_bf16 v[52:55], v[198:201], v[166:169], v[52:55]
	v_mfma_f32_16x16x32_bf16 v[52:55], v[202:205], v[170:173], v[52:55]
	v_mfma_f32_16x16x32_bf16 v[48:51], v[210:213], v[170:173], v[48:51]
	v_mfma_f32_16x16x32_bf16 v[48:51], v[206:209], v[166:169], v[48:51]
	v_mfma_f32_16x16x32_bf16 v[32:35], v[206:209], v[174:177], v[32:35]
	v_mfma_f32_16x16x32_bf16 v[32:35], v[210:213], v[178:181], v[32:35]
	v_mfma_f32_16x16x32_bf16 v[36:39], v[202:205], v[178:181], v[36:39]
	v_mfma_f32_16x16x32_bf16 v[36:39], v[198:201], v[174:177], v[36:39]
	v_mfma_f32_16x16x32_bf16 v[20:23], v[198:201], v[182:185], v[20:23]
	v_mfma_f32_16x16x32_bf16 v[20:23], v[202:205], v[186:189], v[20:23]
	v_mfma_f32_16x16x32_bf16 v[16:19], v[210:213], v[186:189], v[16:19]
	v_mfma_f32_16x16x32_bf16 v[16:19], v[206:209], v[182:185], v[16:19]
	v_mfma_f32_16x16x32_bf16 v[0:3], v[206:209], v[190:193], v[0:3]
	v_mfma_f32_16x16x32_bf16 v[0:3], v[210:213], v[194:197], v[0:3]
	v_mfma_f32_16x16x32_bf16 v[4:7], v[202:205], v[194:197], v[4:7]
	v_mfma_f32_16x16x32_bf16 v[4:7], v[198:201], v[190:193], v[4:7]
	s_setprio 0
	s_add_u32 s59, s59, 0x100
	s_addc_u32 s60, s60, 0
	s_cmp_ge_i32 s61, s42
	s_mov_b64 s[24:25], s[26:27]
	s_mov_b32 s28, s61
	s_barrier
	s_cbranch_scc0 .LBB0_1852
	s_branch .LBB0_1839
